# on top of v15: GEMM K-loops, duplicate lgkmcnt(0) after the pre-MFMA barrier dropped, s_setprio 1 raised before that barrier, s_setprio 0 lowered after the post-MFMA barrier (mid-block flip kept)
# speedup vs baseline: 1.0520x; 1.0023x over previous
.LBB0_274:
	ds_read_b128 v[146:149], v153
	ds_read_b128 v[156:159], v153 offset:1024
	ds_read_b128 v[160:163], v153 offset:2048
	ds_read_b128 v[164:167], v153 offset:3072
	ds_read_b128 v[168:171], v154
	ds_read_b128 v[172:175], v154 offset:1024
	ds_read_b128 v[176:179], v154 offset:2048
	ds_read_b128 v[180:183], v154 offset:3072
	s_add_u32 s34, s76, 0xfff80080
	s_addc_u32 s35, s77, -1
	s_cmp_eq_u32 s85, 28
	s_cselect_b32 s79, s0, s35
	s_cselect_b32 s78, s1, s34
	s_cselect_b32 s35, s67, s84
	s_cselect_b32 s34, s69, s83
	v_lshl_add_u64 v[218:219], s[76:77], 0, v[138:139]
	s_add_i32 m0, s54, 0xc000
	ds_read_b128 v[184:187], v155
	ds_read_b128 v[188:191], v155 offset:1024
	ds_read_b128 v[192:195], v155 offset:2048
	ds_read_b128 v[196:199], v155 offset:3072
	ds_read_b128 v[200:203], v155 offset:4096
	ds_read_b128 v[204:207], v155 offset:5120
	ds_read_b128 v[208:211], v155 offset:6144
	ds_read_b128 v[212:215], v155 offset:7168
	global_load_lds_dwordx4 v[218:219], off
	v_lshl_add_u64 v[218:219], s[76:77], 0, v[140:141]
	s_add_i32 m0, s54, 0xe000
	s_nop 0
	global_load_lds_dwordx4 v[218:219], off
	s_waitcnt vmcnt(8)
	s_waitcnt lgkmcnt(0)
	s_setprio 1
	s_barrier
	v_mfma_f32_16x16x32_bf16 v[126:129], v[146:149], v[184:187], v[126:129]
	v_mfma_f32_16x16x32_bf16 v[118:121], v[160:163], v[184:187], v[118:121]
	v_mfma_f32_16x16x32_bf16 v[110:113], v[146:149], v[192:195], v[110:113]
	v_mfma_f32_16x16x32_bf16 v[102:105], v[160:163], v[192:195], v[102:105]
	v_mfma_f32_16x16x32_bf16 v[94:97], v[146:149], v[200:203], v[94:97]
	v_mfma_f32_16x16x32_bf16 v[86:89], v[160:163], v[200:203], v[86:89]
	v_mfma_f32_16x16x32_bf16 v[78:81], v[146:149], v[208:211], v[78:81]
	v_mfma_f32_16x16x32_bf16 v[70:73], v[160:163], v[208:211], v[70:73]
	v_mfma_f32_16x16x32_bf16 v[126:129], v[156:159], v[188:191], v[126:129]
	v_mfma_f32_16x16x32_bf16 v[118:121], v[164:167], v[188:191], v[118:121]
	v_mfma_f32_16x16x32_bf16 v[110:113], v[156:159], v[196:199], v[110:113]
	v_mfma_f32_16x16x32_bf16 v[102:105], v[164:167], v[196:199], v[102:105]
	v_mfma_f32_16x16x32_bf16 v[94:97], v[156:159], v[204:207], v[94:97]
	v_mfma_f32_16x16x32_bf16 v[86:89], v[164:167], v[204:207], v[86:89]
	v_mfma_f32_16x16x32_bf16 v[78:81], v[156:159], v[212:215], v[78:81]
	v_mfma_f32_16x16x32_bf16 v[70:73], v[164:167], v[212:215], v[70:73]
	s_setprio 0
	s_setprio 1
	v_mfma_f32_16x16x32_bf16 v[122:125], v[168:171], v[184:187], v[122:125]
	v_mfma_f32_16x16x32_bf16 v[114:117], v[176:179], v[184:187], v[114:117]
	v_mfma_f32_16x16x32_bf16 v[106:109], v[168:171], v[192:195], v[106:109]
	v_mfma_f32_16x16x32_bf16 v[98:101], v[176:179], v[192:195], v[98:101]
	v_mfma_f32_16x16x32_bf16 v[90:93], v[168:171], v[200:203], v[90:93]
	v_mfma_f32_16x16x32_bf16 v[82:85], v[176:179], v[200:203], v[82:85]
	v_mfma_f32_16x16x32_bf16 v[74:77], v[168:171], v[208:211], v[74:77]
	v_mfma_f32_16x16x32_bf16 v[66:69], v[176:179], v[208:211], v[66:69]
	v_mfma_f32_16x16x32_bf16 v[122:125], v[172:175], v[188:191], v[122:125]
	v_mfma_f32_16x16x32_bf16 v[114:117], v[180:183], v[188:191], v[114:117]
	v_mfma_f32_16x16x32_bf16 v[106:109], v[172:175], v[196:199], v[106:109]
	v_mfma_f32_16x16x32_bf16 v[98:101], v[180:183], v[196:199], v[98:101]
	v_mfma_f32_16x16x32_bf16 v[90:93], v[172:175], v[204:207], v[90:93]
	v_mfma_f32_16x16x32_bf16 v[82:85], v[180:183], v[204:207], v[82:85]
	v_mfma_f32_16x16x32_bf16 v[74:77], v[172:175], v[212:215], v[74:77]
	v_mfma_f32_16x16x32_bf16 v[66:69], v[180:183], v[212:215], v[66:69]
	s_barrier
	s_setprio 0
	s_add_i32 s62, s75, s33
	v_lshl_add_u64 v[218:219], s[34:35], 0, v[134:135]
	s_mov_b32 m0, s62
	ds_read_b128 v[184:187], v155 offset:16384
	ds_read_b128 v[188:191], v155 offset:17408
	ds_read_b128 v[192:195], v155 offset:18432
	ds_read_b128 v[196:199], v155 offset:19456
	ds_read_b128 v[200:203], v155 offset:20480
	ds_read_b128 v[204:207], v155 offset:21504
	ds_read_b128 v[208:211], v155 offset:22528
	ds_read_b128 v[212:215], v155 offset:23552
	global_load_lds_dwordx4 v[218:219], off
	s_add_i32 m0, s62, 0x2000
	s_add_u32 s62, s34, 0x80000
	v_lshl_add_u64 v[220:221], s[34:35], 0, v[130:131]
	s_addc_u32 s63, s35, 0
	s_add_i32 s86, s80, s33
	global_load_lds_dwordx4 v[220:221], off
	v_lshl_add_u64 v[222:223], s[62:63], 0, v[134:135]
	s_mov_b32 m0, s86
	v_lshl_add_u64 v[224:225], s[78:79], 0, v[132:133]
	global_load_lds_dwordx4 v[222:223], off
	v_lshl_add_u64 v[222:223], s[62:63], 0, v[130:131]
	s_add_i32 m0, s86, 0x2000
	s_nop 0
	global_load_lds_dwordx4 v[222:223], off
	v_lshl_add_u64 v[222:223], s[78:79], 0, v[136:137]
	s_mov_b32 m0, s54
	s_nop 0
	global_load_lds_dwordx4 v[222:223], off
	s_mov_b32 m0, s55
	s_nop 0
	global_load_lds_dwordx4 v[224:225], off
	s_waitcnt vmcnt(8)
	s_waitcnt lgkmcnt(0)
	s_setprio 1
	s_barrier
	v_mfma_f32_16x16x32_bf16 v[62:65], v[146:149], v[184:187], v[62:65]
	v_mfma_f32_16x16x32_bf16 v[54:57], v[160:163], v[184:187], v[54:57]
	v_mfma_f32_16x16x32_bf16 v[46:49], v[146:149], v[192:195], v[46:49]
	v_mfma_f32_16x16x32_bf16 v[38:41], v[160:163], v[192:195], v[38:41]
	v_mfma_f32_16x16x32_bf16 v[30:33], v[146:149], v[200:203], v[30:33]
	v_mfma_f32_16x16x32_bf16 v[22:25], v[160:163], v[200:203], v[22:25]
	v_mfma_f32_16x16x32_bf16 v[14:17], v[146:149], v[208:211], v[14:17]
	v_mfma_f32_16x16x32_bf16 v[6:9], v[160:163], v[208:211], v[6:9]
	v_mfma_f32_16x16x32_bf16 v[62:65], v[156:159], v[188:191], v[62:65]
	v_mfma_f32_16x16x32_bf16 v[54:57], v[164:167], v[188:191], v[54:57]
	v_mfma_f32_16x16x32_bf16 v[46:49], v[156:159], v[196:199], v[46:49]
	v_mfma_f32_16x16x32_bf16 v[38:41], v[164:167], v[196:199], v[38:41]
	v_mfma_f32_16x16x32_bf16 v[30:33], v[156:159], v[204:207], v[30:33]
	v_mfma_f32_16x16x32_bf16 v[22:25], v[164:167], v[204:207], v[22:25]
	v_mfma_f32_16x16x32_bf16 v[14:17], v[156:159], v[212:215], v[14:17]
	v_mfma_f32_16x16x32_bf16 v[6:9], v[164:167], v[212:215], v[6:9]
	s_setprio 0
	s_setprio 1
	v_mfma_f32_16x16x32_bf16 v[58:61], v[168:171], v[184:187], v[58:61]
	v_mfma_f32_16x16x32_bf16 v[50:53], v[176:179], v[184:187], v[50:53]
	v_mfma_f32_16x16x32_bf16 v[42:45], v[168:171], v[192:195], v[42:45]
	v_mfma_f32_16x16x32_bf16 v[34:37], v[176:179], v[192:195], v[34:37]
	v_mfma_f32_16x16x32_bf16 v[26:29], v[168:171], v[200:203], v[26:29]
	v_mfma_f32_16x16x32_bf16 v[18:21], v[176:179], v[200:203], v[18:21]
	v_mfma_f32_16x16x32_bf16 v[10:13], v[168:171], v[208:211], v[10:13]
	v_mfma_f32_16x16x32_bf16 v[2:5], v[176:179], v[208:211], v[2:5]
	v_mfma_f32_16x16x32_bf16 v[58:61], v[172:175], v[188:191], v[58:61]
	v_mfma_f32_16x16x32_bf16 v[50:53], v[180:183], v[188:191], v[50:53]
	v_mfma_f32_16x16x32_bf16 v[42:45], v[172:175], v[196:199], v[42:45]
	v_mfma_f32_16x16x32_bf16 v[34:37], v[180:183], v[196:199], v[34:37]
	v_mfma_f32_16x16x32_bf16 v[26:29], v[172:175], v[204:207], v[26:29]
	v_mfma_f32_16x16x32_bf16 v[18:21], v[180:183], v[204:207], v[18:21]
	v_mfma_f32_16x16x32_bf16 v[10:13], v[172:175], v[212:215], v[10:13]
	v_mfma_f32_16x16x32_bf16 v[2:5], v[180:183], v[212:215], v[2:5]
	s_barrier
	s_setprio 0
	s_add_i32 s86, 0, 0x18000
	s_add_i32 s87, 0, 0x1c000
	v_add_u32_e32 v164, s86, v151
	v_add_u32_e32 v180, s87, v151
	ds_read_b128 v[146:149], v164
	ds_read_b128 v[156:159], v164 offset:1024
	ds_read_b128 v[160:163], v164 offset:2048
	ds_read_b128 v[164:167], v164 offset:3072
	ds_read_b128 v[168:171], v180
	ds_read_b128 v[172:175], v180 offset:1024
	ds_read_b128 v[176:179], v180 offset:2048
	ds_read_b128 v[180:183], v180 offset:3072
	s_add_u32 s62, s78, 0x80000
	s_addc_u32 s63, s79, 0
	s_mov_b32 m0, s56
	v_lshl_add_u64 v[226:227], s[62:63], 0, v[136:137]
	ds_read_b128 v[184:187], v155 offset:32768
	ds_read_b128 v[188:191], v155 offset:33792
	ds_read_b128 v[192:195], v155 offset:34816
	ds_read_b128 v[196:199], v155 offset:35840
	ds_read_b128 v[200:203], v155 offset:36864
	ds_read_b128 v[204:207], v155 offset:37888
	ds_read_b128 v[208:211], v155 offset:38912
	ds_read_b128 v[212:215], v155 offset:39936
	global_load_lds_dwordx4 v[226:227], off
	v_lshl_add_u64 v[226:227], s[62:63], 0, v[132:133]
	s_mov_b32 m0, s57
	s_nop 0
	global_load_lds_dwordx4 v[226:227], off
	s_waitcnt vmcnt(8)
	s_waitcnt lgkmcnt(0)
	s_setprio 1
	s_barrier
	v_mfma_f32_16x16x32_bf16 v[126:129], v[146:149], v[184:187], v[126:129]
	v_mfma_f32_16x16x32_bf16 v[118:121], v[160:163], v[184:187], v[118:121]
	v_mfma_f32_16x16x32_bf16 v[110:113], v[146:149], v[192:195], v[110:113]
	v_mfma_f32_16x16x32_bf16 v[102:105], v[160:163], v[192:195], v[102:105]
	v_mfma_f32_16x16x32_bf16 v[94:97], v[146:149], v[200:203], v[94:97]
	v_mfma_f32_16x16x32_bf16 v[86:89], v[160:163], v[200:203], v[86:89]
	v_mfma_f32_16x16x32_bf16 v[78:81], v[146:149], v[208:211], v[78:81]
	v_mfma_f32_16x16x32_bf16 v[70:73], v[160:163], v[208:211], v[70:73]
	v_mfma_f32_16x16x32_bf16 v[126:129], v[156:159], v[188:191], v[126:129]
	v_mfma_f32_16x16x32_bf16 v[118:121], v[164:167], v[188:191], v[118:121]
	v_mfma_f32_16x16x32_bf16 v[110:113], v[156:159], v[196:199], v[110:113]
	v_mfma_f32_16x16x32_bf16 v[102:105], v[164:167], v[196:199], v[102:105]
	v_mfma_f32_16x16x32_bf16 v[94:97], v[156:159], v[204:207], v[94:97]
	v_mfma_f32_16x16x32_bf16 v[86:89], v[164:167], v[204:207], v[86:89]
	v_mfma_f32_16x16x32_bf16 v[78:81], v[156:159], v[212:215], v[78:81]
	v_mfma_f32_16x16x32_bf16 v[70:73], v[164:167], v[212:215], v[70:73]
	s_setprio 0
	s_setprio 1
	v_mfma_f32_16x16x32_bf16 v[122:125], v[168:171], v[184:187], v[122:125]
	v_mfma_f32_16x16x32_bf16 v[114:117], v[176:179], v[184:187], v[114:117]
	v_mfma_f32_16x16x32_bf16 v[106:109], v[168:171], v[192:195], v[106:109]
	v_mfma_f32_16x16x32_bf16 v[98:101], v[176:179], v[192:195], v[98:101]
	v_mfma_f32_16x16x32_bf16 v[90:93], v[168:171], v[200:203], v[90:93]
	v_mfma_f32_16x16x32_bf16 v[82:85], v[176:179], v[200:203], v[82:85]
	v_mfma_f32_16x16x32_bf16 v[74:77], v[168:171], v[208:211], v[74:77]
	v_mfma_f32_16x16x32_bf16 v[66:69], v[176:179], v[208:211], v[66:69]
	v_mfma_f32_16x16x32_bf16 v[122:125], v[172:175], v[188:191], v[122:125]
	v_mfma_f32_16x16x32_bf16 v[114:117], v[180:183], v[188:191], v[114:117]
	v_mfma_f32_16x16x32_bf16 v[106:109], v[172:175], v[196:199], v[106:109]
	v_mfma_f32_16x16x32_bf16 v[98:101], v[180:183], v[196:199], v[98:101]
	v_mfma_f32_16x16x32_bf16 v[90:93], v[172:175], v[204:207], v[90:93]
	v_mfma_f32_16x16x32_bf16 v[82:85], v[180:183], v[204:207], v[82:85]
	v_mfma_f32_16x16x32_bf16 v[74:77], v[172:175], v[212:215], v[74:77]
	v_mfma_f32_16x16x32_bf16 v[66:69], v[180:183], v[212:215], v[66:69]
	s_barrier
	s_setprio 0
	s_add_i32 s62, s86, s33
	v_lshl_add_u64 v[218:219], v[218:219], 0, s[8:9]
	s_mov_b32 m0, s62
	ds_read_b128 v[184:187], v155 offset:49152
	ds_read_b128 v[188:191], v155 offset:50176
	ds_read_b128 v[192:195], v155 offset:51200
	ds_read_b128 v[196:199], v155 offset:52224
	ds_read_b128 v[200:203], v155 offset:53248
	ds_read_b128 v[204:207], v155 offset:54272
	ds_read_b128 v[208:211], v155 offset:55296
	ds_read_b128 v[212:215], v155 offset:56320
	global_load_lds_dwordx4 v[218:219], off
	s_add_i32 m0, s62, 0x2000
	s_add_u32 s34, s34, 0x80080
	v_lshl_add_u64 v[218:219], v[220:221], 0, s[8:9]
	s_addc_u32 s35, s35, 0
	s_add_i32 s62, s87, s33
	global_load_lds_dwordx4 v[218:219], off
	v_lshl_add_u64 v[218:219], s[34:35], 0, v[134:135]
	s_mov_b32 m0, s62
	s_nop 0
	global_load_lds_dwordx4 v[218:219], off
	v_lshl_add_u64 v[218:219], s[34:35], 0, v[130:131]
	s_add_i32 m0, s62, 0x2000
	s_nop 0
	global_load_lds_dwordx4 v[218:219], off
	v_lshl_add_u64 v[218:219], v[222:223], 0, s[8:9]
	s_mov_b32 m0, s59
	s_nop 0
	global_load_lds_dwordx4 v[218:219], off
	v_lshl_add_u64 v[218:219], v[224:225], 0, s[8:9]
	s_mov_b32 m0, s60
	s_nop 0
	global_load_lds_dwordx4 v[218:219], off
	s_waitcnt vmcnt(8)
	s_waitcnt lgkmcnt(0)
	s_setprio 1
	s_barrier
	v_mfma_f32_16x16x32_bf16 v[62:65], v[146:149], v[184:187], v[62:65]
	v_mfma_f32_16x16x32_bf16 v[54:57], v[160:163], v[184:187], v[54:57]
	v_mfma_f32_16x16x32_bf16 v[46:49], v[146:149], v[192:195], v[46:49]
	v_mfma_f32_16x16x32_bf16 v[38:41], v[160:163], v[192:195], v[38:41]
	v_mfma_f32_16x16x32_bf16 v[30:33], v[146:149], v[200:203], v[30:33]
	v_mfma_f32_16x16x32_bf16 v[22:25], v[160:163], v[200:203], v[22:25]
	v_mfma_f32_16x16x32_bf16 v[14:17], v[146:149], v[208:211], v[14:17]
	v_mfma_f32_16x16x32_bf16 v[6:9], v[160:163], v[208:211], v[6:9]
	v_mfma_f32_16x16x32_bf16 v[62:65], v[156:159], v[188:191], v[62:65]
	v_mfma_f32_16x16x32_bf16 v[54:57], v[164:167], v[188:191], v[54:57]
	v_mfma_f32_16x16x32_bf16 v[46:49], v[156:159], v[196:199], v[46:49]
	v_mfma_f32_16x16x32_bf16 v[38:41], v[164:167], v[196:199], v[38:41]
	v_mfma_f32_16x16x32_bf16 v[30:33], v[156:159], v[204:207], v[30:33]
	v_mfma_f32_16x16x32_bf16 v[22:25], v[164:167], v[204:207], v[22:25]
	v_mfma_f32_16x16x32_bf16 v[14:17], v[156:159], v[212:215], v[14:17]
	v_mfma_f32_16x16x32_bf16 v[6:9], v[164:167], v[212:215], v[6:9]
	s_setprio 0
	s_setprio 1
	v_mfma_f32_16x16x32_bf16 v[58:61], v[168:171], v[184:187], v[58:61]
	v_mfma_f32_16x16x32_bf16 v[50:53], v[176:179], v[184:187], v[50:53]
	v_mfma_f32_16x16x32_bf16 v[42:45], v[168:171], v[192:195], v[42:45]
	v_mfma_f32_16x16x32_bf16 v[34:37], v[176:179], v[192:195], v[34:37]
	v_mfma_f32_16x16x32_bf16 v[26:29], v[168:171], v[200:203], v[26:29]
	v_mfma_f32_16x16x32_bf16 v[18:21], v[176:179], v[200:203], v[18:21]
	v_mfma_f32_16x16x32_bf16 v[10:13], v[168:171], v[208:211], v[10:13]
	v_mfma_f32_16x16x32_bf16 v[2:5], v[176:179], v[208:211], v[2:5]
	v_mfma_f32_16x16x32_bf16 v[58:61], v[172:175], v[188:191], v[58:61]
	v_mfma_f32_16x16x32_bf16 v[50:53], v[180:183], v[188:191], v[50:53]
	v_mfma_f32_16x16x32_bf16 v[42:45], v[172:175], v[196:199], v[42:45]
	v_mfma_f32_16x16x32_bf16 v[34:37], v[180:183], v[196:199], v[34:37]
	v_mfma_f32_16x16x32_bf16 v[26:29], v[172:175], v[204:207], v[26:29]
	v_mfma_f32_16x16x32_bf16 v[18:21], v[180:183], v[204:207], v[18:21]
	v_mfma_f32_16x16x32_bf16 v[10:13], v[172:175], v[212:215], v[10:13]
	v_mfma_f32_16x16x32_bf16 v[2:5], v[180:183], v[212:215], v[2:5]
	s_barrier
	s_setprio 0
	s_add_i32 s85, s85, 2
	s_add_u32 s76, s76, 0x100
	s_addc_u32 s77, s77, 0
	s_add_u32 s83, s83, 0x100
	s_addc_u32 s84, s84, 0
	s_cmp_gt_u32 s85, 29
	s_cbranch_scc0 .LBB0_274
	s_and_b64 vcc, exec, s[64:65]
	s_cbranch_vccz .LBB0_277
	s_barrier

.LBB0_387:
	ds_read_b128 v[146:149], v154
	ds_read_b128 v[158:161], v154 offset:1024
	ds_read_b128 v[162:165], v154 offset:2048
	ds_read_b128 v[166:169], v154 offset:3072
	ds_read_b128 v[170:173], v155
	ds_read_b128 v[174:177], v155 offset:1024
	ds_read_b128 v[178:181], v155 offset:2048
	ds_read_b128 v[182:185], v155 offset:3072
	s_add_u32 s34, s72, 0xffea0080
	s_addc_u32 s35, s73, -1
	s_cmpk_eq_i32 s81, 0x54
	s_cselect_b32 s75, s5, s35
	s_cselect_b32 s74, s4, s34
	s_cselect_b32 s35, s71, s1
	s_cselect_b32 s34, s70, s0
	v_lshl_add_u64 v[150:151], s[72:73], 0, v[138:139]
	s_add_i32 m0, s53, 0xc000
	ds_read_b128 v[186:189], v156
	ds_read_b128 v[190:193], v156 offset:1024
	ds_read_b128 v[194:197], v156 offset:2048
	ds_read_b128 v[198:201], v156 offset:3072
	ds_read_b128 v[202:205], v156 offset:4096
	ds_read_b128 v[206:209], v156 offset:5120
	ds_read_b128 v[210:213], v156 offset:6144
	ds_read_b128 v[218:221], v156 offset:7168
	global_load_lds_dwordx4 v[150:151], off
	v_lshl_add_u64 v[150:151], s[72:73], 0, v[140:141]
	s_add_i32 m0, s53, 0xe000
	s_nop 0
	global_load_lds_dwordx4 v[150:151], off
	s_waitcnt vmcnt(8)
	s_waitcnt lgkmcnt(0)
	s_setprio 1
	s_barrier
	v_mfma_f32_16x16x32_bf16 v[126:129], v[146:149], v[186:189], v[126:129]
	v_mfma_f32_16x16x32_bf16 v[122:125], v[162:165], v[186:189], v[122:125]
	v_mfma_f32_16x16x32_bf16 v[118:121], v[146:149], v[194:197], v[118:121]
	v_mfma_f32_16x16x32_bf16 v[114:117], v[162:165], v[194:197], v[114:117]
	v_mfma_f32_16x16x32_bf16 v[94:97], v[146:149], v[202:205], v[94:97]
	v_mfma_f32_16x16x32_bf16 v[90:93], v[162:165], v[202:205], v[90:93]
	v_mfma_f32_16x16x32_bf16 v[86:89], v[146:149], v[210:213], v[86:89]
	v_mfma_f32_16x16x32_bf16 v[82:85], v[162:165], v[210:213], v[82:85]
	v_mfma_f32_16x16x32_bf16 v[126:129], v[158:161], v[190:193], v[126:129]
	v_mfma_f32_16x16x32_bf16 v[122:125], v[166:169], v[190:193], v[122:125]
	v_mfma_f32_16x16x32_bf16 v[118:121], v[158:161], v[198:201], v[118:121]
	v_mfma_f32_16x16x32_bf16 v[114:117], v[166:169], v[198:201], v[114:117]
	v_mfma_f32_16x16x32_bf16 v[94:97], v[158:161], v[206:209], v[94:97]
	v_mfma_f32_16x16x32_bf16 v[90:93], v[166:169], v[206:209], v[90:93]
	v_mfma_f32_16x16x32_bf16 v[86:89], v[158:161], v[218:221], v[86:89]
	v_mfma_f32_16x16x32_bf16 v[82:85], v[166:169], v[218:221], v[82:85]
	s_setprio 0
	s_setprio 1
	v_mfma_f32_16x16x32_bf16 v[110:113], v[170:173], v[186:189], v[110:113]
	v_mfma_f32_16x16x32_bf16 v[106:109], v[178:181], v[186:189], v[106:109]
	v_mfma_f32_16x16x32_bf16 v[102:105], v[170:173], v[194:197], v[102:105]
	v_mfma_f32_16x16x32_bf16 v[98:101], v[178:181], v[194:197], v[98:101]
	v_mfma_f32_16x16x32_bf16 v[78:81], v[170:173], v[202:205], v[78:81]
	v_mfma_f32_16x16x32_bf16 v[74:77], v[178:181], v[202:205], v[74:77]
	v_mfma_f32_16x16x32_bf16 v[70:73], v[170:173], v[210:213], v[70:73]
	v_mfma_f32_16x16x32_bf16 v[66:69], v[178:181], v[210:213], v[66:69]
	v_mfma_f32_16x16x32_bf16 v[110:113], v[174:177], v[190:193], v[110:113]
	v_mfma_f32_16x16x32_bf16 v[106:109], v[182:185], v[190:193], v[106:109]
	v_mfma_f32_16x16x32_bf16 v[102:105], v[174:177], v[198:201], v[102:105]
	v_mfma_f32_16x16x32_bf16 v[98:101], v[182:185], v[198:201], v[98:101]
	v_mfma_f32_16x16x32_bf16 v[78:81], v[174:177], v[206:209], v[78:81]
	v_mfma_f32_16x16x32_bf16 v[74:77], v[182:185], v[206:209], v[74:77]
	v_mfma_f32_16x16x32_bf16 v[70:73], v[174:177], v[218:221], v[70:73]
	v_mfma_f32_16x16x32_bf16 v[66:69], v[182:185], v[218:221], v[66:69]
	s_barrier
	s_setprio 0
	s_add_i32 s62, s61, s52
	v_lshl_add_u64 v[150:151], s[34:35], 0, v[132:133]
	s_mov_b32 m0, s62
	ds_read_b128 v[186:189], v156 offset:16384
	ds_read_b128 v[190:193], v156 offset:17408
	ds_read_b128 v[194:197], v156 offset:18432
	ds_read_b128 v[198:201], v156 offset:19456
	ds_read_b128 v[202:205], v156 offset:20480
	ds_read_b128 v[206:209], v156 offset:21504
	ds_read_b128 v[210:213], v156 offset:22528
	ds_read_b128 v[218:221], v156 offset:23552
	global_load_lds_dwordx4 v[150:151], off
	s_add_i32 m0, s62, 0x2000
	s_add_u32 s62, s34, 0x160000
	v_lshl_add_u64 v[214:215], s[34:35], 0, v[136:137]
	s_addc_u32 s63, s35, 0
	s_add_i32 s82, s76, s52
	global_load_lds_dwordx4 v[214:215], off
	v_lshl_add_u64 v[222:223], s[62:63], 0, v[132:133]
	s_mov_b32 m0, s82
	v_lshl_add_u64 v[224:225], s[74:75], 0, v[134:135]
	global_load_lds_dwordx4 v[222:223], off
	v_lshl_add_u64 v[222:223], s[62:63], 0, v[136:137]
	s_add_i32 m0, s82, 0x2000
	s_nop 0
	global_load_lds_dwordx4 v[222:223], off
	v_lshl_add_u64 v[222:223], s[74:75], 0, v[130:131]
	s_mov_b32 m0, s53
	s_nop 0
	global_load_lds_dwordx4 v[222:223], off
	s_mov_b32 m0, s54
	s_nop 0
	global_load_lds_dwordx4 v[224:225], off
	s_waitcnt vmcnt(8)
	s_waitcnt lgkmcnt(0)
	s_setprio 1
	s_barrier
	v_mfma_f32_16x16x32_bf16 v[62:65], v[146:149], v[186:189], v[62:65]
	v_mfma_f32_16x16x32_bf16 v[58:61], v[162:165], v[186:189], v[58:61]
	v_mfma_f32_16x16x32_bf16 v[54:57], v[146:149], v[194:197], v[54:57]
	v_mfma_f32_16x16x32_bf16 v[50:53], v[162:165], v[194:197], v[50:53]
	v_mfma_f32_16x16x32_bf16 v[30:33], v[146:149], v[202:205], v[30:33]
	v_mfma_f32_16x16x32_bf16 v[26:29], v[162:165], v[202:205], v[26:29]
	v_mfma_f32_16x16x32_bf16 v[22:25], v[146:149], v[210:213], v[22:25]
	v_mfma_f32_16x16x32_bf16 v[18:21], v[162:165], v[210:213], v[18:21]
	v_mfma_f32_16x16x32_bf16 v[62:65], v[158:161], v[190:193], v[62:65]
	v_mfma_f32_16x16x32_bf16 v[58:61], v[166:169], v[190:193], v[58:61]
	v_mfma_f32_16x16x32_bf16 v[54:57], v[158:161], v[198:201], v[54:57]
	v_mfma_f32_16x16x32_bf16 v[50:53], v[166:169], v[198:201], v[50:53]
	v_mfma_f32_16x16x32_bf16 v[30:33], v[158:161], v[206:209], v[30:33]
	v_mfma_f32_16x16x32_bf16 v[26:29], v[166:169], v[206:209], v[26:29]
	v_mfma_f32_16x16x32_bf16 v[22:25], v[158:161], v[218:221], v[22:25]
	v_mfma_f32_16x16x32_bf16 v[18:21], v[166:169], v[218:221], v[18:21]
	s_setprio 0
	s_setprio 1
	v_mfma_f32_16x16x32_bf16 v[46:49], v[170:173], v[186:189], v[46:49]
	v_mfma_f32_16x16x32_bf16 v[42:45], v[178:181], v[186:189], v[42:45]
	v_mfma_f32_16x16x32_bf16 v[38:41], v[170:173], v[194:197], v[38:41]
	v_mfma_f32_16x16x32_bf16 v[34:37], v[178:181], v[194:197], v[34:37]
	v_mfma_f32_16x16x32_bf16 v[14:17], v[170:173], v[202:205], v[14:17]
	v_mfma_f32_16x16x32_bf16 v[10:13], v[178:181], v[202:205], v[10:13]
	v_mfma_f32_16x16x32_bf16 v[6:9], v[170:173], v[210:213], v[6:9]
	v_mfma_f32_16x16x32_bf16 v[2:5], v[178:181], v[210:213], v[2:5]
	v_mfma_f32_16x16x32_bf16 v[46:49], v[174:177], v[190:193], v[46:49]
	v_mfma_f32_16x16x32_bf16 v[42:45], v[182:185], v[190:193], v[42:45]
	v_mfma_f32_16x16x32_bf16 v[38:41], v[174:177], v[198:201], v[38:41]
	v_mfma_f32_16x16x32_bf16 v[34:37], v[182:185], v[198:201], v[34:37]
	v_mfma_f32_16x16x32_bf16 v[14:17], v[174:177], v[206:209], v[14:17]
	v_mfma_f32_16x16x32_bf16 v[10:13], v[182:185], v[206:209], v[10:13]
	v_mfma_f32_16x16x32_bf16 v[6:9], v[174:177], v[218:221], v[6:9]
	v_mfma_f32_16x16x32_bf16 v[2:5], v[182:185], v[218:221], v[2:5]
	s_barrier
	s_setprio 0
	s_add_i32 s82, 0, 0x18000
	v_add_u32_e32 v157, s82, v152
	s_add_i32 s83, 0, 0x1c000
	ds_read_b128 v[146:149], v157
	ds_read_b128 v[158:161], v157 offset:1024
	ds_read_b128 v[162:165], v157 offset:2048
	ds_read_b128 v[166:169], v157 offset:3072
	v_add_u32_e32 v157, s83, v152
	ds_read_b128 v[170:173], v157
	ds_read_b128 v[174:177], v157 offset:1024
	ds_read_b128 v[178:181], v157 offset:2048
	ds_read_b128 v[182:185], v157 offset:3072
	s_add_u32 s62, s74, 0x160000
	s_addc_u32 s63, s75, 0
	s_mov_b32 m0, s55
	v_lshl_add_u64 v[226:227], s[62:63], 0, v[130:131]
	ds_read_b128 v[186:189], v156 offset:32768
	ds_read_b128 v[190:193], v156 offset:33792
	ds_read_b128 v[194:197], v156 offset:34816
	ds_read_b128 v[198:201], v156 offset:35840
	ds_read_b128 v[202:205], v156 offset:36864
	ds_read_b128 v[206:209], v156 offset:37888
	ds_read_b128 v[210:213], v156 offset:38912
	ds_read_b128 v[218:221], v156 offset:39936
	global_load_lds_dwordx4 v[226:227], off
	v_lshl_add_u64 v[226:227], s[62:63], 0, v[134:135]
	s_mov_b32 m0, s56
	s_nop 0
	global_load_lds_dwordx4 v[226:227], off
	s_waitcnt vmcnt(8)
	s_waitcnt lgkmcnt(0)
	s_setprio 1
	s_barrier
	v_mfma_f32_16x16x32_bf16 v[126:129], v[146:149], v[186:189], v[126:129]
	v_mfma_f32_16x16x32_bf16 v[122:125], v[162:165], v[186:189], v[122:125]
	v_mfma_f32_16x16x32_bf16 v[118:121], v[146:149], v[194:197], v[118:121]
	v_mfma_f32_16x16x32_bf16 v[114:117], v[162:165], v[194:197], v[114:117]
	v_mfma_f32_16x16x32_bf16 v[94:97], v[146:149], v[202:205], v[94:97]
	v_mfma_f32_16x16x32_bf16 v[90:93], v[162:165], v[202:205], v[90:93]
	v_mfma_f32_16x16x32_bf16 v[86:89], v[146:149], v[210:213], v[86:89]
	v_mfma_f32_16x16x32_bf16 v[82:85], v[162:165], v[210:213], v[82:85]
	v_mfma_f32_16x16x32_bf16 v[126:129], v[158:161], v[190:193], v[126:129]
	v_mfma_f32_16x16x32_bf16 v[122:125], v[166:169], v[190:193], v[122:125]
	v_mfma_f32_16x16x32_bf16 v[118:121], v[158:161], v[198:201], v[118:121]
	v_mfma_f32_16x16x32_bf16 v[114:117], v[166:169], v[198:201], v[114:117]
	v_mfma_f32_16x16x32_bf16 v[94:97], v[158:161], v[206:209], v[94:97]
	v_mfma_f32_16x16x32_bf16 v[90:93], v[166:169], v[206:209], v[90:93]
	v_mfma_f32_16x16x32_bf16 v[86:89], v[158:161], v[218:221], v[86:89]
	v_mfma_f32_16x16x32_bf16 v[82:85], v[166:169], v[218:221], v[82:85]
	s_setprio 0
	s_setprio 1
	v_mfma_f32_16x16x32_bf16 v[110:113], v[170:173], v[186:189], v[110:113]
	v_mfma_f32_16x16x32_bf16 v[106:109], v[178:181], v[186:189], v[106:109]
	v_mfma_f32_16x16x32_bf16 v[102:105], v[170:173], v[194:197], v[102:105]
	v_mfma_f32_16x16x32_bf16 v[98:101], v[178:181], v[194:197], v[98:101]
	v_mfma_f32_16x16x32_bf16 v[78:81], v[170:173], v[202:205], v[78:81]
	v_mfma_f32_16x16x32_bf16 v[74:77], v[178:181], v[202:205], v[74:77]
	v_mfma_f32_16x16x32_bf16 v[70:73], v[170:173], v[210:213], v[70:73]
	v_mfma_f32_16x16x32_bf16 v[66:69], v[178:181], v[210:213], v[66:69]
	v_mfma_f32_16x16x32_bf16 v[110:113], v[174:177], v[190:193], v[110:113]
	v_mfma_f32_16x16x32_bf16 v[106:109], v[182:185], v[190:193], v[106:109]
	v_mfma_f32_16x16x32_bf16 v[102:105], v[174:177], v[198:201], v[102:105]
	v_mfma_f32_16x16x32_bf16 v[98:101], v[182:185], v[198:201], v[98:101]
	v_mfma_f32_16x16x32_bf16 v[78:81], v[174:177], v[206:209], v[78:81]
	v_mfma_f32_16x16x32_bf16 v[74:77], v[182:185], v[206:209], v[74:77]
	v_mfma_f32_16x16x32_bf16 v[70:73], v[174:177], v[218:221], v[70:73]
	v_mfma_f32_16x16x32_bf16 v[66:69], v[182:185], v[218:221], v[66:69]
	s_barrier
	s_setprio 0
	s_add_i32 s62, s82, s52
	v_lshl_add_u64 v[150:151], v[150:151], 0, s[66:67]
	s_mov_b32 m0, s62
	ds_read_b128 v[186:189], v156 offset:49152
	ds_read_b128 v[190:193], v156 offset:50176
	ds_read_b128 v[194:197], v156 offset:51200
	ds_read_b128 v[198:201], v156 offset:52224
	ds_read_b128 v[202:205], v156 offset:53248
	ds_read_b128 v[206:209], v156 offset:54272
	ds_read_b128 v[210:213], v156 offset:55296
	ds_read_b128 v[218:221], v156 offset:56320
	global_load_lds_dwordx4 v[150:151], off
	s_add_i32 m0, s62, 0x2000
	s_add_u32 s34, s34, 0x160080
	v_lshl_add_u64 v[150:151], v[214:215], 0, s[66:67]
	s_addc_u32 s35, s35, 0
	s_add_i32 s62, s83, s52
	global_load_lds_dwordx4 v[150:151], off
	v_lshl_add_u64 v[150:151], s[34:35], 0, v[132:133]
	s_mov_b32 m0, s62
	s_nop 0
	global_load_lds_dwordx4 v[150:151], off
	v_lshl_add_u64 v[150:151], s[34:35], 0, v[136:137]
	s_add_i32 m0, s62, 0x2000
	s_nop 0
	global_load_lds_dwordx4 v[150:151], off
	v_lshl_add_u64 v[150:151], v[222:223], 0, s[66:67]
	s_mov_b32 m0, s58
	s_nop 0
	global_load_lds_dwordx4 v[150:151], off
	v_lshl_add_u64 v[150:151], v[224:225], 0, s[66:67]
	s_mov_b32 m0, s59
	s_nop 0
	global_load_lds_dwordx4 v[150:151], off
	s_waitcnt vmcnt(8)
	s_waitcnt lgkmcnt(0)
	s_setprio 1
	s_barrier
	v_mfma_f32_16x16x32_bf16 v[62:65], v[146:149], v[186:189], v[62:65]
	v_mfma_f32_16x16x32_bf16 v[58:61], v[162:165], v[186:189], v[58:61]
	v_mfma_f32_16x16x32_bf16 v[54:57], v[146:149], v[194:197], v[54:57]
	v_mfma_f32_16x16x32_bf16 v[50:53], v[162:165], v[194:197], v[50:53]
	v_mfma_f32_16x16x32_bf16 v[30:33], v[146:149], v[202:205], v[30:33]
	v_mfma_f32_16x16x32_bf16 v[26:29], v[162:165], v[202:205], v[26:29]
	v_mfma_f32_16x16x32_bf16 v[22:25], v[146:149], v[210:213], v[22:25]
	v_mfma_f32_16x16x32_bf16 v[18:21], v[162:165], v[210:213], v[18:21]
	v_mfma_f32_16x16x32_bf16 v[62:65], v[158:161], v[190:193], v[62:65]
	v_mfma_f32_16x16x32_bf16 v[58:61], v[166:169], v[190:193], v[58:61]
	v_mfma_f32_16x16x32_bf16 v[54:57], v[158:161], v[198:201], v[54:57]
	v_mfma_f32_16x16x32_bf16 v[50:53], v[166:169], v[198:201], v[50:53]
	v_mfma_f32_16x16x32_bf16 v[30:33], v[158:161], v[206:209], v[30:33]
	v_mfma_f32_16x16x32_bf16 v[26:29], v[166:169], v[206:209], v[26:29]
	v_mfma_f32_16x16x32_bf16 v[22:25], v[158:161], v[218:221], v[22:25]
	v_mfma_f32_16x16x32_bf16 v[18:21], v[166:169], v[218:221], v[18:21]
	s_setprio 0
	s_setprio 1
	v_mfma_f32_16x16x32_bf16 v[46:49], v[170:173], v[186:189], v[46:49]
	v_mfma_f32_16x16x32_bf16 v[42:45], v[178:181], v[186:189], v[42:45]
	v_mfma_f32_16x16x32_bf16 v[38:41], v[170:173], v[194:197], v[38:41]
	v_mfma_f32_16x16x32_bf16 v[34:37], v[178:181], v[194:197], v[34:37]
	v_mfma_f32_16x16x32_bf16 v[14:17], v[170:173], v[202:205], v[14:17]
	v_mfma_f32_16x16x32_bf16 v[10:13], v[178:181], v[202:205], v[10:13]
	v_mfma_f32_16x16x32_bf16 v[6:9], v[170:173], v[210:213], v[6:9]
	v_mfma_f32_16x16x32_bf16 v[2:5], v[178:181], v[210:213], v[2:5]
	v_mfma_f32_16x16x32_bf16 v[46:49], v[174:177], v[190:193], v[46:49]
	v_mfma_f32_16x16x32_bf16 v[42:45], v[182:185], v[190:193], v[42:45]
	v_mfma_f32_16x16x32_bf16 v[38:41], v[174:177], v[198:201], v[38:41]
	v_mfma_f32_16x16x32_bf16 v[34:37], v[182:185], v[198:201], v[34:37]
	v_mfma_f32_16x16x32_bf16 v[14:17], v[174:177], v[206:209], v[14:17]
	v_mfma_f32_16x16x32_bf16 v[10:13], v[182:185], v[206:209], v[10:13]
	v_mfma_f32_16x16x32_bf16 v[6:9], v[174:177], v[218:221], v[6:9]
	v_mfma_f32_16x16x32_bf16 v[2:5], v[182:185], v[218:221], v[2:5]
	s_barrier
	s_setprio 0
	s_add_i32 s81, s81, 2
	s_add_u32 s72, s72, 0x100
	s_addc_u32 s73, s73, 0
	s_add_u32 s0, s0, 0x100
	s_addc_u32 s1, s1, 0
	s_cmpk_gt_u32 s81, 0x55
	s_cbranch_scc0 .LBB0_387
	s_and_b64 vcc, exec, s[68:69]
	s_cbranch_vccz .LBB0_390
	s_barrier

.LBB0_518:
	ds_read_b128 v[160:163], v155
	ds_read_b128 v[164:167], v155 offset:1024
	ds_read_b128 v[168:171], v155 offset:2048
	ds_read_b128 v[172:175], v155 offset:3072
	ds_read_b128 v[176:179], v156
	ds_read_b128 v[180:183], v156 offset:1024
	ds_read_b128 v[184:187], v156 offset:2048
	ds_read_b128 v[188:191], v156 offset:3072
	s_add_u32 s34, s90, 0xfff80080
	s_addc_u32 s35, s91, -1
	s_cmp_eq_u32 s83, 28
	s_cselect_b32 s93, s0, s35
	s_cselect_b32 s92, s1, s34
	s_cselect_b32 s35, s7, s68
	s_cselect_b32 s34, s9, s52
	v_lshl_add_u64 v[152:153], s[90:91], 0, v[144:145]
	s_add_i32 m0, s56, 0xc000
	ds_read_b128 v[192:195], v157
	ds_read_b128 v[196:199], v157 offset:1024
	ds_read_b128 v[200:203], v157 offset:2048
	ds_read_b128 v[204:207], v157 offset:3072
	ds_read_b128 v[208:211], v157 offset:4096
	ds_read_b128 v[212:215], v157 offset:5120
	ds_read_b128 v[218:221], v157 offset:6144
	ds_read_b128 v[222:225], v157 offset:7168
	global_load_lds_dwordx4 v[152:153], off
	v_lshl_add_u64 v[152:153], s[90:91], 0, v[146:147]
	s_add_i32 m0, s56, 0xe000
	s_nop 0
	global_load_lds_dwordx4 v[152:153], off
	s_waitcnt vmcnt(8)
	s_waitcnt lgkmcnt(0)
	s_setprio 1
	s_barrier
	v_mfma_f32_16x16x32_bf16 v[126:129], v[160:163], v[192:195], v[126:129]
	v_mfma_f32_16x16x32_bf16 v[122:125], v[168:171], v[192:195], v[122:125]
	v_mfma_f32_16x16x32_bf16 v[110:113], v[160:163], v[200:203], v[110:113]
	v_mfma_f32_16x16x32_bf16 v[106:109], v[168:171], v[200:203], v[106:109]
	v_mfma_f32_16x16x32_bf16 v[94:97], v[160:163], v[208:211], v[94:97]
	v_mfma_f32_16x16x32_bf16 v[90:93], v[168:171], v[208:211], v[90:93]
	v_mfma_f32_16x16x32_bf16 v[78:81], v[160:163], v[218:221], v[78:81]
	v_mfma_f32_16x16x32_bf16 v[74:77], v[168:171], v[218:221], v[74:77]
	v_mfma_f32_16x16x32_bf16 v[126:129], v[164:167], v[196:199], v[126:129]
	v_mfma_f32_16x16x32_bf16 v[122:125], v[172:175], v[196:199], v[122:125]
	v_mfma_f32_16x16x32_bf16 v[110:113], v[164:167], v[204:207], v[110:113]
	v_mfma_f32_16x16x32_bf16 v[106:109], v[172:175], v[204:207], v[106:109]
	v_mfma_f32_16x16x32_bf16 v[94:97], v[164:167], v[212:215], v[94:97]
	v_mfma_f32_16x16x32_bf16 v[90:93], v[172:175], v[212:215], v[90:93]
	v_mfma_f32_16x16x32_bf16 v[78:81], v[164:167], v[222:225], v[78:81]
	v_mfma_f32_16x16x32_bf16 v[74:77], v[172:175], v[222:225], v[74:77]
	s_setprio 0
	s_setprio 1
	v_mfma_f32_16x16x32_bf16 v[118:121], v[176:179], v[192:195], v[118:121]
	v_mfma_f32_16x16x32_bf16 v[114:117], v[184:187], v[192:195], v[114:117]
	v_mfma_f32_16x16x32_bf16 v[102:105], v[176:179], v[200:203], v[102:105]
	v_mfma_f32_16x16x32_bf16 v[98:101], v[184:187], v[200:203], v[98:101]
	v_mfma_f32_16x16x32_bf16 v[86:89], v[176:179], v[208:211], v[86:89]
	v_mfma_f32_16x16x32_bf16 v[82:85], v[184:187], v[208:211], v[82:85]
	v_mfma_f32_16x16x32_bf16 v[70:73], v[176:179], v[218:221], v[70:73]
	v_mfma_f32_16x16x32_bf16 v[66:69], v[184:187], v[218:221], v[66:69]
	v_mfma_f32_16x16x32_bf16 v[118:121], v[180:183], v[196:199], v[118:121]
	v_mfma_f32_16x16x32_bf16 v[114:117], v[188:191], v[196:199], v[114:117]
	v_mfma_f32_16x16x32_bf16 v[102:105], v[180:183], v[204:207], v[102:105]
	v_mfma_f32_16x16x32_bf16 v[98:101], v[188:191], v[204:207], v[98:101]
	v_mfma_f32_16x16x32_bf16 v[86:89], v[180:183], v[212:215], v[86:89]
	v_mfma_f32_16x16x32_bf16 v[82:85], v[188:191], v[212:215], v[82:85]
	v_mfma_f32_16x16x32_bf16 v[70:73], v[180:183], v[222:225], v[70:73]
	v_mfma_f32_16x16x32_bf16 v[66:69], v[188:191], v[222:225], v[66:69]
	s_barrier
	s_setprio 0
	s_add_i32 s53, s75, s30
	v_lshl_add_u64 v[152:153], s[34:35], 0, v[132:133]
	s_mov_b32 m0, s53
	ds_read_b128 v[192:195], v157 offset:16384
	ds_read_b128 v[196:199], v157 offset:17408
	ds_read_b128 v[200:203], v157 offset:18432
	ds_read_b128 v[204:207], v157 offset:19456
	ds_read_b128 v[208:211], v157 offset:20480
	ds_read_b128 v[212:215], v157 offset:21504
	ds_read_b128 v[218:221], v157 offset:22528
	ds_read_b128 v[222:225], v157 offset:23552
	global_load_lds_dwordx4 v[152:153], off
	s_add_i32 m0, s53, 0x2000
	s_add_u32 s54, s34, 0x80000
	v_lshl_add_u64 v[226:227], s[34:35], 0, v[136:137]
	s_addc_u32 s55, s35, 0
	s_add_i32 s53, s94, s30
	global_load_lds_dwordx4 v[226:227], off
	v_lshl_add_u64 v[228:229], s[54:55], 0, v[132:133]
	s_mov_b32 m0, s53
	v_lshl_add_u64 v[230:231], s[92:93], 0, v[134:135]
	global_load_lds_dwordx4 v[228:229], off
	v_lshl_add_u64 v[228:229], s[54:55], 0, v[136:137]
	s_add_i32 m0, s53, 0x2000
	s_nop 0
	global_load_lds_dwordx4 v[228:229], off
	v_lshl_add_u64 v[228:229], s[92:93], 0, v[130:131]
	s_mov_b32 m0, s56
	s_nop 0
	global_load_lds_dwordx4 v[228:229], off
	s_mov_b32 m0, s57
	s_nop 0
	global_load_lds_dwordx4 v[230:231], off
	s_waitcnt vmcnt(8)
	s_waitcnt lgkmcnt(0)
	s_setprio 1
	s_barrier
	v_mfma_f32_16x16x32_bf16 v[62:65], v[160:163], v[192:195], v[62:65]
	v_mfma_f32_16x16x32_bf16 v[58:61], v[168:171], v[192:195], v[58:61]
	v_mfma_f32_16x16x32_bf16 v[46:49], v[160:163], v[200:203], v[46:49]
	v_mfma_f32_16x16x32_bf16 v[42:45], v[168:171], v[200:203], v[42:45]
	v_mfma_f32_16x16x32_bf16 v[30:33], v[160:163], v[208:211], v[30:33]
	v_mfma_f32_16x16x32_bf16 v[26:29], v[168:171], v[208:211], v[26:29]
	v_mfma_f32_16x16x32_bf16 v[14:17], v[160:163], v[218:221], v[14:17]
	v_mfma_f32_16x16x32_bf16 v[10:13], v[168:171], v[218:221], v[10:13]
	v_mfma_f32_16x16x32_bf16 v[62:65], v[164:167], v[196:199], v[62:65]
	v_mfma_f32_16x16x32_bf16 v[58:61], v[172:175], v[196:199], v[58:61]
	v_mfma_f32_16x16x32_bf16 v[46:49], v[164:167], v[204:207], v[46:49]
	v_mfma_f32_16x16x32_bf16 v[42:45], v[172:175], v[204:207], v[42:45]
	v_mfma_f32_16x16x32_bf16 v[30:33], v[164:167], v[212:215], v[30:33]
	v_mfma_f32_16x16x32_bf16 v[26:29], v[172:175], v[212:215], v[26:29]
	v_mfma_f32_16x16x32_bf16 v[14:17], v[164:167], v[222:225], v[14:17]
	v_mfma_f32_16x16x32_bf16 v[10:13], v[172:175], v[222:225], v[10:13]
	s_setprio 0
	s_setprio 1
	v_mfma_f32_16x16x32_bf16 v[54:57], v[176:179], v[192:195], v[54:57]
	v_mfma_f32_16x16x32_bf16 v[50:53], v[184:187], v[192:195], v[50:53]
	v_mfma_f32_16x16x32_bf16 v[38:41], v[176:179], v[200:203], v[38:41]
	v_mfma_f32_16x16x32_bf16 v[34:37], v[184:187], v[200:203], v[34:37]
	v_mfma_f32_16x16x32_bf16 v[22:25], v[176:179], v[208:211], v[22:25]
	v_mfma_f32_16x16x32_bf16 v[18:21], v[184:187], v[208:211], v[18:21]
	v_mfma_f32_16x16x32_bf16 v[6:9], v[176:179], v[218:221], v[6:9]
	v_mfma_f32_16x16x32_bf16 v[2:5], v[184:187], v[218:221], v[2:5]
	v_mfma_f32_16x16x32_bf16 v[54:57], v[180:183], v[196:199], v[54:57]
	v_mfma_f32_16x16x32_bf16 v[50:53], v[188:191], v[196:199], v[50:53]
	v_mfma_f32_16x16x32_bf16 v[38:41], v[180:183], v[204:207], v[38:41]
	v_mfma_f32_16x16x32_bf16 v[34:37], v[188:191], v[204:207], v[34:37]
	v_mfma_f32_16x16x32_bf16 v[22:25], v[180:183], v[212:215], v[22:25]
	v_mfma_f32_16x16x32_bf16 v[18:21], v[188:191], v[212:215], v[18:21]
	v_mfma_f32_16x16x32_bf16 v[6:9], v[180:183], v[222:225], v[6:9]
	v_mfma_f32_16x16x32_bf16 v[2:5], v[188:191], v[222:225], v[2:5]
	s_barrier
	s_setprio 0
	s_add_i32 s53, 0, 0x18000
	v_add_u32_e32 v138, s53, v154
	s_add_i32 s62, 0, 0x1c000
	ds_read_b128 v[160:163], v138
	ds_read_b128 v[164:167], v138 offset:1024
	ds_read_b128 v[168:171], v138 offset:2048
	ds_read_b128 v[172:175], v138 offset:3072
	v_add_u32_e32 v138, s62, v154
	ds_read_b128 v[176:179], v138
	ds_read_b128 v[180:183], v138 offset:1024
	ds_read_b128 v[184:187], v138 offset:2048
	ds_read_b128 v[188:191], v138 offset:3072
	s_add_u32 s54, s92, 0x80000
	s_addc_u32 s55, s93, 0
	s_mov_b32 m0, s58
	v_lshl_add_u64 v[232:233], s[54:55], 0, v[130:131]
	ds_read_b128 v[192:195], v157 offset:32768
	ds_read_b128 v[196:199], v157 offset:33792
	ds_read_b128 v[200:203], v157 offset:34816
	ds_read_b128 v[204:207], v157 offset:35840
	ds_read_b128 v[208:211], v157 offset:36864
	ds_read_b128 v[212:215], v157 offset:37888
	ds_read_b128 v[218:221], v157 offset:38912
	ds_read_b128 v[222:225], v157 offset:39936
	global_load_lds_dwordx4 v[232:233], off
	v_lshl_add_u64 v[232:233], s[54:55], 0, v[134:135]
	s_mov_b32 m0, s59
	s_nop 0
	global_load_lds_dwordx4 v[232:233], off
	s_waitcnt vmcnt(8)
	s_waitcnt lgkmcnt(0)
	s_setprio 1
	s_barrier
	v_mfma_f32_16x16x32_bf16 v[126:129], v[160:163], v[192:195], v[126:129]
	v_mfma_f32_16x16x32_bf16 v[122:125], v[168:171], v[192:195], v[122:125]
	v_mfma_f32_16x16x32_bf16 v[110:113], v[160:163], v[200:203], v[110:113]
	v_mfma_f32_16x16x32_bf16 v[106:109], v[168:171], v[200:203], v[106:109]
	v_mfma_f32_16x16x32_bf16 v[94:97], v[160:163], v[208:211], v[94:97]
	v_mfma_f32_16x16x32_bf16 v[90:93], v[168:171], v[208:211], v[90:93]
	v_mfma_f32_16x16x32_bf16 v[78:81], v[160:163], v[218:221], v[78:81]
	v_mfma_f32_16x16x32_bf16 v[74:77], v[168:171], v[218:221], v[74:77]
	v_mfma_f32_16x16x32_bf16 v[126:129], v[164:167], v[196:199], v[126:129]
	v_mfma_f32_16x16x32_bf16 v[122:125], v[172:175], v[196:199], v[122:125]
	v_mfma_f32_16x16x32_bf16 v[110:113], v[164:167], v[204:207], v[110:113]
	v_mfma_f32_16x16x32_bf16 v[106:109], v[172:175], v[204:207], v[106:109]
	v_mfma_f32_16x16x32_bf16 v[94:97], v[164:167], v[212:215], v[94:97]
	v_mfma_f32_16x16x32_bf16 v[90:93], v[172:175], v[212:215], v[90:93]
	v_mfma_f32_16x16x32_bf16 v[78:81], v[164:167], v[222:225], v[78:81]
	v_mfma_f32_16x16x32_bf16 v[74:77], v[172:175], v[222:225], v[74:77]
	s_setprio 0
	s_setprio 1
	v_mfma_f32_16x16x32_bf16 v[118:121], v[176:179], v[192:195], v[118:121]
	v_mfma_f32_16x16x32_bf16 v[114:117], v[184:187], v[192:195], v[114:117]
	v_mfma_f32_16x16x32_bf16 v[102:105], v[176:179], v[200:203], v[102:105]
	v_mfma_f32_16x16x32_bf16 v[98:101], v[184:187], v[200:203], v[98:101]
	v_mfma_f32_16x16x32_bf16 v[86:89], v[176:179], v[208:211], v[86:89]
	v_mfma_f32_16x16x32_bf16 v[82:85], v[184:187], v[208:211], v[82:85]
	v_mfma_f32_16x16x32_bf16 v[70:73], v[176:179], v[218:221], v[70:73]
	v_mfma_f32_16x16x32_bf16 v[66:69], v[184:187], v[218:221], v[66:69]
	v_mfma_f32_16x16x32_bf16 v[118:121], v[180:183], v[196:199], v[118:121]
	v_mfma_f32_16x16x32_bf16 v[114:117], v[188:191], v[196:199], v[114:117]
	v_mfma_f32_16x16x32_bf16 v[102:105], v[180:183], v[204:207], v[102:105]
	v_mfma_f32_16x16x32_bf16 v[98:101], v[188:191], v[204:207], v[98:101]
	v_mfma_f32_16x16x32_bf16 v[86:89], v[180:183], v[212:215], v[86:89]
	v_mfma_f32_16x16x32_bf16 v[82:85], v[188:191], v[212:215], v[82:85]
	v_mfma_f32_16x16x32_bf16 v[70:73], v[180:183], v[222:225], v[70:73]
	v_mfma_f32_16x16x32_bf16 v[66:69], v[188:191], v[222:225], v[66:69]
	s_barrier
	s_setprio 0
	s_add_i32 s53, s53, s30
	v_lshl_add_u64 v[152:153], v[152:153], 0, s[76:77]
	s_mov_b32 m0, s53
	ds_read_b128 v[192:195], v157 offset:49152
	ds_read_b128 v[196:199], v157 offset:50176
	ds_read_b128 v[200:203], v157 offset:51200
	ds_read_b128 v[204:207], v157 offset:52224
	ds_read_b128 v[208:211], v157 offset:53248
	ds_read_b128 v[212:215], v157 offset:54272
	ds_read_b128 v[218:221], v157 offset:55296
	ds_read_b128 v[222:225], v157 offset:56320
	global_load_lds_dwordx4 v[152:153], off
	s_add_i32 m0, s53, 0x2000
	s_add_u32 s34, s34, 0x80080
	v_lshl_add_u64 v[152:153], v[226:227], 0, s[76:77]
	s_addc_u32 s35, s35, 0
	s_add_i32 s53, s62, s30
	global_load_lds_dwordx4 v[152:153], off
	v_lshl_add_u64 v[152:153], s[34:35], 0, v[132:133]
	s_mov_b32 m0, s53
	s_nop 0
	global_load_lds_dwordx4 v[152:153], off
	v_lshl_add_u64 v[152:153], s[34:35], 0, v[136:137]
	s_add_i32 m0, s53, 0x2000
	s_nop 0
	global_load_lds_dwordx4 v[152:153], off
	v_lshl_add_u64 v[152:153], v[228:229], 0, s[76:77]
	s_mov_b32 m0, s61
	s_nop 0
	global_load_lds_dwordx4 v[152:153], off
	v_lshl_add_u64 v[152:153], v[230:231], 0, s[76:77]
	s_mov_b32 m0, s72
	s_nop 0
	global_load_lds_dwordx4 v[152:153], off
	s_waitcnt vmcnt(8)
	s_waitcnt lgkmcnt(0)
	s_setprio 1
	s_barrier
	v_mfma_f32_16x16x32_bf16 v[62:65], v[160:163], v[192:195], v[62:65]
	v_mfma_f32_16x16x32_bf16 v[58:61], v[168:171], v[192:195], v[58:61]
	v_mfma_f32_16x16x32_bf16 v[46:49], v[160:163], v[200:203], v[46:49]
	v_mfma_f32_16x16x32_bf16 v[42:45], v[168:171], v[200:203], v[42:45]
	v_mfma_f32_16x16x32_bf16 v[30:33], v[160:163], v[208:211], v[30:33]
	v_mfma_f32_16x16x32_bf16 v[26:29], v[168:171], v[208:211], v[26:29]
	v_mfma_f32_16x16x32_bf16 v[14:17], v[160:163], v[218:221], v[14:17]
	v_mfma_f32_16x16x32_bf16 v[10:13], v[168:171], v[218:221], v[10:13]
	v_mfma_f32_16x16x32_bf16 v[62:65], v[164:167], v[196:199], v[62:65]
	v_mfma_f32_16x16x32_bf16 v[58:61], v[172:175], v[196:199], v[58:61]
	v_mfma_f32_16x16x32_bf16 v[46:49], v[164:167], v[204:207], v[46:49]
	v_mfma_f32_16x16x32_bf16 v[42:45], v[172:175], v[204:207], v[42:45]
	v_mfma_f32_16x16x32_bf16 v[30:33], v[164:167], v[212:215], v[30:33]
	v_mfma_f32_16x16x32_bf16 v[26:29], v[172:175], v[212:215], v[26:29]
	v_mfma_f32_16x16x32_bf16 v[14:17], v[164:167], v[222:225], v[14:17]
	v_mfma_f32_16x16x32_bf16 v[10:13], v[172:175], v[222:225], v[10:13]
	s_setprio 0
	s_setprio 1
	v_mfma_f32_16x16x32_bf16 v[54:57], v[176:179], v[192:195], v[54:57]
	v_mfma_f32_16x16x32_bf16 v[50:53], v[184:187], v[192:195], v[50:53]
	v_mfma_f32_16x16x32_bf16 v[38:41], v[176:179], v[200:203], v[38:41]
	v_mfma_f32_16x16x32_bf16 v[34:37], v[184:187], v[200:203], v[34:37]
	v_mfma_f32_16x16x32_bf16 v[22:25], v[176:179], v[208:211], v[22:25]
	v_mfma_f32_16x16x32_bf16 v[18:21], v[184:187], v[208:211], v[18:21]
	v_mfma_f32_16x16x32_bf16 v[6:9], v[176:179], v[218:221], v[6:9]
	v_mfma_f32_16x16x32_bf16 v[2:5], v[184:187], v[218:221], v[2:5]
	v_mfma_f32_16x16x32_bf16 v[54:57], v[180:183], v[196:199], v[54:57]
	v_mfma_f32_16x16x32_bf16 v[50:53], v[188:191], v[196:199], v[50:53]
	v_mfma_f32_16x16x32_bf16 v[38:41], v[180:183], v[204:207], v[38:41]
	v_mfma_f32_16x16x32_bf16 v[34:37], v[188:191], v[204:207], v[34:37]
	v_mfma_f32_16x16x32_bf16 v[22:25], v[180:183], v[212:215], v[22:25]
	v_mfma_f32_16x16x32_bf16 v[18:21], v[188:191], v[212:215], v[18:21]
	v_mfma_f32_16x16x32_bf16 v[6:9], v[180:183], v[222:225], v[6:9]
	v_mfma_f32_16x16x32_bf16 v[2:5], v[188:191], v[222:225], v[2:5]
	s_barrier
	s_setprio 0
	s_add_i32 s83, s83, 2
	s_add_u32 s90, s90, 0x100
	s_addc_u32 s91, s91, 0
	s_add_u32 s52, s52, 0x100
	s_addc_u32 s68, s68, 0
	s_cmp_gt_u32 s83, 29
	s_cbranch_scc0 .LBB0_518
	s_and_b64 vcc, exec, s[78:79]
	s_cbranch_vccz .LBB0_521
	s_barrier

.LBB0_685:
	ds_read_b128 v[146:149], v165
	ds_read_b128 v[150:153], v165 offset:1024
	ds_read_b128 v[168:171], v165 offset:2048
	ds_read_b128 v[172:175], v165 offset:3072
	ds_read_b128 v[176:179], v166
	ds_read_b128 v[180:183], v166 offset:1024
	ds_read_b128 v[184:187], v166 offset:2048
	ds_read_b128 v[188:191], v166 offset:3072
	s_add_u32 s34, s84, 0xfffe0080
	s_addc_u32 s35, s85, -1
	s_cmp_eq_u32 s89, 4
	s_cselect_b32 s87, s0, s35
	s_cselect_b32 s86, s1, s34
	s_cselect_b32 s35, s52, s88
	s_cselect_b32 s34, s71, s77
	v_lshl_add_u64 v[226:227], s[84:85], 0, v[138:139]
	s_add_i32 m0, s33, 0xc000
	ds_read_b128 v[192:195], v167
	ds_read_b128 v[196:199], v167 offset:1024
	ds_read_b128 v[200:203], v167 offset:2048
	ds_read_b128 v[204:207], v167 offset:3072
	ds_read_b128 v[208:211], v167 offset:4096
	ds_read_b128 v[212:215], v167 offset:5120
	ds_read_b128 v[218:221], v167 offset:6144
	ds_read_b128 v[222:225], v167 offset:7168
	global_load_lds_dwordx4 v[226:227], off
	v_lshl_add_u64 v[226:227], s[84:85], 0, v[140:141]
	s_add_i32 m0, s33, 0xe000
	s_nop 0
	global_load_lds_dwordx4 v[226:227], off
	s_waitcnt vmcnt(8)
	s_waitcnt lgkmcnt(0)
	s_setprio 1
	s_barrier
	v_mfma_f32_16x16x32_bf16 v[126:129], v[146:149], v[192:195], v[126:129]
	v_mfma_f32_16x16x32_bf16 v[122:125], v[168:171], v[192:195], v[122:125]
	v_mfma_f32_16x16x32_bf16 v[114:117], v[146:149], v[200:203], v[114:117]
	v_mfma_f32_16x16x32_bf16 v[106:109], v[168:171], v[200:203], v[106:109]
	v_mfma_f32_16x16x32_bf16 v[98:101], v[146:149], v[208:211], v[98:101]
	v_mfma_f32_16x16x32_bf16 v[90:93], v[168:171], v[208:211], v[90:93]
	v_mfma_f32_16x16x32_bf16 v[82:85], v[146:149], v[218:221], v[82:85]
	v_mfma_f32_16x16x32_bf16 v[74:77], v[168:171], v[218:221], v[74:77]
	v_mfma_f32_16x16x32_bf16 v[126:129], v[150:153], v[196:199], v[126:129]
	v_mfma_f32_16x16x32_bf16 v[122:125], v[172:175], v[196:199], v[122:125]
	v_mfma_f32_16x16x32_bf16 v[114:117], v[150:153], v[204:207], v[114:117]
	v_mfma_f32_16x16x32_bf16 v[106:109], v[172:175], v[204:207], v[106:109]
	v_mfma_f32_16x16x32_bf16 v[98:101], v[150:153], v[212:215], v[98:101]
	v_mfma_f32_16x16x32_bf16 v[90:93], v[172:175], v[212:215], v[90:93]
	v_mfma_f32_16x16x32_bf16 v[82:85], v[150:153], v[222:225], v[82:85]
	v_mfma_f32_16x16x32_bf16 v[74:77], v[172:175], v[222:225], v[74:77]
	s_setprio 0
	s_setprio 1
	v_mfma_f32_16x16x32_bf16 v[118:121], v[176:179], v[192:195], v[118:121]
	v_mfma_f32_16x16x32_bf16 v[110:113], v[184:187], v[192:195], v[110:113]
	v_mfma_f32_16x16x32_bf16 v[102:105], v[176:179], v[200:203], v[102:105]
	v_mfma_f32_16x16x32_bf16 v[94:97], v[184:187], v[200:203], v[94:97]
	v_mfma_f32_16x16x32_bf16 v[86:89], v[176:179], v[208:211], v[86:89]
	v_mfma_f32_16x16x32_bf16 v[78:81], v[184:187], v[208:211], v[78:81]
	v_mfma_f32_16x16x32_bf16 v[70:73], v[176:179], v[218:221], v[70:73]
	v_mfma_f32_16x16x32_bf16 v[66:69], v[184:187], v[218:221], v[66:69]
	v_mfma_f32_16x16x32_bf16 v[118:121], v[180:183], v[196:199], v[118:121]
	v_mfma_f32_16x16x32_bf16 v[110:113], v[188:191], v[196:199], v[110:113]
	v_mfma_f32_16x16x32_bf16 v[102:105], v[180:183], v[204:207], v[102:105]
	v_mfma_f32_16x16x32_bf16 v[94:97], v[188:191], v[204:207], v[94:97]
	v_mfma_f32_16x16x32_bf16 v[86:89], v[180:183], v[212:215], v[86:89]
	v_mfma_f32_16x16x32_bf16 v[78:81], v[188:191], v[212:215], v[78:81]
	v_mfma_f32_16x16x32_bf16 v[70:73], v[180:183], v[222:225], v[70:73]
	v_mfma_f32_16x16x32_bf16 v[66:69], v[188:191], v[222:225], v[66:69]
	s_barrier
	s_setprio 0
	s_add_i32 s53, s73, s12
	v_lshl_add_u64 v[226:227], s[34:35], 0, v[132:133]
	s_mov_b32 m0, s53
	ds_read_b128 v[192:195], v167 offset:16384
	ds_read_b128 v[196:199], v167 offset:17408
	ds_read_b128 v[200:203], v167 offset:18432
	ds_read_b128 v[204:207], v167 offset:19456
	ds_read_b128 v[208:211], v167 offset:20480
	ds_read_b128 v[212:215], v167 offset:21504
	ds_read_b128 v[218:221], v167 offset:22528
	ds_read_b128 v[222:225], v167 offset:23552
	global_load_lds_dwordx4 v[226:227], off
	s_add_i32 m0, s53, 0x2000
	s_add_u32 s54, s34, 0x20000
	v_lshl_add_u64 v[228:229], s[34:35], 0, v[136:137]
	s_addc_u32 s55, s35, 0
	s_add_i32 s53, s74, s12
	global_load_lds_dwordx4 v[228:229], off
	v_lshl_add_u64 v[230:231], s[54:55], 0, v[132:133]
	s_mov_b32 m0, s53
	v_lshl_add_u64 v[232:233], s[86:87], 0, v[134:135]
	global_load_lds_dwordx4 v[230:231], off
	v_lshl_add_u64 v[230:231], s[54:55], 0, v[136:137]
	s_add_i32 m0, s53, 0x2000
	s_nop 0
	global_load_lds_dwordx4 v[230:231], off
	v_lshl_add_u64 v[230:231], s[86:87], 0, v[130:131]
	s_mov_b32 m0, s33
	s_nop 0
	global_load_lds_dwordx4 v[230:231], off
	s_mov_b32 m0, s56
	s_nop 0
	global_load_lds_dwordx4 v[232:233], off
	s_waitcnt vmcnt(8)
	s_waitcnt lgkmcnt(0)
	s_setprio 1
	s_barrier
	v_mfma_f32_16x16x32_bf16 v[62:65], v[146:149], v[192:195], v[62:65]
	v_mfma_f32_16x16x32_bf16 v[58:61], v[168:171], v[192:195], v[58:61]
	v_mfma_f32_16x16x32_bf16 v[50:53], v[146:149], v[200:203], v[50:53]
	v_mfma_f32_16x16x32_bf16 v[42:45], v[168:171], v[200:203], v[42:45]
	v_mfma_f32_16x16x32_bf16 v[34:37], v[146:149], v[208:211], v[34:37]
	v_mfma_f32_16x16x32_bf16 v[26:29], v[168:171], v[208:211], v[26:29]
	v_mfma_f32_16x16x32_bf16 v[18:21], v[146:149], v[218:221], v[18:21]
	v_mfma_f32_16x16x32_bf16 v[10:13], v[168:171], v[218:221], v[10:13]
	v_mfma_f32_16x16x32_bf16 v[62:65], v[150:153], v[196:199], v[62:65]
	v_mfma_f32_16x16x32_bf16 v[58:61], v[172:175], v[196:199], v[58:61]
	v_mfma_f32_16x16x32_bf16 v[50:53], v[150:153], v[204:207], v[50:53]
	v_mfma_f32_16x16x32_bf16 v[42:45], v[172:175], v[204:207], v[42:45]
	v_mfma_f32_16x16x32_bf16 v[34:37], v[150:153], v[212:215], v[34:37]
	v_mfma_f32_16x16x32_bf16 v[26:29], v[172:175], v[212:215], v[26:29]
	v_mfma_f32_16x16x32_bf16 v[18:21], v[150:153], v[222:225], v[18:21]
	v_mfma_f32_16x16x32_bf16 v[10:13], v[172:175], v[222:225], v[10:13]
	s_setprio 0
	s_setprio 1
	v_mfma_f32_16x16x32_bf16 v[54:57], v[176:179], v[192:195], v[54:57]
	v_mfma_f32_16x16x32_bf16 v[46:49], v[184:187], v[192:195], v[46:49]
	v_mfma_f32_16x16x32_bf16 v[38:41], v[176:179], v[200:203], v[38:41]
	v_mfma_f32_16x16x32_bf16 v[30:33], v[184:187], v[200:203], v[30:33]
	v_mfma_f32_16x16x32_bf16 v[22:25], v[176:179], v[208:211], v[22:25]
	v_mfma_f32_16x16x32_bf16 v[14:17], v[184:187], v[208:211], v[14:17]
	v_mfma_f32_16x16x32_bf16 v[6:9], v[176:179], v[218:221], v[6:9]
	v_mfma_f32_16x16x32_bf16 v[2:5], v[184:187], v[218:221], v[2:5]
	v_mfma_f32_16x16x32_bf16 v[54:57], v[180:183], v[196:199], v[54:57]
	v_mfma_f32_16x16x32_bf16 v[46:49], v[188:191], v[196:199], v[46:49]
	v_mfma_f32_16x16x32_bf16 v[38:41], v[180:183], v[204:207], v[38:41]
	v_mfma_f32_16x16x32_bf16 v[30:33], v[188:191], v[204:207], v[30:33]
	v_mfma_f32_16x16x32_bf16 v[22:25], v[180:183], v[212:215], v[22:25]
	v_mfma_f32_16x16x32_bf16 v[14:17], v[188:191], v[212:215], v[14:17]
	v_mfma_f32_16x16x32_bf16 v[6:9], v[180:183], v[222:225], v[6:9]
	v_mfma_f32_16x16x32_bf16 v[2:5], v[188:191], v[222:225], v[2:5]
	s_barrier
	s_setprio 0
	s_add_i32 s53, 0, 0x18000
	s_add_i32 s62, 0, 0x1c000
	v_add_u32_e32 v172, s53, v162
	v_add_u32_e32 v188, s62, v162
	ds_read_b128 v[146:149], v172
	ds_read_b128 v[150:153], v172 offset:1024
	ds_read_b128 v[168:171], v172 offset:2048
	ds_read_b128 v[172:175], v172 offset:3072
	ds_read_b128 v[176:179], v188
	ds_read_b128 v[180:183], v188 offset:1024
	ds_read_b128 v[184:187], v188 offset:2048
	ds_read_b128 v[188:191], v188 offset:3072
	s_add_u32 s54, s86, 0x20000
	s_addc_u32 s55, s87, 0
	s_mov_b32 m0, s57
	v_lshl_add_u64 v[234:235], s[54:55], 0, v[130:131]
	ds_read_b128 v[192:195], v167 offset:32768
	ds_read_b128 v[196:199], v167 offset:33792
	ds_read_b128 v[200:203], v167 offset:34816
	ds_read_b128 v[204:207], v167 offset:35840
	ds_read_b128 v[208:211], v167 offset:36864
	ds_read_b128 v[212:215], v167 offset:37888
	ds_read_b128 v[218:221], v167 offset:38912
	ds_read_b128 v[222:225], v167 offset:39936
	global_load_lds_dwordx4 v[234:235], off
	v_lshl_add_u64 v[234:235], s[54:55], 0, v[134:135]
	s_mov_b32 m0, s58
	s_nop 0
	global_load_lds_dwordx4 v[234:235], off
	s_waitcnt vmcnt(8)
	s_waitcnt lgkmcnt(0)
	s_setprio 1
	s_barrier
	v_mfma_f32_16x16x32_bf16 v[126:129], v[146:149], v[192:195], v[126:129]
	v_mfma_f32_16x16x32_bf16 v[122:125], v[168:171], v[192:195], v[122:125]
	v_mfma_f32_16x16x32_bf16 v[114:117], v[146:149], v[200:203], v[114:117]
	v_mfma_f32_16x16x32_bf16 v[106:109], v[168:171], v[200:203], v[106:109]
	v_mfma_f32_16x16x32_bf16 v[98:101], v[146:149], v[208:211], v[98:101]
	v_mfma_f32_16x16x32_bf16 v[90:93], v[168:171], v[208:211], v[90:93]
	v_mfma_f32_16x16x32_bf16 v[82:85], v[146:149], v[218:221], v[82:85]
	v_mfma_f32_16x16x32_bf16 v[74:77], v[168:171], v[218:221], v[74:77]
	v_mfma_f32_16x16x32_bf16 v[126:129], v[150:153], v[196:199], v[126:129]
	v_mfma_f32_16x16x32_bf16 v[122:125], v[172:175], v[196:199], v[122:125]
	v_mfma_f32_16x16x32_bf16 v[114:117], v[150:153], v[204:207], v[114:117]
	v_mfma_f32_16x16x32_bf16 v[106:109], v[172:175], v[204:207], v[106:109]
	v_mfma_f32_16x16x32_bf16 v[98:101], v[150:153], v[212:215], v[98:101]
	v_mfma_f32_16x16x32_bf16 v[90:93], v[172:175], v[212:215], v[90:93]
	v_mfma_f32_16x16x32_bf16 v[82:85], v[150:153], v[222:225], v[82:85]
	v_mfma_f32_16x16x32_bf16 v[74:77], v[172:175], v[222:225], v[74:77]
	s_setprio 0
	s_setprio 1
	v_mfma_f32_16x16x32_bf16 v[118:121], v[176:179], v[192:195], v[118:121]
	v_mfma_f32_16x16x32_bf16 v[110:113], v[184:187], v[192:195], v[110:113]
	v_mfma_f32_16x16x32_bf16 v[102:105], v[176:179], v[200:203], v[102:105]
	v_mfma_f32_16x16x32_bf16 v[94:97], v[184:187], v[200:203], v[94:97]
	v_mfma_f32_16x16x32_bf16 v[86:89], v[176:179], v[208:211], v[86:89]
	v_mfma_f32_16x16x32_bf16 v[78:81], v[184:187], v[208:211], v[78:81]
	v_mfma_f32_16x16x32_bf16 v[70:73], v[176:179], v[218:221], v[70:73]
	v_mfma_f32_16x16x32_bf16 v[66:69], v[184:187], v[218:221], v[66:69]
	v_mfma_f32_16x16x32_bf16 v[118:121], v[180:183], v[196:199], v[118:121]
	v_mfma_f32_16x16x32_bf16 v[110:113], v[188:191], v[196:199], v[110:113]
	v_mfma_f32_16x16x32_bf16 v[102:105], v[180:183], v[204:207], v[102:105]
	v_mfma_f32_16x16x32_bf16 v[94:97], v[188:191], v[204:207], v[94:97]
	v_mfma_f32_16x16x32_bf16 v[86:89], v[180:183], v[212:215], v[86:89]
	v_mfma_f32_16x16x32_bf16 v[78:81], v[188:191], v[212:215], v[78:81]
	v_mfma_f32_16x16x32_bf16 v[70:73], v[180:183], v[222:225], v[70:73]
	v_mfma_f32_16x16x32_bf16 v[66:69], v[188:191], v[222:225], v[66:69]
	s_barrier
	s_setprio 0
	s_add_i32 s53, s53, s12
	v_lshl_add_u64 v[226:227], v[226:227], 0, s[8:9]
	s_mov_b32 m0, s53
	ds_read_b128 v[192:195], v167 offset:49152
	ds_read_b128 v[196:199], v167 offset:50176
	ds_read_b128 v[200:203], v167 offset:51200
	ds_read_b128 v[204:207], v167 offset:52224
	ds_read_b128 v[208:211], v167 offset:53248
	ds_read_b128 v[212:215], v167 offset:54272
	ds_read_b128 v[218:221], v167 offset:55296
	ds_read_b128 v[222:225], v167 offset:56320
	global_load_lds_dwordx4 v[226:227], off
	s_add_i32 m0, s53, 0x2000
	s_add_u32 s34, s34, 0x20080
	v_lshl_add_u64 v[226:227], v[228:229], 0, s[8:9]
	s_addc_u32 s35, s35, 0
	s_add_i32 s53, s62, s12
	global_load_lds_dwordx4 v[226:227], off
	v_lshl_add_u64 v[226:227], s[34:35], 0, v[132:133]
	s_mov_b32 m0, s53
	s_nop 0
	global_load_lds_dwordx4 v[226:227], off
	v_lshl_add_u64 v[226:227], s[34:35], 0, v[136:137]
	s_add_i32 m0, s53, 0x2000
	s_nop 0
	global_load_lds_dwordx4 v[226:227], off
	v_lshl_add_u64 v[226:227], v[230:231], 0, s[8:9]
	s_mov_b32 m0, s60
	s_nop 0
	global_load_lds_dwordx4 v[226:227], off
	v_lshl_add_u64 v[226:227], v[232:233], 0, s[8:9]
	s_mov_b32 m0, s61
	s_nop 0
	global_load_lds_dwordx4 v[226:227], off
	s_waitcnt vmcnt(8)
	s_waitcnt lgkmcnt(0)
	s_setprio 1
	s_barrier
	v_mfma_f32_16x16x32_bf16 v[62:65], v[146:149], v[192:195], v[62:65]
	v_mfma_f32_16x16x32_bf16 v[58:61], v[168:171], v[192:195], v[58:61]
	v_mfma_f32_16x16x32_bf16 v[50:53], v[146:149], v[200:203], v[50:53]
	v_mfma_f32_16x16x32_bf16 v[42:45], v[168:171], v[200:203], v[42:45]
	v_mfma_f32_16x16x32_bf16 v[34:37], v[146:149], v[208:211], v[34:37]
	v_mfma_f32_16x16x32_bf16 v[26:29], v[168:171], v[208:211], v[26:29]
	v_mfma_f32_16x16x32_bf16 v[18:21], v[146:149], v[218:221], v[18:21]
	v_mfma_f32_16x16x32_bf16 v[10:13], v[168:171], v[218:221], v[10:13]
	v_mfma_f32_16x16x32_bf16 v[62:65], v[150:153], v[196:199], v[62:65]
	v_mfma_f32_16x16x32_bf16 v[58:61], v[172:175], v[196:199], v[58:61]
	v_mfma_f32_16x16x32_bf16 v[50:53], v[150:153], v[204:207], v[50:53]
	v_mfma_f32_16x16x32_bf16 v[42:45], v[172:175], v[204:207], v[42:45]
	v_mfma_f32_16x16x32_bf16 v[34:37], v[150:153], v[212:215], v[34:37]
	v_mfma_f32_16x16x32_bf16 v[26:29], v[172:175], v[212:215], v[26:29]
	v_mfma_f32_16x16x32_bf16 v[18:21], v[150:153], v[222:225], v[18:21]
	v_mfma_f32_16x16x32_bf16 v[10:13], v[172:175], v[222:225], v[10:13]
	s_setprio 0
	s_setprio 1
	v_mfma_f32_16x16x32_bf16 v[54:57], v[176:179], v[192:195], v[54:57]
	v_mfma_f32_16x16x32_bf16 v[46:49], v[184:187], v[192:195], v[46:49]
	v_mfma_f32_16x16x32_bf16 v[38:41], v[176:179], v[200:203], v[38:41]
	v_mfma_f32_16x16x32_bf16 v[30:33], v[184:187], v[200:203], v[30:33]
	v_mfma_f32_16x16x32_bf16 v[22:25], v[176:179], v[208:211], v[22:25]
	v_mfma_f32_16x16x32_bf16 v[14:17], v[184:187], v[208:211], v[14:17]
	v_mfma_f32_16x16x32_bf16 v[6:9], v[176:179], v[218:221], v[6:9]
	v_mfma_f32_16x16x32_bf16 v[2:5], v[184:187], v[218:221], v[2:5]
	v_mfma_f32_16x16x32_bf16 v[54:57], v[180:183], v[196:199], v[54:57]
	v_mfma_f32_16x16x32_bf16 v[46:49], v[188:191], v[196:199], v[46:49]
	v_mfma_f32_16x16x32_bf16 v[38:41], v[180:183], v[204:207], v[38:41]
	v_mfma_f32_16x16x32_bf16 v[30:33], v[188:191], v[204:207], v[30:33]
	v_mfma_f32_16x16x32_bf16 v[22:25], v[180:183], v[212:215], v[22:25]
	v_mfma_f32_16x16x32_bf16 v[14:17], v[188:191], v[212:215], v[14:17]
	v_mfma_f32_16x16x32_bf16 v[6:9], v[180:183], v[222:225], v[6:9]
	v_mfma_f32_16x16x32_bf16 v[2:5], v[188:191], v[222:225], v[2:5]
	s_barrier
	s_setprio 0
	s_add_i32 s89, s89, 2
	s_add_u32 s84, s84, 0x100
	s_addc_u32 s85, s85, 0
	s_add_u32 s77, s77, 0x100
	s_addc_u32 s88, s88, 0
	s_cmp_gt_u32 s89, 5
	s_cbranch_scc0 .LBB0_685
	s_and_b64 vcc, exec, s[66:67]
	s_cbranch_vccz .LBB0_688
	s_barrier

.LBB0_715:
	ds_read_b128 v[146:149], v1
	ds_read_b128 v[160:163], v1 offset:1024
	ds_read_b128 v[164:167], v1 offset:2048
	ds_read_b128 v[168:171], v1 offset:3072
	ds_read_b128 v[172:175], v154
	ds_read_b128 v[176:179], v154 offset:1024
	ds_read_b128 v[180:183], v154 offset:2048
	ds_read_b128 v[184:187], v154 offset:3072
	s_add_u32 s34, s84, 0xfffe0080
	s_addc_u32 s35, s85, -1
	s_cmp_eq_u32 s88, 4
	s_cselect_b32 s87, s0, s35
	s_cselect_b32 s86, s1, s34
	s_cselect_b32 s35, s52, s83
	s_cselect_b32 s34, s71, s77
	v_lshl_add_u64 v[150:151], s[84:85], 0, v[138:139]
	s_add_i32 m0, s33, 0xc000
	ds_read_b128 v[188:191], v155
	ds_read_b128 v[192:195], v155 offset:1024
	ds_read_b128 v[196:199], v155 offset:2048
	ds_read_b128 v[200:203], v155 offset:3072
	ds_read_b128 v[204:207], v155 offset:4096
	ds_read_b128 v[208:211], v155 offset:5120
	ds_read_b128 v[212:215], v155 offset:6144
	ds_read_b128 v[218:221], v155 offset:7168
	global_load_lds_dwordx4 v[150:151], off
	v_lshl_add_u64 v[150:151], s[84:85], 0, v[140:141]
	s_add_i32 m0, s33, 0xe000
	s_nop 0
	global_load_lds_dwordx4 v[150:151], off
	s_waitcnt vmcnt(8)
	s_waitcnt lgkmcnt(0)
	s_setprio 1
	s_barrier
	v_mfma_f32_16x16x32_bf16 v[126:129], v[146:149], v[188:191], v[126:129]
	v_mfma_f32_16x16x32_bf16 v[122:125], v[164:167], v[188:191], v[122:125]
	v_mfma_f32_16x16x32_bf16 v[110:113], v[146:149], v[196:199], v[110:113]
	v_mfma_f32_16x16x32_bf16 v[106:109], v[164:167], v[196:199], v[106:109]
	v_mfma_f32_16x16x32_bf16 v[94:97], v[146:149], v[204:207], v[94:97]
	v_mfma_f32_16x16x32_bf16 v[90:93], v[164:167], v[204:207], v[90:93]
	v_mfma_f32_16x16x32_bf16 v[78:81], v[146:149], v[212:215], v[78:81]
	v_mfma_f32_16x16x32_bf16 v[74:77], v[164:167], v[212:215], v[74:77]
	v_mfma_f32_16x16x32_bf16 v[126:129], v[160:163], v[192:195], v[126:129]
	v_mfma_f32_16x16x32_bf16 v[122:125], v[168:171], v[192:195], v[122:125]
	v_mfma_f32_16x16x32_bf16 v[110:113], v[160:163], v[200:203], v[110:113]
	v_mfma_f32_16x16x32_bf16 v[106:109], v[168:171], v[200:203], v[106:109]
	v_mfma_f32_16x16x32_bf16 v[94:97], v[160:163], v[208:211], v[94:97]
	v_mfma_f32_16x16x32_bf16 v[90:93], v[168:171], v[208:211], v[90:93]
	v_mfma_f32_16x16x32_bf16 v[78:81], v[160:163], v[218:221], v[78:81]
	v_mfma_f32_16x16x32_bf16 v[74:77], v[168:171], v[218:221], v[74:77]
	s_setprio 0
	s_setprio 1
	v_mfma_f32_16x16x32_bf16 v[118:121], v[172:175], v[188:191], v[118:121]
	v_mfma_f32_16x16x32_bf16 v[114:117], v[180:183], v[188:191], v[114:117]
	v_mfma_f32_16x16x32_bf16 v[102:105], v[172:175], v[196:199], v[102:105]
	v_mfma_f32_16x16x32_bf16 v[98:101], v[180:183], v[196:199], v[98:101]
	v_mfma_f32_16x16x32_bf16 v[86:89], v[172:175], v[204:207], v[86:89]
	v_mfma_f32_16x16x32_bf16 v[82:85], v[180:183], v[204:207], v[82:85]
	v_mfma_f32_16x16x32_bf16 v[70:73], v[172:175], v[212:215], v[70:73]
	v_mfma_f32_16x16x32_bf16 v[66:69], v[180:183], v[212:215], v[66:69]
	v_mfma_f32_16x16x32_bf16 v[118:121], v[176:179], v[192:195], v[118:121]
	v_mfma_f32_16x16x32_bf16 v[114:117], v[184:187], v[192:195], v[114:117]
	v_mfma_f32_16x16x32_bf16 v[102:105], v[176:179], v[200:203], v[102:105]
	v_mfma_f32_16x16x32_bf16 v[98:101], v[184:187], v[200:203], v[98:101]
	v_mfma_f32_16x16x32_bf16 v[86:89], v[176:179], v[208:211], v[86:89]
	v_mfma_f32_16x16x32_bf16 v[82:85], v[184:187], v[208:211], v[82:85]
	v_mfma_f32_16x16x32_bf16 v[70:73], v[176:179], v[218:221], v[70:73]
	v_mfma_f32_16x16x32_bf16 v[66:69], v[184:187], v[218:221], v[66:69]
	s_barrier
	s_setprio 0
	s_add_i32 s53, s73, s13
	v_lshl_add_u64 v[150:151], s[34:35], 0, v[132:133]
	s_mov_b32 m0, s53
	ds_read_b128 v[188:191], v155 offset:16384
	ds_read_b128 v[192:195], v155 offset:17408
	ds_read_b128 v[196:199], v155 offset:18432
	ds_read_b128 v[200:203], v155 offset:19456
	ds_read_b128 v[204:207], v155 offset:20480
	ds_read_b128 v[208:211], v155 offset:21504
	ds_read_b128 v[212:215], v155 offset:22528
	ds_read_b128 v[218:221], v155 offset:23552
	global_load_lds_dwordx4 v[150:151], off
	s_add_i32 m0, s53, 0x2000
	s_add_u32 s54, s34, 0x20000
	v_lshl_add_u64 v[222:223], s[34:35], 0, v[136:137]
	s_addc_u32 s55, s35, 0
	s_add_i32 s53, s74, s13
	global_load_lds_dwordx4 v[222:223], off
	v_lshl_add_u64 v[224:225], s[54:55], 0, v[132:133]
	s_mov_b32 m0, s53
	v_lshl_add_u64 v[226:227], s[86:87], 0, v[134:135]
	global_load_lds_dwordx4 v[224:225], off
	v_lshl_add_u64 v[224:225], s[54:55], 0, v[136:137]
	s_add_i32 m0, s53, 0x2000
	s_nop 0
	global_load_lds_dwordx4 v[224:225], off
	v_lshl_add_u64 v[224:225], s[86:87], 0, v[130:131]
	s_mov_b32 m0, s33
	s_nop 0
	global_load_lds_dwordx4 v[224:225], off
	s_mov_b32 m0, s56
	s_nop 0
	global_load_lds_dwordx4 v[226:227], off
	s_waitcnt vmcnt(8)
	s_waitcnt lgkmcnt(0)
	s_setprio 1
	s_barrier
	v_mfma_f32_16x16x32_bf16 v[62:65], v[146:149], v[188:191], v[62:65]
	v_mfma_f32_16x16x32_bf16 v[58:61], v[164:167], v[188:191], v[58:61]
	v_mfma_f32_16x16x32_bf16 v[50:53], v[146:149], v[196:199], v[50:53]
	v_mfma_f32_16x16x32_bf16 v[42:45], v[164:167], v[196:199], v[42:45]
	v_mfma_f32_16x16x32_bf16 v[34:37], v[146:149], v[204:207], v[34:37]
	v_mfma_f32_16x16x32_bf16 v[26:29], v[164:167], v[204:207], v[26:29]
	v_mfma_f32_16x16x32_bf16 v[18:21], v[146:149], v[212:215], v[18:21]
	v_mfma_f32_16x16x32_bf16 v[10:13], v[164:167], v[212:215], v[10:13]
	v_mfma_f32_16x16x32_bf16 v[62:65], v[160:163], v[192:195], v[62:65]
	v_mfma_f32_16x16x32_bf16 v[58:61], v[168:171], v[192:195], v[58:61]
	v_mfma_f32_16x16x32_bf16 v[50:53], v[160:163], v[200:203], v[50:53]
	v_mfma_f32_16x16x32_bf16 v[42:45], v[168:171], v[200:203], v[42:45]
	v_mfma_f32_16x16x32_bf16 v[34:37], v[160:163], v[208:211], v[34:37]
	v_mfma_f32_16x16x32_bf16 v[26:29], v[168:171], v[208:211], v[26:29]
	v_mfma_f32_16x16x32_bf16 v[18:21], v[160:163], v[218:221], v[18:21]
	v_mfma_f32_16x16x32_bf16 v[10:13], v[168:171], v[218:221], v[10:13]
	s_setprio 0
	s_setprio 1
	v_mfma_f32_16x16x32_bf16 v[54:57], v[172:175], v[188:191], v[54:57]
	v_mfma_f32_16x16x32_bf16 v[46:49], v[180:183], v[188:191], v[46:49]
	v_mfma_f32_16x16x32_bf16 v[38:41], v[172:175], v[196:199], v[38:41]
	v_mfma_f32_16x16x32_bf16 v[30:33], v[180:183], v[196:199], v[30:33]
	v_mfma_f32_16x16x32_bf16 v[22:25], v[172:175], v[204:207], v[22:25]
	v_mfma_f32_16x16x32_bf16 v[14:17], v[180:183], v[204:207], v[14:17]
	v_mfma_f32_16x16x32_bf16 v[6:9], v[172:175], v[212:215], v[6:9]
	v_mfma_f32_16x16x32_bf16 v[2:5], v[180:183], v[212:215], v[2:5]
	v_mfma_f32_16x16x32_bf16 v[54:57], v[176:179], v[192:195], v[54:57]
	v_mfma_f32_16x16x32_bf16 v[46:49], v[184:187], v[192:195], v[46:49]
	v_mfma_f32_16x16x32_bf16 v[38:41], v[176:179], v[200:203], v[38:41]
	v_mfma_f32_16x16x32_bf16 v[30:33], v[184:187], v[200:203], v[30:33]
	v_mfma_f32_16x16x32_bf16 v[22:25], v[176:179], v[208:211], v[22:25]
	v_mfma_f32_16x16x32_bf16 v[14:17], v[184:187], v[208:211], v[14:17]
	v_mfma_f32_16x16x32_bf16 v[6:9], v[176:179], v[218:221], v[6:9]
	v_mfma_f32_16x16x32_bf16 v[2:5], v[184:187], v[218:221], v[2:5]
	s_barrier
	s_setprio 0
	s_add_i32 s53, 0, 0x18000
	v_add_u32_e32 v156, s53, v153
	s_add_i32 s62, 0, 0x1c000
	ds_read_b128 v[146:149], v156
	ds_read_b128 v[160:163], v156 offset:1024
	ds_read_b128 v[164:167], v156 offset:2048
	ds_read_b128 v[168:171], v156 offset:3072
	v_add_u32_e32 v156, s62, v153
	ds_read_b128 v[172:175], v156
	ds_read_b128 v[176:179], v156 offset:1024
	ds_read_b128 v[180:183], v156 offset:2048
	ds_read_b128 v[184:187], v156 offset:3072
	s_add_u32 s54, s86, 0x20000
	s_addc_u32 s55, s87, 0
	s_mov_b32 m0, s57
	v_lshl_add_u64 v[228:229], s[54:55], 0, v[130:131]
	ds_read_b128 v[188:191], v155 offset:32768
	ds_read_b128 v[192:195], v155 offset:33792
	ds_read_b128 v[196:199], v155 offset:34816
	ds_read_b128 v[200:203], v155 offset:35840
	ds_read_b128 v[204:207], v155 offset:36864
	ds_read_b128 v[208:211], v155 offset:37888
	ds_read_b128 v[212:215], v155 offset:38912
	ds_read_b128 v[218:221], v155 offset:39936
	global_load_lds_dwordx4 v[228:229], off
	v_lshl_add_u64 v[228:229], s[54:55], 0, v[134:135]
	s_mov_b32 m0, s58
	s_nop 0
	global_load_lds_dwordx4 v[228:229], off
	s_waitcnt vmcnt(8)
	s_waitcnt lgkmcnt(0)
	s_setprio 1
	s_barrier
	v_mfma_f32_16x16x32_bf16 v[126:129], v[146:149], v[188:191], v[126:129]
	v_mfma_f32_16x16x32_bf16 v[122:125], v[164:167], v[188:191], v[122:125]
	v_mfma_f32_16x16x32_bf16 v[110:113], v[146:149], v[196:199], v[110:113]
	v_mfma_f32_16x16x32_bf16 v[106:109], v[164:167], v[196:199], v[106:109]
	v_mfma_f32_16x16x32_bf16 v[94:97], v[146:149], v[204:207], v[94:97]
	v_mfma_f32_16x16x32_bf16 v[90:93], v[164:167], v[204:207], v[90:93]
	v_mfma_f32_16x16x32_bf16 v[78:81], v[146:149], v[212:215], v[78:81]
	v_mfma_f32_16x16x32_bf16 v[74:77], v[164:167], v[212:215], v[74:77]
	v_mfma_f32_16x16x32_bf16 v[126:129], v[160:163], v[192:195], v[126:129]
	v_mfma_f32_16x16x32_bf16 v[122:125], v[168:171], v[192:195], v[122:125]
	v_mfma_f32_16x16x32_bf16 v[110:113], v[160:163], v[200:203], v[110:113]
	v_mfma_f32_16x16x32_bf16 v[106:109], v[168:171], v[200:203], v[106:109]
	v_mfma_f32_16x16x32_bf16 v[94:97], v[160:163], v[208:211], v[94:97]
	v_mfma_f32_16x16x32_bf16 v[90:93], v[168:171], v[208:211], v[90:93]
	v_mfma_f32_16x16x32_bf16 v[78:81], v[160:163], v[218:221], v[78:81]
	v_mfma_f32_16x16x32_bf16 v[74:77], v[168:171], v[218:221], v[74:77]
	s_setprio 0
	s_setprio 1
	v_mfma_f32_16x16x32_bf16 v[118:121], v[172:175], v[188:191], v[118:121]
	v_mfma_f32_16x16x32_bf16 v[114:117], v[180:183], v[188:191], v[114:117]
	v_mfma_f32_16x16x32_bf16 v[102:105], v[172:175], v[196:199], v[102:105]
	v_mfma_f32_16x16x32_bf16 v[98:101], v[180:183], v[196:199], v[98:101]
	v_mfma_f32_16x16x32_bf16 v[86:89], v[172:175], v[204:207], v[86:89]
	v_mfma_f32_16x16x32_bf16 v[82:85], v[180:183], v[204:207], v[82:85]
	v_mfma_f32_16x16x32_bf16 v[70:73], v[172:175], v[212:215], v[70:73]
	v_mfma_f32_16x16x32_bf16 v[66:69], v[180:183], v[212:215], v[66:69]
	v_mfma_f32_16x16x32_bf16 v[118:121], v[176:179], v[192:195], v[118:121]
	v_mfma_f32_16x16x32_bf16 v[114:117], v[184:187], v[192:195], v[114:117]
	v_mfma_f32_16x16x32_bf16 v[102:105], v[176:179], v[200:203], v[102:105]
	v_mfma_f32_16x16x32_bf16 v[98:101], v[184:187], v[200:203], v[98:101]
	v_mfma_f32_16x16x32_bf16 v[86:89], v[176:179], v[208:211], v[86:89]
	v_mfma_f32_16x16x32_bf16 v[82:85], v[184:187], v[208:211], v[82:85]
	v_mfma_f32_16x16x32_bf16 v[70:73], v[176:179], v[218:221], v[70:73]
	v_mfma_f32_16x16x32_bf16 v[66:69], v[184:187], v[218:221], v[66:69]
	s_barrier
	s_setprio 0
	s_add_i32 s53, s53, s13
	v_lshl_add_u64 v[150:151], v[150:151], 0, s[8:9]
	s_mov_b32 m0, s53
	ds_read_b128 v[188:191], v155 offset:49152
	ds_read_b128 v[192:195], v155 offset:50176
	ds_read_b128 v[196:199], v155 offset:51200
	ds_read_b128 v[200:203], v155 offset:52224
	ds_read_b128 v[204:207], v155 offset:53248
	ds_read_b128 v[208:211], v155 offset:54272
	ds_read_b128 v[212:215], v155 offset:55296
	ds_read_b128 v[218:221], v155 offset:56320
	global_load_lds_dwordx4 v[150:151], off
	s_add_i32 m0, s53, 0x2000
	s_add_u32 s34, s34, 0x20080
	v_lshl_add_u64 v[150:151], v[222:223], 0, s[8:9]
	s_addc_u32 s35, s35, 0
	s_add_i32 s53, s62, s13
	global_load_lds_dwordx4 v[150:151], off
	v_lshl_add_u64 v[150:151], s[34:35], 0, v[132:133]
	s_mov_b32 m0, s53
	s_nop 0
	global_load_lds_dwordx4 v[150:151], off
	v_lshl_add_u64 v[150:151], s[34:35], 0, v[136:137]
	s_add_i32 m0, s53, 0x2000
	s_nop 0
	global_load_lds_dwordx4 v[150:151], off
	v_lshl_add_u64 v[150:151], v[224:225], 0, s[8:9]
	s_mov_b32 m0, s60
	s_nop 0
	global_load_lds_dwordx4 v[150:151], off
	v_lshl_add_u64 v[150:151], v[226:227], 0, s[8:9]
	s_mov_b32 m0, s61
	s_nop 0
	global_load_lds_dwordx4 v[150:151], off
	s_waitcnt vmcnt(8)
	s_waitcnt lgkmcnt(0)
	s_setprio 1
	s_barrier
	v_mfma_f32_16x16x32_bf16 v[62:65], v[146:149], v[188:191], v[62:65]
	v_mfma_f32_16x16x32_bf16 v[58:61], v[164:167], v[188:191], v[58:61]
	v_mfma_f32_16x16x32_bf16 v[50:53], v[146:149], v[196:199], v[50:53]
	v_mfma_f32_16x16x32_bf16 v[42:45], v[164:167], v[196:199], v[42:45]
	v_mfma_f32_16x16x32_bf16 v[34:37], v[146:149], v[204:207], v[34:37]
	v_mfma_f32_16x16x32_bf16 v[26:29], v[164:167], v[204:207], v[26:29]
	v_mfma_f32_16x16x32_bf16 v[18:21], v[146:149], v[212:215], v[18:21]
	v_mfma_f32_16x16x32_bf16 v[10:13], v[164:167], v[212:215], v[10:13]
	v_mfma_f32_16x16x32_bf16 v[62:65], v[160:163], v[192:195], v[62:65]
	v_mfma_f32_16x16x32_bf16 v[58:61], v[168:171], v[192:195], v[58:61]
	v_mfma_f32_16x16x32_bf16 v[50:53], v[160:163], v[200:203], v[50:53]
	v_mfma_f32_16x16x32_bf16 v[42:45], v[168:171], v[200:203], v[42:45]
	v_mfma_f32_16x16x32_bf16 v[34:37], v[160:163], v[208:211], v[34:37]
	v_mfma_f32_16x16x32_bf16 v[26:29], v[168:171], v[208:211], v[26:29]
	v_mfma_f32_16x16x32_bf16 v[18:21], v[160:163], v[218:221], v[18:21]
	v_mfma_f32_16x16x32_bf16 v[10:13], v[168:171], v[218:221], v[10:13]
	s_setprio 0
	s_setprio 1
	v_mfma_f32_16x16x32_bf16 v[54:57], v[172:175], v[188:191], v[54:57]
	v_mfma_f32_16x16x32_bf16 v[46:49], v[180:183], v[188:191], v[46:49]
	v_mfma_f32_16x16x32_bf16 v[38:41], v[172:175], v[196:199], v[38:41]
	v_mfma_f32_16x16x32_bf16 v[30:33], v[180:183], v[196:199], v[30:33]
	v_mfma_f32_16x16x32_bf16 v[22:25], v[172:175], v[204:207], v[22:25]
	v_mfma_f32_16x16x32_bf16 v[14:17], v[180:183], v[204:207], v[14:17]
	v_mfma_f32_16x16x32_bf16 v[6:9], v[172:175], v[212:215], v[6:9]
	v_mfma_f32_16x16x32_bf16 v[2:5], v[180:183], v[212:215], v[2:5]
	v_mfma_f32_16x16x32_bf16 v[54:57], v[176:179], v[192:195], v[54:57]
	v_mfma_f32_16x16x32_bf16 v[46:49], v[184:187], v[192:195], v[46:49]
	v_mfma_f32_16x16x32_bf16 v[38:41], v[176:179], v[200:203], v[38:41]
	v_mfma_f32_16x16x32_bf16 v[30:33], v[184:187], v[200:203], v[30:33]
	v_mfma_f32_16x16x32_bf16 v[22:25], v[176:179], v[208:211], v[22:25]
	v_mfma_f32_16x16x32_bf16 v[14:17], v[184:187], v[208:211], v[14:17]
	v_mfma_f32_16x16x32_bf16 v[6:9], v[176:179], v[218:221], v[6:9]
	v_mfma_f32_16x16x32_bf16 v[2:5], v[184:187], v[218:221], v[2:5]
	s_barrier
	s_setprio 0
	s_add_i32 s88, s88, 2
	s_add_u32 s84, s84, 0x100
	s_addc_u32 s85, s85, 0
	s_add_u32 s77, s77, 0x100
	s_addc_u32 s83, s83, 0
	s_cmp_gt_u32 s88, 5
	s_cbranch_scc0 .LBB0_715
	s_and_b64 vcc, exec, s[66:67]
	s_cbranch_vccz .LBB0_718
	s_barrier

.LBB0_995:
	ds_read_b128 v[146:149], v164
	ds_read_b128 v[150:153], v164 offset:1024
	ds_read_b128 v[154:157], v164 offset:2048
	ds_read_b128 v[158:161], v164 offset:3072
	ds_read_b128 v[168:171], v165
	ds_read_b128 v[172:175], v165 offset:1024
	ds_read_b128 v[176:179], v165 offset:2048
	ds_read_b128 v[180:183], v165 offset:3072
	s_add_u32 s34, s88, 0xfff80080
	s_addc_u32 s35, s89, -1
	s_cmp_eq_u32 s81, 28
	s_cselect_b32 s91, s0, s35
	s_cselect_b32 s90, s1, s34
	s_cselect_b32 s35, s52, s77
	s_cselect_b32 s34, s74, s75
	v_lshl_add_u64 v[218:219], s[88:89], 0, v[138:139]
	s_add_i32 m0, s33, 0xc000
	ds_read_b128 v[184:187], v166
	ds_read_b128 v[188:191], v166 offset:1024
	ds_read_b128 v[192:195], v166 offset:2048
	ds_read_b128 v[196:199], v166 offset:3072
	ds_read_b128 v[200:203], v166 offset:4096
	ds_read_b128 v[204:207], v166 offset:5120
	ds_read_b128 v[208:211], v166 offset:6144
	ds_read_b128 v[212:215], v166 offset:7168
	global_load_lds_dwordx4 v[218:219], off
	v_lshl_add_u64 v[218:219], s[88:89], 0, v[140:141]
	s_add_i32 m0, s33, 0xe000
	s_nop 0
	global_load_lds_dwordx4 v[218:219], off
	s_waitcnt vmcnt(8)
	s_waitcnt lgkmcnt(0)
	s_setprio 1
	s_barrier
	v_mfma_f32_16x16x32_bf16 v[126:129], v[146:149], v[184:187], v[126:129]
	v_mfma_f32_16x16x32_bf16 v[122:125], v[154:157], v[184:187], v[122:125]
	v_mfma_f32_16x16x32_bf16 v[110:113], v[146:149], v[192:195], v[110:113]
	v_mfma_f32_16x16x32_bf16 v[106:109], v[154:157], v[192:195], v[106:109]
	v_mfma_f32_16x16x32_bf16 v[94:97], v[146:149], v[200:203], v[94:97]
	v_mfma_f32_16x16x32_bf16 v[90:93], v[154:157], v[200:203], v[90:93]
	v_mfma_f32_16x16x32_bf16 v[78:81], v[146:149], v[208:211], v[78:81]
	v_mfma_f32_16x16x32_bf16 v[74:77], v[154:157], v[208:211], v[74:77]
	v_mfma_f32_16x16x32_bf16 v[126:129], v[150:153], v[188:191], v[126:129]
	v_mfma_f32_16x16x32_bf16 v[122:125], v[158:161], v[188:191], v[122:125]
	v_mfma_f32_16x16x32_bf16 v[110:113], v[150:153], v[196:199], v[110:113]
	v_mfma_f32_16x16x32_bf16 v[106:109], v[158:161], v[196:199], v[106:109]
	v_mfma_f32_16x16x32_bf16 v[94:97], v[150:153], v[204:207], v[94:97]
	v_mfma_f32_16x16x32_bf16 v[90:93], v[158:161], v[204:207], v[90:93]
	v_mfma_f32_16x16x32_bf16 v[78:81], v[150:153], v[212:215], v[78:81]
	v_mfma_f32_16x16x32_bf16 v[74:77], v[158:161], v[212:215], v[74:77]
	s_setprio 0
	s_setprio 1
	v_mfma_f32_16x16x32_bf16 v[118:121], v[168:171], v[184:187], v[118:121]
	v_mfma_f32_16x16x32_bf16 v[114:117], v[176:179], v[184:187], v[114:117]
	v_mfma_f32_16x16x32_bf16 v[102:105], v[168:171], v[192:195], v[102:105]
	v_mfma_f32_16x16x32_bf16 v[98:101], v[176:179], v[192:195], v[98:101]
	v_mfma_f32_16x16x32_bf16 v[86:89], v[168:171], v[200:203], v[86:89]
	v_mfma_f32_16x16x32_bf16 v[82:85], v[176:179], v[200:203], v[82:85]
	v_mfma_f32_16x16x32_bf16 v[70:73], v[168:171], v[208:211], v[70:73]
	v_mfma_f32_16x16x32_bf16 v[66:69], v[176:179], v[208:211], v[66:69]
	v_mfma_f32_16x16x32_bf16 v[118:121], v[172:175], v[188:191], v[118:121]
	v_mfma_f32_16x16x32_bf16 v[114:117], v[180:183], v[188:191], v[114:117]
	v_mfma_f32_16x16x32_bf16 v[102:105], v[172:175], v[196:199], v[102:105]
	v_mfma_f32_16x16x32_bf16 v[98:101], v[180:183], v[196:199], v[98:101]
	v_mfma_f32_16x16x32_bf16 v[86:89], v[172:175], v[204:207], v[86:89]
	v_mfma_f32_16x16x32_bf16 v[82:85], v[180:183], v[204:207], v[82:85]
	v_mfma_f32_16x16x32_bf16 v[70:73], v[172:175], v[212:215], v[70:73]
	v_mfma_f32_16x16x32_bf16 v[66:69], v[180:183], v[212:215], v[66:69]
	s_barrier
	s_setprio 0
	s_add_i32 s53, s71, s31
	v_lshl_add_u64 v[218:219], s[34:35], 0, v[132:133]
	s_mov_b32 m0, s53
	ds_read_b128 v[184:187], v166 offset:16384
	ds_read_b128 v[188:191], v166 offset:17408
	ds_read_b128 v[192:195], v166 offset:18432
	ds_read_b128 v[196:199], v166 offset:19456
	ds_read_b128 v[200:203], v166 offset:20480
	ds_read_b128 v[204:207], v166 offset:21504
	ds_read_b128 v[208:211], v166 offset:22528
	ds_read_b128 v[212:215], v166 offset:23552
	global_load_lds_dwordx4 v[218:219], off
	s_add_i32 m0, s53, 0x2000
	s_add_u32 s54, s34, 0x80000
	v_lshl_add_u64 v[220:221], s[34:35], 0, v[136:137]
	s_addc_u32 s55, s35, 0
	s_add_i32 s53, s72, s31
	global_load_lds_dwordx4 v[220:221], off
	v_lshl_add_u64 v[222:223], s[54:55], 0, v[132:133]
	s_mov_b32 m0, s53
	v_lshl_add_u64 v[224:225], s[90:91], 0, v[134:135]
	global_load_lds_dwordx4 v[222:223], off
	v_lshl_add_u64 v[222:223], s[54:55], 0, v[136:137]
	s_add_i32 m0, s53, 0x2000
	s_nop 0
	global_load_lds_dwordx4 v[222:223], off
	v_lshl_add_u64 v[222:223], s[90:91], 0, v[130:131]
	s_mov_b32 m0, s33
	s_nop 0
	global_load_lds_dwordx4 v[222:223], off
	s_mov_b32 m0, s56
	s_nop 0
	global_load_lds_dwordx4 v[224:225], off
	s_waitcnt vmcnt(8)
	s_waitcnt lgkmcnt(0)
	s_setprio 1
	s_barrier
	v_mfma_f32_16x16x32_bf16 v[62:65], v[146:149], v[184:187], v[62:65]
	v_mfma_f32_16x16x32_bf16 v[58:61], v[154:157], v[184:187], v[58:61]
	v_mfma_f32_16x16x32_bf16 v[46:49], v[146:149], v[192:195], v[46:49]
	v_mfma_f32_16x16x32_bf16 v[42:45], v[154:157], v[192:195], v[42:45]
	v_mfma_f32_16x16x32_bf16 v[30:33], v[146:149], v[200:203], v[30:33]
	v_mfma_f32_16x16x32_bf16 v[26:29], v[154:157], v[200:203], v[26:29]
	v_mfma_f32_16x16x32_bf16 v[14:17], v[146:149], v[208:211], v[14:17]
	v_mfma_f32_16x16x32_bf16 v[10:13], v[154:157], v[208:211], v[10:13]
	v_mfma_f32_16x16x32_bf16 v[62:65], v[150:153], v[188:191], v[62:65]
	v_mfma_f32_16x16x32_bf16 v[58:61], v[158:161], v[188:191], v[58:61]
	v_mfma_f32_16x16x32_bf16 v[46:49], v[150:153], v[196:199], v[46:49]
	v_mfma_f32_16x16x32_bf16 v[42:45], v[158:161], v[196:199], v[42:45]
	v_mfma_f32_16x16x32_bf16 v[30:33], v[150:153], v[204:207], v[30:33]
	v_mfma_f32_16x16x32_bf16 v[26:29], v[158:161], v[204:207], v[26:29]
	v_mfma_f32_16x16x32_bf16 v[14:17], v[150:153], v[212:215], v[14:17]
	v_mfma_f32_16x16x32_bf16 v[10:13], v[158:161], v[212:215], v[10:13]
	s_setprio 0
	s_setprio 1
	v_mfma_f32_16x16x32_bf16 v[54:57], v[168:171], v[184:187], v[54:57]
	v_mfma_f32_16x16x32_bf16 v[50:53], v[176:179], v[184:187], v[50:53]
	v_mfma_f32_16x16x32_bf16 v[38:41], v[168:171], v[192:195], v[38:41]
	v_mfma_f32_16x16x32_bf16 v[34:37], v[176:179], v[192:195], v[34:37]
	v_mfma_f32_16x16x32_bf16 v[22:25], v[168:171], v[200:203], v[22:25]
	v_mfma_f32_16x16x32_bf16 v[18:21], v[176:179], v[200:203], v[18:21]
	v_mfma_f32_16x16x32_bf16 v[6:9], v[168:171], v[208:211], v[6:9]
	v_mfma_f32_16x16x32_bf16 v[2:5], v[176:179], v[208:211], v[2:5]
	v_mfma_f32_16x16x32_bf16 v[54:57], v[172:175], v[188:191], v[54:57]
	v_mfma_f32_16x16x32_bf16 v[50:53], v[180:183], v[188:191], v[50:53]
	v_mfma_f32_16x16x32_bf16 v[38:41], v[172:175], v[196:199], v[38:41]
	v_mfma_f32_16x16x32_bf16 v[34:37], v[180:183], v[196:199], v[34:37]
	v_mfma_f32_16x16x32_bf16 v[22:25], v[172:175], v[204:207], v[22:25]
	v_mfma_f32_16x16x32_bf16 v[18:21], v[180:183], v[204:207], v[18:21]
	v_mfma_f32_16x16x32_bf16 v[6:9], v[172:175], v[212:215], v[6:9]
	v_mfma_f32_16x16x32_bf16 v[2:5], v[180:183], v[212:215], v[2:5]
	s_barrier
	s_setprio 0
	s_add_i32 s53, 0, 0x18000
	s_add_i32 s62, 0, 0x1c000
	v_add_u32_e32 v158, s53, v162
	v_add_u32_e32 v167, s62, v162
	ds_read_b128 v[146:149], v158
	ds_read_b128 v[150:153], v158 offset:1024
	ds_read_b128 v[154:157], v158 offset:2048
	ds_read_b128 v[158:161], v158 offset:3072
	ds_read_b128 v[168:171], v167
	ds_read_b128 v[172:175], v167 offset:1024
	ds_read_b128 v[176:179], v167 offset:2048
	ds_read_b128 v[180:183], v167 offset:3072
	s_add_u32 s54, s90, 0x80000
	s_addc_u32 s55, s91, 0
	s_mov_b32 m0, s57
	v_lshl_add_u64 v[226:227], s[54:55], 0, v[130:131]
	ds_read_b128 v[184:187], v166 offset:32768
	ds_read_b128 v[188:191], v166 offset:33792
	ds_read_b128 v[192:195], v166 offset:34816
	ds_read_b128 v[196:199], v166 offset:35840
	ds_read_b128 v[200:203], v166 offset:36864
	ds_read_b128 v[204:207], v166 offset:37888
	ds_read_b128 v[208:211], v166 offset:38912
	ds_read_b128 v[212:215], v166 offset:39936
	global_load_lds_dwordx4 v[226:227], off
	v_lshl_add_u64 v[226:227], s[54:55], 0, v[134:135]
	s_mov_b32 m0, s58
	s_nop 0
	global_load_lds_dwordx4 v[226:227], off
	s_waitcnt vmcnt(8)
	s_waitcnt lgkmcnt(0)
	s_setprio 1
	s_barrier
	v_mfma_f32_16x16x32_bf16 v[126:129], v[146:149], v[184:187], v[126:129]
	v_mfma_f32_16x16x32_bf16 v[122:125], v[154:157], v[184:187], v[122:125]
	v_mfma_f32_16x16x32_bf16 v[110:113], v[146:149], v[192:195], v[110:113]
	v_mfma_f32_16x16x32_bf16 v[106:109], v[154:157], v[192:195], v[106:109]
	v_mfma_f32_16x16x32_bf16 v[94:97], v[146:149], v[200:203], v[94:97]
	v_mfma_f32_16x16x32_bf16 v[90:93], v[154:157], v[200:203], v[90:93]
	v_mfma_f32_16x16x32_bf16 v[78:81], v[146:149], v[208:211], v[78:81]
	v_mfma_f32_16x16x32_bf16 v[74:77], v[154:157], v[208:211], v[74:77]
	v_mfma_f32_16x16x32_bf16 v[126:129], v[150:153], v[188:191], v[126:129]
	v_mfma_f32_16x16x32_bf16 v[122:125], v[158:161], v[188:191], v[122:125]
	v_mfma_f32_16x16x32_bf16 v[110:113], v[150:153], v[196:199], v[110:113]
	v_mfma_f32_16x16x32_bf16 v[106:109], v[158:161], v[196:199], v[106:109]
	v_mfma_f32_16x16x32_bf16 v[94:97], v[150:153], v[204:207], v[94:97]
	v_mfma_f32_16x16x32_bf16 v[90:93], v[158:161], v[204:207], v[90:93]
	v_mfma_f32_16x16x32_bf16 v[78:81], v[150:153], v[212:215], v[78:81]
	v_mfma_f32_16x16x32_bf16 v[74:77], v[158:161], v[212:215], v[74:77]
	s_setprio 0
	s_setprio 1
	v_mfma_f32_16x16x32_bf16 v[118:121], v[168:171], v[184:187], v[118:121]
	v_mfma_f32_16x16x32_bf16 v[114:117], v[176:179], v[184:187], v[114:117]
	v_mfma_f32_16x16x32_bf16 v[102:105], v[168:171], v[192:195], v[102:105]
	v_mfma_f32_16x16x32_bf16 v[98:101], v[176:179], v[192:195], v[98:101]
	v_mfma_f32_16x16x32_bf16 v[86:89], v[168:171], v[200:203], v[86:89]
	v_mfma_f32_16x16x32_bf16 v[82:85], v[176:179], v[200:203], v[82:85]
	v_mfma_f32_16x16x32_bf16 v[70:73], v[168:171], v[208:211], v[70:73]
	v_mfma_f32_16x16x32_bf16 v[66:69], v[176:179], v[208:211], v[66:69]
	v_mfma_f32_16x16x32_bf16 v[118:121], v[172:175], v[188:191], v[118:121]
	v_mfma_f32_16x16x32_bf16 v[114:117], v[180:183], v[188:191], v[114:117]
	v_mfma_f32_16x16x32_bf16 v[102:105], v[172:175], v[196:199], v[102:105]
	v_mfma_f32_16x16x32_bf16 v[98:101], v[180:183], v[196:199], v[98:101]
	v_mfma_f32_16x16x32_bf16 v[86:89], v[172:175], v[204:207], v[86:89]
	v_mfma_f32_16x16x32_bf16 v[82:85], v[180:183], v[204:207], v[82:85]
	v_mfma_f32_16x16x32_bf16 v[70:73], v[172:175], v[212:215], v[70:73]
	v_mfma_f32_16x16x32_bf16 v[66:69], v[180:183], v[212:215], v[66:69]
	s_barrier
	s_setprio 0
	s_add_i32 s53, s53, s31
	v_lshl_add_u64 v[218:219], v[218:219], 0, s[8:9]
	s_mov_b32 m0, s53
	ds_read_b128 v[184:187], v166 offset:49152
	ds_read_b128 v[188:191], v166 offset:50176
	ds_read_b128 v[192:195], v166 offset:51200
	ds_read_b128 v[196:199], v166 offset:52224
	ds_read_b128 v[200:203], v166 offset:53248
	ds_read_b128 v[204:207], v166 offset:54272
	ds_read_b128 v[208:211], v166 offset:55296
	ds_read_b128 v[212:215], v166 offset:56320
	global_load_lds_dwordx4 v[218:219], off
	s_add_i32 m0, s53, 0x2000
	s_add_u32 s34, s34, 0x80080
	v_lshl_add_u64 v[218:219], v[220:221], 0, s[8:9]
	s_addc_u32 s35, s35, 0
	s_add_i32 s53, s62, s31
	global_load_lds_dwordx4 v[218:219], off
	v_lshl_add_u64 v[218:219], s[34:35], 0, v[132:133]
	s_mov_b32 m0, s53
	s_nop 0
	global_load_lds_dwordx4 v[218:219], off
	v_lshl_add_u64 v[218:219], s[34:35], 0, v[136:137]
	s_add_i32 m0, s53, 0x2000
	s_nop 0
	global_load_lds_dwordx4 v[218:219], off
	v_lshl_add_u64 v[218:219], v[222:223], 0, s[8:9]
	s_mov_b32 m0, s60
	s_nop 0
	global_load_lds_dwordx4 v[218:219], off
	v_lshl_add_u64 v[218:219], v[224:225], 0, s[8:9]
	s_mov_b32 m0, s61
	s_nop 0
	global_load_lds_dwordx4 v[218:219], off
	s_waitcnt vmcnt(8)
	s_waitcnt lgkmcnt(0)
	s_setprio 1
	s_barrier
	v_mfma_f32_16x16x32_bf16 v[62:65], v[146:149], v[184:187], v[62:65]
	v_mfma_f32_16x16x32_bf16 v[58:61], v[154:157], v[184:187], v[58:61]
	v_mfma_f32_16x16x32_bf16 v[46:49], v[146:149], v[192:195], v[46:49]
	v_mfma_f32_16x16x32_bf16 v[42:45], v[154:157], v[192:195], v[42:45]
	v_mfma_f32_16x16x32_bf16 v[30:33], v[146:149], v[200:203], v[30:33]
	v_mfma_f32_16x16x32_bf16 v[26:29], v[154:157], v[200:203], v[26:29]
	v_mfma_f32_16x16x32_bf16 v[14:17], v[146:149], v[208:211], v[14:17]
	v_mfma_f32_16x16x32_bf16 v[10:13], v[154:157], v[208:211], v[10:13]
	v_mfma_f32_16x16x32_bf16 v[62:65], v[150:153], v[188:191], v[62:65]
	v_mfma_f32_16x16x32_bf16 v[58:61], v[158:161], v[188:191], v[58:61]
	v_mfma_f32_16x16x32_bf16 v[46:49], v[150:153], v[196:199], v[46:49]
	v_mfma_f32_16x16x32_bf16 v[42:45], v[158:161], v[196:199], v[42:45]
	v_mfma_f32_16x16x32_bf16 v[30:33], v[150:153], v[204:207], v[30:33]
	v_mfma_f32_16x16x32_bf16 v[26:29], v[158:161], v[204:207], v[26:29]
	v_mfma_f32_16x16x32_bf16 v[14:17], v[150:153], v[212:215], v[14:17]
	v_mfma_f32_16x16x32_bf16 v[10:13], v[158:161], v[212:215], v[10:13]
	s_setprio 0
	s_setprio 1
	v_mfma_f32_16x16x32_bf16 v[54:57], v[168:171], v[184:187], v[54:57]
	v_mfma_f32_16x16x32_bf16 v[50:53], v[176:179], v[184:187], v[50:53]
	v_mfma_f32_16x16x32_bf16 v[38:41], v[168:171], v[192:195], v[38:41]
	v_mfma_f32_16x16x32_bf16 v[34:37], v[176:179], v[192:195], v[34:37]
	v_mfma_f32_16x16x32_bf16 v[22:25], v[168:171], v[200:203], v[22:25]
	v_mfma_f32_16x16x32_bf16 v[18:21], v[176:179], v[200:203], v[18:21]
	v_mfma_f32_16x16x32_bf16 v[6:9], v[168:171], v[208:211], v[6:9]
	v_mfma_f32_16x16x32_bf16 v[2:5], v[176:179], v[208:211], v[2:5]
	v_mfma_f32_16x16x32_bf16 v[54:57], v[172:175], v[188:191], v[54:57]
	v_mfma_f32_16x16x32_bf16 v[50:53], v[180:183], v[188:191], v[50:53]
	v_mfma_f32_16x16x32_bf16 v[38:41], v[172:175], v[196:199], v[38:41]
	v_mfma_f32_16x16x32_bf16 v[34:37], v[180:183], v[196:199], v[34:37]
	v_mfma_f32_16x16x32_bf16 v[22:25], v[172:175], v[204:207], v[22:25]
	v_mfma_f32_16x16x32_bf16 v[18:21], v[180:183], v[204:207], v[18:21]
	v_mfma_f32_16x16x32_bf16 v[6:9], v[172:175], v[212:215], v[6:9]
	v_mfma_f32_16x16x32_bf16 v[2:5], v[180:183], v[212:215], v[2:5]
	s_barrier
	s_setprio 0
	s_add_i32 s81, s81, 2
	s_add_u32 s88, s88, 0x100
	s_addc_u32 s89, s89, 0
	s_add_u32 s75, s75, 0x100
	s_addc_u32 s77, s77, 0
	s_cmp_gt_u32 s81, 29
	s_cbranch_scc0 .LBB0_995
	s_and_b64 vcc, exec, s[78:79]
	s_cbranch_vccz .LBB0_998
	s_barrier

.LBB0_1124:
	ds_read_b128 v[146:149], v153
	ds_read_b128 v[156:159], v153 offset:1024
	ds_read_b128 v[160:163], v153 offset:2048
	ds_read_b128 v[164:167], v153 offset:3072
	ds_read_b128 v[168:171], v154
	ds_read_b128 v[172:175], v154 offset:1024
	ds_read_b128 v[176:179], v154 offset:2048
	ds_read_b128 v[180:183], v154 offset:3072
	s_add_u32 s34, s88, 0xfff80080
	s_addc_u32 s35, s89, -1
	s_cmp_eq_u32 s92, 28
	s_cselect_b32 s91, s0, s35
	s_cselect_b32 s90, s1, s34
	s_cselect_b32 s35, s52, s83
	s_cselect_b32 s34, s77, s81
	v_lshl_add_u64 v[218:219], s[88:89], 0, v[138:139]
	s_add_i32 m0, s56, 0xc000
	ds_read_b128 v[184:187], v155
	ds_read_b128 v[188:191], v155 offset:1024
	ds_read_b128 v[192:195], v155 offset:2048
	ds_read_b128 v[196:199], v155 offset:3072
	ds_read_b128 v[200:203], v155 offset:4096
	ds_read_b128 v[204:207], v155 offset:5120
	ds_read_b128 v[208:211], v155 offset:6144
	ds_read_b128 v[212:215], v155 offset:7168
	global_load_lds_dwordx4 v[218:219], off
	v_lshl_add_u64 v[218:219], s[88:89], 0, v[140:141]
	s_add_i32 m0, s56, 0xe000
	s_nop 0
	global_load_lds_dwordx4 v[218:219], off
	s_waitcnt vmcnt(8)
	s_waitcnt lgkmcnt(0)
	s_setprio 1
	s_barrier
	v_mfma_f32_16x16x32_bf16 v[126:129], v[146:149], v[184:187], v[126:129]
	v_mfma_f32_16x16x32_bf16 v[118:121], v[160:163], v[184:187], v[118:121]
	v_mfma_f32_16x16x32_bf16 v[110:113], v[146:149], v[192:195], v[110:113]
	v_mfma_f32_16x16x32_bf16 v[102:105], v[160:163], v[192:195], v[102:105]
	v_mfma_f32_16x16x32_bf16 v[94:97], v[146:149], v[200:203], v[94:97]
	v_mfma_f32_16x16x32_bf16 v[86:89], v[160:163], v[200:203], v[86:89]
	v_mfma_f32_16x16x32_bf16 v[78:81], v[146:149], v[208:211], v[78:81]
	v_mfma_f32_16x16x32_bf16 v[70:73], v[160:163], v[208:211], v[70:73]
	v_mfma_f32_16x16x32_bf16 v[126:129], v[156:159], v[188:191], v[126:129]
	v_mfma_f32_16x16x32_bf16 v[118:121], v[164:167], v[188:191], v[118:121]
	v_mfma_f32_16x16x32_bf16 v[110:113], v[156:159], v[196:199], v[110:113]
	v_mfma_f32_16x16x32_bf16 v[102:105], v[164:167], v[196:199], v[102:105]
	v_mfma_f32_16x16x32_bf16 v[94:97], v[156:159], v[204:207], v[94:97]
	v_mfma_f32_16x16x32_bf16 v[86:89], v[164:167], v[204:207], v[86:89]
	v_mfma_f32_16x16x32_bf16 v[78:81], v[156:159], v[212:215], v[78:81]
	v_mfma_f32_16x16x32_bf16 v[70:73], v[164:167], v[212:215], v[70:73]
	s_setprio 0
	s_setprio 1
	v_mfma_f32_16x16x32_bf16 v[122:125], v[168:171], v[184:187], v[122:125]
	v_mfma_f32_16x16x32_bf16 v[114:117], v[176:179], v[184:187], v[114:117]
	v_mfma_f32_16x16x32_bf16 v[106:109], v[168:171], v[192:195], v[106:109]
	v_mfma_f32_16x16x32_bf16 v[98:101], v[176:179], v[192:195], v[98:101]
	v_mfma_f32_16x16x32_bf16 v[90:93], v[168:171], v[200:203], v[90:93]
	v_mfma_f32_16x16x32_bf16 v[82:85], v[176:179], v[200:203], v[82:85]
	v_mfma_f32_16x16x32_bf16 v[74:77], v[168:171], v[208:211], v[74:77]
	v_mfma_f32_16x16x32_bf16 v[66:69], v[176:179], v[208:211], v[66:69]
	v_mfma_f32_16x16x32_bf16 v[122:125], v[172:175], v[188:191], v[122:125]
	v_mfma_f32_16x16x32_bf16 v[114:117], v[180:183], v[188:191], v[114:117]
	v_mfma_f32_16x16x32_bf16 v[106:109], v[172:175], v[196:199], v[106:109]
	v_mfma_f32_16x16x32_bf16 v[98:101], v[180:183], v[196:199], v[98:101]
	v_mfma_f32_16x16x32_bf16 v[90:93], v[172:175], v[204:207], v[90:93]
	v_mfma_f32_16x16x32_bf16 v[82:85], v[180:183], v[204:207], v[82:85]
	v_mfma_f32_16x16x32_bf16 v[74:77], v[172:175], v[212:215], v[74:77]
	v_mfma_f32_16x16x32_bf16 v[66:69], v[180:183], v[212:215], v[66:69]
	s_barrier
	s_setprio 0
	s_add_i32 s53, s72, s30
	v_lshl_add_u64 v[218:219], s[34:35], 0, v[134:135]
	s_mov_b32 m0, s53
	ds_read_b128 v[184:187], v155 offset:16384
	ds_read_b128 v[188:191], v155 offset:17408
	ds_read_b128 v[192:195], v155 offset:18432
	ds_read_b128 v[196:199], v155 offset:19456
	ds_read_b128 v[200:203], v155 offset:20480
	ds_read_b128 v[204:207], v155 offset:21504
	ds_read_b128 v[208:211], v155 offset:22528
	ds_read_b128 v[212:215], v155 offset:23552
	global_load_lds_dwordx4 v[218:219], off
	s_add_i32 m0, s53, 0x2000
	s_add_u32 s54, s34, 0x80000
	v_lshl_add_u64 v[220:221], s[34:35], 0, v[130:131]
	s_addc_u32 s55, s35, 0
	s_add_i32 s53, s73, s30
	global_load_lds_dwordx4 v[220:221], off
	v_lshl_add_u64 v[222:223], s[54:55], 0, v[134:135]
	s_mov_b32 m0, s53
	v_lshl_add_u64 v[224:225], s[90:91], 0, v[132:133]
	global_load_lds_dwordx4 v[222:223], off
	v_lshl_add_u64 v[222:223], s[54:55], 0, v[130:131]
	s_add_i32 m0, s53, 0x2000
	s_nop 0
	global_load_lds_dwordx4 v[222:223], off
	v_lshl_add_u64 v[222:223], s[90:91], 0, v[136:137]
	s_mov_b32 m0, s56
	s_nop 0
	global_load_lds_dwordx4 v[222:223], off
	s_mov_b32 m0, s57
	s_nop 0
	global_load_lds_dwordx4 v[224:225], off
	s_waitcnt vmcnt(8)
	s_waitcnt lgkmcnt(0)
	s_setprio 1
	s_barrier
	v_mfma_f32_16x16x32_bf16 v[62:65], v[146:149], v[184:187], v[62:65]
	v_mfma_f32_16x16x32_bf16 v[54:57], v[160:163], v[184:187], v[54:57]
	v_mfma_f32_16x16x32_bf16 v[46:49], v[146:149], v[192:195], v[46:49]
	v_mfma_f32_16x16x32_bf16 v[38:41], v[160:163], v[192:195], v[38:41]
	v_mfma_f32_16x16x32_bf16 v[30:33], v[146:149], v[200:203], v[30:33]
	v_mfma_f32_16x16x32_bf16 v[22:25], v[160:163], v[200:203], v[22:25]
	v_mfma_f32_16x16x32_bf16 v[14:17], v[146:149], v[208:211], v[14:17]
	v_mfma_f32_16x16x32_bf16 v[6:9], v[160:163], v[208:211], v[6:9]
	v_mfma_f32_16x16x32_bf16 v[62:65], v[156:159], v[188:191], v[62:65]
	v_mfma_f32_16x16x32_bf16 v[54:57], v[164:167], v[188:191], v[54:57]
	v_mfma_f32_16x16x32_bf16 v[46:49], v[156:159], v[196:199], v[46:49]
	v_mfma_f32_16x16x32_bf16 v[38:41], v[164:167], v[196:199], v[38:41]
	v_mfma_f32_16x16x32_bf16 v[30:33], v[156:159], v[204:207], v[30:33]
	v_mfma_f32_16x16x32_bf16 v[22:25], v[164:167], v[204:207], v[22:25]
	v_mfma_f32_16x16x32_bf16 v[14:17], v[156:159], v[212:215], v[14:17]
	v_mfma_f32_16x16x32_bf16 v[6:9], v[164:167], v[212:215], v[6:9]
	s_setprio 0
	s_setprio 1
	v_mfma_f32_16x16x32_bf16 v[58:61], v[168:171], v[184:187], v[58:61]
	v_mfma_f32_16x16x32_bf16 v[50:53], v[176:179], v[184:187], v[50:53]
	v_mfma_f32_16x16x32_bf16 v[42:45], v[168:171], v[192:195], v[42:45]
	v_mfma_f32_16x16x32_bf16 v[34:37], v[176:179], v[192:195], v[34:37]
	v_mfma_f32_16x16x32_bf16 v[26:29], v[168:171], v[200:203], v[26:29]
	v_mfma_f32_16x16x32_bf16 v[18:21], v[176:179], v[200:203], v[18:21]
	v_mfma_f32_16x16x32_bf16 v[10:13], v[168:171], v[208:211], v[10:13]
	v_mfma_f32_16x16x32_bf16 v[2:5], v[176:179], v[208:211], v[2:5]
	v_mfma_f32_16x16x32_bf16 v[58:61], v[172:175], v[188:191], v[58:61]
	v_mfma_f32_16x16x32_bf16 v[50:53], v[180:183], v[188:191], v[50:53]
	v_mfma_f32_16x16x32_bf16 v[42:45], v[172:175], v[196:199], v[42:45]
	v_mfma_f32_16x16x32_bf16 v[34:37], v[180:183], v[196:199], v[34:37]
	v_mfma_f32_16x16x32_bf16 v[26:29], v[172:175], v[204:207], v[26:29]
	v_mfma_f32_16x16x32_bf16 v[18:21], v[180:183], v[204:207], v[18:21]
	v_mfma_f32_16x16x32_bf16 v[10:13], v[172:175], v[212:215], v[10:13]
	v_mfma_f32_16x16x32_bf16 v[2:5], v[180:183], v[212:215], v[2:5]
	s_barrier
	s_setprio 0
	s_add_i32 s53, 0, 0x18000
	s_add_i32 s62, 0, 0x1c000
	v_add_u32_e32 v164, s53, v151
	v_add_u32_e32 v180, s62, v151
	ds_read_b128 v[146:149], v164
	ds_read_b128 v[156:159], v164 offset:1024
	ds_read_b128 v[160:163], v164 offset:2048
	ds_read_b128 v[164:167], v164 offset:3072
	ds_read_b128 v[168:171], v180
	ds_read_b128 v[172:175], v180 offset:1024
	ds_read_b128 v[176:179], v180 offset:2048
	ds_read_b128 v[180:183], v180 offset:3072
	s_add_u32 s54, s90, 0x80000
	s_addc_u32 s55, s91, 0
	s_mov_b32 m0, s58
	v_lshl_add_u64 v[226:227], s[54:55], 0, v[136:137]
	ds_read_b128 v[184:187], v155 offset:32768
	ds_read_b128 v[188:191], v155 offset:33792
	ds_read_b128 v[192:195], v155 offset:34816
	ds_read_b128 v[196:199], v155 offset:35840
	ds_read_b128 v[200:203], v155 offset:36864
	ds_read_b128 v[204:207], v155 offset:37888
	ds_read_b128 v[208:211], v155 offset:38912
	ds_read_b128 v[212:215], v155 offset:39936
	global_load_lds_dwordx4 v[226:227], off
	v_lshl_add_u64 v[226:227], s[54:55], 0, v[132:133]
	s_mov_b32 m0, s59
	s_nop 0
	global_load_lds_dwordx4 v[226:227], off
	s_waitcnt vmcnt(8)
	s_waitcnt lgkmcnt(0)
	s_setprio 1
	s_barrier
	v_mfma_f32_16x16x32_bf16 v[126:129], v[146:149], v[184:187], v[126:129]
	v_mfma_f32_16x16x32_bf16 v[118:121], v[160:163], v[184:187], v[118:121]
	v_mfma_f32_16x16x32_bf16 v[110:113], v[146:149], v[192:195], v[110:113]
	v_mfma_f32_16x16x32_bf16 v[102:105], v[160:163], v[192:195], v[102:105]
	v_mfma_f32_16x16x32_bf16 v[94:97], v[146:149], v[200:203], v[94:97]
	v_mfma_f32_16x16x32_bf16 v[86:89], v[160:163], v[200:203], v[86:89]
	v_mfma_f32_16x16x32_bf16 v[78:81], v[146:149], v[208:211], v[78:81]
	v_mfma_f32_16x16x32_bf16 v[70:73], v[160:163], v[208:211], v[70:73]
	v_mfma_f32_16x16x32_bf16 v[126:129], v[156:159], v[188:191], v[126:129]
	v_mfma_f32_16x16x32_bf16 v[118:121], v[164:167], v[188:191], v[118:121]
	v_mfma_f32_16x16x32_bf16 v[110:113], v[156:159], v[196:199], v[110:113]
	v_mfma_f32_16x16x32_bf16 v[102:105], v[164:167], v[196:199], v[102:105]
	v_mfma_f32_16x16x32_bf16 v[94:97], v[156:159], v[204:207], v[94:97]
	v_mfma_f32_16x16x32_bf16 v[86:89], v[164:167], v[204:207], v[86:89]
	v_mfma_f32_16x16x32_bf16 v[78:81], v[156:159], v[212:215], v[78:81]
	v_mfma_f32_16x16x32_bf16 v[70:73], v[164:167], v[212:215], v[70:73]
	s_setprio 0
	s_setprio 1
	v_mfma_f32_16x16x32_bf16 v[122:125], v[168:171], v[184:187], v[122:125]
	v_mfma_f32_16x16x32_bf16 v[114:117], v[176:179], v[184:187], v[114:117]
	v_mfma_f32_16x16x32_bf16 v[106:109], v[168:171], v[192:195], v[106:109]
	v_mfma_f32_16x16x32_bf16 v[98:101], v[176:179], v[192:195], v[98:101]
	v_mfma_f32_16x16x32_bf16 v[90:93], v[168:171], v[200:203], v[90:93]
	v_mfma_f32_16x16x32_bf16 v[82:85], v[176:179], v[200:203], v[82:85]
	v_mfma_f32_16x16x32_bf16 v[74:77], v[168:171], v[208:211], v[74:77]
	v_mfma_f32_16x16x32_bf16 v[66:69], v[176:179], v[208:211], v[66:69]
	v_mfma_f32_16x16x32_bf16 v[122:125], v[172:175], v[188:191], v[122:125]
	v_mfma_f32_16x16x32_bf16 v[114:117], v[180:183], v[188:191], v[114:117]
	v_mfma_f32_16x16x32_bf16 v[106:109], v[172:175], v[196:199], v[106:109]
	v_mfma_f32_16x16x32_bf16 v[98:101], v[180:183], v[196:199], v[98:101]
	v_mfma_f32_16x16x32_bf16 v[90:93], v[172:175], v[204:207], v[90:93]
	v_mfma_f32_16x16x32_bf16 v[82:85], v[180:183], v[204:207], v[82:85]
	v_mfma_f32_16x16x32_bf16 v[74:77], v[172:175], v[212:215], v[74:77]
	v_mfma_f32_16x16x32_bf16 v[66:69], v[180:183], v[212:215], v[66:69]
	s_barrier
	s_setprio 0
	s_add_i32 s53, s53, s30
	v_lshl_add_u64 v[218:219], v[218:219], 0, s[8:9]
	s_mov_b32 m0, s53
	ds_read_b128 v[184:187], v155 offset:49152
	ds_read_b128 v[188:191], v155 offset:50176
	ds_read_b128 v[192:195], v155 offset:51200
	ds_read_b128 v[196:199], v155 offset:52224
	ds_read_b128 v[200:203], v155 offset:53248
	ds_read_b128 v[204:207], v155 offset:54272
	ds_read_b128 v[208:211], v155 offset:55296
	ds_read_b128 v[212:215], v155 offset:56320
	global_load_lds_dwordx4 v[218:219], off
	s_add_i32 m0, s53, 0x2000
	s_add_u32 s34, s34, 0x80080
	v_lshl_add_u64 v[218:219], v[220:221], 0, s[8:9]
	s_addc_u32 s35, s35, 0
	s_add_i32 s53, s62, s30
	global_load_lds_dwordx4 v[218:219], off
	v_lshl_add_u64 v[218:219], s[34:35], 0, v[134:135]
	s_mov_b32 m0, s53
	s_nop 0
	global_load_lds_dwordx4 v[218:219], off
	v_lshl_add_u64 v[218:219], s[34:35], 0, v[130:131]
	s_add_i32 m0, s53, 0x2000
	s_nop 0
	global_load_lds_dwordx4 v[218:219], off
	v_lshl_add_u64 v[218:219], v[222:223], 0, s[8:9]
	s_mov_b32 m0, s61
	s_nop 0
	global_load_lds_dwordx4 v[218:219], off
	v_lshl_add_u64 v[218:219], v[224:225], 0, s[8:9]
	s_mov_b32 m0, s70
	s_nop 0
	global_load_lds_dwordx4 v[218:219], off
	s_waitcnt vmcnt(8)
	s_waitcnt lgkmcnt(0)
	s_setprio 1
	s_barrier
	v_mfma_f32_16x16x32_bf16 v[62:65], v[146:149], v[184:187], v[62:65]
	v_mfma_f32_16x16x32_bf16 v[54:57], v[160:163], v[184:187], v[54:57]
	v_mfma_f32_16x16x32_bf16 v[46:49], v[146:149], v[192:195], v[46:49]
	v_mfma_f32_16x16x32_bf16 v[38:41], v[160:163], v[192:195], v[38:41]
	v_mfma_f32_16x16x32_bf16 v[30:33], v[146:149], v[200:203], v[30:33]
	v_mfma_f32_16x16x32_bf16 v[22:25], v[160:163], v[200:203], v[22:25]
	v_mfma_f32_16x16x32_bf16 v[14:17], v[146:149], v[208:211], v[14:17]
	v_mfma_f32_16x16x32_bf16 v[6:9], v[160:163], v[208:211], v[6:9]
	v_mfma_f32_16x16x32_bf16 v[62:65], v[156:159], v[188:191], v[62:65]
	v_mfma_f32_16x16x32_bf16 v[54:57], v[164:167], v[188:191], v[54:57]
	v_mfma_f32_16x16x32_bf16 v[46:49], v[156:159], v[196:199], v[46:49]
	v_mfma_f32_16x16x32_bf16 v[38:41], v[164:167], v[196:199], v[38:41]
	v_mfma_f32_16x16x32_bf16 v[30:33], v[156:159], v[204:207], v[30:33]
	v_mfma_f32_16x16x32_bf16 v[22:25], v[164:167], v[204:207], v[22:25]
	v_mfma_f32_16x16x32_bf16 v[14:17], v[156:159], v[212:215], v[14:17]
	v_mfma_f32_16x16x32_bf16 v[6:9], v[164:167], v[212:215], v[6:9]
	s_setprio 0
	s_setprio 1
	v_mfma_f32_16x16x32_bf16 v[58:61], v[168:171], v[184:187], v[58:61]
	v_mfma_f32_16x16x32_bf16 v[50:53], v[176:179], v[184:187], v[50:53]
	v_mfma_f32_16x16x32_bf16 v[42:45], v[168:171], v[192:195], v[42:45]
	v_mfma_f32_16x16x32_bf16 v[34:37], v[176:179], v[192:195], v[34:37]
	v_mfma_f32_16x16x32_bf16 v[26:29], v[168:171], v[200:203], v[26:29]
	v_mfma_f32_16x16x32_bf16 v[18:21], v[176:179], v[200:203], v[18:21]
	v_mfma_f32_16x16x32_bf16 v[10:13], v[168:171], v[208:211], v[10:13]
	v_mfma_f32_16x16x32_bf16 v[2:5], v[176:179], v[208:211], v[2:5]
	v_mfma_f32_16x16x32_bf16 v[58:61], v[172:175], v[188:191], v[58:61]
	v_mfma_f32_16x16x32_bf16 v[50:53], v[180:183], v[188:191], v[50:53]
	v_mfma_f32_16x16x32_bf16 v[42:45], v[172:175], v[196:199], v[42:45]
	v_mfma_f32_16x16x32_bf16 v[34:37], v[180:183], v[196:199], v[34:37]
	v_mfma_f32_16x16x32_bf16 v[26:29], v[172:175], v[204:207], v[26:29]
	v_mfma_f32_16x16x32_bf16 v[18:21], v[180:183], v[204:207], v[18:21]
	v_mfma_f32_16x16x32_bf16 v[10:13], v[172:175], v[212:215], v[10:13]
	v_mfma_f32_16x16x32_bf16 v[2:5], v[180:183], v[212:215], v[2:5]
	s_barrier
	s_setprio 0
	s_add_i32 s92, s92, 2
	s_add_u32 s88, s88, 0x100
	s_addc_u32 s89, s89, 0
	s_add_u32 s81, s81, 0x100
	s_addc_u32 s83, s83, 0
	s_cmp_gt_u32 s92, 29
	s_cbranch_scc0 .LBB0_1124
	s_and_b64 vcc, exec, s[78:79]
	s_cbranch_vccz .LBB0_1127
	s_barrier

.LBB0_1237:
	ds_read_b128 v[146:149], v164
	ds_read_b128 v[150:153], v164 offset:1024
	ds_read_b128 v[154:157], v164 offset:2048
	ds_read_b128 v[158:161], v164 offset:3072
	ds_read_b128 v[168:171], v165
	ds_read_b128 v[172:175], v165 offset:1024
	ds_read_b128 v[176:179], v165 offset:2048
	ds_read_b128 v[180:183], v165 offset:3072
	s_add_u32 s34, s76, 0xffea0080
	s_addc_u32 s35, s77, -1
	s_cmpk_eq_i32 s52, 0x54
	s_cselect_b32 s85, s5, s35
	s_cselect_b32 s84, s4, s34
	s_cselect_b32 s35, s83, s1
	s_cselect_b32 s34, s82, s0
	v_lshl_add_u64 v[218:219], s[76:77], 0, v[138:139]
	s_add_i32 m0, s33, 0xc000
	ds_read_b128 v[184:187], v166
	ds_read_b128 v[188:191], v166 offset:1024
	ds_read_b128 v[192:195], v166 offset:2048
	ds_read_b128 v[196:199], v166 offset:3072
	ds_read_b128 v[200:203], v166 offset:4096
	ds_read_b128 v[204:207], v166 offset:5120
	ds_read_b128 v[208:211], v166 offset:6144
	ds_read_b128 v[212:215], v166 offset:7168
	global_load_lds_dwordx4 v[218:219], off
	v_lshl_add_u64 v[218:219], s[76:77], 0, v[140:141]
	s_add_i32 m0, s33, 0xe000
	s_nop 0
	global_load_lds_dwordx4 v[218:219], off
	s_waitcnt vmcnt(8)
	s_waitcnt lgkmcnt(0)
	s_setprio 1
	s_barrier
	v_mfma_f32_16x16x32_bf16 v[126:129], v[146:149], v[184:187], v[126:129]
	v_mfma_f32_16x16x32_bf16 v[122:125], v[154:157], v[184:187], v[122:125]
	v_mfma_f32_16x16x32_bf16 v[110:113], v[146:149], v[192:195], v[110:113]
	v_mfma_f32_16x16x32_bf16 v[106:109], v[154:157], v[192:195], v[106:109]
	v_mfma_f32_16x16x32_bf16 v[94:97], v[146:149], v[200:203], v[94:97]
	v_mfma_f32_16x16x32_bf16 v[90:93], v[154:157], v[200:203], v[90:93]
	v_mfma_f32_16x16x32_bf16 v[78:81], v[146:149], v[208:211], v[78:81]
	v_mfma_f32_16x16x32_bf16 v[74:77], v[154:157], v[208:211], v[74:77]
	v_mfma_f32_16x16x32_bf16 v[126:129], v[150:153], v[188:191], v[126:129]
	v_mfma_f32_16x16x32_bf16 v[122:125], v[158:161], v[188:191], v[122:125]
	v_mfma_f32_16x16x32_bf16 v[110:113], v[150:153], v[196:199], v[110:113]
	v_mfma_f32_16x16x32_bf16 v[106:109], v[158:161], v[196:199], v[106:109]
	v_mfma_f32_16x16x32_bf16 v[94:97], v[150:153], v[204:207], v[94:97]
	v_mfma_f32_16x16x32_bf16 v[90:93], v[158:161], v[204:207], v[90:93]
	v_mfma_f32_16x16x32_bf16 v[78:81], v[150:153], v[212:215], v[78:81]
	v_mfma_f32_16x16x32_bf16 v[74:77], v[158:161], v[212:215], v[74:77]
	s_setprio 0
	s_setprio 1
	v_mfma_f32_16x16x32_bf16 v[118:121], v[168:171], v[184:187], v[118:121]
	v_mfma_f32_16x16x32_bf16 v[114:117], v[176:179], v[184:187], v[114:117]
	v_mfma_f32_16x16x32_bf16 v[102:105], v[168:171], v[192:195], v[102:105]
	v_mfma_f32_16x16x32_bf16 v[98:101], v[176:179], v[192:195], v[98:101]
	v_mfma_f32_16x16x32_bf16 v[86:89], v[168:171], v[200:203], v[86:89]
	v_mfma_f32_16x16x32_bf16 v[82:85], v[176:179], v[200:203], v[82:85]
	v_mfma_f32_16x16x32_bf16 v[70:73], v[168:171], v[208:211], v[70:73]
	v_mfma_f32_16x16x32_bf16 v[66:69], v[176:179], v[208:211], v[66:69]
	v_mfma_f32_16x16x32_bf16 v[118:121], v[172:175], v[188:191], v[118:121]
	v_mfma_f32_16x16x32_bf16 v[114:117], v[180:183], v[188:191], v[114:117]
	v_mfma_f32_16x16x32_bf16 v[102:105], v[172:175], v[196:199], v[102:105]
	v_mfma_f32_16x16x32_bf16 v[98:101], v[180:183], v[196:199], v[98:101]
	v_mfma_f32_16x16x32_bf16 v[86:89], v[172:175], v[204:207], v[86:89]
	v_mfma_f32_16x16x32_bf16 v[82:85], v[180:183], v[204:207], v[82:85]
	v_mfma_f32_16x16x32_bf16 v[70:73], v[172:175], v[212:215], v[70:73]
	v_mfma_f32_16x16x32_bf16 v[66:69], v[180:183], v[212:215], v[66:69]
	s_barrier
	s_setprio 0
	s_add_i32 s53, s71, s31
	v_lshl_add_u64 v[218:219], s[34:35], 0, v[132:133]
	s_mov_b32 m0, s53
	ds_read_b128 v[184:187], v166 offset:16384
	ds_read_b128 v[188:191], v166 offset:17408
	ds_read_b128 v[192:195], v166 offset:18432
	ds_read_b128 v[196:199], v166 offset:19456
	ds_read_b128 v[200:203], v166 offset:20480
	ds_read_b128 v[204:207], v166 offset:21504
	ds_read_b128 v[208:211], v166 offset:22528
	ds_read_b128 v[212:215], v166 offset:23552
	global_load_lds_dwordx4 v[218:219], off
	s_add_i32 m0, s53, 0x2000
	s_add_u32 s54, s34, 0x160000
	v_lshl_add_u64 v[220:221], s[34:35], 0, v[136:137]
	s_addc_u32 s55, s35, 0
	s_add_i32 s53, s72, s31
	global_load_lds_dwordx4 v[220:221], off
	v_lshl_add_u64 v[222:223], s[54:55], 0, v[132:133]
	s_mov_b32 m0, s53
	v_lshl_add_u64 v[224:225], s[84:85], 0, v[134:135]
	global_load_lds_dwordx4 v[222:223], off
	v_lshl_add_u64 v[222:223], s[54:55], 0, v[136:137]
	s_add_i32 m0, s53, 0x2000
	s_nop 0
	global_load_lds_dwordx4 v[222:223], off
	v_lshl_add_u64 v[222:223], s[84:85], 0, v[130:131]
	s_mov_b32 m0, s33
	s_nop 0
	global_load_lds_dwordx4 v[222:223], off
	s_mov_b32 m0, s56
	s_nop 0
	global_load_lds_dwordx4 v[224:225], off
	s_waitcnt vmcnt(8)
	s_waitcnt lgkmcnt(0)
	s_setprio 1
	s_barrier
	v_mfma_f32_16x16x32_bf16 v[62:65], v[146:149], v[184:187], v[62:65]
	v_mfma_f32_16x16x32_bf16 v[58:61], v[154:157], v[184:187], v[58:61]
	v_mfma_f32_16x16x32_bf16 v[46:49], v[146:149], v[192:195], v[46:49]
	v_mfma_f32_16x16x32_bf16 v[42:45], v[154:157], v[192:195], v[42:45]
	v_mfma_f32_16x16x32_bf16 v[30:33], v[146:149], v[200:203], v[30:33]
	v_mfma_f32_16x16x32_bf16 v[26:29], v[154:157], v[200:203], v[26:29]
	v_mfma_f32_16x16x32_bf16 v[14:17], v[146:149], v[208:211], v[14:17]
	v_mfma_f32_16x16x32_bf16 v[10:13], v[154:157], v[208:211], v[10:13]
	v_mfma_f32_16x16x32_bf16 v[62:65], v[150:153], v[188:191], v[62:65]
	v_mfma_f32_16x16x32_bf16 v[58:61], v[158:161], v[188:191], v[58:61]
	v_mfma_f32_16x16x32_bf16 v[46:49], v[150:153], v[196:199], v[46:49]
	v_mfma_f32_16x16x32_bf16 v[42:45], v[158:161], v[196:199], v[42:45]
	v_mfma_f32_16x16x32_bf16 v[30:33], v[150:153], v[204:207], v[30:33]
	v_mfma_f32_16x16x32_bf16 v[26:29], v[158:161], v[204:207], v[26:29]
	v_mfma_f32_16x16x32_bf16 v[14:17], v[150:153], v[212:215], v[14:17]
	v_mfma_f32_16x16x32_bf16 v[10:13], v[158:161], v[212:215], v[10:13]
	s_setprio 0
	s_setprio 1
	v_mfma_f32_16x16x32_bf16 v[54:57], v[168:171], v[184:187], v[54:57]
	v_mfma_f32_16x16x32_bf16 v[50:53], v[176:179], v[184:187], v[50:53]
	v_mfma_f32_16x16x32_bf16 v[38:41], v[168:171], v[192:195], v[38:41]
	v_mfma_f32_16x16x32_bf16 v[34:37], v[176:179], v[192:195], v[34:37]
	v_mfma_f32_16x16x32_bf16 v[22:25], v[168:171], v[200:203], v[22:25]
	v_mfma_f32_16x16x32_bf16 v[18:21], v[176:179], v[200:203], v[18:21]
	v_mfma_f32_16x16x32_bf16 v[6:9], v[168:171], v[208:211], v[6:9]
	v_mfma_f32_16x16x32_bf16 v[2:5], v[176:179], v[208:211], v[2:5]
	v_mfma_f32_16x16x32_bf16 v[54:57], v[172:175], v[188:191], v[54:57]
	v_mfma_f32_16x16x32_bf16 v[50:53], v[180:183], v[188:191], v[50:53]
	v_mfma_f32_16x16x32_bf16 v[38:41], v[172:175], v[196:199], v[38:41]
	v_mfma_f32_16x16x32_bf16 v[34:37], v[180:183], v[196:199], v[34:37]
	v_mfma_f32_16x16x32_bf16 v[22:25], v[172:175], v[204:207], v[22:25]
	v_mfma_f32_16x16x32_bf16 v[18:21], v[180:183], v[204:207], v[18:21]
	v_mfma_f32_16x16x32_bf16 v[6:9], v[172:175], v[212:215], v[6:9]
	v_mfma_f32_16x16x32_bf16 v[2:5], v[180:183], v[212:215], v[2:5]
	s_barrier
	s_setprio 0
	s_add_i32 s53, 0, 0x18000
	s_add_i32 s62, 0, 0x1c000
	v_add_u32_e32 v158, s53, v162
	v_add_u32_e32 v167, s62, v162
	ds_read_b128 v[146:149], v158
	ds_read_b128 v[150:153], v158 offset:1024
	ds_read_b128 v[154:157], v158 offset:2048
	ds_read_b128 v[158:161], v158 offset:3072
	ds_read_b128 v[168:171], v167
	ds_read_b128 v[172:175], v167 offset:1024
	ds_read_b128 v[176:179], v167 offset:2048
	ds_read_b128 v[180:183], v167 offset:3072
	s_add_u32 s54, s84, 0x160000
	s_addc_u32 s55, s85, 0
	s_mov_b32 m0, s57
	v_lshl_add_u64 v[226:227], s[54:55], 0, v[130:131]
	ds_read_b128 v[184:187], v166 offset:32768
	ds_read_b128 v[188:191], v166 offset:33792
	ds_read_b128 v[192:195], v166 offset:34816
	ds_read_b128 v[196:199], v166 offset:35840
	ds_read_b128 v[200:203], v166 offset:36864
	ds_read_b128 v[204:207], v166 offset:37888
	ds_read_b128 v[208:211], v166 offset:38912
	ds_read_b128 v[212:215], v166 offset:39936
	global_load_lds_dwordx4 v[226:227], off
	v_lshl_add_u64 v[226:227], s[54:55], 0, v[134:135]
	s_mov_b32 m0, s58
	s_nop 0
	global_load_lds_dwordx4 v[226:227], off
	s_waitcnt vmcnt(8)
	s_waitcnt lgkmcnt(0)
	s_setprio 1
	s_barrier
	v_mfma_f32_16x16x32_bf16 v[126:129], v[146:149], v[184:187], v[126:129]
	v_mfma_f32_16x16x32_bf16 v[122:125], v[154:157], v[184:187], v[122:125]
	v_mfma_f32_16x16x32_bf16 v[110:113], v[146:149], v[192:195], v[110:113]
	v_mfma_f32_16x16x32_bf16 v[106:109], v[154:157], v[192:195], v[106:109]
	v_mfma_f32_16x16x32_bf16 v[94:97], v[146:149], v[200:203], v[94:97]
	v_mfma_f32_16x16x32_bf16 v[90:93], v[154:157], v[200:203], v[90:93]
	v_mfma_f32_16x16x32_bf16 v[78:81], v[146:149], v[208:211], v[78:81]
	v_mfma_f32_16x16x32_bf16 v[74:77], v[154:157], v[208:211], v[74:77]
	v_mfma_f32_16x16x32_bf16 v[126:129], v[150:153], v[188:191], v[126:129]
	v_mfma_f32_16x16x32_bf16 v[122:125], v[158:161], v[188:191], v[122:125]
	v_mfma_f32_16x16x32_bf16 v[110:113], v[150:153], v[196:199], v[110:113]
	v_mfma_f32_16x16x32_bf16 v[106:109], v[158:161], v[196:199], v[106:109]
	v_mfma_f32_16x16x32_bf16 v[94:97], v[150:153], v[204:207], v[94:97]
	v_mfma_f32_16x16x32_bf16 v[90:93], v[158:161], v[204:207], v[90:93]
	v_mfma_f32_16x16x32_bf16 v[78:81], v[150:153], v[212:215], v[78:81]
	v_mfma_f32_16x16x32_bf16 v[74:77], v[158:161], v[212:215], v[74:77]
	s_setprio 0
	s_setprio 1
	v_mfma_f32_16x16x32_bf16 v[118:121], v[168:171], v[184:187], v[118:121]
	v_mfma_f32_16x16x32_bf16 v[114:117], v[176:179], v[184:187], v[114:117]
	v_mfma_f32_16x16x32_bf16 v[102:105], v[168:171], v[192:195], v[102:105]
	v_mfma_f32_16x16x32_bf16 v[98:101], v[176:179], v[192:195], v[98:101]
	v_mfma_f32_16x16x32_bf16 v[86:89], v[168:171], v[200:203], v[86:89]
	v_mfma_f32_16x16x32_bf16 v[82:85], v[176:179], v[200:203], v[82:85]
	v_mfma_f32_16x16x32_bf16 v[70:73], v[168:171], v[208:211], v[70:73]
	v_mfma_f32_16x16x32_bf16 v[66:69], v[176:179], v[208:211], v[66:69]
	v_mfma_f32_16x16x32_bf16 v[118:121], v[172:175], v[188:191], v[118:121]
	v_mfma_f32_16x16x32_bf16 v[114:117], v[180:183], v[188:191], v[114:117]
	v_mfma_f32_16x16x32_bf16 v[102:105], v[172:175], v[196:199], v[102:105]
	v_mfma_f32_16x16x32_bf16 v[98:101], v[180:183], v[196:199], v[98:101]
	v_mfma_f32_16x16x32_bf16 v[86:89], v[172:175], v[204:207], v[86:89]
	v_mfma_f32_16x16x32_bf16 v[82:85], v[180:183], v[204:207], v[82:85]
	v_mfma_f32_16x16x32_bf16 v[70:73], v[172:175], v[212:215], v[70:73]
	v_mfma_f32_16x16x32_bf16 v[66:69], v[180:183], v[212:215], v[66:69]
	s_barrier
	s_setprio 0
	s_add_i32 s53, s53, s31
	v_lshl_add_u64 v[218:219], v[218:219], 0, s[78:79]
	s_mov_b32 m0, s53
	ds_read_b128 v[184:187], v166 offset:49152
	ds_read_b128 v[188:191], v166 offset:50176
	ds_read_b128 v[192:195], v166 offset:51200
	ds_read_b128 v[196:199], v166 offset:52224
	ds_read_b128 v[200:203], v166 offset:53248
	ds_read_b128 v[204:207], v166 offset:54272
	ds_read_b128 v[208:211], v166 offset:55296
	ds_read_b128 v[212:215], v166 offset:56320
	global_load_lds_dwordx4 v[218:219], off
	s_add_i32 m0, s53, 0x2000
	s_add_u32 s34, s34, 0x160080
	v_lshl_add_u64 v[218:219], v[220:221], 0, s[78:79]
	s_addc_u32 s35, s35, 0
	s_add_i32 s53, s62, s31
	global_load_lds_dwordx4 v[218:219], off
	v_lshl_add_u64 v[218:219], s[34:35], 0, v[132:133]
	s_mov_b32 m0, s53
	s_nop 0
	global_load_lds_dwordx4 v[218:219], off
	v_lshl_add_u64 v[218:219], s[34:35], 0, v[136:137]
	s_add_i32 m0, s53, 0x2000
	s_nop 0
	global_load_lds_dwordx4 v[218:219], off
	v_lshl_add_u64 v[218:219], v[222:223], 0, s[78:79]
	s_mov_b32 m0, s60
	s_nop 0
	global_load_lds_dwordx4 v[218:219], off
	v_lshl_add_u64 v[218:219], v[224:225], 0, s[78:79]
	s_mov_b32 m0, s61
	s_nop 0
	global_load_lds_dwordx4 v[218:219], off
	s_waitcnt vmcnt(8)
	s_waitcnt lgkmcnt(0)
	s_setprio 1
	s_barrier
	v_mfma_f32_16x16x32_bf16 v[62:65], v[146:149], v[184:187], v[62:65]
	v_mfma_f32_16x16x32_bf16 v[58:61], v[154:157], v[184:187], v[58:61]
	v_mfma_f32_16x16x32_bf16 v[46:49], v[146:149], v[192:195], v[46:49]
	v_mfma_f32_16x16x32_bf16 v[42:45], v[154:157], v[192:195], v[42:45]
	v_mfma_f32_16x16x32_bf16 v[30:33], v[146:149], v[200:203], v[30:33]
	v_mfma_f32_16x16x32_bf16 v[26:29], v[154:157], v[200:203], v[26:29]
	v_mfma_f32_16x16x32_bf16 v[14:17], v[146:149], v[208:211], v[14:17]
	v_mfma_f32_16x16x32_bf16 v[10:13], v[154:157], v[208:211], v[10:13]
	v_mfma_f32_16x16x32_bf16 v[62:65], v[150:153], v[188:191], v[62:65]
	v_mfma_f32_16x16x32_bf16 v[58:61], v[158:161], v[188:191], v[58:61]
	v_mfma_f32_16x16x32_bf16 v[46:49], v[150:153], v[196:199], v[46:49]
	v_mfma_f32_16x16x32_bf16 v[42:45], v[158:161], v[196:199], v[42:45]
	v_mfma_f32_16x16x32_bf16 v[30:33], v[150:153], v[204:207], v[30:33]
	v_mfma_f32_16x16x32_bf16 v[26:29], v[158:161], v[204:207], v[26:29]
	v_mfma_f32_16x16x32_bf16 v[14:17], v[150:153], v[212:215], v[14:17]
	v_mfma_f32_16x16x32_bf16 v[10:13], v[158:161], v[212:215], v[10:13]
	s_setprio 0
	s_setprio 1
	v_mfma_f32_16x16x32_bf16 v[54:57], v[168:171], v[184:187], v[54:57]
	v_mfma_f32_16x16x32_bf16 v[50:53], v[176:179], v[184:187], v[50:53]
	v_mfma_f32_16x16x32_bf16 v[38:41], v[168:171], v[192:195], v[38:41]
	v_mfma_f32_16x16x32_bf16 v[34:37], v[176:179], v[192:195], v[34:37]
	v_mfma_f32_16x16x32_bf16 v[22:25], v[168:171], v[200:203], v[22:25]
	v_mfma_f32_16x16x32_bf16 v[18:21], v[176:179], v[200:203], v[18:21]
	v_mfma_f32_16x16x32_bf16 v[6:9], v[168:171], v[208:211], v[6:9]
	v_mfma_f32_16x16x32_bf16 v[2:5], v[176:179], v[208:211], v[2:5]
	v_mfma_f32_16x16x32_bf16 v[54:57], v[172:175], v[188:191], v[54:57]
	v_mfma_f32_16x16x32_bf16 v[50:53], v[180:183], v[188:191], v[50:53]
	v_mfma_f32_16x16x32_bf16 v[38:41], v[172:175], v[196:199], v[38:41]
	v_mfma_f32_16x16x32_bf16 v[34:37], v[180:183], v[196:199], v[34:37]
	v_mfma_f32_16x16x32_bf16 v[22:25], v[172:175], v[204:207], v[22:25]
	v_mfma_f32_16x16x32_bf16 v[18:21], v[180:183], v[204:207], v[18:21]
	v_mfma_f32_16x16x32_bf16 v[6:9], v[172:175], v[212:215], v[6:9]
	v_mfma_f32_16x16x32_bf16 v[2:5], v[180:183], v[212:215], v[2:5]
	s_barrier
	s_setprio 0
	s_add_i32 s52, s52, 2
	s_add_u32 s76, s76, 0x100
	s_addc_u32 s77, s77, 0
	s_add_u32 s0, s0, 0x100
	s_addc_u32 s1, s1, 0
	s_cmpk_gt_u32 s52, 0x55
	s_cbranch_scc0 .LBB0_1237
	s_and_b64 vcc, exec, s[80:81]
	s_cbranch_vccz .LBB0_1240
	s_barrier

.LBB0_1624:
	ds_read_b128 v[154:157], v151
	ds_read_b128 v[158:161], v151 offset:1024
	ds_read_b128 v[162:165], v151 offset:2048
	ds_read_b128 v[166:169], v151 offset:3072
	ds_read_b128 v[170:173], v152
	ds_read_b128 v[174:177], v152 offset:1024
	ds_read_b128 v[178:181], v152 offset:2048
	ds_read_b128 v[182:185], v152 offset:3072
	s_add_u32 s34, s88, 0xfff80080
	s_addc_u32 s35, s89, -1
	s_cmp_eq_u32 s83, 28
	s_cselect_b32 s91, s0, s35
	s_cselect_b32 s90, s1, s34
	s_cselect_b32 s35, s52, s81
	s_cselect_b32 s34, s75, s77
	v_lshl_add_u64 v[146:147], s[88:89], 0, v[138:139]
	s_add_i32 m0, s33, 0xc000
	ds_read_b128 v[186:189], v153
	ds_read_b128 v[190:193], v153 offset:1024
	ds_read_b128 v[194:197], v153 offset:2048
	ds_read_b128 v[198:201], v153 offset:3072
	ds_read_b128 v[202:205], v153 offset:4096
	ds_read_b128 v[206:209], v153 offset:5120
	ds_read_b128 v[210:213], v153 offset:6144
	ds_read_b128 v[218:221], v153 offset:7168
	global_load_lds_dwordx4 v[146:147], off
	v_lshl_add_u64 v[146:147], s[88:89], 0, v[140:141]
	s_add_i32 m0, s33, 0xe000
	s_nop 0
	global_load_lds_dwordx4 v[146:147], off
	s_waitcnt vmcnt(8)
	s_waitcnt lgkmcnt(0)
	s_setprio 1
	s_barrier
	v_mfma_f32_16x16x32_bf16 v[126:129], v[154:157], v[186:189], v[126:129]
	v_mfma_f32_16x16x32_bf16 v[122:125], v[162:165], v[186:189], v[122:125]
	v_mfma_f32_16x16x32_bf16 v[114:117], v[154:157], v[194:197], v[114:117]
	v_mfma_f32_16x16x32_bf16 v[106:109], v[162:165], v[194:197], v[106:109]
	v_mfma_f32_16x16x32_bf16 v[98:101], v[154:157], v[202:205], v[98:101]
	v_mfma_f32_16x16x32_bf16 v[90:93], v[162:165], v[202:205], v[90:93]
	v_mfma_f32_16x16x32_bf16 v[82:85], v[154:157], v[210:213], v[82:85]
	v_mfma_f32_16x16x32_bf16 v[74:77], v[162:165], v[210:213], v[74:77]
	v_mfma_f32_16x16x32_bf16 v[126:129], v[158:161], v[190:193], v[126:129]
	v_mfma_f32_16x16x32_bf16 v[122:125], v[166:169], v[190:193], v[122:125]
	v_mfma_f32_16x16x32_bf16 v[114:117], v[158:161], v[198:201], v[114:117]
	v_mfma_f32_16x16x32_bf16 v[106:109], v[166:169], v[198:201], v[106:109]
	v_mfma_f32_16x16x32_bf16 v[98:101], v[158:161], v[206:209], v[98:101]
	v_mfma_f32_16x16x32_bf16 v[90:93], v[166:169], v[206:209], v[90:93]
	v_mfma_f32_16x16x32_bf16 v[82:85], v[158:161], v[218:221], v[82:85]
	v_mfma_f32_16x16x32_bf16 v[74:77], v[166:169], v[218:221], v[74:77]
	s_setprio 0
	s_setprio 1
	v_mfma_f32_16x16x32_bf16 v[118:121], v[170:173], v[186:189], v[118:121]
	v_mfma_f32_16x16x32_bf16 v[110:113], v[178:181], v[186:189], v[110:113]
	v_mfma_f32_16x16x32_bf16 v[102:105], v[170:173], v[194:197], v[102:105]
	v_mfma_f32_16x16x32_bf16 v[94:97], v[178:181], v[194:197], v[94:97]
	v_mfma_f32_16x16x32_bf16 v[86:89], v[170:173], v[202:205], v[86:89]
	v_mfma_f32_16x16x32_bf16 v[78:81], v[178:181], v[202:205], v[78:81]
	v_mfma_f32_16x16x32_bf16 v[70:73], v[170:173], v[210:213], v[70:73]
	v_mfma_f32_16x16x32_bf16 v[66:69], v[178:181], v[210:213], v[66:69]
	v_mfma_f32_16x16x32_bf16 v[118:121], v[174:177], v[190:193], v[118:121]
	v_mfma_f32_16x16x32_bf16 v[110:113], v[182:185], v[190:193], v[110:113]
	v_mfma_f32_16x16x32_bf16 v[102:105], v[174:177], v[198:201], v[102:105]
	v_mfma_f32_16x16x32_bf16 v[94:97], v[182:185], v[198:201], v[94:97]
	v_mfma_f32_16x16x32_bf16 v[86:89], v[174:177], v[206:209], v[86:89]
	v_mfma_f32_16x16x32_bf16 v[78:81], v[182:185], v[206:209], v[78:81]
	v_mfma_f32_16x16x32_bf16 v[70:73], v[174:177], v[218:221], v[70:73]
	v_mfma_f32_16x16x32_bf16 v[66:69], v[182:185], v[218:221], v[66:69]
	s_barrier
	s_setprio 0
	s_add_i32 s53, s71, s12
	v_lshl_add_u64 v[146:147], s[34:35], 0, v[134:135]
	s_mov_b32 m0, s53
	ds_read_b128 v[186:189], v153 offset:16384
	ds_read_b128 v[190:193], v153 offset:17408
	ds_read_b128 v[194:197], v153 offset:18432
	ds_read_b128 v[198:201], v153 offset:19456
	ds_read_b128 v[202:205], v153 offset:20480
	ds_read_b128 v[206:209], v153 offset:21504
	ds_read_b128 v[210:213], v153 offset:22528
	ds_read_b128 v[218:221], v153 offset:23552
	global_load_lds_dwordx4 v[146:147], off
	s_add_i32 m0, s53, 0x2000
	s_add_u32 s54, s34, 0x80000
	v_lshl_add_u64 v[214:215], s[34:35], 0, v[130:131]
	s_addc_u32 s55, s35, 0
	s_add_i32 s53, s72, s12
	global_load_lds_dwordx4 v[214:215], off
	v_lshl_add_u64 v[222:223], s[54:55], 0, v[134:135]
	s_mov_b32 m0, s53
	v_lshl_add_u64 v[224:225], s[90:91], 0, v[132:133]
	global_load_lds_dwordx4 v[222:223], off
	v_lshl_add_u64 v[222:223], s[54:55], 0, v[130:131]
	s_add_i32 m0, s53, 0x2000
	s_nop 0
	global_load_lds_dwordx4 v[222:223], off
	v_lshl_add_u64 v[222:223], s[90:91], 0, v[136:137]
	s_mov_b32 m0, s33
	s_nop 0
	global_load_lds_dwordx4 v[222:223], off
	s_mov_b32 m0, s56
	s_nop 0
	global_load_lds_dwordx4 v[224:225], off
	s_waitcnt vmcnt(8)
	s_waitcnt lgkmcnt(0)
	s_setprio 1
	s_barrier
	v_mfma_f32_16x16x32_bf16 v[62:65], v[154:157], v[186:189], v[62:65]
	v_mfma_f32_16x16x32_bf16 v[58:61], v[162:165], v[186:189], v[58:61]
	v_mfma_f32_16x16x32_bf16 v[50:53], v[154:157], v[194:197], v[50:53]
	v_mfma_f32_16x16x32_bf16 v[42:45], v[162:165], v[194:197], v[42:45]
	v_mfma_f32_16x16x32_bf16 v[34:37], v[154:157], v[202:205], v[34:37]
	v_mfma_f32_16x16x32_bf16 v[26:29], v[162:165], v[202:205], v[26:29]
	v_mfma_f32_16x16x32_bf16 v[18:21], v[154:157], v[210:213], v[18:21]
	v_mfma_f32_16x16x32_bf16 v[10:13], v[162:165], v[210:213], v[10:13]
	v_mfma_f32_16x16x32_bf16 v[62:65], v[158:161], v[190:193], v[62:65]
	v_mfma_f32_16x16x32_bf16 v[58:61], v[166:169], v[190:193], v[58:61]
	v_mfma_f32_16x16x32_bf16 v[50:53], v[158:161], v[198:201], v[50:53]
	v_mfma_f32_16x16x32_bf16 v[42:45], v[166:169], v[198:201], v[42:45]
	v_mfma_f32_16x16x32_bf16 v[34:37], v[158:161], v[206:209], v[34:37]
	v_mfma_f32_16x16x32_bf16 v[26:29], v[166:169], v[206:209], v[26:29]
	v_mfma_f32_16x16x32_bf16 v[18:21], v[158:161], v[218:221], v[18:21]
	v_mfma_f32_16x16x32_bf16 v[10:13], v[166:169], v[218:221], v[10:13]
	s_setprio 0
	s_setprio 1
	v_mfma_f32_16x16x32_bf16 v[54:57], v[170:173], v[186:189], v[54:57]
	v_mfma_f32_16x16x32_bf16 v[46:49], v[178:181], v[186:189], v[46:49]
	v_mfma_f32_16x16x32_bf16 v[38:41], v[170:173], v[194:197], v[38:41]
	v_mfma_f32_16x16x32_bf16 v[30:33], v[178:181], v[194:197], v[30:33]
	v_mfma_f32_16x16x32_bf16 v[22:25], v[170:173], v[202:205], v[22:25]
	v_mfma_f32_16x16x32_bf16 v[14:17], v[178:181], v[202:205], v[14:17]
	v_mfma_f32_16x16x32_bf16 v[6:9], v[170:173], v[210:213], v[6:9]
	v_mfma_f32_16x16x32_bf16 v[2:5], v[178:181], v[210:213], v[2:5]
	v_mfma_f32_16x16x32_bf16 v[54:57], v[174:177], v[190:193], v[54:57]
	v_mfma_f32_16x16x32_bf16 v[46:49], v[182:185], v[190:193], v[46:49]
	v_mfma_f32_16x16x32_bf16 v[38:41], v[174:177], v[198:201], v[38:41]
	v_mfma_f32_16x16x32_bf16 v[30:33], v[182:185], v[198:201], v[30:33]
	v_mfma_f32_16x16x32_bf16 v[22:25], v[174:177], v[206:209], v[22:25]
	v_mfma_f32_16x16x32_bf16 v[14:17], v[182:185], v[206:209], v[14:17]
	v_mfma_f32_16x16x32_bf16 v[6:9], v[174:177], v[218:221], v[6:9]
	v_mfma_f32_16x16x32_bf16 v[2:5], v[182:185], v[218:221], v[2:5]
	s_barrier
	s_setprio 0
	s_add_i32 s53, 0, 0x18000
	s_add_i32 s62, 0, 0x1c000
	v_add_u32_e32 v166, s53, v149
	v_add_u32_e32 v182, s62, v149
	ds_read_b128 v[154:157], v166
	ds_read_b128 v[158:161], v166 offset:1024
	ds_read_b128 v[162:165], v166 offset:2048
	ds_read_b128 v[166:169], v166 offset:3072
	ds_read_b128 v[170:173], v182
	ds_read_b128 v[174:177], v182 offset:1024
	ds_read_b128 v[178:181], v182 offset:2048
	ds_read_b128 v[182:185], v182 offset:3072
	s_add_u32 s54, s90, 0x80000
	s_addc_u32 s55, s91, 0
	s_mov_b32 m0, s57
	v_lshl_add_u64 v[226:227], s[54:55], 0, v[136:137]
	ds_read_b128 v[186:189], v153 offset:32768
	ds_read_b128 v[190:193], v153 offset:33792
	ds_read_b128 v[194:197], v153 offset:34816
	ds_read_b128 v[198:201], v153 offset:35840
	ds_read_b128 v[202:205], v153 offset:36864
	ds_read_b128 v[206:209], v153 offset:37888
	ds_read_b128 v[210:213], v153 offset:38912
	ds_read_b128 v[218:221], v153 offset:39936
	global_load_lds_dwordx4 v[226:227], off
	v_lshl_add_u64 v[226:227], s[54:55], 0, v[132:133]
	s_mov_b32 m0, s58
	s_nop 0
	global_load_lds_dwordx4 v[226:227], off
	s_waitcnt vmcnt(8)
	s_waitcnt lgkmcnt(0)
	s_setprio 1
	s_barrier
	v_mfma_f32_16x16x32_bf16 v[126:129], v[154:157], v[186:189], v[126:129]
	v_mfma_f32_16x16x32_bf16 v[122:125], v[162:165], v[186:189], v[122:125]
	v_mfma_f32_16x16x32_bf16 v[114:117], v[154:157], v[194:197], v[114:117]
	v_mfma_f32_16x16x32_bf16 v[106:109], v[162:165], v[194:197], v[106:109]
	v_mfma_f32_16x16x32_bf16 v[98:101], v[154:157], v[202:205], v[98:101]
	v_mfma_f32_16x16x32_bf16 v[90:93], v[162:165], v[202:205], v[90:93]
	v_mfma_f32_16x16x32_bf16 v[82:85], v[154:157], v[210:213], v[82:85]
	v_mfma_f32_16x16x32_bf16 v[74:77], v[162:165], v[210:213], v[74:77]
	v_mfma_f32_16x16x32_bf16 v[126:129], v[158:161], v[190:193], v[126:129]
	v_mfma_f32_16x16x32_bf16 v[122:125], v[166:169], v[190:193], v[122:125]
	v_mfma_f32_16x16x32_bf16 v[114:117], v[158:161], v[198:201], v[114:117]
	v_mfma_f32_16x16x32_bf16 v[106:109], v[166:169], v[198:201], v[106:109]
	v_mfma_f32_16x16x32_bf16 v[98:101], v[158:161], v[206:209], v[98:101]
	v_mfma_f32_16x16x32_bf16 v[90:93], v[166:169], v[206:209], v[90:93]
	v_mfma_f32_16x16x32_bf16 v[82:85], v[158:161], v[218:221], v[82:85]
	v_mfma_f32_16x16x32_bf16 v[74:77], v[166:169], v[218:221], v[74:77]
	s_setprio 0
	s_setprio 1
	v_mfma_f32_16x16x32_bf16 v[118:121], v[170:173], v[186:189], v[118:121]
	v_mfma_f32_16x16x32_bf16 v[110:113], v[178:181], v[186:189], v[110:113]
	v_mfma_f32_16x16x32_bf16 v[102:105], v[170:173], v[194:197], v[102:105]
	v_mfma_f32_16x16x32_bf16 v[94:97], v[178:181], v[194:197], v[94:97]
	v_mfma_f32_16x16x32_bf16 v[86:89], v[170:173], v[202:205], v[86:89]
	v_mfma_f32_16x16x32_bf16 v[78:81], v[178:181], v[202:205], v[78:81]
	v_mfma_f32_16x16x32_bf16 v[70:73], v[170:173], v[210:213], v[70:73]
	v_mfma_f32_16x16x32_bf16 v[66:69], v[178:181], v[210:213], v[66:69]
	v_mfma_f32_16x16x32_bf16 v[118:121], v[174:177], v[190:193], v[118:121]
	v_mfma_f32_16x16x32_bf16 v[110:113], v[182:185], v[190:193], v[110:113]
	v_mfma_f32_16x16x32_bf16 v[102:105], v[174:177], v[198:201], v[102:105]
	v_mfma_f32_16x16x32_bf16 v[94:97], v[182:185], v[198:201], v[94:97]
	v_mfma_f32_16x16x32_bf16 v[86:89], v[174:177], v[206:209], v[86:89]
	v_mfma_f32_16x16x32_bf16 v[78:81], v[182:185], v[206:209], v[78:81]
	v_mfma_f32_16x16x32_bf16 v[70:73], v[174:177], v[218:221], v[70:73]
	v_mfma_f32_16x16x32_bf16 v[66:69], v[182:185], v[218:221], v[66:69]
	s_barrier
	s_setprio 0
	s_add_i32 s53, s53, s12
	v_lshl_add_u64 v[146:147], v[146:147], 0, s[8:9]
	s_mov_b32 m0, s53
	ds_read_b128 v[186:189], v153 offset:49152
	ds_read_b128 v[190:193], v153 offset:50176
	ds_read_b128 v[194:197], v153 offset:51200
	ds_read_b128 v[198:201], v153 offset:52224
	ds_read_b128 v[202:205], v153 offset:53248
	ds_read_b128 v[206:209], v153 offset:54272
	ds_read_b128 v[210:213], v153 offset:55296
	ds_read_b128 v[218:221], v153 offset:56320
	global_load_lds_dwordx4 v[146:147], off
	s_add_i32 m0, s53, 0x2000
	s_add_u32 s34, s34, 0x80080
	v_lshl_add_u64 v[146:147], v[214:215], 0, s[8:9]
	s_addc_u32 s35, s35, 0
	s_add_i32 s53, s62, s12
	global_load_lds_dwordx4 v[146:147], off
	v_lshl_add_u64 v[146:147], s[34:35], 0, v[134:135]
	s_mov_b32 m0, s53
	s_nop 0
	global_load_lds_dwordx4 v[146:147], off
	v_lshl_add_u64 v[146:147], s[34:35], 0, v[130:131]
	s_add_i32 m0, s53, 0x2000
	s_nop 0
	global_load_lds_dwordx4 v[146:147], off
	v_lshl_add_u64 v[146:147], v[222:223], 0, s[8:9]
	s_mov_b32 m0, s60
	s_nop 0
	global_load_lds_dwordx4 v[146:147], off
	v_lshl_add_u64 v[146:147], v[224:225], 0, s[8:9]
	s_mov_b32 m0, s61
	s_nop 0
	global_load_lds_dwordx4 v[146:147], off
	s_waitcnt vmcnt(8)
	s_waitcnt lgkmcnt(0)
	s_setprio 1
	s_barrier
	v_mfma_f32_16x16x32_bf16 v[62:65], v[154:157], v[186:189], v[62:65]
	v_mfma_f32_16x16x32_bf16 v[58:61], v[162:165], v[186:189], v[58:61]
	v_mfma_f32_16x16x32_bf16 v[50:53], v[154:157], v[194:197], v[50:53]
	v_mfma_f32_16x16x32_bf16 v[42:45], v[162:165], v[194:197], v[42:45]
	v_mfma_f32_16x16x32_bf16 v[34:37], v[154:157], v[202:205], v[34:37]
	v_mfma_f32_16x16x32_bf16 v[26:29], v[162:165], v[202:205], v[26:29]
	v_mfma_f32_16x16x32_bf16 v[18:21], v[154:157], v[210:213], v[18:21]
	v_mfma_f32_16x16x32_bf16 v[10:13], v[162:165], v[210:213], v[10:13]
	v_mfma_f32_16x16x32_bf16 v[62:65], v[158:161], v[190:193], v[62:65]
	v_mfma_f32_16x16x32_bf16 v[58:61], v[166:169], v[190:193], v[58:61]
	v_mfma_f32_16x16x32_bf16 v[50:53], v[158:161], v[198:201], v[50:53]
	v_mfma_f32_16x16x32_bf16 v[42:45], v[166:169], v[198:201], v[42:45]
	v_mfma_f32_16x16x32_bf16 v[34:37], v[158:161], v[206:209], v[34:37]
	v_mfma_f32_16x16x32_bf16 v[26:29], v[166:169], v[206:209], v[26:29]
	v_mfma_f32_16x16x32_bf16 v[18:21], v[158:161], v[218:221], v[18:21]
	v_mfma_f32_16x16x32_bf16 v[10:13], v[166:169], v[218:221], v[10:13]
	s_setprio 0
	s_setprio 1
	v_mfma_f32_16x16x32_bf16 v[54:57], v[170:173], v[186:189], v[54:57]
	v_mfma_f32_16x16x32_bf16 v[46:49], v[178:181], v[186:189], v[46:49]
	v_mfma_f32_16x16x32_bf16 v[38:41], v[170:173], v[194:197], v[38:41]
	v_mfma_f32_16x16x32_bf16 v[30:33], v[178:181], v[194:197], v[30:33]
	v_mfma_f32_16x16x32_bf16 v[22:25], v[170:173], v[202:205], v[22:25]
	v_mfma_f32_16x16x32_bf16 v[14:17], v[178:181], v[202:205], v[14:17]
	v_mfma_f32_16x16x32_bf16 v[6:9], v[170:173], v[210:213], v[6:9]
	v_mfma_f32_16x16x32_bf16 v[2:5], v[178:181], v[210:213], v[2:5]
	v_mfma_f32_16x16x32_bf16 v[54:57], v[174:177], v[190:193], v[54:57]
	v_mfma_f32_16x16x32_bf16 v[46:49], v[182:185], v[190:193], v[46:49]
	v_mfma_f32_16x16x32_bf16 v[38:41], v[174:177], v[198:201], v[38:41]
	v_mfma_f32_16x16x32_bf16 v[30:33], v[182:185], v[198:201], v[30:33]
	v_mfma_f32_16x16x32_bf16 v[22:25], v[174:177], v[206:209], v[22:25]
	v_mfma_f32_16x16x32_bf16 v[14:17], v[182:185], v[206:209], v[14:17]
	v_mfma_f32_16x16x32_bf16 v[6:9], v[174:177], v[218:221], v[6:9]
	v_mfma_f32_16x16x32_bf16 v[2:5], v[182:185], v[218:221], v[2:5]
	s_barrier
	s_setprio 0
	s_add_i32 s83, s83, 2
	s_add_u32 s88, s88, 0x100
	s_addc_u32 s89, s89, 0
	s_add_u32 s77, s77, 0x100
	s_addc_u32 s81, s81, 0
	s_cmp_gt_u32 s83, 29
	s_cbranch_scc0 .LBB0_1624
	s_and_b64 vcc, exec, s[78:79]
	s_cbranch_vccz .LBB0_1627
	s_barrier

.LBB0_2089:
	ds_read_b128 v[130:133], v178
	ds_read_b128 v[134:137], v178 offset:1024
	ds_read_b128 v[138:141], v178 offset:2048
	ds_read_b128 v[142:145], v178 offset:3072
	ds_read_b128 v[162:165], v179
	ds_read_b128 v[166:169], v179 offset:1024
	ds_read_b128 v[170:173], v179 offset:2048
	ds_read_b128 v[182:185], v179 offset:3072
	s_add_u32 s34, s38, 0xffea0080
	s_addc_u32 s35, s39, -1
	s_cmpk_eq_i32 s52, 0x54
	s_cselect_b32 s41, s5, s35
	s_cselect_b32 s40, s4, s34
	s_cselect_b32 s35, s37, s1
	s_cselect_b32 s34, s36, s0
	v_lshl_add_u64 v[174:175], s[38:39], 0, v[154:155]
	s_add_i32 m0, s33, 0xc000
	ds_read_b128 v[186:189], v180
	ds_read_b128 v[190:193], v180 offset:1024
	ds_read_b128 v[194:197], v180 offset:2048
	ds_read_b128 v[198:201], v180 offset:3072
	ds_read_b128 v[202:205], v180 offset:4096
	ds_read_b128 v[206:209], v180 offset:5120
	ds_read_b128 v[210:213], v180 offset:6144
	ds_read_b128 v[218:221], v180 offset:7168
	global_load_lds_dwordx4 v[174:175], off
	v_lshl_add_u64 v[174:175], s[38:39], 0, v[156:157]
	s_add_i32 m0, s33, 0xe000
	s_nop 0
	global_load_lds_dwordx4 v[174:175], off
	s_waitcnt vmcnt(8)
	s_waitcnt lgkmcnt(0)
	s_setprio 1
	s_barrier
	v_mfma_f32_16x16x32_bf16 v[126:129], v[130:133], v[186:189], v[126:129]
	v_mfma_f32_16x16x32_bf16 v[122:125], v[138:141], v[186:189], v[122:125]
	v_mfma_f32_16x16x32_bf16 v[110:113], v[130:133], v[194:197], v[110:113]
	v_mfma_f32_16x16x32_bf16 v[106:109], v[138:141], v[194:197], v[106:109]
	v_mfma_f32_16x16x32_bf16 v[94:97], v[130:133], v[202:205], v[94:97]
	v_mfma_f32_16x16x32_bf16 v[90:93], v[138:141], v[202:205], v[90:93]
	v_mfma_f32_16x16x32_bf16 v[78:81], v[130:133], v[210:213], v[78:81]
	v_mfma_f32_16x16x32_bf16 v[74:77], v[138:141], v[210:213], v[74:77]
	v_mfma_f32_16x16x32_bf16 v[126:129], v[134:137], v[190:193], v[126:129]
	v_mfma_f32_16x16x32_bf16 v[122:125], v[142:145], v[190:193], v[122:125]
	v_mfma_f32_16x16x32_bf16 v[110:113], v[134:137], v[198:201], v[110:113]
	v_mfma_f32_16x16x32_bf16 v[106:109], v[142:145], v[198:201], v[106:109]
	v_mfma_f32_16x16x32_bf16 v[94:97], v[134:137], v[206:209], v[94:97]
	v_mfma_f32_16x16x32_bf16 v[90:93], v[142:145], v[206:209], v[90:93]
	v_mfma_f32_16x16x32_bf16 v[78:81], v[134:137], v[218:221], v[78:81]
	v_mfma_f32_16x16x32_bf16 v[74:77], v[142:145], v[218:221], v[74:77]
	s_setprio 0
	s_setprio 1
	v_mfma_f32_16x16x32_bf16 v[118:121], v[162:165], v[186:189], v[118:121]
	v_mfma_f32_16x16x32_bf16 v[114:117], v[170:173], v[186:189], v[114:117]
	v_mfma_f32_16x16x32_bf16 v[102:105], v[162:165], v[194:197], v[102:105]
	v_mfma_f32_16x16x32_bf16 v[98:101], v[170:173], v[194:197], v[98:101]
	v_mfma_f32_16x16x32_bf16 v[86:89], v[162:165], v[202:205], v[86:89]
	v_mfma_f32_16x16x32_bf16 v[82:85], v[170:173], v[202:205], v[82:85]
	v_mfma_f32_16x16x32_bf16 v[70:73], v[162:165], v[210:213], v[70:73]
	v_mfma_f32_16x16x32_bf16 v[66:69], v[170:173], v[210:213], v[66:69]
	v_mfma_f32_16x16x32_bf16 v[118:121], v[166:169], v[190:193], v[118:121]
	v_mfma_f32_16x16x32_bf16 v[114:117], v[182:185], v[190:193], v[114:117]
	v_mfma_f32_16x16x32_bf16 v[102:105], v[166:169], v[198:201], v[102:105]
	v_mfma_f32_16x16x32_bf16 v[98:101], v[182:185], v[198:201], v[98:101]
	v_mfma_f32_16x16x32_bf16 v[86:89], v[166:169], v[206:209], v[86:89]
	v_mfma_f32_16x16x32_bf16 v[82:85], v[182:185], v[206:209], v[82:85]
	v_mfma_f32_16x16x32_bf16 v[70:73], v[166:169], v[218:221], v[70:73]
	v_mfma_f32_16x16x32_bf16 v[66:69], v[182:185], v[218:221], v[66:69]
	s_barrier
	s_setprio 0
	s_add_i32 s53, s61, s31
	v_lshl_add_u64 v[174:175], s[34:35], 0, v[148:149]
	s_mov_b32 m0, s53
	ds_read_b128 v[186:189], v180 offset:16384
	ds_read_b128 v[190:193], v180 offset:17408
	ds_read_b128 v[194:197], v180 offset:18432
	ds_read_b128 v[198:201], v180 offset:19456
	ds_read_b128 v[202:205], v180 offset:20480
	ds_read_b128 v[206:209], v180 offset:21504
	ds_read_b128 v[210:213], v180 offset:22528
	ds_read_b128 v[218:221], v180 offset:23552
	global_load_lds_dwordx4 v[174:175], off
	s_add_i32 m0, s53, 0x2000
	s_add_u32 s54, s34, 0x160000
	v_lshl_add_u64 v[214:215], s[34:35], 0, v[152:153]
	s_addc_u32 s55, s35, 0
	s_add_i32 s53, s70, s31
	global_load_lds_dwordx4 v[214:215], off
	v_lshl_add_u64 v[222:223], s[54:55], 0, v[148:149]
	s_mov_b32 m0, s53
	v_lshl_add_u64 v[224:225], s[40:41], 0, v[150:151]
	global_load_lds_dwordx4 v[222:223], off
	v_lshl_add_u64 v[222:223], s[54:55], 0, v[152:153]
	s_add_i32 m0, s53, 0x2000
	s_nop 0
	global_load_lds_dwordx4 v[222:223], off
	v_lshl_add_u64 v[222:223], s[40:41], 0, v[146:147]
	s_mov_b32 m0, s33
	s_nop 0
	global_load_lds_dwordx4 v[222:223], off
	s_mov_b32 m0, s46
	s_nop 0
	global_load_lds_dwordx4 v[224:225], off
	s_waitcnt vmcnt(8)
	s_waitcnt lgkmcnt(0)
	s_setprio 1
	s_barrier
	v_mfma_f32_16x16x32_bf16 v[62:65], v[130:133], v[186:189], v[62:65]
	v_mfma_f32_16x16x32_bf16 v[58:61], v[138:141], v[186:189], v[58:61]
	v_mfma_f32_16x16x32_bf16 v[50:53], v[130:133], v[194:197], v[50:53]
	v_mfma_f32_16x16x32_bf16 v[42:45], v[138:141], v[194:197], v[42:45]
	v_mfma_f32_16x16x32_bf16 v[38:41], v[130:133], v[202:205], v[38:41]
	v_mfma_f32_16x16x32_bf16 v[34:37], v[138:141], v[202:205], v[34:37]
	v_mfma_f32_16x16x32_bf16 v[14:17], v[130:133], v[210:213], v[14:17]
	v_mfma_f32_16x16x32_bf16 v[10:13], v[138:141], v[210:213], v[10:13]
	v_mfma_f32_16x16x32_bf16 v[62:65], v[134:137], v[190:193], v[62:65]
	v_mfma_f32_16x16x32_bf16 v[58:61], v[142:145], v[190:193], v[58:61]
	v_mfma_f32_16x16x32_bf16 v[50:53], v[134:137], v[198:201], v[50:53]
	v_mfma_f32_16x16x32_bf16 v[42:45], v[142:145], v[198:201], v[42:45]
	v_mfma_f32_16x16x32_bf16 v[38:41], v[134:137], v[206:209], v[38:41]
	v_mfma_f32_16x16x32_bf16 v[34:37], v[142:145], v[206:209], v[34:37]
	v_mfma_f32_16x16x32_bf16 v[14:17], v[134:137], v[218:221], v[14:17]
	v_mfma_f32_16x16x32_bf16 v[10:13], v[142:145], v[218:221], v[10:13]
	s_setprio 0
	s_setprio 1
	v_mfma_f32_16x16x32_bf16 v[54:57], v[162:165], v[186:189], v[54:57]
	v_mfma_f32_16x16x32_bf16 v[46:49], v[170:173], v[186:189], v[46:49]
	v_mfma_f32_16x16x32_bf16 v[30:33], v[162:165], v[194:197], v[30:33]
	v_mfma_f32_16x16x32_bf16 v[26:29], v[170:173], v[194:197], v[26:29]
	v_mfma_f32_16x16x32_bf16 v[22:25], v[162:165], v[202:205], v[22:25]
	v_mfma_f32_16x16x32_bf16 v[18:21], v[170:173], v[202:205], v[18:21]
	v_mfma_f32_16x16x32_bf16 v[6:9], v[162:165], v[210:213], v[6:9]
	v_mfma_f32_16x16x32_bf16 v[2:5], v[170:173], v[210:213], v[2:5]
	v_mfma_f32_16x16x32_bf16 v[54:57], v[166:169], v[190:193], v[54:57]
	v_mfma_f32_16x16x32_bf16 v[46:49], v[182:185], v[190:193], v[46:49]
	v_mfma_f32_16x16x32_bf16 v[30:33], v[166:169], v[198:201], v[30:33]
	v_mfma_f32_16x16x32_bf16 v[26:29], v[182:185], v[198:201], v[26:29]
	v_mfma_f32_16x16x32_bf16 v[22:25], v[166:169], v[206:209], v[22:25]
	v_mfma_f32_16x16x32_bf16 v[18:21], v[182:185], v[206:209], v[18:21]
	v_mfma_f32_16x16x32_bf16 v[6:9], v[166:169], v[218:221], v[6:9]
	v_mfma_f32_16x16x32_bf16 v[2:5], v[182:185], v[218:221], v[2:5]
	s_barrier
	s_setprio 0
	s_add_i32 s53, 0, 0x18000
	s_add_i32 s54, 0, 0x1c000
	v_add_u32_e32 v142, s53, v176
	v_add_u32_e32 v181, s54, v176
	ds_read_b128 v[130:133], v142
	ds_read_b128 v[134:137], v142 offset:1024
	ds_read_b128 v[138:141], v142 offset:2048
	ds_read_b128 v[142:145], v142 offset:3072
	ds_read_b128 v[162:165], v181
	ds_read_b128 v[166:169], v181 offset:1024
	ds_read_b128 v[170:173], v181 offset:2048
	ds_read_b128 v[182:185], v181 offset:3072
	s_add_u32 s40, s40, 0x160000
	s_addc_u32 s41, s41, 0
	s_mov_b32 m0, s47
	v_lshl_add_u64 v[226:227], s[40:41], 0, v[146:147]
	ds_read_b128 v[186:189], v180 offset:32768
	ds_read_b128 v[190:193], v180 offset:33792
	ds_read_b128 v[194:197], v180 offset:34816
	ds_read_b128 v[198:201], v180 offset:35840
	ds_read_b128 v[202:205], v180 offset:36864
	ds_read_b128 v[206:209], v180 offset:37888
	ds_read_b128 v[210:213], v180 offset:38912
	ds_read_b128 v[218:221], v180 offset:39936
	global_load_lds_dwordx4 v[226:227], off
	v_lshl_add_u64 v[226:227], s[40:41], 0, v[150:151]
	s_mov_b32 m0, s56
	s_nop 0
	global_load_lds_dwordx4 v[226:227], off
	s_waitcnt vmcnt(8)
	s_waitcnt lgkmcnt(0)
	s_setprio 1
	s_barrier
	v_mfma_f32_16x16x32_bf16 v[126:129], v[130:133], v[186:189], v[126:129]
	v_mfma_f32_16x16x32_bf16 v[122:125], v[138:141], v[186:189], v[122:125]
	v_mfma_f32_16x16x32_bf16 v[110:113], v[130:133], v[194:197], v[110:113]
	v_mfma_f32_16x16x32_bf16 v[106:109], v[138:141], v[194:197], v[106:109]
	v_mfma_f32_16x16x32_bf16 v[94:97], v[130:133], v[202:205], v[94:97]
	v_mfma_f32_16x16x32_bf16 v[90:93], v[138:141], v[202:205], v[90:93]
	v_mfma_f32_16x16x32_bf16 v[78:81], v[130:133], v[210:213], v[78:81]
	v_mfma_f32_16x16x32_bf16 v[74:77], v[138:141], v[210:213], v[74:77]
	v_mfma_f32_16x16x32_bf16 v[126:129], v[134:137], v[190:193], v[126:129]
	v_mfma_f32_16x16x32_bf16 v[122:125], v[142:145], v[190:193], v[122:125]
	v_mfma_f32_16x16x32_bf16 v[110:113], v[134:137], v[198:201], v[110:113]
	v_mfma_f32_16x16x32_bf16 v[106:109], v[142:145], v[198:201], v[106:109]
	v_mfma_f32_16x16x32_bf16 v[94:97], v[134:137], v[206:209], v[94:97]
	v_mfma_f32_16x16x32_bf16 v[90:93], v[142:145], v[206:209], v[90:93]
	v_mfma_f32_16x16x32_bf16 v[78:81], v[134:137], v[218:221], v[78:81]
	v_mfma_f32_16x16x32_bf16 v[74:77], v[142:145], v[218:221], v[74:77]
	s_setprio 0
	s_setprio 1
	v_mfma_f32_16x16x32_bf16 v[118:121], v[162:165], v[186:189], v[118:121]
	v_mfma_f32_16x16x32_bf16 v[114:117], v[170:173], v[186:189], v[114:117]
	v_mfma_f32_16x16x32_bf16 v[102:105], v[162:165], v[194:197], v[102:105]
	v_mfma_f32_16x16x32_bf16 v[98:101], v[170:173], v[194:197], v[98:101]
	v_mfma_f32_16x16x32_bf16 v[86:89], v[162:165], v[202:205], v[86:89]
	v_mfma_f32_16x16x32_bf16 v[82:85], v[170:173], v[202:205], v[82:85]
	v_mfma_f32_16x16x32_bf16 v[70:73], v[162:165], v[210:213], v[70:73]
	v_mfma_f32_16x16x32_bf16 v[66:69], v[170:173], v[210:213], v[66:69]
	v_mfma_f32_16x16x32_bf16 v[118:121], v[166:169], v[190:193], v[118:121]
	v_mfma_f32_16x16x32_bf16 v[114:117], v[182:185], v[190:193], v[114:117]
	v_mfma_f32_16x16x32_bf16 v[102:105], v[166:169], v[198:201], v[102:105]
	v_mfma_f32_16x16x32_bf16 v[98:101], v[182:185], v[198:201], v[98:101]
	v_mfma_f32_16x16x32_bf16 v[86:89], v[166:169], v[206:209], v[86:89]
	v_mfma_f32_16x16x32_bf16 v[82:85], v[182:185], v[206:209], v[82:85]
	v_mfma_f32_16x16x32_bf16 v[70:73], v[166:169], v[218:221], v[70:73]
	v_mfma_f32_16x16x32_bf16 v[66:69], v[182:185], v[218:221], v[66:69]
	s_barrier
	s_setprio 0
	s_add_i32 s40, s53, s31
	v_lshl_add_u64 v[174:175], v[174:175], 0, s[24:25]
	s_mov_b32 m0, s40
	ds_read_b128 v[186:189], v180 offset:49152
	ds_read_b128 v[190:193], v180 offset:50176
	ds_read_b128 v[194:197], v180 offset:51200
	ds_read_b128 v[198:201], v180 offset:52224
	ds_read_b128 v[202:205], v180 offset:53248
	ds_read_b128 v[206:209], v180 offset:54272
	ds_read_b128 v[210:213], v180 offset:55296
	ds_read_b128 v[218:221], v180 offset:56320
	global_load_lds_dwordx4 v[174:175], off
	s_add_i32 m0, s40, 0x2000
	s_add_u32 s34, s34, 0x160080
	v_lshl_add_u64 v[174:175], v[214:215], 0, s[24:25]
	s_addc_u32 s35, s35, 0
	s_add_i32 s40, s54, s31
	global_load_lds_dwordx4 v[174:175], off
	v_lshl_add_u64 v[174:175], s[34:35], 0, v[148:149]
	s_mov_b32 m0, s40
	s_nop 0
	global_load_lds_dwordx4 v[174:175], off
	v_lshl_add_u64 v[174:175], s[34:35], 0, v[152:153]
	s_add_i32 m0, s40, 0x2000
	s_nop 0
	global_load_lds_dwordx4 v[174:175], off
	v_lshl_add_u64 v[174:175], v[222:223], 0, s[24:25]
	s_mov_b32 m0, s58
	s_nop 0
	global_load_lds_dwordx4 v[174:175], off
	v_lshl_add_u64 v[174:175], v[224:225], 0, s[24:25]
	s_mov_b32 m0, s59
	s_nop 0
	global_load_lds_dwordx4 v[174:175], off
	s_waitcnt vmcnt(8)
	s_waitcnt lgkmcnt(0)
	s_setprio 1
	s_barrier
	v_mfma_f32_16x16x32_bf16 v[62:65], v[130:133], v[186:189], v[62:65]
	v_mfma_f32_16x16x32_bf16 v[58:61], v[138:141], v[186:189], v[58:61]
	v_mfma_f32_16x16x32_bf16 v[50:53], v[130:133], v[194:197], v[50:53]
	v_mfma_f32_16x16x32_bf16 v[42:45], v[138:141], v[194:197], v[42:45]
	v_mfma_f32_16x16x32_bf16 v[38:41], v[130:133], v[202:205], v[38:41]
	v_mfma_f32_16x16x32_bf16 v[34:37], v[138:141], v[202:205], v[34:37]
	v_mfma_f32_16x16x32_bf16 v[14:17], v[130:133], v[210:213], v[14:17]
	v_mfma_f32_16x16x32_bf16 v[10:13], v[138:141], v[210:213], v[10:13]
	v_mfma_f32_16x16x32_bf16 v[62:65], v[134:137], v[190:193], v[62:65]
	v_mfma_f32_16x16x32_bf16 v[58:61], v[142:145], v[190:193], v[58:61]
	v_mfma_f32_16x16x32_bf16 v[50:53], v[134:137], v[198:201], v[50:53]
	v_mfma_f32_16x16x32_bf16 v[42:45], v[142:145], v[198:201], v[42:45]
	v_mfma_f32_16x16x32_bf16 v[38:41], v[134:137], v[206:209], v[38:41]
	v_mfma_f32_16x16x32_bf16 v[34:37], v[142:145], v[206:209], v[34:37]
	v_mfma_f32_16x16x32_bf16 v[14:17], v[134:137], v[218:221], v[14:17]
	v_mfma_f32_16x16x32_bf16 v[10:13], v[142:145], v[218:221], v[10:13]
	s_setprio 0
	s_setprio 1
	v_mfma_f32_16x16x32_bf16 v[54:57], v[162:165], v[186:189], v[54:57]
	v_mfma_f32_16x16x32_bf16 v[46:49], v[170:173], v[186:189], v[46:49]
	v_mfma_f32_16x16x32_bf16 v[30:33], v[162:165], v[194:197], v[30:33]
	v_mfma_f32_16x16x32_bf16 v[26:29], v[170:173], v[194:197], v[26:29]
	v_mfma_f32_16x16x32_bf16 v[22:25], v[162:165], v[202:205], v[22:25]
	v_mfma_f32_16x16x32_bf16 v[18:21], v[170:173], v[202:205], v[18:21]
	v_mfma_f32_16x16x32_bf16 v[6:9], v[162:165], v[210:213], v[6:9]
	v_mfma_f32_16x16x32_bf16 v[2:5], v[170:173], v[210:213], v[2:5]
	v_mfma_f32_16x16x32_bf16 v[54:57], v[166:169], v[190:193], v[54:57]
	v_mfma_f32_16x16x32_bf16 v[46:49], v[182:185], v[190:193], v[46:49]
	v_mfma_f32_16x16x32_bf16 v[30:33], v[166:169], v[198:201], v[30:33]
	v_mfma_f32_16x16x32_bf16 v[26:29], v[182:185], v[198:201], v[26:29]
	v_mfma_f32_16x16x32_bf16 v[22:25], v[166:169], v[206:209], v[22:25]
	v_mfma_f32_16x16x32_bf16 v[18:21], v[182:185], v[206:209], v[18:21]
	v_mfma_f32_16x16x32_bf16 v[6:9], v[166:169], v[218:221], v[6:9]
	v_mfma_f32_16x16x32_bf16 v[2:5], v[182:185], v[218:221], v[2:5]
	s_barrier
	s_setprio 0
	s_add_i32 s52, s52, 2
	s_add_u32 s38, s38, 0x100
	s_addc_u32 s39, s39, 0
	s_add_u32 s0, s0, 0x100
	s_addc_u32 s1, s1, 0
	s_cmpk_gt_u32 s52, 0x55
	s_cbranch_scc0 .LBB0_2089
	s_and_b64 vcc, exec, s[26:27]
	s_cbranch_vccz .LBB0_2092
	s_barrier

.LBB0_2218:
	ds_read_b128 v[146:149], v153
	ds_read_b128 v[156:159], v153 offset:1024
	ds_read_b128 v[160:163], v153 offset:2048
	ds_read_b128 v[164:167], v153 offset:3072
	ds_read_b128 v[168:171], v154
	ds_read_b128 v[172:175], v154 offset:1024
	ds_read_b128 v[176:179], v154 offset:2048
	ds_read_b128 v[180:183], v154 offset:3072
	s_add_u32 s34, s76, 0xfff80080
	s_addc_u32 s35, s77, -1
	s_cmp_eq_u32 s80, 28
	s_cselect_b32 s79, s0, s35
	s_cselect_b32 s78, s1, s34
	s_cselect_b32 s35, s27, s75
	s_cselect_b32 s34, s37, s52
	v_lshl_add_u64 v[218:219], s[76:77], 0, v[138:139]
	s_add_i32 m0, s47, 0xc000
	ds_read_b128 v[184:187], v155
	ds_read_b128 v[188:191], v155 offset:1024
	ds_read_b128 v[192:195], v155 offset:2048
	ds_read_b128 v[196:199], v155 offset:3072
	ds_read_b128 v[200:203], v155 offset:4096
	ds_read_b128 v[204:207], v155 offset:5120
	ds_read_b128 v[208:211], v155 offset:6144
	ds_read_b128 v[212:215], v155 offset:7168
	global_load_lds_dwordx4 v[218:219], off
	v_lshl_add_u64 v[218:219], s[76:77], 0, v[140:141]
	s_add_i32 m0, s47, 0xe000
	s_nop 0
	global_load_lds_dwordx4 v[218:219], off
	s_waitcnt vmcnt(8)
	s_waitcnt lgkmcnt(0)
	s_setprio 1
	s_barrier
	v_mfma_f32_16x16x32_bf16 v[126:129], v[146:149], v[184:187], v[126:129]
	v_mfma_f32_16x16x32_bf16 v[118:121], v[160:163], v[184:187], v[118:121]
	v_mfma_f32_16x16x32_bf16 v[110:113], v[146:149], v[192:195], v[110:113]
	v_mfma_f32_16x16x32_bf16 v[102:105], v[160:163], v[192:195], v[102:105]
	v_mfma_f32_16x16x32_bf16 v[94:97], v[146:149], v[200:203], v[94:97]
	v_mfma_f32_16x16x32_bf16 v[86:89], v[160:163], v[200:203], v[86:89]
	v_mfma_f32_16x16x32_bf16 v[78:81], v[146:149], v[208:211], v[78:81]
	v_mfma_f32_16x16x32_bf16 v[70:73], v[160:163], v[208:211], v[70:73]
	v_mfma_f32_16x16x32_bf16 v[126:129], v[156:159], v[188:191], v[126:129]
	v_mfma_f32_16x16x32_bf16 v[118:121], v[164:167], v[188:191], v[118:121]
	v_mfma_f32_16x16x32_bf16 v[110:113], v[156:159], v[196:199], v[110:113]
	v_mfma_f32_16x16x32_bf16 v[102:105], v[164:167], v[196:199], v[102:105]
	v_mfma_f32_16x16x32_bf16 v[94:97], v[156:159], v[204:207], v[94:97]
	v_mfma_f32_16x16x32_bf16 v[86:89], v[164:167], v[204:207], v[86:89]
	v_mfma_f32_16x16x32_bf16 v[78:81], v[156:159], v[212:215], v[78:81]
	v_mfma_f32_16x16x32_bf16 v[70:73], v[164:167], v[212:215], v[70:73]
	s_setprio 0
	s_setprio 1
	v_mfma_f32_16x16x32_bf16 v[122:125], v[168:171], v[184:187], v[122:125]
	v_mfma_f32_16x16x32_bf16 v[114:117], v[176:179], v[184:187], v[114:117]
	v_mfma_f32_16x16x32_bf16 v[106:109], v[168:171], v[192:195], v[106:109]
	v_mfma_f32_16x16x32_bf16 v[98:101], v[176:179], v[192:195], v[98:101]
	v_mfma_f32_16x16x32_bf16 v[90:93], v[168:171], v[200:203], v[90:93]
	v_mfma_f32_16x16x32_bf16 v[82:85], v[176:179], v[200:203], v[82:85]
	v_mfma_f32_16x16x32_bf16 v[74:77], v[168:171], v[208:211], v[74:77]
	v_mfma_f32_16x16x32_bf16 v[66:69], v[176:179], v[208:211], v[66:69]
	v_mfma_f32_16x16x32_bf16 v[122:125], v[172:175], v[188:191], v[122:125]
	v_mfma_f32_16x16x32_bf16 v[114:117], v[180:183], v[188:191], v[114:117]
	v_mfma_f32_16x16x32_bf16 v[106:109], v[172:175], v[196:199], v[106:109]
	v_mfma_f32_16x16x32_bf16 v[98:101], v[180:183], v[196:199], v[98:101]
	v_mfma_f32_16x16x32_bf16 v[90:93], v[172:175], v[204:207], v[90:93]
	v_mfma_f32_16x16x32_bf16 v[82:85], v[180:183], v[204:207], v[82:85]
	v_mfma_f32_16x16x32_bf16 v[74:77], v[172:175], v[212:215], v[74:77]
	v_mfma_f32_16x16x32_bf16 v[66:69], v[180:183], v[212:215], v[66:69]
	s_barrier
	s_setprio 0
	s_add_i32 s53, s71, s30
	v_lshl_add_u64 v[218:219], s[34:35], 0, v[134:135]
	s_mov_b32 m0, s53
	ds_read_b128 v[184:187], v155 offset:16384
	ds_read_b128 v[188:191], v155 offset:17408
	ds_read_b128 v[192:195], v155 offset:18432
	ds_read_b128 v[196:199], v155 offset:19456
	ds_read_b128 v[200:203], v155 offset:20480
	ds_read_b128 v[204:207], v155 offset:21504
	ds_read_b128 v[208:211], v155 offset:22528
	ds_read_b128 v[212:215], v155 offset:23552
	global_load_lds_dwordx4 v[218:219], off
	s_add_i32 m0, s53, 0x2000
	s_add_u32 s54, s34, 0x80000
	v_lshl_add_u64 v[220:221], s[34:35], 0, v[130:131]
	s_addc_u32 s55, s35, 0
	s_add_i32 s53, s72, s30
	global_load_lds_dwordx4 v[220:221], off
	v_lshl_add_u64 v[222:223], s[54:55], 0, v[134:135]
	s_mov_b32 m0, s53
	v_lshl_add_u64 v[224:225], s[78:79], 0, v[132:133]
	global_load_lds_dwordx4 v[222:223], off
	v_lshl_add_u64 v[222:223], s[54:55], 0, v[130:131]
	s_add_i32 m0, s53, 0x2000
	s_nop 0
	global_load_lds_dwordx4 v[222:223], off
	v_lshl_add_u64 v[222:223], s[78:79], 0, v[136:137]
	s_mov_b32 m0, s47
	s_nop 0
	global_load_lds_dwordx4 v[222:223], off
	s_mov_b32 m0, s56
	s_nop 0
	global_load_lds_dwordx4 v[224:225], off
	s_waitcnt vmcnt(8)
	s_waitcnt lgkmcnt(0)
	s_setprio 1
	s_barrier
	v_mfma_f32_16x16x32_bf16 v[62:65], v[146:149], v[184:187], v[62:65]
	v_mfma_f32_16x16x32_bf16 v[54:57], v[160:163], v[184:187], v[54:57]
	v_mfma_f32_16x16x32_bf16 v[46:49], v[146:149], v[192:195], v[46:49]
	v_mfma_f32_16x16x32_bf16 v[38:41], v[160:163], v[192:195], v[38:41]
	v_mfma_f32_16x16x32_bf16 v[30:33], v[146:149], v[200:203], v[30:33]
	v_mfma_f32_16x16x32_bf16 v[22:25], v[160:163], v[200:203], v[22:25]
	v_mfma_f32_16x16x32_bf16 v[14:17], v[146:149], v[208:211], v[14:17]
	v_mfma_f32_16x16x32_bf16 v[6:9], v[160:163], v[208:211], v[6:9]
	v_mfma_f32_16x16x32_bf16 v[62:65], v[156:159], v[188:191], v[62:65]
	v_mfma_f32_16x16x32_bf16 v[54:57], v[164:167], v[188:191], v[54:57]
	v_mfma_f32_16x16x32_bf16 v[46:49], v[156:159], v[196:199], v[46:49]
	v_mfma_f32_16x16x32_bf16 v[38:41], v[164:167], v[196:199], v[38:41]
	v_mfma_f32_16x16x32_bf16 v[30:33], v[156:159], v[204:207], v[30:33]
	v_mfma_f32_16x16x32_bf16 v[22:25], v[164:167], v[204:207], v[22:25]
	v_mfma_f32_16x16x32_bf16 v[14:17], v[156:159], v[212:215], v[14:17]
	v_mfma_f32_16x16x32_bf16 v[6:9], v[164:167], v[212:215], v[6:9]
	s_setprio 0
	s_setprio 1
	v_mfma_f32_16x16x32_bf16 v[58:61], v[168:171], v[184:187], v[58:61]
	v_mfma_f32_16x16x32_bf16 v[50:53], v[176:179], v[184:187], v[50:53]
	v_mfma_f32_16x16x32_bf16 v[42:45], v[168:171], v[192:195], v[42:45]
	v_mfma_f32_16x16x32_bf16 v[34:37], v[176:179], v[192:195], v[34:37]
	v_mfma_f32_16x16x32_bf16 v[26:29], v[168:171], v[200:203], v[26:29]
	v_mfma_f32_16x16x32_bf16 v[18:21], v[176:179], v[200:203], v[18:21]
	v_mfma_f32_16x16x32_bf16 v[10:13], v[168:171], v[208:211], v[10:13]
	v_mfma_f32_16x16x32_bf16 v[2:5], v[176:179], v[208:211], v[2:5]
	v_mfma_f32_16x16x32_bf16 v[58:61], v[172:175], v[188:191], v[58:61]
	v_mfma_f32_16x16x32_bf16 v[50:53], v[180:183], v[188:191], v[50:53]
	v_mfma_f32_16x16x32_bf16 v[42:45], v[172:175], v[196:199], v[42:45]
	v_mfma_f32_16x16x32_bf16 v[34:37], v[180:183], v[196:199], v[34:37]
	v_mfma_f32_16x16x32_bf16 v[26:29], v[172:175], v[204:207], v[26:29]
	v_mfma_f32_16x16x32_bf16 v[18:21], v[180:183], v[204:207], v[18:21]
	v_mfma_f32_16x16x32_bf16 v[10:13], v[172:175], v[212:215], v[10:13]
	v_mfma_f32_16x16x32_bf16 v[2:5], v[180:183], v[212:215], v[2:5]
	s_barrier
	s_setprio 0
	s_add_i32 s53, 0, 0x18000
	s_add_i32 s62, 0, 0x1c000
	v_add_u32_e32 v164, s53, v151
	v_add_u32_e32 v180, s62, v151
	ds_read_b128 v[146:149], v164
	ds_read_b128 v[156:159], v164 offset:1024
	ds_read_b128 v[160:163], v164 offset:2048
	ds_read_b128 v[164:167], v164 offset:3072
	ds_read_b128 v[168:171], v180
	ds_read_b128 v[172:175], v180 offset:1024
	ds_read_b128 v[176:179], v180 offset:2048
	ds_read_b128 v[180:183], v180 offset:3072
	s_add_u32 s54, s78, 0x80000
	s_addc_u32 s55, s79, 0
	s_mov_b32 m0, s57
	v_lshl_add_u64 v[226:227], s[54:55], 0, v[136:137]
	ds_read_b128 v[184:187], v155 offset:32768
	ds_read_b128 v[188:191], v155 offset:33792
	ds_read_b128 v[192:195], v155 offset:34816
	ds_read_b128 v[196:199], v155 offset:35840
	ds_read_b128 v[200:203], v155 offset:36864
	ds_read_b128 v[204:207], v155 offset:37888
	ds_read_b128 v[208:211], v155 offset:38912
	ds_read_b128 v[212:215], v155 offset:39936
	global_load_lds_dwordx4 v[226:227], off
	v_lshl_add_u64 v[226:227], s[54:55], 0, v[132:133]
	s_mov_b32 m0, s58
	s_nop 0
	global_load_lds_dwordx4 v[226:227], off
	s_waitcnt vmcnt(8)
	s_waitcnt lgkmcnt(0)
	s_setprio 1
	s_barrier
	v_mfma_f32_16x16x32_bf16 v[126:129], v[146:149], v[184:187], v[126:129]
	v_mfma_f32_16x16x32_bf16 v[118:121], v[160:163], v[184:187], v[118:121]
	v_mfma_f32_16x16x32_bf16 v[110:113], v[146:149], v[192:195], v[110:113]
	v_mfma_f32_16x16x32_bf16 v[102:105], v[160:163], v[192:195], v[102:105]
	v_mfma_f32_16x16x32_bf16 v[94:97], v[146:149], v[200:203], v[94:97]
	v_mfma_f32_16x16x32_bf16 v[86:89], v[160:163], v[200:203], v[86:89]
	v_mfma_f32_16x16x32_bf16 v[78:81], v[146:149], v[208:211], v[78:81]
	v_mfma_f32_16x16x32_bf16 v[70:73], v[160:163], v[208:211], v[70:73]
	v_mfma_f32_16x16x32_bf16 v[126:129], v[156:159], v[188:191], v[126:129]
	v_mfma_f32_16x16x32_bf16 v[118:121], v[164:167], v[188:191], v[118:121]
	v_mfma_f32_16x16x32_bf16 v[110:113], v[156:159], v[196:199], v[110:113]
	v_mfma_f32_16x16x32_bf16 v[102:105], v[164:167], v[196:199], v[102:105]
	v_mfma_f32_16x16x32_bf16 v[94:97], v[156:159], v[204:207], v[94:97]
	v_mfma_f32_16x16x32_bf16 v[86:89], v[164:167], v[204:207], v[86:89]
	v_mfma_f32_16x16x32_bf16 v[78:81], v[156:159], v[212:215], v[78:81]
	v_mfma_f32_16x16x32_bf16 v[70:73], v[164:167], v[212:215], v[70:73]
	s_setprio 0
	s_setprio 1
	v_mfma_f32_16x16x32_bf16 v[122:125], v[168:171], v[184:187], v[122:125]
	v_mfma_f32_16x16x32_bf16 v[114:117], v[176:179], v[184:187], v[114:117]
	v_mfma_f32_16x16x32_bf16 v[106:109], v[168:171], v[192:195], v[106:109]
	v_mfma_f32_16x16x32_bf16 v[98:101], v[176:179], v[192:195], v[98:101]
	v_mfma_f32_16x16x32_bf16 v[90:93], v[168:171], v[200:203], v[90:93]
	v_mfma_f32_16x16x32_bf16 v[82:85], v[176:179], v[200:203], v[82:85]
	v_mfma_f32_16x16x32_bf16 v[74:77], v[168:171], v[208:211], v[74:77]
	v_mfma_f32_16x16x32_bf16 v[66:69], v[176:179], v[208:211], v[66:69]
	v_mfma_f32_16x16x32_bf16 v[122:125], v[172:175], v[188:191], v[122:125]
	v_mfma_f32_16x16x32_bf16 v[114:117], v[180:183], v[188:191], v[114:117]
	v_mfma_f32_16x16x32_bf16 v[106:109], v[172:175], v[196:199], v[106:109]
	v_mfma_f32_16x16x32_bf16 v[98:101], v[180:183], v[196:199], v[98:101]
	v_mfma_f32_16x16x32_bf16 v[90:93], v[172:175], v[204:207], v[90:93]
	v_mfma_f32_16x16x32_bf16 v[82:85], v[180:183], v[204:207], v[82:85]
	v_mfma_f32_16x16x32_bf16 v[74:77], v[172:175], v[212:215], v[74:77]
	v_mfma_f32_16x16x32_bf16 v[66:69], v[180:183], v[212:215], v[66:69]
	s_barrier
	s_setprio 0
	s_add_i32 s53, s53, s30
	v_lshl_add_u64 v[218:219], v[218:219], 0, s[8:9]
	s_mov_b32 m0, s53
	ds_read_b128 v[184:187], v155 offset:49152
	ds_read_b128 v[188:191], v155 offset:50176
	ds_read_b128 v[192:195], v155 offset:51200
	ds_read_b128 v[196:199], v155 offset:52224
	ds_read_b128 v[200:203], v155 offset:53248
	ds_read_b128 v[204:207], v155 offset:54272
	ds_read_b128 v[208:211], v155 offset:55296
	ds_read_b128 v[212:215], v155 offset:56320
	global_load_lds_dwordx4 v[218:219], off
	s_add_i32 m0, s53, 0x2000
	s_add_u32 s34, s34, 0x80080
	v_lshl_add_u64 v[218:219], v[220:221], 0, s[8:9]
	s_addc_u32 s35, s35, 0
	s_add_i32 s53, s62, s30
	global_load_lds_dwordx4 v[218:219], off
	v_lshl_add_u64 v[218:219], s[34:35], 0, v[134:135]
	s_mov_b32 m0, s53
	s_nop 0
	global_load_lds_dwordx4 v[218:219], off
	v_lshl_add_u64 v[218:219], s[34:35], 0, v[130:131]
	s_add_i32 m0, s53, 0x2000
	s_nop 0
	global_load_lds_dwordx4 v[218:219], off
	v_lshl_add_u64 v[218:219], v[222:223], 0, s[8:9]
	s_mov_b32 m0, s60
	s_nop 0
	global_load_lds_dwordx4 v[218:219], off
	v_lshl_add_u64 v[218:219], v[224:225], 0, s[8:9]
	s_mov_b32 m0, s61
	s_nop 0
	global_load_lds_dwordx4 v[218:219], off
	s_waitcnt vmcnt(8)
	s_waitcnt lgkmcnt(0)
	s_setprio 1
	s_barrier
	v_mfma_f32_16x16x32_bf16 v[62:65], v[146:149], v[184:187], v[62:65]
	v_mfma_f32_16x16x32_bf16 v[54:57], v[160:163], v[184:187], v[54:57]
	v_mfma_f32_16x16x32_bf16 v[46:49], v[146:149], v[192:195], v[46:49]
	v_mfma_f32_16x16x32_bf16 v[38:41], v[160:163], v[192:195], v[38:41]
	v_mfma_f32_16x16x32_bf16 v[30:33], v[146:149], v[200:203], v[30:33]
	v_mfma_f32_16x16x32_bf16 v[22:25], v[160:163], v[200:203], v[22:25]
	v_mfma_f32_16x16x32_bf16 v[14:17], v[146:149], v[208:211], v[14:17]
	v_mfma_f32_16x16x32_bf16 v[6:9], v[160:163], v[208:211], v[6:9]
	v_mfma_f32_16x16x32_bf16 v[62:65], v[156:159], v[188:191], v[62:65]
	v_mfma_f32_16x16x32_bf16 v[54:57], v[164:167], v[188:191], v[54:57]
	v_mfma_f32_16x16x32_bf16 v[46:49], v[156:159], v[196:199], v[46:49]
	v_mfma_f32_16x16x32_bf16 v[38:41], v[164:167], v[196:199], v[38:41]
	v_mfma_f32_16x16x32_bf16 v[30:33], v[156:159], v[204:207], v[30:33]
	v_mfma_f32_16x16x32_bf16 v[22:25], v[164:167], v[204:207], v[22:25]
	v_mfma_f32_16x16x32_bf16 v[14:17], v[156:159], v[212:215], v[14:17]
	v_mfma_f32_16x16x32_bf16 v[6:9], v[164:167], v[212:215], v[6:9]
	s_setprio 0
	s_setprio 1
	v_mfma_f32_16x16x32_bf16 v[58:61], v[168:171], v[184:187], v[58:61]
	v_mfma_f32_16x16x32_bf16 v[50:53], v[176:179], v[184:187], v[50:53]
	v_mfma_f32_16x16x32_bf16 v[42:45], v[168:171], v[192:195], v[42:45]
	v_mfma_f32_16x16x32_bf16 v[34:37], v[176:179], v[192:195], v[34:37]
	v_mfma_f32_16x16x32_bf16 v[26:29], v[168:171], v[200:203], v[26:29]
	v_mfma_f32_16x16x32_bf16 v[18:21], v[176:179], v[200:203], v[18:21]
	v_mfma_f32_16x16x32_bf16 v[10:13], v[168:171], v[208:211], v[10:13]
	v_mfma_f32_16x16x32_bf16 v[2:5], v[176:179], v[208:211], v[2:5]
	v_mfma_f32_16x16x32_bf16 v[58:61], v[172:175], v[188:191], v[58:61]
	v_mfma_f32_16x16x32_bf16 v[50:53], v[180:183], v[188:191], v[50:53]
	v_mfma_f32_16x16x32_bf16 v[42:45], v[172:175], v[196:199], v[42:45]
	v_mfma_f32_16x16x32_bf16 v[34:37], v[180:183], v[196:199], v[34:37]
	v_mfma_f32_16x16x32_bf16 v[26:29], v[172:175], v[204:207], v[26:29]
	v_mfma_f32_16x16x32_bf16 v[18:21], v[180:183], v[204:207], v[18:21]
	v_mfma_f32_16x16x32_bf16 v[10:13], v[172:175], v[212:215], v[10:13]
	v_mfma_f32_16x16x32_bf16 v[2:5], v[180:183], v[212:215], v[2:5]
	s_barrier
	s_setprio 0
	s_add_i32 s80, s80, 2
	s_add_u32 s76, s76, 0x100
	s_addc_u32 s77, s77, 0
	s_add_u32 s52, s52, 0x100
	s_addc_u32 s75, s75, 0
	s_cmp_gt_u32 s80, 29
	s_cbranch_scc0 .LBB0_2218
	s_and_b64 vcc, exec, s[24:25]
	s_cbranch_vccz .LBB0_2221
	s_barrier

.LBB0_2462:
	ds_read_b128 v[160:163], v155
	ds_read_b128 v[164:167], v155 offset:1024
	ds_read_b128 v[168:171], v155 offset:2048
	ds_read_b128 v[172:175], v155 offset:3072
	ds_read_b128 v[176:179], v156
	ds_read_b128 v[180:183], v156 offset:1024
	ds_read_b128 v[184:187], v156 offset:2048
	ds_read_b128 v[188:191], v156 offset:3072
	s_add_u32 s34, s76, 0xfff80080
	s_addc_u32 s35, s77, -1
	s_cmp_eq_u32 s74, 28
	s_cselect_b32 s89, s0, s35
	s_cselect_b32 s88, s1, s34
	s_cselect_b32 s35, s7, s52
	s_cselect_b32 s34, s9, s36
	v_lshl_add_u64 v[152:153], s[76:77], 0, v[144:145]
	s_add_i32 m0, s31, 0xc000
	ds_read_b128 v[192:195], v157
	ds_read_b128 v[196:199], v157 offset:1024
	ds_read_b128 v[200:203], v157 offset:2048
	ds_read_b128 v[204:207], v157 offset:3072
	ds_read_b128 v[208:211], v157 offset:4096
	ds_read_b128 v[212:215], v157 offset:5120
	ds_read_b128 v[218:221], v157 offset:6144
	ds_read_b128 v[222:225], v157 offset:7168
	global_load_lds_dwordx4 v[152:153], off
	v_lshl_add_u64 v[152:153], s[76:77], 0, v[146:147]
	s_add_i32 m0, s31, 0xe000
	s_nop 0
	global_load_lds_dwordx4 v[152:153], off
	s_waitcnt vmcnt(8)
	s_waitcnt lgkmcnt(0)
	s_setprio 1
	s_barrier
	v_mfma_f32_16x16x32_bf16 v[126:129], v[160:163], v[192:195], v[126:129]
	v_mfma_f32_16x16x32_bf16 v[122:125], v[168:171], v[192:195], v[122:125]
	v_mfma_f32_16x16x32_bf16 v[110:113], v[160:163], v[200:203], v[110:113]
	v_mfma_f32_16x16x32_bf16 v[106:109], v[168:171], v[200:203], v[106:109]
	v_mfma_f32_16x16x32_bf16 v[94:97], v[160:163], v[208:211], v[94:97]
	v_mfma_f32_16x16x32_bf16 v[90:93], v[168:171], v[208:211], v[90:93]
	v_mfma_f32_16x16x32_bf16 v[78:81], v[160:163], v[218:221], v[78:81]
	v_mfma_f32_16x16x32_bf16 v[74:77], v[168:171], v[218:221], v[74:77]
	v_mfma_f32_16x16x32_bf16 v[126:129], v[164:167], v[196:199], v[126:129]
	v_mfma_f32_16x16x32_bf16 v[122:125], v[172:175], v[196:199], v[122:125]
	v_mfma_f32_16x16x32_bf16 v[110:113], v[164:167], v[204:207], v[110:113]
	v_mfma_f32_16x16x32_bf16 v[106:109], v[172:175], v[204:207], v[106:109]
	v_mfma_f32_16x16x32_bf16 v[94:97], v[164:167], v[212:215], v[94:97]
	v_mfma_f32_16x16x32_bf16 v[90:93], v[172:175], v[212:215], v[90:93]
	v_mfma_f32_16x16x32_bf16 v[78:81], v[164:167], v[222:225], v[78:81]
	v_mfma_f32_16x16x32_bf16 v[74:77], v[172:175], v[222:225], v[74:77]
	s_setprio 0
	s_setprio 1
	v_mfma_f32_16x16x32_bf16 v[118:121], v[176:179], v[192:195], v[118:121]
	v_mfma_f32_16x16x32_bf16 v[114:117], v[184:187], v[192:195], v[114:117]
	v_mfma_f32_16x16x32_bf16 v[102:105], v[176:179], v[200:203], v[102:105]
	v_mfma_f32_16x16x32_bf16 v[98:101], v[184:187], v[200:203], v[98:101]
	v_mfma_f32_16x16x32_bf16 v[86:89], v[176:179], v[208:211], v[86:89]
	v_mfma_f32_16x16x32_bf16 v[82:85], v[184:187], v[208:211], v[82:85]
	v_mfma_f32_16x16x32_bf16 v[70:73], v[176:179], v[218:221], v[70:73]
	v_mfma_f32_16x16x32_bf16 v[66:69], v[184:187], v[218:221], v[66:69]
	v_mfma_f32_16x16x32_bf16 v[118:121], v[180:183], v[196:199], v[118:121]
	v_mfma_f32_16x16x32_bf16 v[114:117], v[188:191], v[196:199], v[114:117]
	v_mfma_f32_16x16x32_bf16 v[102:105], v[180:183], v[204:207], v[102:105]
	v_mfma_f32_16x16x32_bf16 v[98:101], v[188:191], v[204:207], v[98:101]
	v_mfma_f32_16x16x32_bf16 v[86:89], v[180:183], v[212:215], v[86:89]
	v_mfma_f32_16x16x32_bf16 v[82:85], v[188:191], v[212:215], v[82:85]
	v_mfma_f32_16x16x32_bf16 v[70:73], v[180:183], v[222:225], v[70:73]
	v_mfma_f32_16x16x32_bf16 v[66:69], v[188:191], v[222:225], v[66:69]
	s_barrier
	s_setprio 0
	s_add_i32 s53, s71, s12
	v_lshl_add_u64 v[152:153], s[34:35], 0, v[132:133]
	s_mov_b32 m0, s53
	ds_read_b128 v[192:195], v157 offset:16384
	ds_read_b128 v[196:199], v157 offset:17408
	ds_read_b128 v[200:203], v157 offset:18432
	ds_read_b128 v[204:207], v157 offset:19456
	ds_read_b128 v[208:211], v157 offset:20480
	ds_read_b128 v[212:215], v157 offset:21504
	ds_read_b128 v[218:221], v157 offset:22528
	ds_read_b128 v[222:225], v157 offset:23552
	global_load_lds_dwordx4 v[152:153], off
	s_add_i32 m0, s53, 0x2000
	s_add_u32 s54, s34, 0x80000
	v_lshl_add_u64 v[226:227], s[34:35], 0, v[136:137]
	s_addc_u32 s55, s35, 0
	s_add_i32 s53, s72, s12
	global_load_lds_dwordx4 v[226:227], off
	v_lshl_add_u64 v[228:229], s[54:55], 0, v[132:133]
	s_mov_b32 m0, s53
	v_lshl_add_u64 v[230:231], s[88:89], 0, v[134:135]
	global_load_lds_dwordx4 v[228:229], off
	v_lshl_add_u64 v[228:229], s[54:55], 0, v[136:137]
	s_add_i32 m0, s53, 0x2000
	s_nop 0
	global_load_lds_dwordx4 v[228:229], off
	v_lshl_add_u64 v[228:229], s[88:89], 0, v[130:131]
	s_mov_b32 m0, s31
	s_nop 0
	global_load_lds_dwordx4 v[228:229], off
	s_mov_b32 m0, s33
	s_nop 0
	global_load_lds_dwordx4 v[230:231], off
	s_waitcnt vmcnt(8)
	s_waitcnt lgkmcnt(0)
	s_setprio 1
	s_barrier
	v_mfma_f32_16x16x32_bf16 v[62:65], v[160:163], v[192:195], v[62:65]
	v_mfma_f32_16x16x32_bf16 v[58:61], v[168:171], v[192:195], v[58:61]
	v_mfma_f32_16x16x32_bf16 v[46:49], v[160:163], v[200:203], v[46:49]
	v_mfma_f32_16x16x32_bf16 v[42:45], v[168:171], v[200:203], v[42:45]
	v_mfma_f32_16x16x32_bf16 v[30:33], v[160:163], v[208:211], v[30:33]
	v_mfma_f32_16x16x32_bf16 v[26:29], v[168:171], v[208:211], v[26:29]
	v_mfma_f32_16x16x32_bf16 v[14:17], v[160:163], v[218:221], v[14:17]
	v_mfma_f32_16x16x32_bf16 v[10:13], v[168:171], v[218:221], v[10:13]
	v_mfma_f32_16x16x32_bf16 v[62:65], v[164:167], v[196:199], v[62:65]
	v_mfma_f32_16x16x32_bf16 v[58:61], v[172:175], v[196:199], v[58:61]
	v_mfma_f32_16x16x32_bf16 v[46:49], v[164:167], v[204:207], v[46:49]
	v_mfma_f32_16x16x32_bf16 v[42:45], v[172:175], v[204:207], v[42:45]
	v_mfma_f32_16x16x32_bf16 v[30:33], v[164:167], v[212:215], v[30:33]
	v_mfma_f32_16x16x32_bf16 v[26:29], v[172:175], v[212:215], v[26:29]
	v_mfma_f32_16x16x32_bf16 v[14:17], v[164:167], v[222:225], v[14:17]
	v_mfma_f32_16x16x32_bf16 v[10:13], v[172:175], v[222:225], v[10:13]
	s_setprio 0
	s_setprio 1
	v_mfma_f32_16x16x32_bf16 v[54:57], v[176:179], v[192:195], v[54:57]
	v_mfma_f32_16x16x32_bf16 v[50:53], v[184:187], v[192:195], v[50:53]
	v_mfma_f32_16x16x32_bf16 v[38:41], v[176:179], v[200:203], v[38:41]
	v_mfma_f32_16x16x32_bf16 v[34:37], v[184:187], v[200:203], v[34:37]
	v_mfma_f32_16x16x32_bf16 v[22:25], v[176:179], v[208:211], v[22:25]
	v_mfma_f32_16x16x32_bf16 v[18:21], v[184:187], v[208:211], v[18:21]
	v_mfma_f32_16x16x32_bf16 v[6:9], v[176:179], v[218:221], v[6:9]
	v_mfma_f32_16x16x32_bf16 v[2:5], v[184:187], v[218:221], v[2:5]
	v_mfma_f32_16x16x32_bf16 v[54:57], v[180:183], v[196:199], v[54:57]
	v_mfma_f32_16x16x32_bf16 v[50:53], v[188:191], v[196:199], v[50:53]
	v_mfma_f32_16x16x32_bf16 v[38:41], v[180:183], v[204:207], v[38:41]
	v_mfma_f32_16x16x32_bf16 v[34:37], v[188:191], v[204:207], v[34:37]
	v_mfma_f32_16x16x32_bf16 v[22:25], v[180:183], v[212:215], v[22:25]
	v_mfma_f32_16x16x32_bf16 v[18:21], v[188:191], v[212:215], v[18:21]
	v_mfma_f32_16x16x32_bf16 v[6:9], v[180:183], v[222:225], v[6:9]
	v_mfma_f32_16x16x32_bf16 v[2:5], v[188:191], v[222:225], v[2:5]
	s_barrier
	s_setprio 0
	s_add_i32 s53, 0, 0x18000
	v_add_u32_e32 v138, s53, v154
	s_add_i32 s62, 0, 0x1c000
	ds_read_b128 v[160:163], v138
	ds_read_b128 v[164:167], v138 offset:1024
	ds_read_b128 v[168:171], v138 offset:2048
	ds_read_b128 v[172:175], v138 offset:3072
	v_add_u32_e32 v138, s62, v154
	ds_read_b128 v[176:179], v138
	ds_read_b128 v[180:183], v138 offset:1024
	ds_read_b128 v[184:187], v138 offset:2048
	ds_read_b128 v[188:191], v138 offset:3072
	s_add_u32 s54, s88, 0x80000
	s_addc_u32 s55, s89, 0
	s_mov_b32 m0, s56
	v_lshl_add_u64 v[232:233], s[54:55], 0, v[130:131]
	ds_read_b128 v[192:195], v157 offset:32768
	ds_read_b128 v[196:199], v157 offset:33792
	ds_read_b128 v[200:203], v157 offset:34816
	ds_read_b128 v[204:207], v157 offset:35840
	ds_read_b128 v[208:211], v157 offset:36864
	ds_read_b128 v[212:215], v157 offset:37888
	ds_read_b128 v[218:221], v157 offset:38912
	ds_read_b128 v[222:225], v157 offset:39936
	global_load_lds_dwordx4 v[232:233], off
	v_lshl_add_u64 v[232:233], s[54:55], 0, v[134:135]
	s_mov_b32 m0, s57
	s_nop 0
	global_load_lds_dwordx4 v[232:233], off
	s_waitcnt vmcnt(8)
	s_waitcnt lgkmcnt(0)
	s_setprio 1
	s_barrier
	v_mfma_f32_16x16x32_bf16 v[126:129], v[160:163], v[192:195], v[126:129]
	v_mfma_f32_16x16x32_bf16 v[122:125], v[168:171], v[192:195], v[122:125]
	v_mfma_f32_16x16x32_bf16 v[110:113], v[160:163], v[200:203], v[110:113]
	v_mfma_f32_16x16x32_bf16 v[106:109], v[168:171], v[200:203], v[106:109]
	v_mfma_f32_16x16x32_bf16 v[94:97], v[160:163], v[208:211], v[94:97]
	v_mfma_f32_16x16x32_bf16 v[90:93], v[168:171], v[208:211], v[90:93]
	v_mfma_f32_16x16x32_bf16 v[78:81], v[160:163], v[218:221], v[78:81]
	v_mfma_f32_16x16x32_bf16 v[74:77], v[168:171], v[218:221], v[74:77]
	v_mfma_f32_16x16x32_bf16 v[126:129], v[164:167], v[196:199], v[126:129]
	v_mfma_f32_16x16x32_bf16 v[122:125], v[172:175], v[196:199], v[122:125]
	v_mfma_f32_16x16x32_bf16 v[110:113], v[164:167], v[204:207], v[110:113]
	v_mfma_f32_16x16x32_bf16 v[106:109], v[172:175], v[204:207], v[106:109]
	v_mfma_f32_16x16x32_bf16 v[94:97], v[164:167], v[212:215], v[94:97]
	v_mfma_f32_16x16x32_bf16 v[90:93], v[172:175], v[212:215], v[90:93]
	v_mfma_f32_16x16x32_bf16 v[78:81], v[164:167], v[222:225], v[78:81]
	v_mfma_f32_16x16x32_bf16 v[74:77], v[172:175], v[222:225], v[74:77]
	s_setprio 0
	s_setprio 1
	v_mfma_f32_16x16x32_bf16 v[118:121], v[176:179], v[192:195], v[118:121]
	v_mfma_f32_16x16x32_bf16 v[114:117], v[184:187], v[192:195], v[114:117]
	v_mfma_f32_16x16x32_bf16 v[102:105], v[176:179], v[200:203], v[102:105]
	v_mfma_f32_16x16x32_bf16 v[98:101], v[184:187], v[200:203], v[98:101]
	v_mfma_f32_16x16x32_bf16 v[86:89], v[176:179], v[208:211], v[86:89]
	v_mfma_f32_16x16x32_bf16 v[82:85], v[184:187], v[208:211], v[82:85]
	v_mfma_f32_16x16x32_bf16 v[70:73], v[176:179], v[218:221], v[70:73]
	v_mfma_f32_16x16x32_bf16 v[66:69], v[184:187], v[218:221], v[66:69]
	v_mfma_f32_16x16x32_bf16 v[118:121], v[180:183], v[196:199], v[118:121]
	v_mfma_f32_16x16x32_bf16 v[114:117], v[188:191], v[196:199], v[114:117]
	v_mfma_f32_16x16x32_bf16 v[102:105], v[180:183], v[204:207], v[102:105]
	v_mfma_f32_16x16x32_bf16 v[98:101], v[188:191], v[204:207], v[98:101]
	v_mfma_f32_16x16x32_bf16 v[86:89], v[180:183], v[212:215], v[86:89]
	v_mfma_f32_16x16x32_bf16 v[82:85], v[188:191], v[212:215], v[82:85]
	v_mfma_f32_16x16x32_bf16 v[70:73], v[180:183], v[222:225], v[70:73]
	v_mfma_f32_16x16x32_bf16 v[66:69], v[188:191], v[222:225], v[66:69]
	s_barrier
	s_setprio 0
	s_add_i32 s53, s53, s12
	v_lshl_add_u64 v[152:153], v[152:153], 0, s[40:41]
	s_mov_b32 m0, s53
	ds_read_b128 v[192:195], v157 offset:49152
	ds_read_b128 v[196:199], v157 offset:50176
	ds_read_b128 v[200:203], v157 offset:51200
	ds_read_b128 v[204:207], v157 offset:52224
	ds_read_b128 v[208:211], v157 offset:53248
	ds_read_b128 v[212:215], v157 offset:54272
	ds_read_b128 v[218:221], v157 offset:55296
	ds_read_b128 v[222:225], v157 offset:56320
	global_load_lds_dwordx4 v[152:153], off
	s_add_i32 m0, s53, 0x2000
	s_add_u32 s34, s34, 0x80080
	v_lshl_add_u64 v[152:153], v[226:227], 0, s[40:41]
	s_addc_u32 s35, s35, 0
	s_add_i32 s53, s62, s12
	global_load_lds_dwordx4 v[152:153], off
	v_lshl_add_u64 v[152:153], s[34:35], 0, v[132:133]
	s_mov_b32 m0, s53
	s_nop 0
	global_load_lds_dwordx4 v[152:153], off
	v_lshl_add_u64 v[152:153], s[34:35], 0, v[136:137]
	s_add_i32 m0, s53, 0x2000
	s_nop 0
	global_load_lds_dwordx4 v[152:153], off
	v_lshl_add_u64 v[152:153], v[228:229], 0, s[40:41]
	s_mov_b32 m0, s59
	s_nop 0
	global_load_lds_dwordx4 v[152:153], off
	v_lshl_add_u64 v[152:153], v[230:231], 0, s[40:41]
	s_mov_b32 m0, s60
	s_nop 0
	global_load_lds_dwordx4 v[152:153], off
	s_waitcnt vmcnt(8)
	s_waitcnt lgkmcnt(0)
	s_setprio 1
	s_barrier
	v_mfma_f32_16x16x32_bf16 v[62:65], v[160:163], v[192:195], v[62:65]
	v_mfma_f32_16x16x32_bf16 v[58:61], v[168:171], v[192:195], v[58:61]
	v_mfma_f32_16x16x32_bf16 v[46:49], v[160:163], v[200:203], v[46:49]
	v_mfma_f32_16x16x32_bf16 v[42:45], v[168:171], v[200:203], v[42:45]
	v_mfma_f32_16x16x32_bf16 v[30:33], v[160:163], v[208:211], v[30:33]
	v_mfma_f32_16x16x32_bf16 v[26:29], v[168:171], v[208:211], v[26:29]
	v_mfma_f32_16x16x32_bf16 v[14:17], v[160:163], v[218:221], v[14:17]
	v_mfma_f32_16x16x32_bf16 v[10:13], v[168:171], v[218:221], v[10:13]
	v_mfma_f32_16x16x32_bf16 v[62:65], v[164:167], v[196:199], v[62:65]
	v_mfma_f32_16x16x32_bf16 v[58:61], v[172:175], v[196:199], v[58:61]
	v_mfma_f32_16x16x32_bf16 v[46:49], v[164:167], v[204:207], v[46:49]
	v_mfma_f32_16x16x32_bf16 v[42:45], v[172:175], v[204:207], v[42:45]
	v_mfma_f32_16x16x32_bf16 v[30:33], v[164:167], v[212:215], v[30:33]
	v_mfma_f32_16x16x32_bf16 v[26:29], v[172:175], v[212:215], v[26:29]
	v_mfma_f32_16x16x32_bf16 v[14:17], v[164:167], v[222:225], v[14:17]
	v_mfma_f32_16x16x32_bf16 v[10:13], v[172:175], v[222:225], v[10:13]
	s_setprio 0
	s_setprio 1
	v_mfma_f32_16x16x32_bf16 v[54:57], v[176:179], v[192:195], v[54:57]
	v_mfma_f32_16x16x32_bf16 v[50:53], v[184:187], v[192:195], v[50:53]
	v_mfma_f32_16x16x32_bf16 v[38:41], v[176:179], v[200:203], v[38:41]
	v_mfma_f32_16x16x32_bf16 v[34:37], v[184:187], v[200:203], v[34:37]
	v_mfma_f32_16x16x32_bf16 v[22:25], v[176:179], v[208:211], v[22:25]
	v_mfma_f32_16x16x32_bf16 v[18:21], v[184:187], v[208:211], v[18:21]
	v_mfma_f32_16x16x32_bf16 v[6:9], v[176:179], v[218:221], v[6:9]
	v_mfma_f32_16x16x32_bf16 v[2:5], v[184:187], v[218:221], v[2:5]
	v_mfma_f32_16x16x32_bf16 v[54:57], v[180:183], v[196:199], v[54:57]
	v_mfma_f32_16x16x32_bf16 v[50:53], v[188:191], v[196:199], v[50:53]
	v_mfma_f32_16x16x32_bf16 v[38:41], v[180:183], v[204:207], v[38:41]
	v_mfma_f32_16x16x32_bf16 v[34:37], v[188:191], v[204:207], v[34:37]
	v_mfma_f32_16x16x32_bf16 v[22:25], v[180:183], v[212:215], v[22:25]
	v_mfma_f32_16x16x32_bf16 v[18:21], v[188:191], v[212:215], v[18:21]
	v_mfma_f32_16x16x32_bf16 v[6:9], v[180:183], v[222:225], v[6:9]
	v_mfma_f32_16x16x32_bf16 v[2:5], v[188:191], v[222:225], v[2:5]
	s_barrier
	s_setprio 0
	s_add_i32 s74, s74, 2
	s_add_u32 s76, s76, 0x100
	s_addc_u32 s77, s77, 0
	s_add_u32 s36, s36, 0x100
	s_addc_u32 s52, s52, 0
	s_cmp_gt_u32 s74, 29
	s_cbranch_scc0 .LBB0_2462
	s_and_b64 vcc, exec, s[46:47]
	s_cbranch_vccz .LBB0_2465
	s_barrier

.LBB0_2629:
	ds_read_b128 v[146:149], v165
	ds_read_b128 v[150:153], v165 offset:1024
	ds_read_b128 v[168:171], v165 offset:2048
	ds_read_b128 v[172:175], v165 offset:3072
	ds_read_b128 v[176:179], v166
	ds_read_b128 v[180:183], v166 offset:1024
	ds_read_b128 v[184:187], v166 offset:2048
	ds_read_b128 v[188:191], v166 offset:3072
	s_add_u32 s34, s74, 0xfffe0080
	s_addc_u32 s35, s75, -1
	s_cmp_eq_u32 s79, 4
	s_cselect_b32 s77, s0, s35
	s_cselect_b32 s76, s1, s34
	s_cselect_b32 s35, s27, s78
	s_cselect_b32 s34, s37, s52
	v_lshl_add_u64 v[226:227], s[74:75], 0, v[138:139]
	s_add_i32 m0, s33, 0xc000
	ds_read_b128 v[192:195], v167
	ds_read_b128 v[196:199], v167 offset:1024
	ds_read_b128 v[200:203], v167 offset:2048
	ds_read_b128 v[204:207], v167 offset:3072
	ds_read_b128 v[208:211], v167 offset:4096
	ds_read_b128 v[212:215], v167 offset:5120
	ds_read_b128 v[218:221], v167 offset:6144
	ds_read_b128 v[222:225], v167 offset:7168
	global_load_lds_dwordx4 v[226:227], off
	v_lshl_add_u64 v[226:227], s[74:75], 0, v[140:141]
	s_add_i32 m0, s33, 0xe000
	s_nop 0
	global_load_lds_dwordx4 v[226:227], off
	s_waitcnt vmcnt(8)
	s_waitcnt lgkmcnt(0)
	s_setprio 1
	s_barrier
	v_mfma_f32_16x16x32_bf16 v[126:129], v[146:149], v[192:195], v[126:129]
	v_mfma_f32_16x16x32_bf16 v[122:125], v[168:171], v[192:195], v[122:125]
	v_mfma_f32_16x16x32_bf16 v[114:117], v[146:149], v[200:203], v[114:117]
	v_mfma_f32_16x16x32_bf16 v[106:109], v[168:171], v[200:203], v[106:109]
	v_mfma_f32_16x16x32_bf16 v[98:101], v[146:149], v[208:211], v[98:101]
	v_mfma_f32_16x16x32_bf16 v[90:93], v[168:171], v[208:211], v[90:93]
	v_mfma_f32_16x16x32_bf16 v[82:85], v[146:149], v[218:221], v[82:85]
	v_mfma_f32_16x16x32_bf16 v[74:77], v[168:171], v[218:221], v[74:77]
	v_mfma_f32_16x16x32_bf16 v[126:129], v[150:153], v[196:199], v[126:129]
	v_mfma_f32_16x16x32_bf16 v[122:125], v[172:175], v[196:199], v[122:125]
	v_mfma_f32_16x16x32_bf16 v[114:117], v[150:153], v[204:207], v[114:117]
	v_mfma_f32_16x16x32_bf16 v[106:109], v[172:175], v[204:207], v[106:109]
	v_mfma_f32_16x16x32_bf16 v[98:101], v[150:153], v[212:215], v[98:101]
	v_mfma_f32_16x16x32_bf16 v[90:93], v[172:175], v[212:215], v[90:93]
	v_mfma_f32_16x16x32_bf16 v[82:85], v[150:153], v[222:225], v[82:85]
	v_mfma_f32_16x16x32_bf16 v[74:77], v[172:175], v[222:225], v[74:77]
	s_setprio 0
	s_setprio 1
	v_mfma_f32_16x16x32_bf16 v[118:121], v[176:179], v[192:195], v[118:121]
	v_mfma_f32_16x16x32_bf16 v[110:113], v[184:187], v[192:195], v[110:113]
	v_mfma_f32_16x16x32_bf16 v[102:105], v[176:179], v[200:203], v[102:105]
	v_mfma_f32_16x16x32_bf16 v[94:97], v[184:187], v[200:203], v[94:97]
	v_mfma_f32_16x16x32_bf16 v[86:89], v[176:179], v[208:211], v[86:89]
	v_mfma_f32_16x16x32_bf16 v[78:81], v[184:187], v[208:211], v[78:81]
	v_mfma_f32_16x16x32_bf16 v[70:73], v[176:179], v[218:221], v[70:73]
	v_mfma_f32_16x16x32_bf16 v[66:69], v[184:187], v[218:221], v[66:69]
	v_mfma_f32_16x16x32_bf16 v[118:121], v[180:183], v[196:199], v[118:121]
	v_mfma_f32_16x16x32_bf16 v[110:113], v[188:191], v[196:199], v[110:113]
	v_mfma_f32_16x16x32_bf16 v[102:105], v[180:183], v[204:207], v[102:105]
	v_mfma_f32_16x16x32_bf16 v[94:97], v[188:191], v[204:207], v[94:97]
	v_mfma_f32_16x16x32_bf16 v[86:89], v[180:183], v[212:215], v[86:89]
	v_mfma_f32_16x16x32_bf16 v[78:81], v[188:191], v[212:215], v[78:81]
	v_mfma_f32_16x16x32_bf16 v[70:73], v[180:183], v[222:225], v[70:73]
	v_mfma_f32_16x16x32_bf16 v[66:69], v[188:191], v[222:225], v[66:69]
	s_barrier
	s_setprio 0
	s_add_i32 s53, s70, s12
	v_lshl_add_u64 v[226:227], s[34:35], 0, v[132:133]
	s_mov_b32 m0, s53
	ds_read_b128 v[192:195], v167 offset:16384
	ds_read_b128 v[196:199], v167 offset:17408
	ds_read_b128 v[200:203], v167 offset:18432
	ds_read_b128 v[204:207], v167 offset:19456
	ds_read_b128 v[208:211], v167 offset:20480
	ds_read_b128 v[212:215], v167 offset:21504
	ds_read_b128 v[218:221], v167 offset:22528
	ds_read_b128 v[222:225], v167 offset:23552
	global_load_lds_dwordx4 v[226:227], off
	s_add_i32 m0, s53, 0x2000
	s_add_u32 s54, s34, 0x20000
	v_lshl_add_u64 v[228:229], s[34:35], 0, v[136:137]
	s_addc_u32 s55, s35, 0
	s_add_i32 s53, s71, s12
	global_load_lds_dwordx4 v[228:229], off
	v_lshl_add_u64 v[230:231], s[54:55], 0, v[132:133]
	s_mov_b32 m0, s53
	v_lshl_add_u64 v[232:233], s[76:77], 0, v[134:135]
	global_load_lds_dwordx4 v[230:231], off
	v_lshl_add_u64 v[230:231], s[54:55], 0, v[136:137]
	s_add_i32 m0, s53, 0x2000
	s_nop 0
	global_load_lds_dwordx4 v[230:231], off
	v_lshl_add_u64 v[230:231], s[76:77], 0, v[130:131]
	s_mov_b32 m0, s33
	s_nop 0
	global_load_lds_dwordx4 v[230:231], off
	s_mov_b32 m0, s47
	s_nop 0
	global_load_lds_dwordx4 v[232:233], off
	s_waitcnt vmcnt(8)
	s_waitcnt lgkmcnt(0)
	s_setprio 1
	s_barrier
	v_mfma_f32_16x16x32_bf16 v[62:65], v[146:149], v[192:195], v[62:65]
	v_mfma_f32_16x16x32_bf16 v[58:61], v[168:171], v[192:195], v[58:61]
	v_mfma_f32_16x16x32_bf16 v[50:53], v[146:149], v[200:203], v[50:53]
	v_mfma_f32_16x16x32_bf16 v[42:45], v[168:171], v[200:203], v[42:45]
	v_mfma_f32_16x16x32_bf16 v[34:37], v[146:149], v[208:211], v[34:37]
	v_mfma_f32_16x16x32_bf16 v[26:29], v[168:171], v[208:211], v[26:29]
	v_mfma_f32_16x16x32_bf16 v[18:21], v[146:149], v[218:221], v[18:21]
	v_mfma_f32_16x16x32_bf16 v[10:13], v[168:171], v[218:221], v[10:13]
	v_mfma_f32_16x16x32_bf16 v[62:65], v[150:153], v[196:199], v[62:65]
	v_mfma_f32_16x16x32_bf16 v[58:61], v[172:175], v[196:199], v[58:61]
	v_mfma_f32_16x16x32_bf16 v[50:53], v[150:153], v[204:207], v[50:53]
	v_mfma_f32_16x16x32_bf16 v[42:45], v[172:175], v[204:207], v[42:45]
	v_mfma_f32_16x16x32_bf16 v[34:37], v[150:153], v[212:215], v[34:37]
	v_mfma_f32_16x16x32_bf16 v[26:29], v[172:175], v[212:215], v[26:29]
	v_mfma_f32_16x16x32_bf16 v[18:21], v[150:153], v[222:225], v[18:21]
	v_mfma_f32_16x16x32_bf16 v[10:13], v[172:175], v[222:225], v[10:13]
	s_setprio 0
	s_setprio 1
	v_mfma_f32_16x16x32_bf16 v[54:57], v[176:179], v[192:195], v[54:57]
	v_mfma_f32_16x16x32_bf16 v[46:49], v[184:187], v[192:195], v[46:49]
	v_mfma_f32_16x16x32_bf16 v[38:41], v[176:179], v[200:203], v[38:41]
	v_mfma_f32_16x16x32_bf16 v[30:33], v[184:187], v[200:203], v[30:33]
	v_mfma_f32_16x16x32_bf16 v[22:25], v[176:179], v[208:211], v[22:25]
	v_mfma_f32_16x16x32_bf16 v[14:17], v[184:187], v[208:211], v[14:17]
	v_mfma_f32_16x16x32_bf16 v[6:9], v[176:179], v[218:221], v[6:9]
	v_mfma_f32_16x16x32_bf16 v[2:5], v[184:187], v[218:221], v[2:5]
	v_mfma_f32_16x16x32_bf16 v[54:57], v[180:183], v[196:199], v[54:57]
	v_mfma_f32_16x16x32_bf16 v[46:49], v[188:191], v[196:199], v[46:49]
	v_mfma_f32_16x16x32_bf16 v[38:41], v[180:183], v[204:207], v[38:41]
	v_mfma_f32_16x16x32_bf16 v[30:33], v[188:191], v[204:207], v[30:33]
	v_mfma_f32_16x16x32_bf16 v[22:25], v[180:183], v[212:215], v[22:25]
	v_mfma_f32_16x16x32_bf16 v[14:17], v[188:191], v[212:215], v[14:17]
	v_mfma_f32_16x16x32_bf16 v[6:9], v[180:183], v[222:225], v[6:9]
	v_mfma_f32_16x16x32_bf16 v[2:5], v[188:191], v[222:225], v[2:5]
	s_barrier
	s_setprio 0
	s_add_i32 s53, 0, 0x18000
	s_add_i32 s62, 0, 0x1c000
	v_add_u32_e32 v172, s53, v162
	v_add_u32_e32 v188, s62, v162
	ds_read_b128 v[146:149], v172
	ds_read_b128 v[150:153], v172 offset:1024
	ds_read_b128 v[168:171], v172 offset:2048
	ds_read_b128 v[172:175], v172 offset:3072
	ds_read_b128 v[176:179], v188
	ds_read_b128 v[180:183], v188 offset:1024
	ds_read_b128 v[184:187], v188 offset:2048
	ds_read_b128 v[188:191], v188 offset:3072
	s_add_u32 s54, s76, 0x20000
	s_addc_u32 s55, s77, 0
	s_mov_b32 m0, s56
	v_lshl_add_u64 v[234:235], s[54:55], 0, v[130:131]
	ds_read_b128 v[192:195], v167 offset:32768
	ds_read_b128 v[196:199], v167 offset:33792
	ds_read_b128 v[200:203], v167 offset:34816
	ds_read_b128 v[204:207], v167 offset:35840
	ds_read_b128 v[208:211], v167 offset:36864
	ds_read_b128 v[212:215], v167 offset:37888
	ds_read_b128 v[218:221], v167 offset:38912
	ds_read_b128 v[222:225], v167 offset:39936
	global_load_lds_dwordx4 v[234:235], off
	v_lshl_add_u64 v[234:235], s[54:55], 0, v[134:135]
	s_mov_b32 m0, s57
	s_nop 0
	global_load_lds_dwordx4 v[234:235], off
	s_waitcnt vmcnt(8)
	s_waitcnt lgkmcnt(0)
	s_setprio 1
	s_barrier
	v_mfma_f32_16x16x32_bf16 v[126:129], v[146:149], v[192:195], v[126:129]
	v_mfma_f32_16x16x32_bf16 v[122:125], v[168:171], v[192:195], v[122:125]
	v_mfma_f32_16x16x32_bf16 v[114:117], v[146:149], v[200:203], v[114:117]
	v_mfma_f32_16x16x32_bf16 v[106:109], v[168:171], v[200:203], v[106:109]
	v_mfma_f32_16x16x32_bf16 v[98:101], v[146:149], v[208:211], v[98:101]
	v_mfma_f32_16x16x32_bf16 v[90:93], v[168:171], v[208:211], v[90:93]
	v_mfma_f32_16x16x32_bf16 v[82:85], v[146:149], v[218:221], v[82:85]
	v_mfma_f32_16x16x32_bf16 v[74:77], v[168:171], v[218:221], v[74:77]
	v_mfma_f32_16x16x32_bf16 v[126:129], v[150:153], v[196:199], v[126:129]
	v_mfma_f32_16x16x32_bf16 v[122:125], v[172:175], v[196:199], v[122:125]
	v_mfma_f32_16x16x32_bf16 v[114:117], v[150:153], v[204:207], v[114:117]
	v_mfma_f32_16x16x32_bf16 v[106:109], v[172:175], v[204:207], v[106:109]
	v_mfma_f32_16x16x32_bf16 v[98:101], v[150:153], v[212:215], v[98:101]
	v_mfma_f32_16x16x32_bf16 v[90:93], v[172:175], v[212:215], v[90:93]
	v_mfma_f32_16x16x32_bf16 v[82:85], v[150:153], v[222:225], v[82:85]
	v_mfma_f32_16x16x32_bf16 v[74:77], v[172:175], v[222:225], v[74:77]
	s_setprio 0
	s_setprio 1
	v_mfma_f32_16x16x32_bf16 v[118:121], v[176:179], v[192:195], v[118:121]
	v_mfma_f32_16x16x32_bf16 v[110:113], v[184:187], v[192:195], v[110:113]
	v_mfma_f32_16x16x32_bf16 v[102:105], v[176:179], v[200:203], v[102:105]
	v_mfma_f32_16x16x32_bf16 v[94:97], v[184:187], v[200:203], v[94:97]
	v_mfma_f32_16x16x32_bf16 v[86:89], v[176:179], v[208:211], v[86:89]
	v_mfma_f32_16x16x32_bf16 v[78:81], v[184:187], v[208:211], v[78:81]
	v_mfma_f32_16x16x32_bf16 v[70:73], v[176:179], v[218:221], v[70:73]
	v_mfma_f32_16x16x32_bf16 v[66:69], v[184:187], v[218:221], v[66:69]
	v_mfma_f32_16x16x32_bf16 v[118:121], v[180:183], v[196:199], v[118:121]
	v_mfma_f32_16x16x32_bf16 v[110:113], v[188:191], v[196:199], v[110:113]
	v_mfma_f32_16x16x32_bf16 v[102:105], v[180:183], v[204:207], v[102:105]
	v_mfma_f32_16x16x32_bf16 v[94:97], v[188:191], v[204:207], v[94:97]
	v_mfma_f32_16x16x32_bf16 v[86:89], v[180:183], v[212:215], v[86:89]
	v_mfma_f32_16x16x32_bf16 v[78:81], v[188:191], v[212:215], v[78:81]
	v_mfma_f32_16x16x32_bf16 v[70:73], v[180:183], v[222:225], v[70:73]
	v_mfma_f32_16x16x32_bf16 v[66:69], v[188:191], v[222:225], v[66:69]
	s_barrier
	s_setprio 0
	s_add_i32 s53, s53, s12
	v_lshl_add_u64 v[226:227], v[226:227], 0, s[8:9]
	s_mov_b32 m0, s53
	ds_read_b128 v[192:195], v167 offset:49152
	ds_read_b128 v[196:199], v167 offset:50176
	ds_read_b128 v[200:203], v167 offset:51200
	ds_read_b128 v[204:207], v167 offset:52224
	ds_read_b128 v[208:211], v167 offset:53248
	ds_read_b128 v[212:215], v167 offset:54272
	ds_read_b128 v[218:221], v167 offset:55296
	ds_read_b128 v[222:225], v167 offset:56320
	global_load_lds_dwordx4 v[226:227], off
	s_add_i32 m0, s53, 0x2000
	s_add_u32 s34, s34, 0x20080
	v_lshl_add_u64 v[226:227], v[228:229], 0, s[8:9]
	s_addc_u32 s35, s35, 0
	s_add_i32 s53, s62, s12
	global_load_lds_dwordx4 v[226:227], off
	v_lshl_add_u64 v[226:227], s[34:35], 0, v[132:133]
	s_mov_b32 m0, s53
	s_nop 0
	global_load_lds_dwordx4 v[226:227], off
	v_lshl_add_u64 v[226:227], s[34:35], 0, v[136:137]
	s_add_i32 m0, s53, 0x2000
	s_nop 0
	global_load_lds_dwordx4 v[226:227], off
	v_lshl_add_u64 v[226:227], v[230:231], 0, s[8:9]
	s_mov_b32 m0, s59
	s_nop 0
	global_load_lds_dwordx4 v[226:227], off
	v_lshl_add_u64 v[226:227], v[232:233], 0, s[8:9]
	s_mov_b32 m0, s60
	s_nop 0
	global_load_lds_dwordx4 v[226:227], off
	s_waitcnt vmcnt(8)
	s_waitcnt lgkmcnt(0)
	s_setprio 1
	s_barrier
	v_mfma_f32_16x16x32_bf16 v[62:65], v[146:149], v[192:195], v[62:65]
	v_mfma_f32_16x16x32_bf16 v[58:61], v[168:171], v[192:195], v[58:61]
	v_mfma_f32_16x16x32_bf16 v[50:53], v[146:149], v[200:203], v[50:53]
	v_mfma_f32_16x16x32_bf16 v[42:45], v[168:171], v[200:203], v[42:45]
	v_mfma_f32_16x16x32_bf16 v[34:37], v[146:149], v[208:211], v[34:37]
	v_mfma_f32_16x16x32_bf16 v[26:29], v[168:171], v[208:211], v[26:29]
	v_mfma_f32_16x16x32_bf16 v[18:21], v[146:149], v[218:221], v[18:21]
	v_mfma_f32_16x16x32_bf16 v[10:13], v[168:171], v[218:221], v[10:13]
	v_mfma_f32_16x16x32_bf16 v[62:65], v[150:153], v[196:199], v[62:65]
	v_mfma_f32_16x16x32_bf16 v[58:61], v[172:175], v[196:199], v[58:61]
	v_mfma_f32_16x16x32_bf16 v[50:53], v[150:153], v[204:207], v[50:53]
	v_mfma_f32_16x16x32_bf16 v[42:45], v[172:175], v[204:207], v[42:45]
	v_mfma_f32_16x16x32_bf16 v[34:37], v[150:153], v[212:215], v[34:37]
	v_mfma_f32_16x16x32_bf16 v[26:29], v[172:175], v[212:215], v[26:29]
	v_mfma_f32_16x16x32_bf16 v[18:21], v[150:153], v[222:225], v[18:21]
	v_mfma_f32_16x16x32_bf16 v[10:13], v[172:175], v[222:225], v[10:13]
	s_setprio 0
	s_setprio 1
	v_mfma_f32_16x16x32_bf16 v[54:57], v[176:179], v[192:195], v[54:57]
	v_mfma_f32_16x16x32_bf16 v[46:49], v[184:187], v[192:195], v[46:49]
	v_mfma_f32_16x16x32_bf16 v[38:41], v[176:179], v[200:203], v[38:41]
	v_mfma_f32_16x16x32_bf16 v[30:33], v[184:187], v[200:203], v[30:33]
	v_mfma_f32_16x16x32_bf16 v[22:25], v[176:179], v[208:211], v[22:25]
	v_mfma_f32_16x16x32_bf16 v[14:17], v[184:187], v[208:211], v[14:17]
	v_mfma_f32_16x16x32_bf16 v[6:9], v[176:179], v[218:221], v[6:9]
	v_mfma_f32_16x16x32_bf16 v[2:5], v[184:187], v[218:221], v[2:5]
	v_mfma_f32_16x16x32_bf16 v[54:57], v[180:183], v[196:199], v[54:57]
	v_mfma_f32_16x16x32_bf16 v[46:49], v[188:191], v[196:199], v[46:49]
	v_mfma_f32_16x16x32_bf16 v[38:41], v[180:183], v[204:207], v[38:41]
	v_mfma_f32_16x16x32_bf16 v[30:33], v[188:191], v[204:207], v[30:33]
	v_mfma_f32_16x16x32_bf16 v[22:25], v[180:183], v[212:215], v[22:25]
	v_mfma_f32_16x16x32_bf16 v[14:17], v[188:191], v[212:215], v[14:17]
	v_mfma_f32_16x16x32_bf16 v[6:9], v[180:183], v[222:225], v[6:9]
	v_mfma_f32_16x16x32_bf16 v[2:5], v[188:191], v[222:225], v[2:5]
	s_barrier
	s_setprio 0
	s_add_i32 s79, s79, 2
	s_add_u32 s74, s74, 0x100
	s_addc_u32 s75, s75, 0
	s_add_u32 s52, s52, 0x100
	s_addc_u32 s78, s78, 0
	s_cmp_gt_u32 s79, 5
	s_cbranch_scc0 .LBB0_2629
	s_and_b64 vcc, exec, s[24:25]
	s_cbranch_vccz .LBB0_2632
	s_barrier

.LBB0_2659:
	ds_read_b128 v[146:149], v1
	ds_read_b128 v[160:163], v1 offset:1024
	ds_read_b128 v[164:167], v1 offset:2048
	ds_read_b128 v[168:171], v1 offset:3072
	ds_read_b128 v[172:175], v154
	ds_read_b128 v[176:179], v154 offset:1024
	ds_read_b128 v[180:183], v154 offset:2048
	ds_read_b128 v[184:187], v154 offset:3072
	s_add_u32 s34, s74, 0xfffe0080
	s_addc_u32 s35, s75, -1
	s_cmp_eq_u32 s72, 4
	s_cselect_b32 s77, s0, s35
	s_cselect_b32 s76, s1, s34
	s_cselect_b32 s35, s27, s71
	s_cselect_b32 s34, s37, s52
	v_lshl_add_u64 v[150:151], s[74:75], 0, v[138:139]
	s_add_i32 m0, s33, 0xc000
	ds_read_b128 v[188:191], v155
	ds_read_b128 v[192:195], v155 offset:1024
	ds_read_b128 v[196:199], v155 offset:2048
	ds_read_b128 v[200:203], v155 offset:3072
	ds_read_b128 v[204:207], v155 offset:4096
	ds_read_b128 v[208:211], v155 offset:5120
	ds_read_b128 v[212:215], v155 offset:6144
	ds_read_b128 v[218:221], v155 offset:7168
	global_load_lds_dwordx4 v[150:151], off
	v_lshl_add_u64 v[150:151], s[74:75], 0, v[140:141]
	s_add_i32 m0, s33, 0xe000
	s_nop 0
	global_load_lds_dwordx4 v[150:151], off
	s_waitcnt vmcnt(8)
	s_waitcnt lgkmcnt(0)
	s_setprio 1
	s_barrier
	v_mfma_f32_16x16x32_bf16 v[126:129], v[146:149], v[188:191], v[126:129]
	v_mfma_f32_16x16x32_bf16 v[122:125], v[164:167], v[188:191], v[122:125]
	v_mfma_f32_16x16x32_bf16 v[110:113], v[146:149], v[196:199], v[110:113]
	v_mfma_f32_16x16x32_bf16 v[106:109], v[164:167], v[196:199], v[106:109]
	v_mfma_f32_16x16x32_bf16 v[94:97], v[146:149], v[204:207], v[94:97]
	v_mfma_f32_16x16x32_bf16 v[90:93], v[164:167], v[204:207], v[90:93]
	v_mfma_f32_16x16x32_bf16 v[78:81], v[146:149], v[212:215], v[78:81]
	v_mfma_f32_16x16x32_bf16 v[74:77], v[164:167], v[212:215], v[74:77]
	v_mfma_f32_16x16x32_bf16 v[126:129], v[160:163], v[192:195], v[126:129]
	v_mfma_f32_16x16x32_bf16 v[122:125], v[168:171], v[192:195], v[122:125]
	v_mfma_f32_16x16x32_bf16 v[110:113], v[160:163], v[200:203], v[110:113]
	v_mfma_f32_16x16x32_bf16 v[106:109], v[168:171], v[200:203], v[106:109]
	v_mfma_f32_16x16x32_bf16 v[94:97], v[160:163], v[208:211], v[94:97]
	v_mfma_f32_16x16x32_bf16 v[90:93], v[168:171], v[208:211], v[90:93]
	v_mfma_f32_16x16x32_bf16 v[78:81], v[160:163], v[218:221], v[78:81]
	v_mfma_f32_16x16x32_bf16 v[74:77], v[168:171], v[218:221], v[74:77]
	s_setprio 0
	s_setprio 1
	v_mfma_f32_16x16x32_bf16 v[118:121], v[172:175], v[188:191], v[118:121]
	v_mfma_f32_16x16x32_bf16 v[114:117], v[180:183], v[188:191], v[114:117]
	v_mfma_f32_16x16x32_bf16 v[102:105], v[172:175], v[196:199], v[102:105]
	v_mfma_f32_16x16x32_bf16 v[98:101], v[180:183], v[196:199], v[98:101]
	v_mfma_f32_16x16x32_bf16 v[86:89], v[172:175], v[204:207], v[86:89]
	v_mfma_f32_16x16x32_bf16 v[82:85], v[180:183], v[204:207], v[82:85]
	v_mfma_f32_16x16x32_bf16 v[70:73], v[172:175], v[212:215], v[70:73]
	v_mfma_f32_16x16x32_bf16 v[66:69], v[180:183], v[212:215], v[66:69]
	v_mfma_f32_16x16x32_bf16 v[118:121], v[176:179], v[192:195], v[118:121]
	v_mfma_f32_16x16x32_bf16 v[114:117], v[184:187], v[192:195], v[114:117]
	v_mfma_f32_16x16x32_bf16 v[102:105], v[176:179], v[200:203], v[102:105]
	v_mfma_f32_16x16x32_bf16 v[98:101], v[184:187], v[200:203], v[98:101]
	v_mfma_f32_16x16x32_bf16 v[86:89], v[176:179], v[208:211], v[86:89]
	v_mfma_f32_16x16x32_bf16 v[82:85], v[184:187], v[208:211], v[82:85]
	v_mfma_f32_16x16x32_bf16 v[70:73], v[176:179], v[218:221], v[70:73]
	v_mfma_f32_16x16x32_bf16 v[66:69], v[184:187], v[218:221], v[66:69]
	s_barrier
	s_setprio 0
	s_add_i32 s53, s60, s13
	v_lshl_add_u64 v[150:151], s[34:35], 0, v[132:133]
	s_mov_b32 m0, s53
	ds_read_b128 v[188:191], v155 offset:16384
	ds_read_b128 v[192:195], v155 offset:17408
	ds_read_b128 v[196:199], v155 offset:18432
	ds_read_b128 v[200:203], v155 offset:19456
	ds_read_b128 v[204:207], v155 offset:20480
	ds_read_b128 v[208:211], v155 offset:21504
	ds_read_b128 v[212:215], v155 offset:22528
	ds_read_b128 v[218:221], v155 offset:23552
	global_load_lds_dwordx4 v[150:151], off
	s_add_i32 m0, s53, 0x2000
	s_add_u32 s62, s34, 0x20000
	v_lshl_add_u64 v[222:223], s[34:35], 0, v[136:137]
	s_addc_u32 s63, s35, 0
	s_add_i32 s53, s61, s13
	global_load_lds_dwordx4 v[222:223], off
	v_lshl_add_u64 v[224:225], s[62:63], 0, v[132:133]
	s_mov_b32 m0, s53
	v_lshl_add_u64 v[226:227], s[76:77], 0, v[134:135]
	global_load_lds_dwordx4 v[224:225], off
	v_lshl_add_u64 v[224:225], s[62:63], 0, v[136:137]
	s_add_i32 m0, s53, 0x2000
	s_nop 0
	global_load_lds_dwordx4 v[224:225], off
	v_lshl_add_u64 v[224:225], s[76:77], 0, v[130:131]
	s_mov_b32 m0, s33
	s_nop 0
	global_load_lds_dwordx4 v[224:225], off
	s_mov_b32 m0, s47
	s_nop 0
	global_load_lds_dwordx4 v[226:227], off
	s_waitcnt vmcnt(8)
	s_waitcnt lgkmcnt(0)
	s_setprio 1
	s_barrier
	v_mfma_f32_16x16x32_bf16 v[62:65], v[146:149], v[188:191], v[62:65]
	v_mfma_f32_16x16x32_bf16 v[58:61], v[164:167], v[188:191], v[58:61]
	v_mfma_f32_16x16x32_bf16 v[50:53], v[146:149], v[196:199], v[50:53]
	v_mfma_f32_16x16x32_bf16 v[42:45], v[164:167], v[196:199], v[42:45]
	v_mfma_f32_16x16x32_bf16 v[34:37], v[146:149], v[204:207], v[34:37]
	v_mfma_f32_16x16x32_bf16 v[26:29], v[164:167], v[204:207], v[26:29]
	v_mfma_f32_16x16x32_bf16 v[18:21], v[146:149], v[212:215], v[18:21]
	v_mfma_f32_16x16x32_bf16 v[10:13], v[164:167], v[212:215], v[10:13]
	v_mfma_f32_16x16x32_bf16 v[62:65], v[160:163], v[192:195], v[62:65]
	v_mfma_f32_16x16x32_bf16 v[58:61], v[168:171], v[192:195], v[58:61]
	v_mfma_f32_16x16x32_bf16 v[50:53], v[160:163], v[200:203], v[50:53]
	v_mfma_f32_16x16x32_bf16 v[42:45], v[168:171], v[200:203], v[42:45]
	v_mfma_f32_16x16x32_bf16 v[34:37], v[160:163], v[208:211], v[34:37]
	v_mfma_f32_16x16x32_bf16 v[26:29], v[168:171], v[208:211], v[26:29]
	v_mfma_f32_16x16x32_bf16 v[18:21], v[160:163], v[218:221], v[18:21]
	v_mfma_f32_16x16x32_bf16 v[10:13], v[168:171], v[218:221], v[10:13]
	s_setprio 0
	s_setprio 1
	v_mfma_f32_16x16x32_bf16 v[54:57], v[172:175], v[188:191], v[54:57]
	v_mfma_f32_16x16x32_bf16 v[46:49], v[180:183], v[188:191], v[46:49]
	v_mfma_f32_16x16x32_bf16 v[38:41], v[172:175], v[196:199], v[38:41]
	v_mfma_f32_16x16x32_bf16 v[30:33], v[180:183], v[196:199], v[30:33]
	v_mfma_f32_16x16x32_bf16 v[22:25], v[172:175], v[204:207], v[22:25]
	v_mfma_f32_16x16x32_bf16 v[14:17], v[180:183], v[204:207], v[14:17]
	v_mfma_f32_16x16x32_bf16 v[6:9], v[172:175], v[212:215], v[6:9]
	v_mfma_f32_16x16x32_bf16 v[2:5], v[180:183], v[212:215], v[2:5]
	v_mfma_f32_16x16x32_bf16 v[54:57], v[176:179], v[192:195], v[54:57]
	v_mfma_f32_16x16x32_bf16 v[46:49], v[184:187], v[192:195], v[46:49]
	v_mfma_f32_16x16x32_bf16 v[38:41], v[176:179], v[200:203], v[38:41]
	v_mfma_f32_16x16x32_bf16 v[30:33], v[184:187], v[200:203], v[30:33]
	v_mfma_f32_16x16x32_bf16 v[22:25], v[176:179], v[208:211], v[22:25]
	v_mfma_f32_16x16x32_bf16 v[14:17], v[184:187], v[208:211], v[14:17]
	v_mfma_f32_16x16x32_bf16 v[6:9], v[176:179], v[218:221], v[6:9]
	v_mfma_f32_16x16x32_bf16 v[2:5], v[184:187], v[218:221], v[2:5]
	s_barrier
	s_setprio 0
	s_add_i32 s53, 0, 0x18000
	v_add_u32_e32 v156, s53, v153
	s_add_i32 s66, 0, 0x1c000
	ds_read_b128 v[146:149], v156
	ds_read_b128 v[160:163], v156 offset:1024
	ds_read_b128 v[164:167], v156 offset:2048
	ds_read_b128 v[168:171], v156 offset:3072
	v_add_u32_e32 v156, s66, v153
	ds_read_b128 v[172:175], v156
	ds_read_b128 v[176:179], v156 offset:1024
	ds_read_b128 v[180:183], v156 offset:2048
	ds_read_b128 v[184:187], v156 offset:3072
	s_add_u32 s62, s76, 0x20000
	s_addc_u32 s63, s77, 0
	s_mov_b32 m0, s54
	v_lshl_add_u64 v[228:229], s[62:63], 0, v[130:131]
	ds_read_b128 v[188:191], v155 offset:32768
	ds_read_b128 v[192:195], v155 offset:33792
	ds_read_b128 v[196:199], v155 offset:34816
	ds_read_b128 v[200:203], v155 offset:35840
	ds_read_b128 v[204:207], v155 offset:36864
	ds_read_b128 v[208:211], v155 offset:37888
	ds_read_b128 v[212:215], v155 offset:38912
	ds_read_b128 v[218:221], v155 offset:39936
	global_load_lds_dwordx4 v[228:229], off
	v_lshl_add_u64 v[228:229], s[62:63], 0, v[134:135]
	s_mov_b32 m0, s55
	s_nop 0
	global_load_lds_dwordx4 v[228:229], off
	s_waitcnt vmcnt(8)
	s_waitcnt lgkmcnt(0)
	s_setprio 1
	s_barrier
	v_mfma_f32_16x16x32_bf16 v[126:129], v[146:149], v[188:191], v[126:129]
	v_mfma_f32_16x16x32_bf16 v[122:125], v[164:167], v[188:191], v[122:125]
	v_mfma_f32_16x16x32_bf16 v[110:113], v[146:149], v[196:199], v[110:113]
	v_mfma_f32_16x16x32_bf16 v[106:109], v[164:167], v[196:199], v[106:109]
	v_mfma_f32_16x16x32_bf16 v[94:97], v[146:149], v[204:207], v[94:97]
	v_mfma_f32_16x16x32_bf16 v[90:93], v[164:167], v[204:207], v[90:93]
	v_mfma_f32_16x16x32_bf16 v[78:81], v[146:149], v[212:215], v[78:81]
	v_mfma_f32_16x16x32_bf16 v[74:77], v[164:167], v[212:215], v[74:77]
	v_mfma_f32_16x16x32_bf16 v[126:129], v[160:163], v[192:195], v[126:129]
	v_mfma_f32_16x16x32_bf16 v[122:125], v[168:171], v[192:195], v[122:125]
	v_mfma_f32_16x16x32_bf16 v[110:113], v[160:163], v[200:203], v[110:113]
	v_mfma_f32_16x16x32_bf16 v[106:109], v[168:171], v[200:203], v[106:109]
	v_mfma_f32_16x16x32_bf16 v[94:97], v[160:163], v[208:211], v[94:97]
	v_mfma_f32_16x16x32_bf16 v[90:93], v[168:171], v[208:211], v[90:93]
	v_mfma_f32_16x16x32_bf16 v[78:81], v[160:163], v[218:221], v[78:81]
	v_mfma_f32_16x16x32_bf16 v[74:77], v[168:171], v[218:221], v[74:77]
	s_setprio 0
	s_setprio 1
	v_mfma_f32_16x16x32_bf16 v[118:121], v[172:175], v[188:191], v[118:121]
	v_mfma_f32_16x16x32_bf16 v[114:117], v[180:183], v[188:191], v[114:117]
	v_mfma_f32_16x16x32_bf16 v[102:105], v[172:175], v[196:199], v[102:105]
	v_mfma_f32_16x16x32_bf16 v[98:101], v[180:183], v[196:199], v[98:101]
	v_mfma_f32_16x16x32_bf16 v[86:89], v[172:175], v[204:207], v[86:89]
	v_mfma_f32_16x16x32_bf16 v[82:85], v[180:183], v[204:207], v[82:85]
	v_mfma_f32_16x16x32_bf16 v[70:73], v[172:175], v[212:215], v[70:73]
	v_mfma_f32_16x16x32_bf16 v[66:69], v[180:183], v[212:215], v[66:69]
	v_mfma_f32_16x16x32_bf16 v[118:121], v[176:179], v[192:195], v[118:121]
	v_mfma_f32_16x16x32_bf16 v[114:117], v[184:187], v[192:195], v[114:117]
	v_mfma_f32_16x16x32_bf16 v[102:105], v[176:179], v[200:203], v[102:105]
	v_mfma_f32_16x16x32_bf16 v[98:101], v[184:187], v[200:203], v[98:101]
	v_mfma_f32_16x16x32_bf16 v[86:89], v[176:179], v[208:211], v[86:89]
	v_mfma_f32_16x16x32_bf16 v[82:85], v[184:187], v[208:211], v[82:85]
	v_mfma_f32_16x16x32_bf16 v[70:73], v[176:179], v[218:221], v[70:73]
	v_mfma_f32_16x16x32_bf16 v[66:69], v[184:187], v[218:221], v[66:69]
	s_barrier
	s_setprio 0
	s_add_i32 s53, s53, s13
	v_lshl_add_u64 v[150:151], v[150:151], 0, s[8:9]
	s_mov_b32 m0, s53
	ds_read_b128 v[188:191], v155 offset:49152
	ds_read_b128 v[192:195], v155 offset:50176
	ds_read_b128 v[196:199], v155 offset:51200
	ds_read_b128 v[200:203], v155 offset:52224
	ds_read_b128 v[204:207], v155 offset:53248
	ds_read_b128 v[208:211], v155 offset:54272
	ds_read_b128 v[212:215], v155 offset:55296
	ds_read_b128 v[218:221], v155 offset:56320
	global_load_lds_dwordx4 v[150:151], off
	s_add_i32 m0, s53, 0x2000
	s_add_u32 s34, s34, 0x20080
	v_lshl_add_u64 v[150:151], v[222:223], 0, s[8:9]
	s_addc_u32 s35, s35, 0
	s_add_i32 s53, s66, s13
	global_load_lds_dwordx4 v[150:151], off
	v_lshl_add_u64 v[150:151], s[34:35], 0, v[132:133]
	s_mov_b32 m0, s53
	s_nop 0
	global_load_lds_dwordx4 v[150:151], off
	v_lshl_add_u64 v[150:151], s[34:35], 0, v[136:137]
	s_add_i32 m0, s53, 0x2000
	s_nop 0
	global_load_lds_dwordx4 v[150:151], off
	v_lshl_add_u64 v[150:151], v[224:225], 0, s[8:9]
	s_mov_b32 m0, s57
	s_nop 0
	global_load_lds_dwordx4 v[150:151], off
	v_lshl_add_u64 v[150:151], v[226:227], 0, s[8:9]
	s_mov_b32 m0, s58
	s_nop 0
	global_load_lds_dwordx4 v[150:151], off
	s_waitcnt vmcnt(8)
	s_waitcnt lgkmcnt(0)
	s_setprio 1
	s_barrier
	v_mfma_f32_16x16x32_bf16 v[62:65], v[146:149], v[188:191], v[62:65]
	v_mfma_f32_16x16x32_bf16 v[58:61], v[164:167], v[188:191], v[58:61]
	v_mfma_f32_16x16x32_bf16 v[50:53], v[146:149], v[196:199], v[50:53]
	v_mfma_f32_16x16x32_bf16 v[42:45], v[164:167], v[196:199], v[42:45]
	v_mfma_f32_16x16x32_bf16 v[34:37], v[146:149], v[204:207], v[34:37]
	v_mfma_f32_16x16x32_bf16 v[26:29], v[164:167], v[204:207], v[26:29]
	v_mfma_f32_16x16x32_bf16 v[18:21], v[146:149], v[212:215], v[18:21]
	v_mfma_f32_16x16x32_bf16 v[10:13], v[164:167], v[212:215], v[10:13]
	v_mfma_f32_16x16x32_bf16 v[62:65], v[160:163], v[192:195], v[62:65]
	v_mfma_f32_16x16x32_bf16 v[58:61], v[168:171], v[192:195], v[58:61]
	v_mfma_f32_16x16x32_bf16 v[50:53], v[160:163], v[200:203], v[50:53]
	v_mfma_f32_16x16x32_bf16 v[42:45], v[168:171], v[200:203], v[42:45]
	v_mfma_f32_16x16x32_bf16 v[34:37], v[160:163], v[208:211], v[34:37]
	v_mfma_f32_16x16x32_bf16 v[26:29], v[168:171], v[208:211], v[26:29]
	v_mfma_f32_16x16x32_bf16 v[18:21], v[160:163], v[218:221], v[18:21]
	v_mfma_f32_16x16x32_bf16 v[10:13], v[168:171], v[218:221], v[10:13]
	s_setprio 0
	s_setprio 1
	v_mfma_f32_16x16x32_bf16 v[54:57], v[172:175], v[188:191], v[54:57]
	v_mfma_f32_16x16x32_bf16 v[46:49], v[180:183], v[188:191], v[46:49]
	v_mfma_f32_16x16x32_bf16 v[38:41], v[172:175], v[196:199], v[38:41]
	v_mfma_f32_16x16x32_bf16 v[30:33], v[180:183], v[196:199], v[30:33]
	v_mfma_f32_16x16x32_bf16 v[22:25], v[172:175], v[204:207], v[22:25]
	v_mfma_f32_16x16x32_bf16 v[14:17], v[180:183], v[204:207], v[14:17]
	v_mfma_f32_16x16x32_bf16 v[6:9], v[172:175], v[212:215], v[6:9]
	v_mfma_f32_16x16x32_bf16 v[2:5], v[180:183], v[212:215], v[2:5]
	v_mfma_f32_16x16x32_bf16 v[54:57], v[176:179], v[192:195], v[54:57]
	v_mfma_f32_16x16x32_bf16 v[46:49], v[184:187], v[192:195], v[46:49]
	v_mfma_f32_16x16x32_bf16 v[38:41], v[176:179], v[200:203], v[38:41]
	v_mfma_f32_16x16x32_bf16 v[30:33], v[184:187], v[200:203], v[30:33]
	v_mfma_f32_16x16x32_bf16 v[22:25], v[176:179], v[208:211], v[22:25]
	v_mfma_f32_16x16x32_bf16 v[14:17], v[184:187], v[208:211], v[14:17]
	v_mfma_f32_16x16x32_bf16 v[6:9], v[176:179], v[218:221], v[6:9]
	v_mfma_f32_16x16x32_bf16 v[2:5], v[184:187], v[218:221], v[2:5]
	s_barrier
	s_setprio 0
	s_add_i32 s72, s72, 2
	s_add_u32 s74, s74, 0x100
	s_addc_u32 s75, s75, 0
	s_add_u32 s52, s52, 0x100
	s_addc_u32 s71, s71, 0
	s_cmp_gt_u32 s72, 5
	s_cbranch_scc0 .LBB0_2659
	s_and_b64 vcc, exec, s[24:25]
	s_cbranch_vccz .LBB0_2662
	s_barrier

.LBB0_2938:
	ds_read_b128 v[130:133], v174
	ds_read_b128 v[134:137], v174 offset:1024
	ds_read_b128 v[138:141], v174 offset:2048
	ds_read_b128 v[158:161], v174 offset:3072
	ds_read_b128 v[162:165], v175
	ds_read_b128 v[166:169], v175 offset:1024
	ds_read_b128 v[178:181], v175 offset:2048
	ds_read_b128 v[182:185], v175 offset:3072
	s_add_u32 s34, s46, 0xfff80080
	s_addc_u32 s35, s47, -1
	s_cmp_eq_u32 s72, 28
	s_cselect_b32 s69, s0, s35
	s_cselect_b32 s68, s1, s34
	s_cselect_b32 s35, s37, s71
	s_cselect_b32 s34, s39, s70
	v_lshl_add_u64 v[170:171], s[46:47], 0, v[150:151]
	s_add_i32 m0, s33, 0xc000
	ds_read_b128 v[186:189], v176
	ds_read_b128 v[190:193], v176 offset:1024
	ds_read_b128 v[194:197], v176 offset:2048
	ds_read_b128 v[198:201], v176 offset:3072
	ds_read_b128 v[202:205], v176 offset:4096
	ds_read_b128 v[206:209], v176 offset:5120
	ds_read_b128 v[210:213], v176 offset:6144
	ds_read_b128 v[218:221], v176 offset:7168
	global_load_lds_dwordx4 v[170:171], off
	v_lshl_add_u64 v[170:171], s[46:47], 0, v[152:153]
	s_add_i32 m0, s33, 0xe000
	s_nop 0
	global_load_lds_dwordx4 v[170:171], off
	s_waitcnt vmcnt(8)
	s_waitcnt lgkmcnt(0)
	s_setprio 1
	s_barrier
	v_mfma_f32_16x16x32_bf16 v[126:129], v[130:133], v[186:189], v[126:129]
	v_mfma_f32_16x16x32_bf16 v[122:125], v[138:141], v[186:189], v[122:125]
	v_mfma_f32_16x16x32_bf16 v[110:113], v[130:133], v[194:197], v[110:113]
	v_mfma_f32_16x16x32_bf16 v[106:109], v[138:141], v[194:197], v[106:109]
	v_mfma_f32_16x16x32_bf16 v[94:97], v[130:133], v[202:205], v[94:97]
	v_mfma_f32_16x16x32_bf16 v[90:93], v[138:141], v[202:205], v[90:93]
	v_mfma_f32_16x16x32_bf16 v[78:81], v[130:133], v[210:213], v[78:81]
	v_mfma_f32_16x16x32_bf16 v[74:77], v[138:141], v[210:213], v[74:77]
	v_mfma_f32_16x16x32_bf16 v[126:129], v[134:137], v[190:193], v[126:129]
	v_mfma_f32_16x16x32_bf16 v[122:125], v[158:161], v[190:193], v[122:125]
	v_mfma_f32_16x16x32_bf16 v[110:113], v[134:137], v[198:201], v[110:113]
	v_mfma_f32_16x16x32_bf16 v[106:109], v[158:161], v[198:201], v[106:109]
	v_mfma_f32_16x16x32_bf16 v[94:97], v[134:137], v[206:209], v[94:97]
	v_mfma_f32_16x16x32_bf16 v[90:93], v[158:161], v[206:209], v[90:93]
	v_mfma_f32_16x16x32_bf16 v[78:81], v[134:137], v[218:221], v[78:81]
	v_mfma_f32_16x16x32_bf16 v[74:77], v[158:161], v[218:221], v[74:77]
	s_setprio 0
	s_setprio 1
	v_mfma_f32_16x16x32_bf16 v[118:121], v[162:165], v[186:189], v[118:121]
	v_mfma_f32_16x16x32_bf16 v[114:117], v[178:181], v[186:189], v[114:117]
	v_mfma_f32_16x16x32_bf16 v[102:105], v[162:165], v[194:197], v[102:105]
	v_mfma_f32_16x16x32_bf16 v[98:101], v[178:181], v[194:197], v[98:101]
	v_mfma_f32_16x16x32_bf16 v[86:89], v[162:165], v[202:205], v[86:89]
	v_mfma_f32_16x16x32_bf16 v[82:85], v[178:181], v[202:205], v[82:85]
	v_mfma_f32_16x16x32_bf16 v[70:73], v[162:165], v[210:213], v[70:73]
	v_mfma_f32_16x16x32_bf16 v[66:69], v[178:181], v[210:213], v[66:69]
	v_mfma_f32_16x16x32_bf16 v[118:121], v[166:169], v[190:193], v[118:121]
	v_mfma_f32_16x16x32_bf16 v[114:117], v[182:185], v[190:193], v[114:117]
	v_mfma_f32_16x16x32_bf16 v[102:105], v[166:169], v[198:201], v[102:105]
	v_mfma_f32_16x16x32_bf16 v[98:101], v[182:185], v[198:201], v[98:101]
	v_mfma_f32_16x16x32_bf16 v[86:89], v[166:169], v[206:209], v[86:89]
	v_mfma_f32_16x16x32_bf16 v[82:85], v[182:185], v[206:209], v[82:85]
	v_mfma_f32_16x16x32_bf16 v[70:73], v[166:169], v[218:221], v[70:73]
	v_mfma_f32_16x16x32_bf16 v[66:69], v[182:185], v[218:221], v[66:69]
	s_barrier
	s_setprio 0
	s_add_i32 s62, s58, s31
	v_lshl_add_u64 v[170:171], s[34:35], 0, v[144:145]
	s_mov_b32 m0, s62
	ds_read_b128 v[186:189], v176 offset:16384
	ds_read_b128 v[190:193], v176 offset:17408
	ds_read_b128 v[194:197], v176 offset:18432
	ds_read_b128 v[198:201], v176 offset:19456
	ds_read_b128 v[202:205], v176 offset:20480
	ds_read_b128 v[206:209], v176 offset:21504
	ds_read_b128 v[210:213], v176 offset:22528
	ds_read_b128 v[218:221], v176 offset:23552
	global_load_lds_dwordx4 v[170:171], off
	s_add_i32 m0, s62, 0x2000
	s_add_u32 s62, s34, 0x80000
	v_lshl_add_u64 v[214:215], s[34:35], 0, v[148:149]
	s_addc_u32 s63, s35, 0
	s_add_i32 s66, s59, s31
	global_load_lds_dwordx4 v[214:215], off
	v_lshl_add_u64 v[222:223], s[62:63], 0, v[144:145]
	s_mov_b32 m0, s66
	v_lshl_add_u64 v[224:225], s[68:69], 0, v[146:147]
	global_load_lds_dwordx4 v[222:223], off
	v_lshl_add_u64 v[222:223], s[62:63], 0, v[148:149]
	s_add_i32 m0, s66, 0x2000
	s_nop 0
	global_load_lds_dwordx4 v[222:223], off
	v_lshl_add_u64 v[222:223], s[68:69], 0, v[142:143]
	s_mov_b32 m0, s33
	s_nop 0
	global_load_lds_dwordx4 v[222:223], off
	s_mov_b32 m0, s45
	s_nop 0
	global_load_lds_dwordx4 v[224:225], off
	s_waitcnt vmcnt(8)
	s_waitcnt lgkmcnt(0)
	s_setprio 1
	s_barrier
	v_mfma_f32_16x16x32_bf16 v[62:65], v[130:133], v[186:189], v[62:65]
	v_mfma_f32_16x16x32_bf16 v[58:61], v[138:141], v[186:189], v[58:61]
	v_mfma_f32_16x16x32_bf16 v[50:53], v[130:133], v[194:197], v[50:53]
	v_mfma_f32_16x16x32_bf16 v[42:45], v[138:141], v[194:197], v[42:45]
	v_mfma_f32_16x16x32_bf16 v[38:41], v[130:133], v[202:205], v[38:41]
	v_mfma_f32_16x16x32_bf16 v[34:37], v[138:141], v[202:205], v[34:37]
	v_mfma_f32_16x16x32_bf16 v[14:17], v[130:133], v[210:213], v[14:17]
	v_mfma_f32_16x16x32_bf16 v[10:13], v[138:141], v[210:213], v[10:13]
	v_mfma_f32_16x16x32_bf16 v[62:65], v[134:137], v[190:193], v[62:65]
	v_mfma_f32_16x16x32_bf16 v[58:61], v[158:161], v[190:193], v[58:61]
	v_mfma_f32_16x16x32_bf16 v[50:53], v[134:137], v[198:201], v[50:53]
	v_mfma_f32_16x16x32_bf16 v[42:45], v[158:161], v[198:201], v[42:45]
	v_mfma_f32_16x16x32_bf16 v[38:41], v[134:137], v[206:209], v[38:41]
	v_mfma_f32_16x16x32_bf16 v[34:37], v[158:161], v[206:209], v[34:37]
	v_mfma_f32_16x16x32_bf16 v[14:17], v[134:137], v[218:221], v[14:17]
	v_mfma_f32_16x16x32_bf16 v[10:13], v[158:161], v[218:221], v[10:13]
	s_setprio 0
	s_setprio 1
	v_mfma_f32_16x16x32_bf16 v[54:57], v[162:165], v[186:189], v[54:57]
	v_mfma_f32_16x16x32_bf16 v[46:49], v[178:181], v[186:189], v[46:49]
	v_mfma_f32_16x16x32_bf16 v[30:33], v[162:165], v[194:197], v[30:33]
	v_mfma_f32_16x16x32_bf16 v[26:29], v[178:181], v[194:197], v[26:29]
	v_mfma_f32_16x16x32_bf16 v[22:25], v[162:165], v[202:205], v[22:25]
	v_mfma_f32_16x16x32_bf16 v[18:21], v[178:181], v[202:205], v[18:21]
	v_mfma_f32_16x16x32_bf16 v[6:9], v[162:165], v[210:213], v[6:9]
	v_mfma_f32_16x16x32_bf16 v[2:5], v[178:181], v[210:213], v[2:5]
	v_mfma_f32_16x16x32_bf16 v[54:57], v[166:169], v[190:193], v[54:57]
	v_mfma_f32_16x16x32_bf16 v[46:49], v[182:185], v[190:193], v[46:49]
	v_mfma_f32_16x16x32_bf16 v[30:33], v[166:169], v[198:201], v[30:33]
	v_mfma_f32_16x16x32_bf16 v[26:29], v[182:185], v[198:201], v[26:29]
	v_mfma_f32_16x16x32_bf16 v[22:25], v[166:169], v[206:209], v[22:25]
	v_mfma_f32_16x16x32_bf16 v[18:21], v[182:185], v[206:209], v[18:21]
	v_mfma_f32_16x16x32_bf16 v[6:9], v[166:169], v[218:221], v[6:9]
	v_mfma_f32_16x16x32_bf16 v[2:5], v[182:185], v[218:221], v[2:5]
	s_barrier
	s_setprio 0
	s_add_i32 s66, 0, 0x18000
	s_add_i32 s67, 0, 0x1c000
	v_add_u32_e32 v158, s66, v172
	v_add_u32_e32 v177, s67, v172
	ds_read_b128 v[130:133], v158
	ds_read_b128 v[134:137], v158 offset:1024
	ds_read_b128 v[138:141], v158 offset:2048
	ds_read_b128 v[158:161], v158 offset:3072
	ds_read_b128 v[162:165], v177
	ds_read_b128 v[166:169], v177 offset:1024
	ds_read_b128 v[178:181], v177 offset:2048
	ds_read_b128 v[182:185], v177 offset:3072
	s_add_u32 s62, s68, 0x80000
	s_addc_u32 s63, s69, 0
	s_mov_b32 m0, s52
	v_lshl_add_u64 v[226:227], s[62:63], 0, v[142:143]
	ds_read_b128 v[186:189], v176 offset:32768
	ds_read_b128 v[190:193], v176 offset:33792
	ds_read_b128 v[194:197], v176 offset:34816
	ds_read_b128 v[198:201], v176 offset:35840
	ds_read_b128 v[202:205], v176 offset:36864
	ds_read_b128 v[206:209], v176 offset:37888
	ds_read_b128 v[210:213], v176 offset:38912
	ds_read_b128 v[218:221], v176 offset:39936
	global_load_lds_dwordx4 v[226:227], off
	v_lshl_add_u64 v[226:227], s[62:63], 0, v[146:147]
	s_mov_b32 m0, s53
	s_nop 0
	global_load_lds_dwordx4 v[226:227], off
	s_waitcnt vmcnt(8)
	s_waitcnt lgkmcnt(0)
	s_setprio 1
	s_barrier
	v_mfma_f32_16x16x32_bf16 v[126:129], v[130:133], v[186:189], v[126:129]
	v_mfma_f32_16x16x32_bf16 v[122:125], v[138:141], v[186:189], v[122:125]
	v_mfma_f32_16x16x32_bf16 v[110:113], v[130:133], v[194:197], v[110:113]
	v_mfma_f32_16x16x32_bf16 v[106:109], v[138:141], v[194:197], v[106:109]
	v_mfma_f32_16x16x32_bf16 v[94:97], v[130:133], v[202:205], v[94:97]
	v_mfma_f32_16x16x32_bf16 v[90:93], v[138:141], v[202:205], v[90:93]
	v_mfma_f32_16x16x32_bf16 v[78:81], v[130:133], v[210:213], v[78:81]
	v_mfma_f32_16x16x32_bf16 v[74:77], v[138:141], v[210:213], v[74:77]
	v_mfma_f32_16x16x32_bf16 v[126:129], v[134:137], v[190:193], v[126:129]
	v_mfma_f32_16x16x32_bf16 v[122:125], v[158:161], v[190:193], v[122:125]
	v_mfma_f32_16x16x32_bf16 v[110:113], v[134:137], v[198:201], v[110:113]
	v_mfma_f32_16x16x32_bf16 v[106:109], v[158:161], v[198:201], v[106:109]
	v_mfma_f32_16x16x32_bf16 v[94:97], v[134:137], v[206:209], v[94:97]
	v_mfma_f32_16x16x32_bf16 v[90:93], v[158:161], v[206:209], v[90:93]
	v_mfma_f32_16x16x32_bf16 v[78:81], v[134:137], v[218:221], v[78:81]
	v_mfma_f32_16x16x32_bf16 v[74:77], v[158:161], v[218:221], v[74:77]
	s_setprio 0
	s_setprio 1
	v_mfma_f32_16x16x32_bf16 v[118:121], v[162:165], v[186:189], v[118:121]
	v_mfma_f32_16x16x32_bf16 v[114:117], v[178:181], v[186:189], v[114:117]
	v_mfma_f32_16x16x32_bf16 v[102:105], v[162:165], v[194:197], v[102:105]
	v_mfma_f32_16x16x32_bf16 v[98:101], v[178:181], v[194:197], v[98:101]
	v_mfma_f32_16x16x32_bf16 v[86:89], v[162:165], v[202:205], v[86:89]
	v_mfma_f32_16x16x32_bf16 v[82:85], v[178:181], v[202:205], v[82:85]
	v_mfma_f32_16x16x32_bf16 v[70:73], v[162:165], v[210:213], v[70:73]
	v_mfma_f32_16x16x32_bf16 v[66:69], v[178:181], v[210:213], v[66:69]
	v_mfma_f32_16x16x32_bf16 v[118:121], v[166:169], v[190:193], v[118:121]
	v_mfma_f32_16x16x32_bf16 v[114:117], v[182:185], v[190:193], v[114:117]
	v_mfma_f32_16x16x32_bf16 v[102:105], v[166:169], v[198:201], v[102:105]
	v_mfma_f32_16x16x32_bf16 v[98:101], v[182:185], v[198:201], v[98:101]
	v_mfma_f32_16x16x32_bf16 v[86:89], v[166:169], v[206:209], v[86:89]
	v_mfma_f32_16x16x32_bf16 v[82:85], v[182:185], v[206:209], v[82:85]
	v_mfma_f32_16x16x32_bf16 v[70:73], v[166:169], v[218:221], v[70:73]
	v_mfma_f32_16x16x32_bf16 v[66:69], v[182:185], v[218:221], v[66:69]
	s_barrier
	s_setprio 0
	s_add_i32 s62, s66, s31
	v_lshl_add_u64 v[170:171], v[170:171], 0, s[24:25]
	s_mov_b32 m0, s62
	ds_read_b128 v[186:189], v176 offset:49152
	ds_read_b128 v[190:193], v176 offset:50176
	ds_read_b128 v[194:197], v176 offset:51200
	ds_read_b128 v[198:201], v176 offset:52224
	ds_read_b128 v[202:205], v176 offset:53248
	ds_read_b128 v[206:209], v176 offset:54272
	ds_read_b128 v[210:213], v176 offset:55296
	ds_read_b128 v[218:221], v176 offset:56320
	global_load_lds_dwordx4 v[170:171], off
	s_add_i32 m0, s62, 0x2000
	s_add_u32 s34, s34, 0x80080
	v_lshl_add_u64 v[170:171], v[214:215], 0, s[24:25]
	s_addc_u32 s35, s35, 0
	s_add_i32 s62, s67, s31
	global_load_lds_dwordx4 v[170:171], off
	v_lshl_add_u64 v[170:171], s[34:35], 0, v[144:145]
	s_mov_b32 m0, s62
	s_nop 0
	global_load_lds_dwordx4 v[170:171], off
	v_lshl_add_u64 v[170:171], s[34:35], 0, v[148:149]
	s_add_i32 m0, s62, 0x2000
	s_nop 0
	global_load_lds_dwordx4 v[170:171], off
	v_lshl_add_u64 v[170:171], v[222:223], 0, s[24:25]
	s_mov_b32 m0, s55
	s_nop 0
	global_load_lds_dwordx4 v[170:171], off
	v_lshl_add_u64 v[170:171], v[224:225], 0, s[24:25]
	s_mov_b32 m0, s56
	s_nop 0
	global_load_lds_dwordx4 v[170:171], off
	s_waitcnt vmcnt(8)
	s_waitcnt lgkmcnt(0)
	s_setprio 1
	s_barrier
	v_mfma_f32_16x16x32_bf16 v[62:65], v[130:133], v[186:189], v[62:65]
	v_mfma_f32_16x16x32_bf16 v[58:61], v[138:141], v[186:189], v[58:61]
	v_mfma_f32_16x16x32_bf16 v[50:53], v[130:133], v[194:197], v[50:53]
	v_mfma_f32_16x16x32_bf16 v[42:45], v[138:141], v[194:197], v[42:45]
	v_mfma_f32_16x16x32_bf16 v[38:41], v[130:133], v[202:205], v[38:41]
	v_mfma_f32_16x16x32_bf16 v[34:37], v[138:141], v[202:205], v[34:37]
	v_mfma_f32_16x16x32_bf16 v[14:17], v[130:133], v[210:213], v[14:17]
	v_mfma_f32_16x16x32_bf16 v[10:13], v[138:141], v[210:213], v[10:13]
	v_mfma_f32_16x16x32_bf16 v[62:65], v[134:137], v[190:193], v[62:65]
	v_mfma_f32_16x16x32_bf16 v[58:61], v[158:161], v[190:193], v[58:61]
	v_mfma_f32_16x16x32_bf16 v[50:53], v[134:137], v[198:201], v[50:53]
	v_mfma_f32_16x16x32_bf16 v[42:45], v[158:161], v[198:201], v[42:45]
	v_mfma_f32_16x16x32_bf16 v[38:41], v[134:137], v[206:209], v[38:41]
	v_mfma_f32_16x16x32_bf16 v[34:37], v[158:161], v[206:209], v[34:37]
	v_mfma_f32_16x16x32_bf16 v[14:17], v[134:137], v[218:221], v[14:17]
	v_mfma_f32_16x16x32_bf16 v[10:13], v[158:161], v[218:221], v[10:13]
	s_setprio 0
	s_setprio 1
	v_mfma_f32_16x16x32_bf16 v[54:57], v[162:165], v[186:189], v[54:57]
	v_mfma_f32_16x16x32_bf16 v[46:49], v[178:181], v[186:189], v[46:49]
	v_mfma_f32_16x16x32_bf16 v[30:33], v[162:165], v[194:197], v[30:33]
	v_mfma_f32_16x16x32_bf16 v[26:29], v[178:181], v[194:197], v[26:29]
	v_mfma_f32_16x16x32_bf16 v[22:25], v[162:165], v[202:205], v[22:25]
	v_mfma_f32_16x16x32_bf16 v[18:21], v[178:181], v[202:205], v[18:21]
	v_mfma_f32_16x16x32_bf16 v[6:9], v[162:165], v[210:213], v[6:9]
	v_mfma_f32_16x16x32_bf16 v[2:5], v[178:181], v[210:213], v[2:5]
	v_mfma_f32_16x16x32_bf16 v[54:57], v[166:169], v[190:193], v[54:57]
	v_mfma_f32_16x16x32_bf16 v[46:49], v[182:185], v[190:193], v[46:49]
	v_mfma_f32_16x16x32_bf16 v[30:33], v[166:169], v[198:201], v[30:33]
	v_mfma_f32_16x16x32_bf16 v[26:29], v[182:185], v[198:201], v[26:29]
	v_mfma_f32_16x16x32_bf16 v[22:25], v[166:169], v[206:209], v[22:25]
	v_mfma_f32_16x16x32_bf16 v[18:21], v[182:185], v[206:209], v[18:21]
	v_mfma_f32_16x16x32_bf16 v[6:9], v[166:169], v[218:221], v[6:9]
	v_mfma_f32_16x16x32_bf16 v[2:5], v[182:185], v[218:221], v[2:5]
	s_barrier
	s_setprio 0
	s_add_i32 s72, s72, 2
	s_add_u32 s46, s46, 0x100
	s_addc_u32 s47, s47, 0
	s_add_u32 s70, s70, 0x100
	s_addc_u32 s71, s71, 0
	s_cmp_gt_u32 s72, 29
	s_cbranch_scc0 .LBB0_2938
	s_and_b64 vcc, exec, s[26:27]
	s_cbranch_vccz .LBB0_2941
	s_barrier

.LBB0_3067:
	ds_read_b128 v[146:149], v153
	ds_read_b128 v[156:159], v153 offset:1024
	ds_read_b128 v[160:163], v153 offset:2048
	ds_read_b128 v[164:167], v153 offset:3072
	ds_read_b128 v[168:171], v154
	ds_read_b128 v[172:175], v154 offset:1024
	ds_read_b128 v[176:179], v154 offset:2048
	ds_read_b128 v[180:183], v154 offset:3072
	s_add_u32 s34, s44, 0xfff80080
	s_addc_u32 s35, s45, -1
	s_cmp_eq_u32 s71, 28
	s_cselect_b32 s47, s0, s35
	s_cselect_b32 s46, s1, s34
	s_cselect_b32 s35, s27, s70
	s_cselect_b32 s34, s37, s69
	v_lshl_add_u64 v[218:219], s[44:45], 0, v[138:139]
	s_add_i32 m0, s43, 0xc000
	ds_read_b128 v[184:187], v155
	ds_read_b128 v[188:191], v155 offset:1024
	ds_read_b128 v[192:195], v155 offset:2048
	ds_read_b128 v[196:199], v155 offset:3072
	ds_read_b128 v[200:203], v155 offset:4096
	ds_read_b128 v[204:207], v155 offset:5120
	ds_read_b128 v[208:211], v155 offset:6144
	ds_read_b128 v[212:215], v155 offset:7168
	global_load_lds_dwordx4 v[218:219], off
	v_lshl_add_u64 v[218:219], s[44:45], 0, v[140:141]
	s_add_i32 m0, s43, 0xe000
	s_nop 0
	global_load_lds_dwordx4 v[218:219], off
	s_waitcnt vmcnt(8)
	s_waitcnt lgkmcnt(0)
	s_setprio 1
	s_barrier
	v_mfma_f32_16x16x32_bf16 v[126:129], v[146:149], v[184:187], v[126:129]
	v_mfma_f32_16x16x32_bf16 v[118:121], v[160:163], v[184:187], v[118:121]
	v_mfma_f32_16x16x32_bf16 v[110:113], v[146:149], v[192:195], v[110:113]
	v_mfma_f32_16x16x32_bf16 v[102:105], v[160:163], v[192:195], v[102:105]
	v_mfma_f32_16x16x32_bf16 v[94:97], v[146:149], v[200:203], v[94:97]
	v_mfma_f32_16x16x32_bf16 v[86:89], v[160:163], v[200:203], v[86:89]
	v_mfma_f32_16x16x32_bf16 v[78:81], v[146:149], v[208:211], v[78:81]
	v_mfma_f32_16x16x32_bf16 v[70:73], v[160:163], v[208:211], v[70:73]
	v_mfma_f32_16x16x32_bf16 v[126:129], v[156:159], v[188:191], v[126:129]
	v_mfma_f32_16x16x32_bf16 v[118:121], v[164:167], v[188:191], v[118:121]
	v_mfma_f32_16x16x32_bf16 v[110:113], v[156:159], v[196:199], v[110:113]
	v_mfma_f32_16x16x32_bf16 v[102:105], v[164:167], v[196:199], v[102:105]
	v_mfma_f32_16x16x32_bf16 v[94:97], v[156:159], v[204:207], v[94:97]
	v_mfma_f32_16x16x32_bf16 v[86:89], v[164:167], v[204:207], v[86:89]
	v_mfma_f32_16x16x32_bf16 v[78:81], v[156:159], v[212:215], v[78:81]
	v_mfma_f32_16x16x32_bf16 v[70:73], v[164:167], v[212:215], v[70:73]
	s_setprio 0
	s_setprio 1
	v_mfma_f32_16x16x32_bf16 v[122:125], v[168:171], v[184:187], v[122:125]
	v_mfma_f32_16x16x32_bf16 v[114:117], v[176:179], v[184:187], v[114:117]
	v_mfma_f32_16x16x32_bf16 v[106:109], v[168:171], v[192:195], v[106:109]
	v_mfma_f32_16x16x32_bf16 v[98:101], v[176:179], v[192:195], v[98:101]
	v_mfma_f32_16x16x32_bf16 v[90:93], v[168:171], v[200:203], v[90:93]
	v_mfma_f32_16x16x32_bf16 v[82:85], v[176:179], v[200:203], v[82:85]
	v_mfma_f32_16x16x32_bf16 v[74:77], v[168:171], v[208:211], v[74:77]
	v_mfma_f32_16x16x32_bf16 v[66:69], v[176:179], v[208:211], v[66:69]
	v_mfma_f32_16x16x32_bf16 v[122:125], v[172:175], v[188:191], v[122:125]
	v_mfma_f32_16x16x32_bf16 v[114:117], v[180:183], v[188:191], v[114:117]
	v_mfma_f32_16x16x32_bf16 v[106:109], v[172:175], v[196:199], v[106:109]
	v_mfma_f32_16x16x32_bf16 v[98:101], v[180:183], v[196:199], v[98:101]
	v_mfma_f32_16x16x32_bf16 v[90:93], v[172:175], v[204:207], v[90:93]
	v_mfma_f32_16x16x32_bf16 v[82:85], v[180:183], v[204:207], v[82:85]
	v_mfma_f32_16x16x32_bf16 v[74:77], v[172:175], v[212:215], v[74:77]
	v_mfma_f32_16x16x32_bf16 v[66:69], v[180:183], v[212:215], v[66:69]
	s_barrier
	s_setprio 0
	s_add_i32 s62, s59, s30
	v_lshl_add_u64 v[218:219], s[34:35], 0, v[134:135]
	s_mov_b32 m0, s62
	ds_read_b128 v[184:187], v155 offset:16384
	ds_read_b128 v[188:191], v155 offset:17408
	ds_read_b128 v[192:195], v155 offset:18432
	ds_read_b128 v[196:199], v155 offset:19456
	ds_read_b128 v[200:203], v155 offset:20480
	ds_read_b128 v[204:207], v155 offset:21504
	ds_read_b128 v[208:211], v155 offset:22528
	ds_read_b128 v[212:215], v155 offset:23552
	global_load_lds_dwordx4 v[218:219], off
	s_add_i32 m0, s62, 0x2000
	s_add_u32 s62, s34, 0x80000
	v_lshl_add_u64 v[220:221], s[34:35], 0, v[130:131]
	s_addc_u32 s63, s35, 0
	s_add_i32 s66, s60, s30
	global_load_lds_dwordx4 v[220:221], off
	v_lshl_add_u64 v[222:223], s[62:63], 0, v[134:135]
	s_mov_b32 m0, s66
	v_lshl_add_u64 v[224:225], s[46:47], 0, v[132:133]
	global_load_lds_dwordx4 v[222:223], off
	v_lshl_add_u64 v[222:223], s[62:63], 0, v[130:131]
	s_add_i32 m0, s66, 0x2000
	s_nop 0
	global_load_lds_dwordx4 v[222:223], off
	v_lshl_add_u64 v[222:223], s[46:47], 0, v[136:137]
	s_mov_b32 m0, s43
	s_nop 0
	global_load_lds_dwordx4 v[222:223], off
	s_mov_b32 m0, s52
	s_nop 0
	global_load_lds_dwordx4 v[224:225], off
	s_waitcnt vmcnt(8)
	s_waitcnt lgkmcnt(0)
	s_setprio 1
	s_barrier
	v_mfma_f32_16x16x32_bf16 v[62:65], v[146:149], v[184:187], v[62:65]
	v_mfma_f32_16x16x32_bf16 v[54:57], v[160:163], v[184:187], v[54:57]
	v_mfma_f32_16x16x32_bf16 v[46:49], v[146:149], v[192:195], v[46:49]
	v_mfma_f32_16x16x32_bf16 v[38:41], v[160:163], v[192:195], v[38:41]
	v_mfma_f32_16x16x32_bf16 v[30:33], v[146:149], v[200:203], v[30:33]
	v_mfma_f32_16x16x32_bf16 v[22:25], v[160:163], v[200:203], v[22:25]
	v_mfma_f32_16x16x32_bf16 v[14:17], v[146:149], v[208:211], v[14:17]
	v_mfma_f32_16x16x32_bf16 v[6:9], v[160:163], v[208:211], v[6:9]
	v_mfma_f32_16x16x32_bf16 v[62:65], v[156:159], v[188:191], v[62:65]
	v_mfma_f32_16x16x32_bf16 v[54:57], v[164:167], v[188:191], v[54:57]
	v_mfma_f32_16x16x32_bf16 v[46:49], v[156:159], v[196:199], v[46:49]
	v_mfma_f32_16x16x32_bf16 v[38:41], v[164:167], v[196:199], v[38:41]
	v_mfma_f32_16x16x32_bf16 v[30:33], v[156:159], v[204:207], v[30:33]
	v_mfma_f32_16x16x32_bf16 v[22:25], v[164:167], v[204:207], v[22:25]
	v_mfma_f32_16x16x32_bf16 v[14:17], v[156:159], v[212:215], v[14:17]
	v_mfma_f32_16x16x32_bf16 v[6:9], v[164:167], v[212:215], v[6:9]
	s_setprio 0
	s_setprio 1
	v_mfma_f32_16x16x32_bf16 v[58:61], v[168:171], v[184:187], v[58:61]
	v_mfma_f32_16x16x32_bf16 v[50:53], v[176:179], v[184:187], v[50:53]
	v_mfma_f32_16x16x32_bf16 v[42:45], v[168:171], v[192:195], v[42:45]
	v_mfma_f32_16x16x32_bf16 v[34:37], v[176:179], v[192:195], v[34:37]
	v_mfma_f32_16x16x32_bf16 v[26:29], v[168:171], v[200:203], v[26:29]
	v_mfma_f32_16x16x32_bf16 v[18:21], v[176:179], v[200:203], v[18:21]
	v_mfma_f32_16x16x32_bf16 v[10:13], v[168:171], v[208:211], v[10:13]
	v_mfma_f32_16x16x32_bf16 v[2:5], v[176:179], v[208:211], v[2:5]
	v_mfma_f32_16x16x32_bf16 v[58:61], v[172:175], v[188:191], v[58:61]
	v_mfma_f32_16x16x32_bf16 v[50:53], v[180:183], v[188:191], v[50:53]
	v_mfma_f32_16x16x32_bf16 v[42:45], v[172:175], v[196:199], v[42:45]
	v_mfma_f32_16x16x32_bf16 v[34:37], v[180:183], v[196:199], v[34:37]
	v_mfma_f32_16x16x32_bf16 v[26:29], v[172:175], v[204:207], v[26:29]
	v_mfma_f32_16x16x32_bf16 v[18:21], v[180:183], v[204:207], v[18:21]
	v_mfma_f32_16x16x32_bf16 v[10:13], v[172:175], v[212:215], v[10:13]
	v_mfma_f32_16x16x32_bf16 v[2:5], v[180:183], v[212:215], v[2:5]
	s_barrier
	s_setprio 0
	s_add_i32 s62, 0, 0x18000
	s_add_i32 s63, 0, 0x1c000
	v_add_u32_e32 v164, s62, v151
	v_add_u32_e32 v180, s63, v151
	ds_read_b128 v[146:149], v164
	ds_read_b128 v[156:159], v164 offset:1024
	ds_read_b128 v[160:163], v164 offset:2048
	ds_read_b128 v[164:167], v164 offset:3072
	ds_read_b128 v[168:171], v180
	ds_read_b128 v[172:175], v180 offset:1024
	ds_read_b128 v[176:179], v180 offset:2048
	ds_read_b128 v[180:183], v180 offset:3072
	s_add_u32 s46, s46, 0x80000
	s_addc_u32 s47, s47, 0
	s_mov_b32 m0, s53
	v_lshl_add_u64 v[226:227], s[46:47], 0, v[136:137]
	ds_read_b128 v[184:187], v155 offset:32768
	ds_read_b128 v[188:191], v155 offset:33792
	ds_read_b128 v[192:195], v155 offset:34816
	ds_read_b128 v[196:199], v155 offset:35840
	ds_read_b128 v[200:203], v155 offset:36864
	ds_read_b128 v[204:207], v155 offset:37888
	ds_read_b128 v[208:211], v155 offset:38912
	ds_read_b128 v[212:215], v155 offset:39936
	global_load_lds_dwordx4 v[226:227], off
	v_lshl_add_u64 v[226:227], s[46:47], 0, v[132:133]
	s_mov_b32 m0, s54
	s_nop 0
	global_load_lds_dwordx4 v[226:227], off
	s_waitcnt vmcnt(8)
	s_waitcnt lgkmcnt(0)
	s_setprio 1
	s_barrier
	v_mfma_f32_16x16x32_bf16 v[126:129], v[146:149], v[184:187], v[126:129]
	v_mfma_f32_16x16x32_bf16 v[118:121], v[160:163], v[184:187], v[118:121]
	v_mfma_f32_16x16x32_bf16 v[110:113], v[146:149], v[192:195], v[110:113]
	v_mfma_f32_16x16x32_bf16 v[102:105], v[160:163], v[192:195], v[102:105]
	v_mfma_f32_16x16x32_bf16 v[94:97], v[146:149], v[200:203], v[94:97]
	v_mfma_f32_16x16x32_bf16 v[86:89], v[160:163], v[200:203], v[86:89]
	v_mfma_f32_16x16x32_bf16 v[78:81], v[146:149], v[208:211], v[78:81]
	v_mfma_f32_16x16x32_bf16 v[70:73], v[160:163], v[208:211], v[70:73]
	v_mfma_f32_16x16x32_bf16 v[126:129], v[156:159], v[188:191], v[126:129]
	v_mfma_f32_16x16x32_bf16 v[118:121], v[164:167], v[188:191], v[118:121]
	v_mfma_f32_16x16x32_bf16 v[110:113], v[156:159], v[196:199], v[110:113]
	v_mfma_f32_16x16x32_bf16 v[102:105], v[164:167], v[196:199], v[102:105]
	v_mfma_f32_16x16x32_bf16 v[94:97], v[156:159], v[204:207], v[94:97]
	v_mfma_f32_16x16x32_bf16 v[86:89], v[164:167], v[204:207], v[86:89]
	v_mfma_f32_16x16x32_bf16 v[78:81], v[156:159], v[212:215], v[78:81]
	v_mfma_f32_16x16x32_bf16 v[70:73], v[164:167], v[212:215], v[70:73]
	s_setprio 0
	s_setprio 1
	v_mfma_f32_16x16x32_bf16 v[122:125], v[168:171], v[184:187], v[122:125]
	v_mfma_f32_16x16x32_bf16 v[114:117], v[176:179], v[184:187], v[114:117]
	v_mfma_f32_16x16x32_bf16 v[106:109], v[168:171], v[192:195], v[106:109]
	v_mfma_f32_16x16x32_bf16 v[98:101], v[176:179], v[192:195], v[98:101]
	v_mfma_f32_16x16x32_bf16 v[90:93], v[168:171], v[200:203], v[90:93]
	v_mfma_f32_16x16x32_bf16 v[82:85], v[176:179], v[200:203], v[82:85]
	v_mfma_f32_16x16x32_bf16 v[74:77], v[168:171], v[208:211], v[74:77]
	v_mfma_f32_16x16x32_bf16 v[66:69], v[176:179], v[208:211], v[66:69]
	v_mfma_f32_16x16x32_bf16 v[122:125], v[172:175], v[188:191], v[122:125]
	v_mfma_f32_16x16x32_bf16 v[114:117], v[180:183], v[188:191], v[114:117]
	v_mfma_f32_16x16x32_bf16 v[106:109], v[172:175], v[196:199], v[106:109]
	v_mfma_f32_16x16x32_bf16 v[98:101], v[180:183], v[196:199], v[98:101]
	v_mfma_f32_16x16x32_bf16 v[90:93], v[172:175], v[204:207], v[90:93]
	v_mfma_f32_16x16x32_bf16 v[82:85], v[180:183], v[204:207], v[82:85]
	v_mfma_f32_16x16x32_bf16 v[74:77], v[172:175], v[212:215], v[74:77]
	v_mfma_f32_16x16x32_bf16 v[66:69], v[180:183], v[212:215], v[66:69]
	s_barrier
	s_setprio 0
	s_add_i32 s46, s62, s30
	v_lshl_add_u64 v[218:219], v[218:219], 0, s[8:9]
	s_mov_b32 m0, s46
	ds_read_b128 v[184:187], v155 offset:49152
	ds_read_b128 v[188:191], v155 offset:50176
	ds_read_b128 v[192:195], v155 offset:51200
	ds_read_b128 v[196:199], v155 offset:52224
	ds_read_b128 v[200:203], v155 offset:53248
	ds_read_b128 v[204:207], v155 offset:54272
	ds_read_b128 v[208:211], v155 offset:55296
	ds_read_b128 v[212:215], v155 offset:56320
	global_load_lds_dwordx4 v[218:219], off
	s_add_i32 m0, s46, 0x2000
	s_add_u32 s34, s34, 0x80080
	v_lshl_add_u64 v[218:219], v[220:221], 0, s[8:9]
	s_addc_u32 s35, s35, 0
	s_add_i32 s46, s63, s30
	global_load_lds_dwordx4 v[218:219], off
	v_lshl_add_u64 v[218:219], s[34:35], 0, v[134:135]
	s_mov_b32 m0, s46
	s_nop 0
	global_load_lds_dwordx4 v[218:219], off
	v_lshl_add_u64 v[218:219], s[34:35], 0, v[130:131]
	s_add_i32 m0, s46, 0x2000
	s_nop 0
	global_load_lds_dwordx4 v[218:219], off
	v_lshl_add_u64 v[218:219], v[222:223], 0, s[8:9]
	s_mov_b32 m0, s56
	s_nop 0
	global_load_lds_dwordx4 v[218:219], off
	v_lshl_add_u64 v[218:219], v[224:225], 0, s[8:9]
	s_mov_b32 m0, s57
	s_nop 0
	global_load_lds_dwordx4 v[218:219], off
	s_waitcnt vmcnt(8)
	s_waitcnt lgkmcnt(0)
	s_setprio 1
	s_barrier
	v_mfma_f32_16x16x32_bf16 v[62:65], v[146:149], v[184:187], v[62:65]
	v_mfma_f32_16x16x32_bf16 v[54:57], v[160:163], v[184:187], v[54:57]
	v_mfma_f32_16x16x32_bf16 v[46:49], v[146:149], v[192:195], v[46:49]
	v_mfma_f32_16x16x32_bf16 v[38:41], v[160:163], v[192:195], v[38:41]
	v_mfma_f32_16x16x32_bf16 v[30:33], v[146:149], v[200:203], v[30:33]
	v_mfma_f32_16x16x32_bf16 v[22:25], v[160:163], v[200:203], v[22:25]
	v_mfma_f32_16x16x32_bf16 v[14:17], v[146:149], v[208:211], v[14:17]
	v_mfma_f32_16x16x32_bf16 v[6:9], v[160:163], v[208:211], v[6:9]
	v_mfma_f32_16x16x32_bf16 v[62:65], v[156:159], v[188:191], v[62:65]
	v_mfma_f32_16x16x32_bf16 v[54:57], v[164:167], v[188:191], v[54:57]
	v_mfma_f32_16x16x32_bf16 v[46:49], v[156:159], v[196:199], v[46:49]
	v_mfma_f32_16x16x32_bf16 v[38:41], v[164:167], v[196:199], v[38:41]
	v_mfma_f32_16x16x32_bf16 v[30:33], v[156:159], v[204:207], v[30:33]
	v_mfma_f32_16x16x32_bf16 v[22:25], v[164:167], v[204:207], v[22:25]
	v_mfma_f32_16x16x32_bf16 v[14:17], v[156:159], v[212:215], v[14:17]
	v_mfma_f32_16x16x32_bf16 v[6:9], v[164:167], v[212:215], v[6:9]
	s_setprio 0
	s_setprio 1
	v_mfma_f32_16x16x32_bf16 v[58:61], v[168:171], v[184:187], v[58:61]
	v_mfma_f32_16x16x32_bf16 v[50:53], v[176:179], v[184:187], v[50:53]
	v_mfma_f32_16x16x32_bf16 v[42:45], v[168:171], v[192:195], v[42:45]
	v_mfma_f32_16x16x32_bf16 v[34:37], v[176:179], v[192:195], v[34:37]
	v_mfma_f32_16x16x32_bf16 v[26:29], v[168:171], v[200:203], v[26:29]
	v_mfma_f32_16x16x32_bf16 v[18:21], v[176:179], v[200:203], v[18:21]
	v_mfma_f32_16x16x32_bf16 v[10:13], v[168:171], v[208:211], v[10:13]
	v_mfma_f32_16x16x32_bf16 v[2:5], v[176:179], v[208:211], v[2:5]
	v_mfma_f32_16x16x32_bf16 v[58:61], v[172:175], v[188:191], v[58:61]
	v_mfma_f32_16x16x32_bf16 v[50:53], v[180:183], v[188:191], v[50:53]
	v_mfma_f32_16x16x32_bf16 v[42:45], v[172:175], v[196:199], v[42:45]
	v_mfma_f32_16x16x32_bf16 v[34:37], v[180:183], v[196:199], v[34:37]
	v_mfma_f32_16x16x32_bf16 v[26:29], v[172:175], v[204:207], v[26:29]
	v_mfma_f32_16x16x32_bf16 v[18:21], v[180:183], v[204:207], v[18:21]
	v_mfma_f32_16x16x32_bf16 v[10:13], v[172:175], v[212:215], v[10:13]
	v_mfma_f32_16x16x32_bf16 v[2:5], v[180:183], v[212:215], v[2:5]
	s_barrier
	s_setprio 0
	s_add_i32 s71, s71, 2
	s_add_u32 s44, s44, 0x100
	s_addc_u32 s45, s45, 0
	s_add_u32 s69, s69, 0x100
	s_addc_u32 s70, s70, 0
	s_cmp_gt_u32 s71, 29
	s_cbranch_scc0 .LBB0_3067
	s_and_b64 vcc, exec, s[24:25]
	s_cbranch_vccz .LBB0_3070
	s_barrier

.LBB0_3180:
	ds_read_b128 v[130:133], v174
	ds_read_b128 v[134:137], v174 offset:1024
	ds_read_b128 v[138:141], v174 offset:2048
	ds_read_b128 v[158:161], v174 offset:3072
	ds_read_b128 v[162:165], v175
	ds_read_b128 v[166:169], v175 offset:1024
	ds_read_b128 v[178:181], v175 offset:2048
	ds_read_b128 v[182:185], v175 offset:3072
	s_add_u32 s34, s40, 0xffea0080
	s_addc_u32 s35, s41, -1
	s_cmpk_eq_i32 s60, 0x54
	s_cselect_b32 s43, s5, s35
	s_cselect_b32 s42, s4, s34
	s_cselect_b32 s35, s39, s1
	s_cselect_b32 s34, s38, s0
	v_lshl_add_u64 v[170:171], s[40:41], 0, v[150:151]
	s_add_i32 m0, s33, 0xc000
	ds_read_b128 v[186:189], v176
	ds_read_b128 v[190:193], v176 offset:1024
	ds_read_b128 v[194:197], v176 offset:2048
	ds_read_b128 v[198:201], v176 offset:3072
	ds_read_b128 v[202:205], v176 offset:4096
	ds_read_b128 v[206:209], v176 offset:5120
	ds_read_b128 v[210:213], v176 offset:6144
	ds_read_b128 v[218:221], v176 offset:7168
	global_load_lds_dwordx4 v[170:171], off
	v_lshl_add_u64 v[170:171], s[40:41], 0, v[152:153]
	s_add_i32 m0, s33, 0xe000
	s_nop 0
	global_load_lds_dwordx4 v[170:171], off
	s_waitcnt vmcnt(8)
	s_waitcnt lgkmcnt(0)
	s_setprio 1
	s_barrier
	v_mfma_f32_16x16x32_bf16 v[126:129], v[130:133], v[186:189], v[126:129]
	v_mfma_f32_16x16x32_bf16 v[122:125], v[138:141], v[186:189], v[122:125]
	v_mfma_f32_16x16x32_bf16 v[110:113], v[130:133], v[194:197], v[110:113]
	v_mfma_f32_16x16x32_bf16 v[106:109], v[138:141], v[194:197], v[106:109]
	v_mfma_f32_16x16x32_bf16 v[94:97], v[130:133], v[202:205], v[94:97]
	v_mfma_f32_16x16x32_bf16 v[90:93], v[138:141], v[202:205], v[90:93]
	v_mfma_f32_16x16x32_bf16 v[78:81], v[130:133], v[210:213], v[78:81]
	v_mfma_f32_16x16x32_bf16 v[74:77], v[138:141], v[210:213], v[74:77]
	v_mfma_f32_16x16x32_bf16 v[126:129], v[134:137], v[190:193], v[126:129]
	v_mfma_f32_16x16x32_bf16 v[122:125], v[158:161], v[190:193], v[122:125]
	v_mfma_f32_16x16x32_bf16 v[110:113], v[134:137], v[198:201], v[110:113]
	v_mfma_f32_16x16x32_bf16 v[106:109], v[158:161], v[198:201], v[106:109]
	v_mfma_f32_16x16x32_bf16 v[94:97], v[134:137], v[206:209], v[94:97]
	v_mfma_f32_16x16x32_bf16 v[90:93], v[158:161], v[206:209], v[90:93]
	v_mfma_f32_16x16x32_bf16 v[78:81], v[134:137], v[218:221], v[78:81]
	v_mfma_f32_16x16x32_bf16 v[74:77], v[158:161], v[218:221], v[74:77]
	s_setprio 0
	s_setprio 1
	v_mfma_f32_16x16x32_bf16 v[118:121], v[162:165], v[186:189], v[118:121]
	v_mfma_f32_16x16x32_bf16 v[114:117], v[178:181], v[186:189], v[114:117]
	v_mfma_f32_16x16x32_bf16 v[102:105], v[162:165], v[194:197], v[102:105]
	v_mfma_f32_16x16x32_bf16 v[98:101], v[178:181], v[194:197], v[98:101]
	v_mfma_f32_16x16x32_bf16 v[86:89], v[162:165], v[202:205], v[86:89]
	v_mfma_f32_16x16x32_bf16 v[82:85], v[178:181], v[202:205], v[82:85]
	v_mfma_f32_16x16x32_bf16 v[70:73], v[162:165], v[210:213], v[70:73]
	v_mfma_f32_16x16x32_bf16 v[66:69], v[178:181], v[210:213], v[66:69]
	v_mfma_f32_16x16x32_bf16 v[118:121], v[166:169], v[190:193], v[118:121]
	v_mfma_f32_16x16x32_bf16 v[114:117], v[182:185], v[190:193], v[114:117]
	v_mfma_f32_16x16x32_bf16 v[102:105], v[166:169], v[198:201], v[102:105]
	v_mfma_f32_16x16x32_bf16 v[98:101], v[182:185], v[198:201], v[98:101]
	v_mfma_f32_16x16x32_bf16 v[86:89], v[166:169], v[206:209], v[86:89]
	v_mfma_f32_16x16x32_bf16 v[82:85], v[182:185], v[206:209], v[82:85]
	v_mfma_f32_16x16x32_bf16 v[70:73], v[166:169], v[218:221], v[70:73]
	v_mfma_f32_16x16x32_bf16 v[66:69], v[182:185], v[218:221], v[66:69]
	s_barrier
	s_setprio 0
	s_add_i32 s61, s53, s31
	v_lshl_add_u64 v[170:171], s[34:35], 0, v[144:145]
	s_mov_b32 m0, s61
	ds_read_b128 v[186:189], v176 offset:16384
	ds_read_b128 v[190:193], v176 offset:17408
	ds_read_b128 v[194:197], v176 offset:18432
	ds_read_b128 v[198:201], v176 offset:19456
	ds_read_b128 v[202:205], v176 offset:20480
	ds_read_b128 v[206:209], v176 offset:21504
	ds_read_b128 v[210:213], v176 offset:22528
	ds_read_b128 v[218:221], v176 offset:23552
	global_load_lds_dwordx4 v[170:171], off
	s_add_i32 m0, s61, 0x2000
	s_add_u32 s62, s34, 0x160000
	v_lshl_add_u64 v[214:215], s[34:35], 0, v[148:149]
	s_addc_u32 s63, s35, 0
	s_add_i32 s61, s54, s31
	global_load_lds_dwordx4 v[214:215], off
	v_lshl_add_u64 v[222:223], s[62:63], 0, v[144:145]
	s_mov_b32 m0, s61
	v_lshl_add_u64 v[224:225], s[42:43], 0, v[146:147]
	global_load_lds_dwordx4 v[222:223], off
	v_lshl_add_u64 v[222:223], s[62:63], 0, v[148:149]
	s_add_i32 m0, s61, 0x2000
	s_nop 0
	global_load_lds_dwordx4 v[222:223], off
	v_lshl_add_u64 v[222:223], s[42:43], 0, v[142:143]
	s_mov_b32 m0, s33
	s_nop 0
	global_load_lds_dwordx4 v[222:223], off
	s_mov_b32 m0, s44
	s_nop 0
	global_load_lds_dwordx4 v[224:225], off
	s_waitcnt vmcnt(8)
	s_waitcnt lgkmcnt(0)
	s_setprio 1
	s_barrier
	v_mfma_f32_16x16x32_bf16 v[62:65], v[130:133], v[186:189], v[62:65]
	v_mfma_f32_16x16x32_bf16 v[58:61], v[138:141], v[186:189], v[58:61]
	v_mfma_f32_16x16x32_bf16 v[50:53], v[130:133], v[194:197], v[50:53]
	v_mfma_f32_16x16x32_bf16 v[42:45], v[138:141], v[194:197], v[42:45]
	v_mfma_f32_16x16x32_bf16 v[38:41], v[130:133], v[202:205], v[38:41]
	v_mfma_f32_16x16x32_bf16 v[34:37], v[138:141], v[202:205], v[34:37]
	v_mfma_f32_16x16x32_bf16 v[14:17], v[130:133], v[210:213], v[14:17]
	v_mfma_f32_16x16x32_bf16 v[10:13], v[138:141], v[210:213], v[10:13]
	v_mfma_f32_16x16x32_bf16 v[62:65], v[134:137], v[190:193], v[62:65]
	v_mfma_f32_16x16x32_bf16 v[58:61], v[158:161], v[190:193], v[58:61]
	v_mfma_f32_16x16x32_bf16 v[50:53], v[134:137], v[198:201], v[50:53]
	v_mfma_f32_16x16x32_bf16 v[42:45], v[158:161], v[198:201], v[42:45]
	v_mfma_f32_16x16x32_bf16 v[38:41], v[134:137], v[206:209], v[38:41]
	v_mfma_f32_16x16x32_bf16 v[34:37], v[158:161], v[206:209], v[34:37]
	v_mfma_f32_16x16x32_bf16 v[14:17], v[134:137], v[218:221], v[14:17]
	v_mfma_f32_16x16x32_bf16 v[10:13], v[158:161], v[218:221], v[10:13]
	s_setprio 0
	s_setprio 1
	v_mfma_f32_16x16x32_bf16 v[54:57], v[162:165], v[186:189], v[54:57]
	v_mfma_f32_16x16x32_bf16 v[46:49], v[178:181], v[186:189], v[46:49]
	v_mfma_f32_16x16x32_bf16 v[30:33], v[162:165], v[194:197], v[30:33]
	v_mfma_f32_16x16x32_bf16 v[26:29], v[178:181], v[194:197], v[26:29]
	v_mfma_f32_16x16x32_bf16 v[22:25], v[162:165], v[202:205], v[22:25]
	v_mfma_f32_16x16x32_bf16 v[18:21], v[178:181], v[202:205], v[18:21]
	v_mfma_f32_16x16x32_bf16 v[6:9], v[162:165], v[210:213], v[6:9]
	v_mfma_f32_16x16x32_bf16 v[2:5], v[178:181], v[210:213], v[2:5]
	v_mfma_f32_16x16x32_bf16 v[54:57], v[166:169], v[190:193], v[54:57]
	v_mfma_f32_16x16x32_bf16 v[46:49], v[182:185], v[190:193], v[46:49]
	v_mfma_f32_16x16x32_bf16 v[30:33], v[166:169], v[198:201], v[30:33]
	v_mfma_f32_16x16x32_bf16 v[26:29], v[182:185], v[198:201], v[26:29]
	v_mfma_f32_16x16x32_bf16 v[22:25], v[166:169], v[206:209], v[22:25]
	v_mfma_f32_16x16x32_bf16 v[18:21], v[182:185], v[206:209], v[18:21]
	v_mfma_f32_16x16x32_bf16 v[6:9], v[166:169], v[218:221], v[6:9]
	v_mfma_f32_16x16x32_bf16 v[2:5], v[182:185], v[218:221], v[2:5]
	s_barrier
	s_setprio 0
	s_add_i32 s61, 0, 0x18000
	s_add_i32 s62, 0, 0x1c000
	v_add_u32_e32 v158, s61, v172
	v_add_u32_e32 v177, s62, v172
	ds_read_b128 v[130:133], v158
	ds_read_b128 v[134:137], v158 offset:1024
	ds_read_b128 v[138:141], v158 offset:2048
	ds_read_b128 v[158:161], v158 offset:3072
	ds_read_b128 v[162:165], v177
	ds_read_b128 v[166:169], v177 offset:1024
	ds_read_b128 v[178:181], v177 offset:2048
	ds_read_b128 v[182:185], v177 offset:3072
	s_add_u32 s42, s42, 0x160000
	s_addc_u32 s43, s43, 0
	s_mov_b32 m0, s45
	v_lshl_add_u64 v[226:227], s[42:43], 0, v[142:143]
	ds_read_b128 v[186:189], v176 offset:32768
	ds_read_b128 v[190:193], v176 offset:33792
	ds_read_b128 v[194:197], v176 offset:34816
	ds_read_b128 v[198:201], v176 offset:35840
	ds_read_b128 v[202:205], v176 offset:36864
	ds_read_b128 v[206:209], v176 offset:37888
	ds_read_b128 v[210:213], v176 offset:38912
	ds_read_b128 v[218:221], v176 offset:39936
	global_load_lds_dwordx4 v[226:227], off
	v_lshl_add_u64 v[226:227], s[42:43], 0, v[146:147]
	s_mov_b32 m0, s46
	s_nop 0
	global_load_lds_dwordx4 v[226:227], off
	s_waitcnt vmcnt(8)
	s_waitcnt lgkmcnt(0)
	s_setprio 1
	s_barrier
	v_mfma_f32_16x16x32_bf16 v[126:129], v[130:133], v[186:189], v[126:129]
	v_mfma_f32_16x16x32_bf16 v[122:125], v[138:141], v[186:189], v[122:125]
	v_mfma_f32_16x16x32_bf16 v[110:113], v[130:133], v[194:197], v[110:113]
	v_mfma_f32_16x16x32_bf16 v[106:109], v[138:141], v[194:197], v[106:109]
	v_mfma_f32_16x16x32_bf16 v[94:97], v[130:133], v[202:205], v[94:97]
	v_mfma_f32_16x16x32_bf16 v[90:93], v[138:141], v[202:205], v[90:93]
	v_mfma_f32_16x16x32_bf16 v[78:81], v[130:133], v[210:213], v[78:81]
	v_mfma_f32_16x16x32_bf16 v[74:77], v[138:141], v[210:213], v[74:77]
	v_mfma_f32_16x16x32_bf16 v[126:129], v[134:137], v[190:193], v[126:129]
	v_mfma_f32_16x16x32_bf16 v[122:125], v[158:161], v[190:193], v[122:125]
	v_mfma_f32_16x16x32_bf16 v[110:113], v[134:137], v[198:201], v[110:113]
	v_mfma_f32_16x16x32_bf16 v[106:109], v[158:161], v[198:201], v[106:109]
	v_mfma_f32_16x16x32_bf16 v[94:97], v[134:137], v[206:209], v[94:97]
	v_mfma_f32_16x16x32_bf16 v[90:93], v[158:161], v[206:209], v[90:93]
	v_mfma_f32_16x16x32_bf16 v[78:81], v[134:137], v[218:221], v[78:81]
	v_mfma_f32_16x16x32_bf16 v[74:77], v[158:161], v[218:221], v[74:77]
	s_setprio 0
	s_setprio 1
	v_mfma_f32_16x16x32_bf16 v[118:121], v[162:165], v[186:189], v[118:121]
	v_mfma_f32_16x16x32_bf16 v[114:117], v[178:181], v[186:189], v[114:117]
	v_mfma_f32_16x16x32_bf16 v[102:105], v[162:165], v[194:197], v[102:105]
	v_mfma_f32_16x16x32_bf16 v[98:101], v[178:181], v[194:197], v[98:101]
	v_mfma_f32_16x16x32_bf16 v[86:89], v[162:165], v[202:205], v[86:89]
	v_mfma_f32_16x16x32_bf16 v[82:85], v[178:181], v[202:205], v[82:85]
	v_mfma_f32_16x16x32_bf16 v[70:73], v[162:165], v[210:213], v[70:73]
	v_mfma_f32_16x16x32_bf16 v[66:69], v[178:181], v[210:213], v[66:69]
	v_mfma_f32_16x16x32_bf16 v[118:121], v[166:169], v[190:193], v[118:121]
	v_mfma_f32_16x16x32_bf16 v[114:117], v[182:185], v[190:193], v[114:117]
	v_mfma_f32_16x16x32_bf16 v[102:105], v[166:169], v[198:201], v[102:105]
	v_mfma_f32_16x16x32_bf16 v[98:101], v[182:185], v[198:201], v[98:101]
	v_mfma_f32_16x16x32_bf16 v[86:89], v[166:169], v[206:209], v[86:89]
	v_mfma_f32_16x16x32_bf16 v[82:85], v[182:185], v[206:209], v[82:85]
	v_mfma_f32_16x16x32_bf16 v[70:73], v[166:169], v[218:221], v[70:73]
	v_mfma_f32_16x16x32_bf16 v[66:69], v[182:185], v[218:221], v[66:69]
	s_barrier
	s_setprio 0
	s_add_i32 s42, s61, s31
	v_lshl_add_u64 v[170:171], v[170:171], 0, s[24:25]
	s_mov_b32 m0, s42
	ds_read_b128 v[186:189], v176 offset:49152
	ds_read_b128 v[190:193], v176 offset:50176
	ds_read_b128 v[194:197], v176 offset:51200
	ds_read_b128 v[198:201], v176 offset:52224
	ds_read_b128 v[202:205], v176 offset:53248
	ds_read_b128 v[206:209], v176 offset:54272
	ds_read_b128 v[210:213], v176 offset:55296
	ds_read_b128 v[218:221], v176 offset:56320
	global_load_lds_dwordx4 v[170:171], off
	s_add_i32 m0, s42, 0x2000
	s_add_u32 s34, s34, 0x160080
	v_lshl_add_u64 v[170:171], v[214:215], 0, s[24:25]
	s_addc_u32 s35, s35, 0
	s_add_i32 s42, s62, s31
	global_load_lds_dwordx4 v[170:171], off
	v_lshl_add_u64 v[170:171], s[34:35], 0, v[144:145]
	s_mov_b32 m0, s42
	s_nop 0
	global_load_lds_dwordx4 v[170:171], off
	v_lshl_add_u64 v[170:171], s[34:35], 0, v[148:149]
	s_add_i32 m0, s42, 0x2000
	s_nop 0
	global_load_lds_dwordx4 v[170:171], off
	v_lshl_add_u64 v[170:171], v[222:223], 0, s[24:25]
	s_mov_b32 m0, s48
	s_nop 0
	global_load_lds_dwordx4 v[170:171], off
	v_lshl_add_u64 v[170:171], v[224:225], 0, s[24:25]
	s_mov_b32 m0, s49
	s_nop 0
	global_load_lds_dwordx4 v[170:171], off
	s_waitcnt vmcnt(8)
	s_waitcnt lgkmcnt(0)
	s_setprio 1
	s_barrier
	v_mfma_f32_16x16x32_bf16 v[62:65], v[130:133], v[186:189], v[62:65]
	v_mfma_f32_16x16x32_bf16 v[58:61], v[138:141], v[186:189], v[58:61]
	v_mfma_f32_16x16x32_bf16 v[50:53], v[130:133], v[194:197], v[50:53]
	v_mfma_f32_16x16x32_bf16 v[42:45], v[138:141], v[194:197], v[42:45]
	v_mfma_f32_16x16x32_bf16 v[38:41], v[130:133], v[202:205], v[38:41]
	v_mfma_f32_16x16x32_bf16 v[34:37], v[138:141], v[202:205], v[34:37]
	v_mfma_f32_16x16x32_bf16 v[14:17], v[130:133], v[210:213], v[14:17]
	v_mfma_f32_16x16x32_bf16 v[10:13], v[138:141], v[210:213], v[10:13]
	v_mfma_f32_16x16x32_bf16 v[62:65], v[134:137], v[190:193], v[62:65]
	v_mfma_f32_16x16x32_bf16 v[58:61], v[158:161], v[190:193], v[58:61]
	v_mfma_f32_16x16x32_bf16 v[50:53], v[134:137], v[198:201], v[50:53]
	v_mfma_f32_16x16x32_bf16 v[42:45], v[158:161], v[198:201], v[42:45]
	v_mfma_f32_16x16x32_bf16 v[38:41], v[134:137], v[206:209], v[38:41]
	v_mfma_f32_16x16x32_bf16 v[34:37], v[158:161], v[206:209], v[34:37]
	v_mfma_f32_16x16x32_bf16 v[14:17], v[134:137], v[218:221], v[14:17]
	v_mfma_f32_16x16x32_bf16 v[10:13], v[158:161], v[218:221], v[10:13]
	s_setprio 0
	s_setprio 1
	v_mfma_f32_16x16x32_bf16 v[54:57], v[162:165], v[186:189], v[54:57]
	v_mfma_f32_16x16x32_bf16 v[46:49], v[178:181], v[186:189], v[46:49]
	v_mfma_f32_16x16x32_bf16 v[30:33], v[162:165], v[194:197], v[30:33]
	v_mfma_f32_16x16x32_bf16 v[26:29], v[178:181], v[194:197], v[26:29]
	v_mfma_f32_16x16x32_bf16 v[22:25], v[162:165], v[202:205], v[22:25]
	v_mfma_f32_16x16x32_bf16 v[18:21], v[178:181], v[202:205], v[18:21]
	v_mfma_f32_16x16x32_bf16 v[6:9], v[162:165], v[210:213], v[6:9]
	v_mfma_f32_16x16x32_bf16 v[2:5], v[178:181], v[210:213], v[2:5]
	v_mfma_f32_16x16x32_bf16 v[54:57], v[166:169], v[190:193], v[54:57]
	v_mfma_f32_16x16x32_bf16 v[46:49], v[182:185], v[190:193], v[46:49]
	v_mfma_f32_16x16x32_bf16 v[30:33], v[166:169], v[198:201], v[30:33]
	v_mfma_f32_16x16x32_bf16 v[26:29], v[182:185], v[198:201], v[26:29]
	v_mfma_f32_16x16x32_bf16 v[22:25], v[166:169], v[206:209], v[22:25]
	v_mfma_f32_16x16x32_bf16 v[18:21], v[182:185], v[206:209], v[18:21]
	v_mfma_f32_16x16x32_bf16 v[6:9], v[166:169], v[218:221], v[6:9]
	v_mfma_f32_16x16x32_bf16 v[2:5], v[182:185], v[218:221], v[2:5]
	s_barrier
	s_setprio 0
	s_add_i32 s60, s60, 2
	s_add_u32 s40, s40, 0x100
	s_addc_u32 s41, s41, 0
	s_add_u32 s0, s0, 0x100
	s_addc_u32 s1, s1, 0
	s_cmpk_gt_u32 s60, 0x55
	s_cbranch_scc0 .LBB0_3180
	s_and_b64 vcc, exec, s[26:27]
	s_cbranch_vccz .LBB0_3183
	s_barrier

.LBB0_3309:
	ds_read_b128 v[146:149], v153
	ds_read_b128 v[156:159], v153 offset:1024
	ds_read_b128 v[160:163], v153 offset:2048
	ds_read_b128 v[164:167], v153 offset:3072
	ds_read_b128 v[168:171], v154
	ds_read_b128 v[172:175], v154 offset:1024
	ds_read_b128 v[176:179], v154 offset:2048
	ds_read_b128 v[180:183], v154 offset:3072
	s_add_u32 s34, s44, 0xfff80080
	s_addc_u32 s35, s45, -1
	s_cmp_eq_u32 s69, 28
	s_cselect_b32 s47, s0, s35
	s_cselect_b32 s46, s1, s34
	s_cselect_b32 s35, s27, s68
	s_cselect_b32 s34, s37, s61
	v_lshl_add_u64 v[218:219], s[44:45], 0, v[138:139]
	s_add_i32 m0, s43, 0xc000
	ds_read_b128 v[184:187], v155
	ds_read_b128 v[188:191], v155 offset:1024
	ds_read_b128 v[192:195], v155 offset:2048
	ds_read_b128 v[196:199], v155 offset:3072
	ds_read_b128 v[200:203], v155 offset:4096
	ds_read_b128 v[204:207], v155 offset:5120
	ds_read_b128 v[208:211], v155 offset:6144
	ds_read_b128 v[212:215], v155 offset:7168
	global_load_lds_dwordx4 v[218:219], off
	v_lshl_add_u64 v[218:219], s[44:45], 0, v[140:141]
	s_add_i32 m0, s43, 0xe000
	s_nop 0
	global_load_lds_dwordx4 v[218:219], off
	s_waitcnt vmcnt(8)
	s_waitcnt lgkmcnt(0)
	s_setprio 1
	s_barrier
	v_mfma_f32_16x16x32_bf16 v[126:129], v[146:149], v[184:187], v[126:129]
	v_mfma_f32_16x16x32_bf16 v[118:121], v[160:163], v[184:187], v[118:121]
	v_mfma_f32_16x16x32_bf16 v[110:113], v[146:149], v[192:195], v[110:113]
	v_mfma_f32_16x16x32_bf16 v[102:105], v[160:163], v[192:195], v[102:105]
	v_mfma_f32_16x16x32_bf16 v[94:97], v[146:149], v[200:203], v[94:97]
	v_mfma_f32_16x16x32_bf16 v[86:89], v[160:163], v[200:203], v[86:89]
	v_mfma_f32_16x16x32_bf16 v[78:81], v[146:149], v[208:211], v[78:81]
	v_mfma_f32_16x16x32_bf16 v[70:73], v[160:163], v[208:211], v[70:73]
	v_mfma_f32_16x16x32_bf16 v[126:129], v[156:159], v[188:191], v[126:129]
	v_mfma_f32_16x16x32_bf16 v[118:121], v[164:167], v[188:191], v[118:121]
	v_mfma_f32_16x16x32_bf16 v[110:113], v[156:159], v[196:199], v[110:113]
	v_mfma_f32_16x16x32_bf16 v[102:105], v[164:167], v[196:199], v[102:105]
	v_mfma_f32_16x16x32_bf16 v[94:97], v[156:159], v[204:207], v[94:97]
	v_mfma_f32_16x16x32_bf16 v[86:89], v[164:167], v[204:207], v[86:89]
	v_mfma_f32_16x16x32_bf16 v[78:81], v[156:159], v[212:215], v[78:81]
	v_mfma_f32_16x16x32_bf16 v[70:73], v[164:167], v[212:215], v[70:73]
	s_setprio 0
	s_setprio 1
	v_mfma_f32_16x16x32_bf16 v[122:125], v[168:171], v[184:187], v[122:125]
	v_mfma_f32_16x16x32_bf16 v[114:117], v[176:179], v[184:187], v[114:117]
	v_mfma_f32_16x16x32_bf16 v[106:109], v[168:171], v[192:195], v[106:109]
	v_mfma_f32_16x16x32_bf16 v[98:101], v[176:179], v[192:195], v[98:101]
	v_mfma_f32_16x16x32_bf16 v[90:93], v[168:171], v[200:203], v[90:93]
	v_mfma_f32_16x16x32_bf16 v[82:85], v[176:179], v[200:203], v[82:85]
	v_mfma_f32_16x16x32_bf16 v[74:77], v[168:171], v[208:211], v[74:77]
	v_mfma_f32_16x16x32_bf16 v[66:69], v[176:179], v[208:211], v[66:69]
	v_mfma_f32_16x16x32_bf16 v[122:125], v[172:175], v[188:191], v[122:125]
	v_mfma_f32_16x16x32_bf16 v[114:117], v[180:183], v[188:191], v[114:117]
	v_mfma_f32_16x16x32_bf16 v[106:109], v[172:175], v[196:199], v[106:109]
	v_mfma_f32_16x16x32_bf16 v[98:101], v[180:183], v[196:199], v[98:101]
	v_mfma_f32_16x16x32_bf16 v[90:93], v[172:175], v[204:207], v[90:93]
	v_mfma_f32_16x16x32_bf16 v[82:85], v[180:183], v[204:207], v[82:85]
	v_mfma_f32_16x16x32_bf16 v[74:77], v[172:175], v[212:215], v[74:77]
	v_mfma_f32_16x16x32_bf16 v[66:69], v[180:183], v[212:215], v[66:69]
	s_barrier
	s_setprio 0
	s_add_i32 s62, s57, s30
	v_lshl_add_u64 v[218:219], s[34:35], 0, v[134:135]
	s_mov_b32 m0, s62
	ds_read_b128 v[184:187], v155 offset:16384
	ds_read_b128 v[188:191], v155 offset:17408
	ds_read_b128 v[192:195], v155 offset:18432
	ds_read_b128 v[196:199], v155 offset:19456
	ds_read_b128 v[200:203], v155 offset:20480
	ds_read_b128 v[204:207], v155 offset:21504
	ds_read_b128 v[208:211], v155 offset:22528
	ds_read_b128 v[212:215], v155 offset:23552
	global_load_lds_dwordx4 v[218:219], off
	s_add_i32 m0, s62, 0x2000
	s_add_u32 s62, s34, 0x80000
	v_lshl_add_u64 v[220:221], s[34:35], 0, v[130:131]
	s_addc_u32 s63, s35, 0
	s_add_i32 s66, s58, s30
	global_load_lds_dwordx4 v[220:221], off
	v_lshl_add_u64 v[222:223], s[62:63], 0, v[134:135]
	s_mov_b32 m0, s66
	v_lshl_add_u64 v[224:225], s[46:47], 0, v[132:133]
	global_load_lds_dwordx4 v[222:223], off
	v_lshl_add_u64 v[222:223], s[62:63], 0, v[130:131]
	s_add_i32 m0, s66, 0x2000
	s_nop 0
	global_load_lds_dwordx4 v[222:223], off
	v_lshl_add_u64 v[222:223], s[46:47], 0, v[136:137]
	s_mov_b32 m0, s43
	s_nop 0
	global_load_lds_dwordx4 v[222:223], off
	s_mov_b32 m0, s48
	s_nop 0
	global_load_lds_dwordx4 v[224:225], off
	s_waitcnt vmcnt(8)
	s_waitcnt lgkmcnt(0)
	s_setprio 1
	s_barrier
	v_mfma_f32_16x16x32_bf16 v[62:65], v[146:149], v[184:187], v[62:65]
	v_mfma_f32_16x16x32_bf16 v[54:57], v[160:163], v[184:187], v[54:57]
	v_mfma_f32_16x16x32_bf16 v[46:49], v[146:149], v[192:195], v[46:49]
	v_mfma_f32_16x16x32_bf16 v[38:41], v[160:163], v[192:195], v[38:41]
	v_mfma_f32_16x16x32_bf16 v[30:33], v[146:149], v[200:203], v[30:33]
	v_mfma_f32_16x16x32_bf16 v[22:25], v[160:163], v[200:203], v[22:25]
	v_mfma_f32_16x16x32_bf16 v[14:17], v[146:149], v[208:211], v[14:17]
	v_mfma_f32_16x16x32_bf16 v[6:9], v[160:163], v[208:211], v[6:9]
	v_mfma_f32_16x16x32_bf16 v[62:65], v[156:159], v[188:191], v[62:65]
	v_mfma_f32_16x16x32_bf16 v[54:57], v[164:167], v[188:191], v[54:57]
	v_mfma_f32_16x16x32_bf16 v[46:49], v[156:159], v[196:199], v[46:49]
	v_mfma_f32_16x16x32_bf16 v[38:41], v[164:167], v[196:199], v[38:41]
	v_mfma_f32_16x16x32_bf16 v[30:33], v[156:159], v[204:207], v[30:33]
	v_mfma_f32_16x16x32_bf16 v[22:25], v[164:167], v[204:207], v[22:25]
	v_mfma_f32_16x16x32_bf16 v[14:17], v[156:159], v[212:215], v[14:17]
	v_mfma_f32_16x16x32_bf16 v[6:9], v[164:167], v[212:215], v[6:9]
	s_setprio 0
	s_setprio 1
	v_mfma_f32_16x16x32_bf16 v[58:61], v[168:171], v[184:187], v[58:61]
	v_mfma_f32_16x16x32_bf16 v[50:53], v[176:179], v[184:187], v[50:53]
	v_mfma_f32_16x16x32_bf16 v[42:45], v[168:171], v[192:195], v[42:45]
	v_mfma_f32_16x16x32_bf16 v[34:37], v[176:179], v[192:195], v[34:37]
	v_mfma_f32_16x16x32_bf16 v[26:29], v[168:171], v[200:203], v[26:29]
	v_mfma_f32_16x16x32_bf16 v[18:21], v[176:179], v[200:203], v[18:21]
	v_mfma_f32_16x16x32_bf16 v[10:13], v[168:171], v[208:211], v[10:13]
	v_mfma_f32_16x16x32_bf16 v[2:5], v[176:179], v[208:211], v[2:5]
	v_mfma_f32_16x16x32_bf16 v[58:61], v[172:175], v[188:191], v[58:61]
	v_mfma_f32_16x16x32_bf16 v[50:53], v[180:183], v[188:191], v[50:53]
	v_mfma_f32_16x16x32_bf16 v[42:45], v[172:175], v[196:199], v[42:45]
	v_mfma_f32_16x16x32_bf16 v[34:37], v[180:183], v[196:199], v[34:37]
	v_mfma_f32_16x16x32_bf16 v[26:29], v[172:175], v[204:207], v[26:29]
	v_mfma_f32_16x16x32_bf16 v[18:21], v[180:183], v[204:207], v[18:21]
	v_mfma_f32_16x16x32_bf16 v[10:13], v[172:175], v[212:215], v[10:13]
	v_mfma_f32_16x16x32_bf16 v[2:5], v[180:183], v[212:215], v[2:5]
	s_barrier
	s_setprio 0
	s_add_i32 s62, 0, 0x18000
	s_add_i32 s63, 0, 0x1c000
	v_add_u32_e32 v164, s62, v151
	v_add_u32_e32 v180, s63, v151
	ds_read_b128 v[146:149], v164
	ds_read_b128 v[156:159], v164 offset:1024
	ds_read_b128 v[160:163], v164 offset:2048
	ds_read_b128 v[164:167], v164 offset:3072
	ds_read_b128 v[168:171], v180
	ds_read_b128 v[172:175], v180 offset:1024
	ds_read_b128 v[176:179], v180 offset:2048
	ds_read_b128 v[180:183], v180 offset:3072
	s_add_u32 s46, s46, 0x80000
	s_addc_u32 s47, s47, 0
	s_mov_b32 m0, s49
	v_lshl_add_u64 v[226:227], s[46:47], 0, v[136:137]
	ds_read_b128 v[184:187], v155 offset:32768
	ds_read_b128 v[188:191], v155 offset:33792
	ds_read_b128 v[192:195], v155 offset:34816
	ds_read_b128 v[196:199], v155 offset:35840
	ds_read_b128 v[200:203], v155 offset:36864
	ds_read_b128 v[204:207], v155 offset:37888
	ds_read_b128 v[208:211], v155 offset:38912
	ds_read_b128 v[212:215], v155 offset:39936
	global_load_lds_dwordx4 v[226:227], off
	v_lshl_add_u64 v[226:227], s[46:47], 0, v[132:133]
	s_mov_b32 m0, s52
	s_nop 0
	global_load_lds_dwordx4 v[226:227], off
	s_waitcnt vmcnt(8)
	s_waitcnt lgkmcnt(0)
	s_setprio 1
	s_barrier
	v_mfma_f32_16x16x32_bf16 v[126:129], v[146:149], v[184:187], v[126:129]
	v_mfma_f32_16x16x32_bf16 v[118:121], v[160:163], v[184:187], v[118:121]
	v_mfma_f32_16x16x32_bf16 v[110:113], v[146:149], v[192:195], v[110:113]
	v_mfma_f32_16x16x32_bf16 v[102:105], v[160:163], v[192:195], v[102:105]
	v_mfma_f32_16x16x32_bf16 v[94:97], v[146:149], v[200:203], v[94:97]
	v_mfma_f32_16x16x32_bf16 v[86:89], v[160:163], v[200:203], v[86:89]
	v_mfma_f32_16x16x32_bf16 v[78:81], v[146:149], v[208:211], v[78:81]
	v_mfma_f32_16x16x32_bf16 v[70:73], v[160:163], v[208:211], v[70:73]
	v_mfma_f32_16x16x32_bf16 v[126:129], v[156:159], v[188:191], v[126:129]
	v_mfma_f32_16x16x32_bf16 v[118:121], v[164:167], v[188:191], v[118:121]
	v_mfma_f32_16x16x32_bf16 v[110:113], v[156:159], v[196:199], v[110:113]
	v_mfma_f32_16x16x32_bf16 v[102:105], v[164:167], v[196:199], v[102:105]
	v_mfma_f32_16x16x32_bf16 v[94:97], v[156:159], v[204:207], v[94:97]
	v_mfma_f32_16x16x32_bf16 v[86:89], v[164:167], v[204:207], v[86:89]
	v_mfma_f32_16x16x32_bf16 v[78:81], v[156:159], v[212:215], v[78:81]
	v_mfma_f32_16x16x32_bf16 v[70:73], v[164:167], v[212:215], v[70:73]
	s_setprio 0
	s_setprio 1
	v_mfma_f32_16x16x32_bf16 v[122:125], v[168:171], v[184:187], v[122:125]
	v_mfma_f32_16x16x32_bf16 v[114:117], v[176:179], v[184:187], v[114:117]
	v_mfma_f32_16x16x32_bf16 v[106:109], v[168:171], v[192:195], v[106:109]
	v_mfma_f32_16x16x32_bf16 v[98:101], v[176:179], v[192:195], v[98:101]
	v_mfma_f32_16x16x32_bf16 v[90:93], v[168:171], v[200:203], v[90:93]
	v_mfma_f32_16x16x32_bf16 v[82:85], v[176:179], v[200:203], v[82:85]
	v_mfma_f32_16x16x32_bf16 v[74:77], v[168:171], v[208:211], v[74:77]
	v_mfma_f32_16x16x32_bf16 v[66:69], v[176:179], v[208:211], v[66:69]
	v_mfma_f32_16x16x32_bf16 v[122:125], v[172:175], v[188:191], v[122:125]
	v_mfma_f32_16x16x32_bf16 v[114:117], v[180:183], v[188:191], v[114:117]
	v_mfma_f32_16x16x32_bf16 v[106:109], v[172:175], v[196:199], v[106:109]
	v_mfma_f32_16x16x32_bf16 v[98:101], v[180:183], v[196:199], v[98:101]
	v_mfma_f32_16x16x32_bf16 v[90:93], v[172:175], v[204:207], v[90:93]
	v_mfma_f32_16x16x32_bf16 v[82:85], v[180:183], v[204:207], v[82:85]
	v_mfma_f32_16x16x32_bf16 v[74:77], v[172:175], v[212:215], v[74:77]
	v_mfma_f32_16x16x32_bf16 v[66:69], v[180:183], v[212:215], v[66:69]
	s_barrier
	s_setprio 0
	s_add_i32 s46, s62, s30
	v_lshl_add_u64 v[218:219], v[218:219], 0, s[8:9]
	s_mov_b32 m0, s46
	ds_read_b128 v[184:187], v155 offset:49152
	ds_read_b128 v[188:191], v155 offset:50176
	ds_read_b128 v[192:195], v155 offset:51200
	ds_read_b128 v[196:199], v155 offset:52224
	ds_read_b128 v[200:203], v155 offset:53248
	ds_read_b128 v[204:207], v155 offset:54272
	ds_read_b128 v[208:211], v155 offset:55296
	ds_read_b128 v[212:215], v155 offset:56320
	global_load_lds_dwordx4 v[218:219], off
	s_add_i32 m0, s46, 0x2000
	s_add_u32 s34, s34, 0x80080
	v_lshl_add_u64 v[218:219], v[220:221], 0, s[8:9]
	s_addc_u32 s35, s35, 0
	s_add_i32 s46, s63, s30
	global_load_lds_dwordx4 v[218:219], off
	v_lshl_add_u64 v[218:219], s[34:35], 0, v[134:135]
	s_mov_b32 m0, s46
	s_nop 0
	global_load_lds_dwordx4 v[218:219], off
	v_lshl_add_u64 v[218:219], s[34:35], 0, v[130:131]
	s_add_i32 m0, s46, 0x2000
	s_nop 0
	global_load_lds_dwordx4 v[218:219], off
	v_lshl_add_u64 v[218:219], v[222:223], 0, s[8:9]
	s_mov_b32 m0, s54
	s_nop 0
	global_load_lds_dwordx4 v[218:219], off
	v_lshl_add_u64 v[218:219], v[224:225], 0, s[8:9]
	s_mov_b32 m0, s55
	s_nop 0
	global_load_lds_dwordx4 v[218:219], off
	s_waitcnt vmcnt(8)
	s_waitcnt lgkmcnt(0)
	s_setprio 1
	s_barrier
	v_mfma_f32_16x16x32_bf16 v[62:65], v[146:149], v[184:187], v[62:65]
	v_mfma_f32_16x16x32_bf16 v[54:57], v[160:163], v[184:187], v[54:57]
	v_mfma_f32_16x16x32_bf16 v[46:49], v[146:149], v[192:195], v[46:49]
	v_mfma_f32_16x16x32_bf16 v[38:41], v[160:163], v[192:195], v[38:41]
	v_mfma_f32_16x16x32_bf16 v[30:33], v[146:149], v[200:203], v[30:33]
	v_mfma_f32_16x16x32_bf16 v[22:25], v[160:163], v[200:203], v[22:25]
	v_mfma_f32_16x16x32_bf16 v[14:17], v[146:149], v[208:211], v[14:17]
	v_mfma_f32_16x16x32_bf16 v[6:9], v[160:163], v[208:211], v[6:9]
	v_mfma_f32_16x16x32_bf16 v[62:65], v[156:159], v[188:191], v[62:65]
	v_mfma_f32_16x16x32_bf16 v[54:57], v[164:167], v[188:191], v[54:57]
	v_mfma_f32_16x16x32_bf16 v[46:49], v[156:159], v[196:199], v[46:49]
	v_mfma_f32_16x16x32_bf16 v[38:41], v[164:167], v[196:199], v[38:41]
	v_mfma_f32_16x16x32_bf16 v[30:33], v[156:159], v[204:207], v[30:33]
	v_mfma_f32_16x16x32_bf16 v[22:25], v[164:167], v[204:207], v[22:25]
	v_mfma_f32_16x16x32_bf16 v[14:17], v[156:159], v[212:215], v[14:17]
	v_mfma_f32_16x16x32_bf16 v[6:9], v[164:167], v[212:215], v[6:9]
	s_setprio 0
	s_setprio 1
	v_mfma_f32_16x16x32_bf16 v[58:61], v[168:171], v[184:187], v[58:61]
	v_mfma_f32_16x16x32_bf16 v[50:53], v[176:179], v[184:187], v[50:53]
	v_mfma_f32_16x16x32_bf16 v[42:45], v[168:171], v[192:195], v[42:45]
	v_mfma_f32_16x16x32_bf16 v[34:37], v[176:179], v[192:195], v[34:37]
	v_mfma_f32_16x16x32_bf16 v[26:29], v[168:171], v[200:203], v[26:29]
	v_mfma_f32_16x16x32_bf16 v[18:21], v[176:179], v[200:203], v[18:21]
	v_mfma_f32_16x16x32_bf16 v[10:13], v[168:171], v[208:211], v[10:13]
	v_mfma_f32_16x16x32_bf16 v[2:5], v[176:179], v[208:211], v[2:5]
	v_mfma_f32_16x16x32_bf16 v[58:61], v[172:175], v[188:191], v[58:61]
	v_mfma_f32_16x16x32_bf16 v[50:53], v[180:183], v[188:191], v[50:53]
	v_mfma_f32_16x16x32_bf16 v[42:45], v[172:175], v[196:199], v[42:45]
	v_mfma_f32_16x16x32_bf16 v[34:37], v[180:183], v[196:199], v[34:37]
	v_mfma_f32_16x16x32_bf16 v[26:29], v[172:175], v[204:207], v[26:29]
	v_mfma_f32_16x16x32_bf16 v[18:21], v[180:183], v[204:207], v[18:21]
	v_mfma_f32_16x16x32_bf16 v[10:13], v[172:175], v[212:215], v[10:13]
	v_mfma_f32_16x16x32_bf16 v[2:5], v[180:183], v[212:215], v[2:5]
	s_barrier
	s_setprio 0
	s_add_i32 s69, s69, 2
	s_add_u32 s44, s44, 0x100
	s_addc_u32 s45, s45, 0
	s_add_u32 s61, s61, 0x100
	s_addc_u32 s68, s68, 0
	s_cmp_gt_u32 s69, 29
	s_cbranch_scc0 .LBB0_3309
	s_and_b64 vcc, exec, s[24:25]
	s_cbranch_vccz .LBB0_3312
	s_barrier

.LBB0_3533:
	ds_read_b128 v[154:157], v151
	ds_read_b128 v[158:161], v151 offset:1024
	ds_read_b128 v[162:165], v151 offset:2048
	ds_read_b128 v[166:169], v151 offset:3072
	ds_read_b128 v[170:173], v152
	ds_read_b128 v[174:177], v152 offset:1024
	ds_read_b128 v[178:181], v152 offset:2048
	ds_read_b128 v[182:185], v152 offset:3072
	s_add_u32 s34, s44, 0xfff80080
	s_addc_u32 s35, s45, -1
	s_cmp_eq_u32 s68, 28
	s_cselect_b32 s47, s0, s35
	s_cselect_b32 s46, s1, s34
	s_cselect_b32 s35, s27, s61
	s_cselect_b32 s34, s37, s60
	v_lshl_add_u64 v[146:147], s[44:45], 0, v[138:139]
	s_add_i32 m0, s33, 0xc000
	ds_read_b128 v[186:189], v153
	ds_read_b128 v[190:193], v153 offset:1024
	ds_read_b128 v[194:197], v153 offset:2048
	ds_read_b128 v[198:201], v153 offset:3072
	ds_read_b128 v[202:205], v153 offset:4096
	ds_read_b128 v[206:209], v153 offset:5120
	ds_read_b128 v[210:213], v153 offset:6144
	ds_read_b128 v[218:221], v153 offset:7168
	global_load_lds_dwordx4 v[146:147], off
	v_lshl_add_u64 v[146:147], s[44:45], 0, v[140:141]
	s_add_i32 m0, s33, 0xe000
	s_nop 0
	global_load_lds_dwordx4 v[146:147], off
	s_waitcnt vmcnt(8)
	s_waitcnt lgkmcnt(0)
	s_setprio 1
	s_barrier
	v_mfma_f32_16x16x32_bf16 v[126:129], v[154:157], v[186:189], v[126:129]
	v_mfma_f32_16x16x32_bf16 v[122:125], v[162:165], v[186:189], v[122:125]
	v_mfma_f32_16x16x32_bf16 v[114:117], v[154:157], v[194:197], v[114:117]
	v_mfma_f32_16x16x32_bf16 v[106:109], v[162:165], v[194:197], v[106:109]
	v_mfma_f32_16x16x32_bf16 v[98:101], v[154:157], v[202:205], v[98:101]
	v_mfma_f32_16x16x32_bf16 v[90:93], v[162:165], v[202:205], v[90:93]
	v_mfma_f32_16x16x32_bf16 v[82:85], v[154:157], v[210:213], v[82:85]
	v_mfma_f32_16x16x32_bf16 v[74:77], v[162:165], v[210:213], v[74:77]
	v_mfma_f32_16x16x32_bf16 v[126:129], v[158:161], v[190:193], v[126:129]
	v_mfma_f32_16x16x32_bf16 v[122:125], v[166:169], v[190:193], v[122:125]
	v_mfma_f32_16x16x32_bf16 v[114:117], v[158:161], v[198:201], v[114:117]
	v_mfma_f32_16x16x32_bf16 v[106:109], v[166:169], v[198:201], v[106:109]
	v_mfma_f32_16x16x32_bf16 v[98:101], v[158:161], v[206:209], v[98:101]
	v_mfma_f32_16x16x32_bf16 v[90:93], v[166:169], v[206:209], v[90:93]
	v_mfma_f32_16x16x32_bf16 v[82:85], v[158:161], v[218:221], v[82:85]
	v_mfma_f32_16x16x32_bf16 v[74:77], v[166:169], v[218:221], v[74:77]
	s_setprio 0
	s_setprio 1
	v_mfma_f32_16x16x32_bf16 v[118:121], v[170:173], v[186:189], v[118:121]
	v_mfma_f32_16x16x32_bf16 v[110:113], v[178:181], v[186:189], v[110:113]
	v_mfma_f32_16x16x32_bf16 v[102:105], v[170:173], v[194:197], v[102:105]
	v_mfma_f32_16x16x32_bf16 v[94:97], v[178:181], v[194:197], v[94:97]
	v_mfma_f32_16x16x32_bf16 v[86:89], v[170:173], v[202:205], v[86:89]
	v_mfma_f32_16x16x32_bf16 v[78:81], v[178:181], v[202:205], v[78:81]
	v_mfma_f32_16x16x32_bf16 v[70:73], v[170:173], v[210:213], v[70:73]
	v_mfma_f32_16x16x32_bf16 v[66:69], v[178:181], v[210:213], v[66:69]
	v_mfma_f32_16x16x32_bf16 v[118:121], v[174:177], v[190:193], v[118:121]
	v_mfma_f32_16x16x32_bf16 v[110:113], v[182:185], v[190:193], v[110:113]
	v_mfma_f32_16x16x32_bf16 v[102:105], v[174:177], v[198:201], v[102:105]
	v_mfma_f32_16x16x32_bf16 v[94:97], v[182:185], v[198:201], v[94:97]
	v_mfma_f32_16x16x32_bf16 v[86:89], v[174:177], v[206:209], v[86:89]
	v_mfma_f32_16x16x32_bf16 v[78:81], v[182:185], v[206:209], v[78:81]
	v_mfma_f32_16x16x32_bf16 v[70:73], v[174:177], v[218:221], v[70:73]
	v_mfma_f32_16x16x32_bf16 v[66:69], v[182:185], v[218:221], v[66:69]
	s_barrier
	s_setprio 0
	s_add_i32 s62, s56, s12
	v_lshl_add_u64 v[146:147], s[34:35], 0, v[134:135]
	s_mov_b32 m0, s62
	ds_read_b128 v[186:189], v153 offset:16384
	ds_read_b128 v[190:193], v153 offset:17408
	ds_read_b128 v[194:197], v153 offset:18432
	ds_read_b128 v[198:201], v153 offset:19456
	ds_read_b128 v[202:205], v153 offset:20480
	ds_read_b128 v[206:209], v153 offset:21504
	ds_read_b128 v[210:213], v153 offset:22528
	ds_read_b128 v[218:221], v153 offset:23552
	global_load_lds_dwordx4 v[146:147], off
	s_add_i32 m0, s62, 0x2000
	s_add_u32 s62, s34, 0x80000
	v_lshl_add_u64 v[214:215], s[34:35], 0, v[130:131]
	s_addc_u32 s63, s35, 0
	s_add_i32 s66, s57, s12
	global_load_lds_dwordx4 v[214:215], off
	v_lshl_add_u64 v[222:223], s[62:63], 0, v[134:135]
	s_mov_b32 m0, s66
	v_lshl_add_u64 v[224:225], s[46:47], 0, v[132:133]
	global_load_lds_dwordx4 v[222:223], off
	v_lshl_add_u64 v[222:223], s[62:63], 0, v[130:131]
	s_add_i32 m0, s66, 0x2000
	s_nop 0
	global_load_lds_dwordx4 v[222:223], off
	v_lshl_add_u64 v[222:223], s[46:47], 0, v[136:137]
	s_mov_b32 m0, s33
	s_nop 0
	global_load_lds_dwordx4 v[222:223], off
	s_mov_b32 m0, s43
	s_nop 0
	global_load_lds_dwordx4 v[224:225], off
	s_waitcnt vmcnt(8)
	s_waitcnt lgkmcnt(0)
	s_setprio 1
	s_barrier
	v_mfma_f32_16x16x32_bf16 v[62:65], v[154:157], v[186:189], v[62:65]
	v_mfma_f32_16x16x32_bf16 v[58:61], v[162:165], v[186:189], v[58:61]
	v_mfma_f32_16x16x32_bf16 v[50:53], v[154:157], v[194:197], v[50:53]
	v_mfma_f32_16x16x32_bf16 v[42:45], v[162:165], v[194:197], v[42:45]
	v_mfma_f32_16x16x32_bf16 v[34:37], v[154:157], v[202:205], v[34:37]
	v_mfma_f32_16x16x32_bf16 v[26:29], v[162:165], v[202:205], v[26:29]
	v_mfma_f32_16x16x32_bf16 v[18:21], v[154:157], v[210:213], v[18:21]
	v_mfma_f32_16x16x32_bf16 v[10:13], v[162:165], v[210:213], v[10:13]
	v_mfma_f32_16x16x32_bf16 v[62:65], v[158:161], v[190:193], v[62:65]
	v_mfma_f32_16x16x32_bf16 v[58:61], v[166:169], v[190:193], v[58:61]
	v_mfma_f32_16x16x32_bf16 v[50:53], v[158:161], v[198:201], v[50:53]
	v_mfma_f32_16x16x32_bf16 v[42:45], v[166:169], v[198:201], v[42:45]
	v_mfma_f32_16x16x32_bf16 v[34:37], v[158:161], v[206:209], v[34:37]
	v_mfma_f32_16x16x32_bf16 v[26:29], v[166:169], v[206:209], v[26:29]
	v_mfma_f32_16x16x32_bf16 v[18:21], v[158:161], v[218:221], v[18:21]
	v_mfma_f32_16x16x32_bf16 v[10:13], v[166:169], v[218:221], v[10:13]
	s_setprio 0
	s_setprio 1
	v_mfma_f32_16x16x32_bf16 v[54:57], v[170:173], v[186:189], v[54:57]
	v_mfma_f32_16x16x32_bf16 v[46:49], v[178:181], v[186:189], v[46:49]
	v_mfma_f32_16x16x32_bf16 v[38:41], v[170:173], v[194:197], v[38:41]
	v_mfma_f32_16x16x32_bf16 v[30:33], v[178:181], v[194:197], v[30:33]
	v_mfma_f32_16x16x32_bf16 v[22:25], v[170:173], v[202:205], v[22:25]
	v_mfma_f32_16x16x32_bf16 v[14:17], v[178:181], v[202:205], v[14:17]
	v_mfma_f32_16x16x32_bf16 v[6:9], v[170:173], v[210:213], v[6:9]
	v_mfma_f32_16x16x32_bf16 v[2:5], v[178:181], v[210:213], v[2:5]
	v_mfma_f32_16x16x32_bf16 v[54:57], v[174:177], v[190:193], v[54:57]
	v_mfma_f32_16x16x32_bf16 v[46:49], v[182:185], v[190:193], v[46:49]
	v_mfma_f32_16x16x32_bf16 v[38:41], v[174:177], v[198:201], v[38:41]
	v_mfma_f32_16x16x32_bf16 v[30:33], v[182:185], v[198:201], v[30:33]
	v_mfma_f32_16x16x32_bf16 v[22:25], v[174:177], v[206:209], v[22:25]
	v_mfma_f32_16x16x32_bf16 v[14:17], v[182:185], v[206:209], v[14:17]
	v_mfma_f32_16x16x32_bf16 v[6:9], v[174:177], v[218:221], v[6:9]
	v_mfma_f32_16x16x32_bf16 v[2:5], v[182:185], v[218:221], v[2:5]
	s_barrier
	s_setprio 0
	s_add_i32 s62, 0, 0x18000
	s_add_i32 s63, 0, 0x1c000
	v_add_u32_e32 v166, s62, v149
	v_add_u32_e32 v182, s63, v149
	ds_read_b128 v[154:157], v166
	ds_read_b128 v[158:161], v166 offset:1024
	ds_read_b128 v[162:165], v166 offset:2048
	ds_read_b128 v[166:169], v166 offset:3072
	ds_read_b128 v[170:173], v182
	ds_read_b128 v[174:177], v182 offset:1024
	ds_read_b128 v[178:181], v182 offset:2048
	ds_read_b128 v[182:185], v182 offset:3072
	s_add_u32 s46, s46, 0x80000
	s_addc_u32 s47, s47, 0
	s_mov_b32 m0, s48
	v_lshl_add_u64 v[226:227], s[46:47], 0, v[136:137]
	ds_read_b128 v[186:189], v153 offset:32768
	ds_read_b128 v[190:193], v153 offset:33792
	ds_read_b128 v[194:197], v153 offset:34816
	ds_read_b128 v[198:201], v153 offset:35840
	ds_read_b128 v[202:205], v153 offset:36864
	ds_read_b128 v[206:209], v153 offset:37888
	ds_read_b128 v[210:213], v153 offset:38912
	ds_read_b128 v[218:221], v153 offset:39936
	global_load_lds_dwordx4 v[226:227], off
	v_lshl_add_u64 v[226:227], s[46:47], 0, v[132:133]
	s_mov_b32 m0, s49
	s_nop 0
	global_load_lds_dwordx4 v[226:227], off
	s_waitcnt vmcnt(8)
	s_waitcnt lgkmcnt(0)
	s_setprio 1
	s_barrier
	v_mfma_f32_16x16x32_bf16 v[126:129], v[154:157], v[186:189], v[126:129]
	v_mfma_f32_16x16x32_bf16 v[122:125], v[162:165], v[186:189], v[122:125]
	v_mfma_f32_16x16x32_bf16 v[114:117], v[154:157], v[194:197], v[114:117]
	v_mfma_f32_16x16x32_bf16 v[106:109], v[162:165], v[194:197], v[106:109]
	v_mfma_f32_16x16x32_bf16 v[98:101], v[154:157], v[202:205], v[98:101]
	v_mfma_f32_16x16x32_bf16 v[90:93], v[162:165], v[202:205], v[90:93]
	v_mfma_f32_16x16x32_bf16 v[82:85], v[154:157], v[210:213], v[82:85]
	v_mfma_f32_16x16x32_bf16 v[74:77], v[162:165], v[210:213], v[74:77]
	v_mfma_f32_16x16x32_bf16 v[126:129], v[158:161], v[190:193], v[126:129]
	v_mfma_f32_16x16x32_bf16 v[122:125], v[166:169], v[190:193], v[122:125]
	v_mfma_f32_16x16x32_bf16 v[114:117], v[158:161], v[198:201], v[114:117]
	v_mfma_f32_16x16x32_bf16 v[106:109], v[166:169], v[198:201], v[106:109]
	v_mfma_f32_16x16x32_bf16 v[98:101], v[158:161], v[206:209], v[98:101]
	v_mfma_f32_16x16x32_bf16 v[90:93], v[166:169], v[206:209], v[90:93]
	v_mfma_f32_16x16x32_bf16 v[82:85], v[158:161], v[218:221], v[82:85]
	v_mfma_f32_16x16x32_bf16 v[74:77], v[166:169], v[218:221], v[74:77]
	s_setprio 0
	s_setprio 1
	v_mfma_f32_16x16x32_bf16 v[118:121], v[170:173], v[186:189], v[118:121]
	v_mfma_f32_16x16x32_bf16 v[110:113], v[178:181], v[186:189], v[110:113]
	v_mfma_f32_16x16x32_bf16 v[102:105], v[170:173], v[194:197], v[102:105]
	v_mfma_f32_16x16x32_bf16 v[94:97], v[178:181], v[194:197], v[94:97]
	v_mfma_f32_16x16x32_bf16 v[86:89], v[170:173], v[202:205], v[86:89]
	v_mfma_f32_16x16x32_bf16 v[78:81], v[178:181], v[202:205], v[78:81]
	v_mfma_f32_16x16x32_bf16 v[70:73], v[170:173], v[210:213], v[70:73]
	v_mfma_f32_16x16x32_bf16 v[66:69], v[178:181], v[210:213], v[66:69]
	v_mfma_f32_16x16x32_bf16 v[118:121], v[174:177], v[190:193], v[118:121]
	v_mfma_f32_16x16x32_bf16 v[110:113], v[182:185], v[190:193], v[110:113]
	v_mfma_f32_16x16x32_bf16 v[102:105], v[174:177], v[198:201], v[102:105]
	v_mfma_f32_16x16x32_bf16 v[94:97], v[182:185], v[198:201], v[94:97]
	v_mfma_f32_16x16x32_bf16 v[86:89], v[174:177], v[206:209], v[86:89]
	v_mfma_f32_16x16x32_bf16 v[78:81], v[182:185], v[206:209], v[78:81]
	v_mfma_f32_16x16x32_bf16 v[70:73], v[174:177], v[218:221], v[70:73]
	v_mfma_f32_16x16x32_bf16 v[66:69], v[182:185], v[218:221], v[66:69]
	s_barrier
	s_setprio 0
	s_add_i32 s46, s62, s12
	v_lshl_add_u64 v[146:147], v[146:147], 0, s[8:9]
	s_mov_b32 m0, s46
	ds_read_b128 v[186:189], v153 offset:49152
	ds_read_b128 v[190:193], v153 offset:50176
	ds_read_b128 v[194:197], v153 offset:51200
	ds_read_b128 v[198:201], v153 offset:52224
	ds_read_b128 v[202:205], v153 offset:53248
	ds_read_b128 v[206:209], v153 offset:54272
	ds_read_b128 v[210:213], v153 offset:55296
	ds_read_b128 v[218:221], v153 offset:56320
	global_load_lds_dwordx4 v[146:147], off
	s_add_i32 m0, s46, 0x2000
	s_add_u32 s34, s34, 0x80080
	v_lshl_add_u64 v[146:147], v[214:215], 0, s[8:9]
	s_addc_u32 s35, s35, 0
	s_add_i32 s46, s63, s12
	global_load_lds_dwordx4 v[146:147], off
	v_lshl_add_u64 v[146:147], s[34:35], 0, v[134:135]
	s_mov_b32 m0, s46
	s_nop 0
	global_load_lds_dwordx4 v[146:147], off
	v_lshl_add_u64 v[146:147], s[34:35], 0, v[130:131]
	s_add_i32 m0, s46, 0x2000
	s_nop 0
	global_load_lds_dwordx4 v[146:147], off
	v_lshl_add_u64 v[146:147], v[222:223], 0, s[8:9]
	s_mov_b32 m0, s53
	s_nop 0
	global_load_lds_dwordx4 v[146:147], off
	v_lshl_add_u64 v[146:147], v[224:225], 0, s[8:9]
	s_mov_b32 m0, s54
	s_nop 0
	global_load_lds_dwordx4 v[146:147], off
	s_waitcnt vmcnt(8)
	s_waitcnt lgkmcnt(0)
	s_setprio 1
	s_barrier
	v_mfma_f32_16x16x32_bf16 v[62:65], v[154:157], v[186:189], v[62:65]
	v_mfma_f32_16x16x32_bf16 v[58:61], v[162:165], v[186:189], v[58:61]
	v_mfma_f32_16x16x32_bf16 v[50:53], v[154:157], v[194:197], v[50:53]
	v_mfma_f32_16x16x32_bf16 v[42:45], v[162:165], v[194:197], v[42:45]
	v_mfma_f32_16x16x32_bf16 v[34:37], v[154:157], v[202:205], v[34:37]
	v_mfma_f32_16x16x32_bf16 v[26:29], v[162:165], v[202:205], v[26:29]
	v_mfma_f32_16x16x32_bf16 v[18:21], v[154:157], v[210:213], v[18:21]
	v_mfma_f32_16x16x32_bf16 v[10:13], v[162:165], v[210:213], v[10:13]
	v_mfma_f32_16x16x32_bf16 v[62:65], v[158:161], v[190:193], v[62:65]
	v_mfma_f32_16x16x32_bf16 v[58:61], v[166:169], v[190:193], v[58:61]
	v_mfma_f32_16x16x32_bf16 v[50:53], v[158:161], v[198:201], v[50:53]
	v_mfma_f32_16x16x32_bf16 v[42:45], v[166:169], v[198:201], v[42:45]
	v_mfma_f32_16x16x32_bf16 v[34:37], v[158:161], v[206:209], v[34:37]
	v_mfma_f32_16x16x32_bf16 v[26:29], v[166:169], v[206:209], v[26:29]
	v_mfma_f32_16x16x32_bf16 v[18:21], v[158:161], v[218:221], v[18:21]
	v_mfma_f32_16x16x32_bf16 v[10:13], v[166:169], v[218:221], v[10:13]
	s_setprio 0
	s_setprio 1
	v_mfma_f32_16x16x32_bf16 v[54:57], v[170:173], v[186:189], v[54:57]
	v_mfma_f32_16x16x32_bf16 v[46:49], v[178:181], v[186:189], v[46:49]
	v_mfma_f32_16x16x32_bf16 v[38:41], v[170:173], v[194:197], v[38:41]
	v_mfma_f32_16x16x32_bf16 v[30:33], v[178:181], v[194:197], v[30:33]
	v_mfma_f32_16x16x32_bf16 v[22:25], v[170:173], v[202:205], v[22:25]
	v_mfma_f32_16x16x32_bf16 v[14:17], v[178:181], v[202:205], v[14:17]
	v_mfma_f32_16x16x32_bf16 v[6:9], v[170:173], v[210:213], v[6:9]
	v_mfma_f32_16x16x32_bf16 v[2:5], v[178:181], v[210:213], v[2:5]
	v_mfma_f32_16x16x32_bf16 v[54:57], v[174:177], v[190:193], v[54:57]
	v_mfma_f32_16x16x32_bf16 v[46:49], v[182:185], v[190:193], v[46:49]
	v_mfma_f32_16x16x32_bf16 v[38:41], v[174:177], v[198:201], v[38:41]
	v_mfma_f32_16x16x32_bf16 v[30:33], v[182:185], v[198:201], v[30:33]
	v_mfma_f32_16x16x32_bf16 v[22:25], v[174:177], v[206:209], v[22:25]
	v_mfma_f32_16x16x32_bf16 v[14:17], v[182:185], v[206:209], v[14:17]
	v_mfma_f32_16x16x32_bf16 v[6:9], v[174:177], v[218:221], v[6:9]
	v_mfma_f32_16x16x32_bf16 v[2:5], v[182:185], v[218:221], v[2:5]
	s_barrier
	s_setprio 0
	s_add_i32 s68, s68, 2
	s_add_u32 s44, s44, 0x100
	s_addc_u32 s45, s45, 0
	s_add_u32 s60, s60, 0x100
	s_addc_u32 s61, s61, 0
	s_cmp_gt_u32 s68, 29
	s_cbranch_scc0 .LBB0_3533
	s_and_b64 vcc, exec, s[24:25]
	s_cbranch_vccz .LBB0_3536
	s_barrier

.LBB0_3706:
	ds_read_b128 v[130:133], v174
	ds_read_b128 v[134:137], v174 offset:1024
	ds_read_b128 v[138:141], v174 offset:2048
	ds_read_b128 v[158:161], v174 offset:3072
	ds_read_b128 v[162:165], v175
	ds_read_b128 v[166:169], v175 offset:1024
	ds_read_b128 v[178:181], v175 offset:2048
	ds_read_b128 v[182:185], v175 offset:3072
	s_add_u32 s34, s42, 0xfff80080
	s_addc_u32 s35, s43, -1
	s_cmp_eq_u32 s60, 28
	s_cselect_b32 s45, s0, s35
	s_cselect_b32 s44, s1, s34
	s_cselect_b32 s35, s25, s59
	s_cselect_b32 s34, s27, s58
	v_lshl_add_u64 v[170:171], s[42:43], 0, v[150:151]
	s_add_i32 m0, s41, 0xc000
	ds_read_b128 v[186:189], v176
	ds_read_b128 v[190:193], v176 offset:1024
	ds_read_b128 v[194:197], v176 offset:2048
	ds_read_b128 v[198:201], v176 offset:3072
	ds_read_b128 v[202:205], v176 offset:4096
	ds_read_b128 v[206:209], v176 offset:5120
	ds_read_b128 v[210:213], v176 offset:6144
	ds_read_b128 v[218:221], v176 offset:7168
	global_load_lds_dwordx4 v[170:171], off
	v_lshl_add_u64 v[170:171], s[42:43], 0, v[152:153]
	s_add_i32 m0, s41, 0xe000
	s_nop 0
	global_load_lds_dwordx4 v[170:171], off
	s_waitcnt vmcnt(8)
	s_waitcnt lgkmcnt(0)
	s_setprio 1
	s_barrier
	v_mfma_f32_16x16x32_bf16 v[126:129], v[130:133], v[186:189], v[126:129]
	v_mfma_f32_16x16x32_bf16 v[122:125], v[138:141], v[186:189], v[122:125]
	v_mfma_f32_16x16x32_bf16 v[110:113], v[130:133], v[194:197], v[110:113]
	v_mfma_f32_16x16x32_bf16 v[106:109], v[138:141], v[194:197], v[106:109]
	v_mfma_f32_16x16x32_bf16 v[94:97], v[130:133], v[202:205], v[94:97]
	v_mfma_f32_16x16x32_bf16 v[90:93], v[138:141], v[202:205], v[90:93]
	v_mfma_f32_16x16x32_bf16 v[78:81], v[130:133], v[210:213], v[78:81]
	v_mfma_f32_16x16x32_bf16 v[74:77], v[138:141], v[210:213], v[74:77]
	v_mfma_f32_16x16x32_bf16 v[126:129], v[134:137], v[190:193], v[126:129]
	v_mfma_f32_16x16x32_bf16 v[122:125], v[158:161], v[190:193], v[122:125]
	v_mfma_f32_16x16x32_bf16 v[110:113], v[134:137], v[198:201], v[110:113]
	v_mfma_f32_16x16x32_bf16 v[106:109], v[158:161], v[198:201], v[106:109]
	v_mfma_f32_16x16x32_bf16 v[94:97], v[134:137], v[206:209], v[94:97]
	v_mfma_f32_16x16x32_bf16 v[90:93], v[158:161], v[206:209], v[90:93]
	v_mfma_f32_16x16x32_bf16 v[78:81], v[134:137], v[218:221], v[78:81]
	v_mfma_f32_16x16x32_bf16 v[74:77], v[158:161], v[218:221], v[74:77]
	s_setprio 0
	s_setprio 1
	v_mfma_f32_16x16x32_bf16 v[118:121], v[162:165], v[186:189], v[118:121]
	v_mfma_f32_16x16x32_bf16 v[114:117], v[178:181], v[186:189], v[114:117]
	v_mfma_f32_16x16x32_bf16 v[102:105], v[162:165], v[194:197], v[102:105]
	v_mfma_f32_16x16x32_bf16 v[98:101], v[178:181], v[194:197], v[98:101]
	v_mfma_f32_16x16x32_bf16 v[86:89], v[162:165], v[202:205], v[86:89]
	v_mfma_f32_16x16x32_bf16 v[82:85], v[178:181], v[202:205], v[82:85]
	v_mfma_f32_16x16x32_bf16 v[70:73], v[162:165], v[210:213], v[70:73]
	v_mfma_f32_16x16x32_bf16 v[66:69], v[178:181], v[210:213], v[66:69]
	v_mfma_f32_16x16x32_bf16 v[118:121], v[166:169], v[190:193], v[118:121]
	v_mfma_f32_16x16x32_bf16 v[114:117], v[182:185], v[190:193], v[114:117]
	v_mfma_f32_16x16x32_bf16 v[102:105], v[166:169], v[198:201], v[102:105]
	v_mfma_f32_16x16x32_bf16 v[98:101], v[182:185], v[198:201], v[98:101]
	v_mfma_f32_16x16x32_bf16 v[86:89], v[166:169], v[206:209], v[86:89]
	v_mfma_f32_16x16x32_bf16 v[82:85], v[182:185], v[206:209], v[82:85]
	v_mfma_f32_16x16x32_bf16 v[70:73], v[166:169], v[218:221], v[70:73]
	v_mfma_f32_16x16x32_bf16 v[66:69], v[182:185], v[218:221], v[66:69]
	s_barrier
	s_setprio 0
	s_add_i32 s61, s54, s46
	v_lshl_add_u64 v[170:171], s[34:35], 0, v[144:145]
	s_mov_b32 m0, s61
	ds_read_b128 v[186:189], v176 offset:16384
	ds_read_b128 v[190:193], v176 offset:17408
	ds_read_b128 v[194:197], v176 offset:18432
	ds_read_b128 v[198:201], v176 offset:19456
	ds_read_b128 v[202:205], v176 offset:20480
	ds_read_b128 v[206:209], v176 offset:21504
	ds_read_b128 v[210:213], v176 offset:22528
	ds_read_b128 v[218:221], v176 offset:23552
	global_load_lds_dwordx4 v[170:171], off
	s_add_i32 m0, s61, 0x2000
	s_add_u32 s62, s34, 0x80000
	v_lshl_add_u64 v[214:215], s[34:35], 0, v[148:149]
	s_addc_u32 s63, s35, 0
	s_add_i32 s61, s55, s46
	global_load_lds_dwordx4 v[214:215], off
	v_lshl_add_u64 v[222:223], s[62:63], 0, v[144:145]
	s_mov_b32 m0, s61
	v_lshl_add_u64 v[224:225], s[44:45], 0, v[146:147]
	global_load_lds_dwordx4 v[222:223], off
	v_lshl_add_u64 v[222:223], s[62:63], 0, v[148:149]
	s_add_i32 m0, s61, 0x2000
	s_nop 0
	global_load_lds_dwordx4 v[222:223], off
	v_lshl_add_u64 v[222:223], s[44:45], 0, v[142:143]
	s_mov_b32 m0, s41
	s_nop 0
	global_load_lds_dwordx4 v[222:223], off
	s_mov_b32 m0, s47
	s_nop 0
	global_load_lds_dwordx4 v[224:225], off
	s_waitcnt vmcnt(8)
	s_waitcnt lgkmcnt(0)
	s_setprio 1
	s_barrier
	v_mfma_f32_16x16x32_bf16 v[62:65], v[130:133], v[186:189], v[62:65]
	v_mfma_f32_16x16x32_bf16 v[58:61], v[138:141], v[186:189], v[58:61]
	v_mfma_f32_16x16x32_bf16 v[50:53], v[130:133], v[194:197], v[50:53]
	v_mfma_f32_16x16x32_bf16 v[42:45], v[138:141], v[194:197], v[42:45]
	v_mfma_f32_16x16x32_bf16 v[38:41], v[130:133], v[202:205], v[38:41]
	v_mfma_f32_16x16x32_bf16 v[34:37], v[138:141], v[202:205], v[34:37]
	v_mfma_f32_16x16x32_bf16 v[14:17], v[130:133], v[210:213], v[14:17]
	v_mfma_f32_16x16x32_bf16 v[10:13], v[138:141], v[210:213], v[10:13]
	v_mfma_f32_16x16x32_bf16 v[62:65], v[134:137], v[190:193], v[62:65]
	v_mfma_f32_16x16x32_bf16 v[58:61], v[158:161], v[190:193], v[58:61]
	v_mfma_f32_16x16x32_bf16 v[50:53], v[134:137], v[198:201], v[50:53]
	v_mfma_f32_16x16x32_bf16 v[42:45], v[158:161], v[198:201], v[42:45]
	v_mfma_f32_16x16x32_bf16 v[38:41], v[134:137], v[206:209], v[38:41]
	v_mfma_f32_16x16x32_bf16 v[34:37], v[158:161], v[206:209], v[34:37]
	v_mfma_f32_16x16x32_bf16 v[14:17], v[134:137], v[218:221], v[14:17]
	v_mfma_f32_16x16x32_bf16 v[10:13], v[158:161], v[218:221], v[10:13]
	s_setprio 0
	s_setprio 1
	v_mfma_f32_16x16x32_bf16 v[54:57], v[162:165], v[186:189], v[54:57]
	v_mfma_f32_16x16x32_bf16 v[46:49], v[178:181], v[186:189], v[46:49]
	v_mfma_f32_16x16x32_bf16 v[30:33], v[162:165], v[194:197], v[30:33]
	v_mfma_f32_16x16x32_bf16 v[26:29], v[178:181], v[194:197], v[26:29]
	v_mfma_f32_16x16x32_bf16 v[22:25], v[162:165], v[202:205], v[22:25]
	v_mfma_f32_16x16x32_bf16 v[18:21], v[178:181], v[202:205], v[18:21]
	v_mfma_f32_16x16x32_bf16 v[6:9], v[162:165], v[210:213], v[6:9]
	v_mfma_f32_16x16x32_bf16 v[2:5], v[178:181], v[210:213], v[2:5]
	v_mfma_f32_16x16x32_bf16 v[54:57], v[166:169], v[190:193], v[54:57]
	v_mfma_f32_16x16x32_bf16 v[46:49], v[182:185], v[190:193], v[46:49]
	v_mfma_f32_16x16x32_bf16 v[30:33], v[166:169], v[198:201], v[30:33]
	v_mfma_f32_16x16x32_bf16 v[26:29], v[182:185], v[198:201], v[26:29]
	v_mfma_f32_16x16x32_bf16 v[22:25], v[166:169], v[206:209], v[22:25]
	v_mfma_f32_16x16x32_bf16 v[18:21], v[182:185], v[206:209], v[18:21]
	v_mfma_f32_16x16x32_bf16 v[6:9], v[166:169], v[218:221], v[6:9]
	v_mfma_f32_16x16x32_bf16 v[2:5], v[182:185], v[218:221], v[2:5]
	s_barrier
	s_setprio 0
	s_add_i32 s61, 0, 0x18000
	s_add_i32 s62, 0, 0x1c000
	v_add_u32_e32 v158, s61, v172
	v_add_u32_e32 v177, s62, v172
	ds_read_b128 v[130:133], v158
	ds_read_b128 v[134:137], v158 offset:1024
	ds_read_b128 v[138:141], v158 offset:2048
	ds_read_b128 v[158:161], v158 offset:3072
	ds_read_b128 v[162:165], v177
	ds_read_b128 v[166:169], v177 offset:1024
	ds_read_b128 v[178:181], v177 offset:2048
	ds_read_b128 v[182:185], v177 offset:3072
	s_add_u32 s44, s44, 0x80000
	s_addc_u32 s45, s45, 0
	s_mov_b32 m0, s48
	v_lshl_add_u64 v[226:227], s[44:45], 0, v[142:143]
	ds_read_b128 v[186:189], v176 offset:32768
	ds_read_b128 v[190:193], v176 offset:33792
	ds_read_b128 v[194:197], v176 offset:34816
	ds_read_b128 v[198:201], v176 offset:35840
	ds_read_b128 v[202:205], v176 offset:36864
	ds_read_b128 v[206:209], v176 offset:37888
	ds_read_b128 v[210:213], v176 offset:38912
	ds_read_b128 v[218:221], v176 offset:39936
	global_load_lds_dwordx4 v[226:227], off
	v_lshl_add_u64 v[226:227], s[44:45], 0, v[146:147]
	s_mov_b32 m0, s49
	s_nop 0
	global_load_lds_dwordx4 v[226:227], off
	s_waitcnt vmcnt(8)
	s_waitcnt lgkmcnt(0)
	s_setprio 1
	s_barrier
	v_mfma_f32_16x16x32_bf16 v[126:129], v[130:133], v[186:189], v[126:129]
	v_mfma_f32_16x16x32_bf16 v[122:125], v[138:141], v[186:189], v[122:125]
	v_mfma_f32_16x16x32_bf16 v[110:113], v[130:133], v[194:197], v[110:113]
	v_mfma_f32_16x16x32_bf16 v[106:109], v[138:141], v[194:197], v[106:109]
	v_mfma_f32_16x16x32_bf16 v[94:97], v[130:133], v[202:205], v[94:97]
	v_mfma_f32_16x16x32_bf16 v[90:93], v[138:141], v[202:205], v[90:93]
	v_mfma_f32_16x16x32_bf16 v[78:81], v[130:133], v[210:213], v[78:81]
	v_mfma_f32_16x16x32_bf16 v[74:77], v[138:141], v[210:213], v[74:77]
	v_mfma_f32_16x16x32_bf16 v[126:129], v[134:137], v[190:193], v[126:129]
	v_mfma_f32_16x16x32_bf16 v[122:125], v[158:161], v[190:193], v[122:125]
	v_mfma_f32_16x16x32_bf16 v[110:113], v[134:137], v[198:201], v[110:113]
	v_mfma_f32_16x16x32_bf16 v[106:109], v[158:161], v[198:201], v[106:109]
	v_mfma_f32_16x16x32_bf16 v[94:97], v[134:137], v[206:209], v[94:97]
	v_mfma_f32_16x16x32_bf16 v[90:93], v[158:161], v[206:209], v[90:93]
	v_mfma_f32_16x16x32_bf16 v[78:81], v[134:137], v[218:221], v[78:81]
	v_mfma_f32_16x16x32_bf16 v[74:77], v[158:161], v[218:221], v[74:77]
	s_setprio 0
	s_setprio 1
	v_mfma_f32_16x16x32_bf16 v[118:121], v[162:165], v[186:189], v[118:121]
	v_mfma_f32_16x16x32_bf16 v[114:117], v[178:181], v[186:189], v[114:117]
	v_mfma_f32_16x16x32_bf16 v[102:105], v[162:165], v[194:197], v[102:105]
	v_mfma_f32_16x16x32_bf16 v[98:101], v[178:181], v[194:197], v[98:101]
	v_mfma_f32_16x16x32_bf16 v[86:89], v[162:165], v[202:205], v[86:89]
	v_mfma_f32_16x16x32_bf16 v[82:85], v[178:181], v[202:205], v[82:85]
	v_mfma_f32_16x16x32_bf16 v[70:73], v[162:165], v[210:213], v[70:73]
	v_mfma_f32_16x16x32_bf16 v[66:69], v[178:181], v[210:213], v[66:69]
	v_mfma_f32_16x16x32_bf16 v[118:121], v[166:169], v[190:193], v[118:121]
	v_mfma_f32_16x16x32_bf16 v[114:117], v[182:185], v[190:193], v[114:117]
	v_mfma_f32_16x16x32_bf16 v[102:105], v[166:169], v[198:201], v[102:105]
	v_mfma_f32_16x16x32_bf16 v[98:101], v[182:185], v[198:201], v[98:101]
	v_mfma_f32_16x16x32_bf16 v[86:89], v[166:169], v[206:209], v[86:89]
	v_mfma_f32_16x16x32_bf16 v[82:85], v[182:185], v[206:209], v[82:85]
	v_mfma_f32_16x16x32_bf16 v[70:73], v[166:169], v[218:221], v[70:73]
	v_mfma_f32_16x16x32_bf16 v[66:69], v[182:185], v[218:221], v[66:69]
	s_barrier
	s_setprio 0
	s_add_i32 s44, s61, s46
	v_lshl_add_u64 v[170:171], v[170:171], 0, s[12:13]
	s_mov_b32 m0, s44
	ds_read_b128 v[186:189], v176 offset:49152
	ds_read_b128 v[190:193], v176 offset:50176
	ds_read_b128 v[194:197], v176 offset:51200
	ds_read_b128 v[198:201], v176 offset:52224
	ds_read_b128 v[202:205], v176 offset:53248
	ds_read_b128 v[206:209], v176 offset:54272
	ds_read_b128 v[210:213], v176 offset:55296
	ds_read_b128 v[218:221], v176 offset:56320
	global_load_lds_dwordx4 v[170:171], off
	s_add_i32 m0, s44, 0x2000
	s_add_u32 s34, s34, 0x80080
	v_lshl_add_u64 v[170:171], v[214:215], 0, s[12:13]
	s_addc_u32 s35, s35, 0
	s_add_i32 s44, s62, s46
	global_load_lds_dwordx4 v[170:171], off
	v_lshl_add_u64 v[170:171], s[34:35], 0, v[144:145]
	s_mov_b32 m0, s44
	s_nop 0
	global_load_lds_dwordx4 v[170:171], off
	v_lshl_add_u64 v[170:171], s[34:35], 0, v[148:149]
	s_add_i32 m0, s44, 0x2000
	s_nop 0
	global_load_lds_dwordx4 v[170:171], off
	v_lshl_add_u64 v[170:171], v[222:223], 0, s[12:13]
	s_mov_b32 m0, s51
	s_nop 0
	global_load_lds_dwordx4 v[170:171], off
	v_lshl_add_u64 v[170:171], v[224:225], 0, s[12:13]
	s_mov_b32 m0, s52
	s_nop 0
	global_load_lds_dwordx4 v[170:171], off
	s_waitcnt vmcnt(8)
	s_waitcnt lgkmcnt(0)
	s_setprio 1
	s_barrier
	v_mfma_f32_16x16x32_bf16 v[62:65], v[130:133], v[186:189], v[62:65]
	v_mfma_f32_16x16x32_bf16 v[58:61], v[138:141], v[186:189], v[58:61]
	v_mfma_f32_16x16x32_bf16 v[50:53], v[130:133], v[194:197], v[50:53]
	v_mfma_f32_16x16x32_bf16 v[42:45], v[138:141], v[194:197], v[42:45]
	v_mfma_f32_16x16x32_bf16 v[38:41], v[130:133], v[202:205], v[38:41]
	v_mfma_f32_16x16x32_bf16 v[34:37], v[138:141], v[202:205], v[34:37]
	v_mfma_f32_16x16x32_bf16 v[14:17], v[130:133], v[210:213], v[14:17]
	v_mfma_f32_16x16x32_bf16 v[10:13], v[138:141], v[210:213], v[10:13]
	v_mfma_f32_16x16x32_bf16 v[62:65], v[134:137], v[190:193], v[62:65]
	v_mfma_f32_16x16x32_bf16 v[58:61], v[158:161], v[190:193], v[58:61]
	v_mfma_f32_16x16x32_bf16 v[50:53], v[134:137], v[198:201], v[50:53]
	v_mfma_f32_16x16x32_bf16 v[42:45], v[158:161], v[198:201], v[42:45]
	v_mfma_f32_16x16x32_bf16 v[38:41], v[134:137], v[206:209], v[38:41]
	v_mfma_f32_16x16x32_bf16 v[34:37], v[158:161], v[206:209], v[34:37]
	v_mfma_f32_16x16x32_bf16 v[14:17], v[134:137], v[218:221], v[14:17]
	v_mfma_f32_16x16x32_bf16 v[10:13], v[158:161], v[218:221], v[10:13]
	s_setprio 0
	s_setprio 1
	v_mfma_f32_16x16x32_bf16 v[54:57], v[162:165], v[186:189], v[54:57]
	v_mfma_f32_16x16x32_bf16 v[46:49], v[178:181], v[186:189], v[46:49]
	v_mfma_f32_16x16x32_bf16 v[30:33], v[162:165], v[194:197], v[30:33]
	v_mfma_f32_16x16x32_bf16 v[26:29], v[178:181], v[194:197], v[26:29]
	v_mfma_f32_16x16x32_bf16 v[22:25], v[162:165], v[202:205], v[22:25]
	v_mfma_f32_16x16x32_bf16 v[18:21], v[178:181], v[202:205], v[18:21]
	v_mfma_f32_16x16x32_bf16 v[6:9], v[162:165], v[210:213], v[6:9]
	v_mfma_f32_16x16x32_bf16 v[2:5], v[178:181], v[210:213], v[2:5]
	v_mfma_f32_16x16x32_bf16 v[54:57], v[166:169], v[190:193], v[54:57]
	v_mfma_f32_16x16x32_bf16 v[46:49], v[182:185], v[190:193], v[46:49]
	v_mfma_f32_16x16x32_bf16 v[30:33], v[166:169], v[198:201], v[30:33]
	v_mfma_f32_16x16x32_bf16 v[26:29], v[182:185], v[198:201], v[26:29]
	v_mfma_f32_16x16x32_bf16 v[22:25], v[166:169], v[206:209], v[22:25]
	v_mfma_f32_16x16x32_bf16 v[18:21], v[182:185], v[206:209], v[18:21]
	v_mfma_f32_16x16x32_bf16 v[6:9], v[166:169], v[218:221], v[6:9]
	v_mfma_f32_16x16x32_bf16 v[2:5], v[182:185], v[218:221], v[2:5]
	s_barrier
	s_setprio 0
	s_add_i32 s60, s60, 2
	s_add_u32 s42, s42, 0x100
	s_addc_u32 s43, s43, 0
	s_add_u32 s58, s58, 0x100
	s_addc_u32 s59, s59, 0
	s_cmp_gt_u32 s60, 29
	s_cbranch_scc0 .LBB0_3706
	s_and_b64 vcc, exec, s[14:15]
	s_cbranch_vccz .LBB0_3709
	s_barrier

.LBB0_3835:
	ds_read_b128 v[146:149], v153
	ds_read_b128 v[156:159], v153 offset:1024
	ds_read_b128 v[160:163], v153 offset:2048
	ds_read_b128 v[164:167], v153 offset:3072
	ds_read_b128 v[168:171], v154
	ds_read_b128 v[172:175], v154 offset:1024
	ds_read_b128 v[176:179], v154 offset:2048
	ds_read_b128 v[180:183], v154 offset:3072
	s_add_u32 s34, s38, 0xfff80080
	s_addc_u32 s35, s39, -1
	s_cmp_eq_u32 s57, 28
	s_cselect_b32 s41, s0, s35
	s_cselect_b32 s40, s1, s34
	s_cselect_b32 s35, s15, s56
	s_cselect_b32 s34, s17, s55
	v_lshl_add_u64 v[218:219], s[38:39], 0, v[138:139]
	s_add_i32 m0, s37, 0xc000
	ds_read_b128 v[184:187], v155
	ds_read_b128 v[188:191], v155 offset:1024
	ds_read_b128 v[192:195], v155 offset:2048
	ds_read_b128 v[196:199], v155 offset:3072
	ds_read_b128 v[200:203], v155 offset:4096
	ds_read_b128 v[204:207], v155 offset:5120
	ds_read_b128 v[208:211], v155 offset:6144
	ds_read_b128 v[212:215], v155 offset:7168
	global_load_lds_dwordx4 v[218:219], off
	v_lshl_add_u64 v[218:219], s[38:39], 0, v[140:141]
	s_add_i32 m0, s37, 0xe000
	s_nop 0
	global_load_lds_dwordx4 v[218:219], off
	s_waitcnt vmcnt(8)
	s_waitcnt lgkmcnt(0)
	s_setprio 1
	s_barrier
	v_mfma_f32_16x16x32_bf16 v[126:129], v[146:149], v[184:187], v[126:129]
	v_mfma_f32_16x16x32_bf16 v[118:121], v[160:163], v[184:187], v[118:121]
	v_mfma_f32_16x16x32_bf16 v[110:113], v[146:149], v[192:195], v[110:113]
	v_mfma_f32_16x16x32_bf16 v[102:105], v[160:163], v[192:195], v[102:105]
	v_mfma_f32_16x16x32_bf16 v[94:97], v[146:149], v[200:203], v[94:97]
	v_mfma_f32_16x16x32_bf16 v[86:89], v[160:163], v[200:203], v[86:89]
	v_mfma_f32_16x16x32_bf16 v[78:81], v[146:149], v[208:211], v[78:81]
	v_mfma_f32_16x16x32_bf16 v[70:73], v[160:163], v[208:211], v[70:73]
	v_mfma_f32_16x16x32_bf16 v[126:129], v[156:159], v[188:191], v[126:129]
	v_mfma_f32_16x16x32_bf16 v[118:121], v[164:167], v[188:191], v[118:121]
	v_mfma_f32_16x16x32_bf16 v[110:113], v[156:159], v[196:199], v[110:113]
	v_mfma_f32_16x16x32_bf16 v[102:105], v[164:167], v[196:199], v[102:105]
	v_mfma_f32_16x16x32_bf16 v[94:97], v[156:159], v[204:207], v[94:97]
	v_mfma_f32_16x16x32_bf16 v[86:89], v[164:167], v[204:207], v[86:89]
	v_mfma_f32_16x16x32_bf16 v[78:81], v[156:159], v[212:215], v[78:81]
	v_mfma_f32_16x16x32_bf16 v[70:73], v[164:167], v[212:215], v[70:73]
	s_setprio 0
	s_setprio 1
	v_mfma_f32_16x16x32_bf16 v[122:125], v[168:171], v[184:187], v[122:125]
	v_mfma_f32_16x16x32_bf16 v[114:117], v[176:179], v[184:187], v[114:117]
	v_mfma_f32_16x16x32_bf16 v[106:109], v[168:171], v[192:195], v[106:109]
	v_mfma_f32_16x16x32_bf16 v[98:101], v[176:179], v[192:195], v[98:101]
	v_mfma_f32_16x16x32_bf16 v[90:93], v[168:171], v[200:203], v[90:93]
	v_mfma_f32_16x16x32_bf16 v[82:85], v[176:179], v[200:203], v[82:85]
	v_mfma_f32_16x16x32_bf16 v[74:77], v[168:171], v[208:211], v[74:77]
	v_mfma_f32_16x16x32_bf16 v[66:69], v[176:179], v[208:211], v[66:69]
	v_mfma_f32_16x16x32_bf16 v[122:125], v[172:175], v[188:191], v[122:125]
	v_mfma_f32_16x16x32_bf16 v[114:117], v[180:183], v[188:191], v[114:117]
	v_mfma_f32_16x16x32_bf16 v[106:109], v[172:175], v[196:199], v[106:109]
	v_mfma_f32_16x16x32_bf16 v[98:101], v[180:183], v[196:199], v[98:101]
	v_mfma_f32_16x16x32_bf16 v[90:93], v[172:175], v[204:207], v[90:93]
	v_mfma_f32_16x16x32_bf16 v[82:85], v[180:183], v[204:207], v[82:85]
	v_mfma_f32_16x16x32_bf16 v[74:77], v[172:175], v[212:215], v[74:77]
	v_mfma_f32_16x16x32_bf16 v[66:69], v[180:183], v[212:215], v[66:69]
	s_barrier
	s_setprio 0
	s_add_i32 s58, s51, s33
	v_lshl_add_u64 v[218:219], s[34:35], 0, v[134:135]
	s_mov_b32 m0, s58
	ds_read_b128 v[184:187], v155 offset:16384
	ds_read_b128 v[188:191], v155 offset:17408
	ds_read_b128 v[192:195], v155 offset:18432
	ds_read_b128 v[196:199], v155 offset:19456
	ds_read_b128 v[200:203], v155 offset:20480
	ds_read_b128 v[204:207], v155 offset:21504
	ds_read_b128 v[208:211], v155 offset:22528
	ds_read_b128 v[212:215], v155 offset:23552
	global_load_lds_dwordx4 v[218:219], off
	s_add_i32 m0, s58, 0x2000
	s_add_u32 s58, s34, 0x80000
	v_lshl_add_u64 v[220:221], s[34:35], 0, v[130:131]
	s_addc_u32 s59, s35, 0
	s_add_i32 s60, s52, s33
	global_load_lds_dwordx4 v[220:221], off
	v_lshl_add_u64 v[222:223], s[58:59], 0, v[134:135]
	s_mov_b32 m0, s60
	v_lshl_add_u64 v[224:225], s[40:41], 0, v[132:133]
	global_load_lds_dwordx4 v[222:223], off
	v_lshl_add_u64 v[222:223], s[58:59], 0, v[130:131]
	s_add_i32 m0, s60, 0x2000
	s_nop 0
	global_load_lds_dwordx4 v[222:223], off
	v_lshl_add_u64 v[222:223], s[40:41], 0, v[136:137]
	s_mov_b32 m0, s37
	s_nop 0
	global_load_lds_dwordx4 v[222:223], off
	s_mov_b32 m0, s44
	s_nop 0
	global_load_lds_dwordx4 v[224:225], off
	s_waitcnt vmcnt(8)
	s_waitcnt lgkmcnt(0)
	s_setprio 1
	s_barrier
	v_mfma_f32_16x16x32_bf16 v[62:65], v[146:149], v[184:187], v[62:65]
	v_mfma_f32_16x16x32_bf16 v[54:57], v[160:163], v[184:187], v[54:57]
	v_mfma_f32_16x16x32_bf16 v[46:49], v[146:149], v[192:195], v[46:49]
	v_mfma_f32_16x16x32_bf16 v[38:41], v[160:163], v[192:195], v[38:41]
	v_mfma_f32_16x16x32_bf16 v[30:33], v[146:149], v[200:203], v[30:33]
	v_mfma_f32_16x16x32_bf16 v[22:25], v[160:163], v[200:203], v[22:25]
	v_mfma_f32_16x16x32_bf16 v[14:17], v[146:149], v[208:211], v[14:17]
	v_mfma_f32_16x16x32_bf16 v[6:9], v[160:163], v[208:211], v[6:9]
	v_mfma_f32_16x16x32_bf16 v[62:65], v[156:159], v[188:191], v[62:65]
	v_mfma_f32_16x16x32_bf16 v[54:57], v[164:167], v[188:191], v[54:57]
	v_mfma_f32_16x16x32_bf16 v[46:49], v[156:159], v[196:199], v[46:49]
	v_mfma_f32_16x16x32_bf16 v[38:41], v[164:167], v[196:199], v[38:41]
	v_mfma_f32_16x16x32_bf16 v[30:33], v[156:159], v[204:207], v[30:33]
	v_mfma_f32_16x16x32_bf16 v[22:25], v[164:167], v[204:207], v[22:25]
	v_mfma_f32_16x16x32_bf16 v[14:17], v[156:159], v[212:215], v[14:17]
	v_mfma_f32_16x16x32_bf16 v[6:9], v[164:167], v[212:215], v[6:9]
	s_setprio 0
	s_setprio 1
	v_mfma_f32_16x16x32_bf16 v[58:61], v[168:171], v[184:187], v[58:61]
	v_mfma_f32_16x16x32_bf16 v[50:53], v[176:179], v[184:187], v[50:53]
	v_mfma_f32_16x16x32_bf16 v[42:45], v[168:171], v[192:195], v[42:45]
	v_mfma_f32_16x16x32_bf16 v[34:37], v[176:179], v[192:195], v[34:37]
	v_mfma_f32_16x16x32_bf16 v[26:29], v[168:171], v[200:203], v[26:29]
	v_mfma_f32_16x16x32_bf16 v[18:21], v[176:179], v[200:203], v[18:21]
	v_mfma_f32_16x16x32_bf16 v[10:13], v[168:171], v[208:211], v[10:13]
	v_mfma_f32_16x16x32_bf16 v[2:5], v[176:179], v[208:211], v[2:5]
	v_mfma_f32_16x16x32_bf16 v[58:61], v[172:175], v[188:191], v[58:61]
	v_mfma_f32_16x16x32_bf16 v[50:53], v[180:183], v[188:191], v[50:53]
	v_mfma_f32_16x16x32_bf16 v[42:45], v[172:175], v[196:199], v[42:45]
	v_mfma_f32_16x16x32_bf16 v[34:37], v[180:183], v[196:199], v[34:37]
	v_mfma_f32_16x16x32_bf16 v[26:29], v[172:175], v[204:207], v[26:29]
	v_mfma_f32_16x16x32_bf16 v[18:21], v[180:183], v[204:207], v[18:21]
	v_mfma_f32_16x16x32_bf16 v[10:13], v[172:175], v[212:215], v[10:13]
	v_mfma_f32_16x16x32_bf16 v[2:5], v[180:183], v[212:215], v[2:5]
	s_barrier
	s_setprio 0
	s_add_i32 s58, 0, 0x18000
	s_add_i32 s59, 0, 0x1c000
	v_add_u32_e32 v164, s58, v151
	v_add_u32_e32 v180, s59, v151
	ds_read_b128 v[146:149], v164
	ds_read_b128 v[156:159], v164 offset:1024
	ds_read_b128 v[160:163], v164 offset:2048
	ds_read_b128 v[164:167], v164 offset:3072
	ds_read_b128 v[168:171], v180
	ds_read_b128 v[172:175], v180 offset:1024
	ds_read_b128 v[176:179], v180 offset:2048
	ds_read_b128 v[180:183], v180 offset:3072
	s_add_u32 s40, s40, 0x80000
	s_addc_u32 s41, s41, 0
	s_mov_b32 m0, s45
	v_lshl_add_u64 v[226:227], s[40:41], 0, v[136:137]
	ds_read_b128 v[184:187], v155 offset:32768
	ds_read_b128 v[188:191], v155 offset:33792
	ds_read_b128 v[192:195], v155 offset:34816
	ds_read_b128 v[196:199], v155 offset:35840
	ds_read_b128 v[200:203], v155 offset:36864
	ds_read_b128 v[204:207], v155 offset:37888
	ds_read_b128 v[208:211], v155 offset:38912
	ds_read_b128 v[212:215], v155 offset:39936
	global_load_lds_dwordx4 v[226:227], off
	v_lshl_add_u64 v[226:227], s[40:41], 0, v[132:133]
	s_mov_b32 m0, s46
	s_nop 0
	global_load_lds_dwordx4 v[226:227], off
	s_waitcnt vmcnt(8)
	s_waitcnt lgkmcnt(0)
	s_setprio 1
	s_barrier
	v_mfma_f32_16x16x32_bf16 v[126:129], v[146:149], v[184:187], v[126:129]
	v_mfma_f32_16x16x32_bf16 v[118:121], v[160:163], v[184:187], v[118:121]
	v_mfma_f32_16x16x32_bf16 v[110:113], v[146:149], v[192:195], v[110:113]
	v_mfma_f32_16x16x32_bf16 v[102:105], v[160:163], v[192:195], v[102:105]
	v_mfma_f32_16x16x32_bf16 v[94:97], v[146:149], v[200:203], v[94:97]
	v_mfma_f32_16x16x32_bf16 v[86:89], v[160:163], v[200:203], v[86:89]
	v_mfma_f32_16x16x32_bf16 v[78:81], v[146:149], v[208:211], v[78:81]
	v_mfma_f32_16x16x32_bf16 v[70:73], v[160:163], v[208:211], v[70:73]
	v_mfma_f32_16x16x32_bf16 v[126:129], v[156:159], v[188:191], v[126:129]
	v_mfma_f32_16x16x32_bf16 v[118:121], v[164:167], v[188:191], v[118:121]
	v_mfma_f32_16x16x32_bf16 v[110:113], v[156:159], v[196:199], v[110:113]
	v_mfma_f32_16x16x32_bf16 v[102:105], v[164:167], v[196:199], v[102:105]
	v_mfma_f32_16x16x32_bf16 v[94:97], v[156:159], v[204:207], v[94:97]
	v_mfma_f32_16x16x32_bf16 v[86:89], v[164:167], v[204:207], v[86:89]
	v_mfma_f32_16x16x32_bf16 v[78:81], v[156:159], v[212:215], v[78:81]
	v_mfma_f32_16x16x32_bf16 v[70:73], v[164:167], v[212:215], v[70:73]
	s_setprio 0
	s_setprio 1
	v_mfma_f32_16x16x32_bf16 v[122:125], v[168:171], v[184:187], v[122:125]
	v_mfma_f32_16x16x32_bf16 v[114:117], v[176:179], v[184:187], v[114:117]
	v_mfma_f32_16x16x32_bf16 v[106:109], v[168:171], v[192:195], v[106:109]
	v_mfma_f32_16x16x32_bf16 v[98:101], v[176:179], v[192:195], v[98:101]
	v_mfma_f32_16x16x32_bf16 v[90:93], v[168:171], v[200:203], v[90:93]
	v_mfma_f32_16x16x32_bf16 v[82:85], v[176:179], v[200:203], v[82:85]
	v_mfma_f32_16x16x32_bf16 v[74:77], v[168:171], v[208:211], v[74:77]
	v_mfma_f32_16x16x32_bf16 v[66:69], v[176:179], v[208:211], v[66:69]
	v_mfma_f32_16x16x32_bf16 v[122:125], v[172:175], v[188:191], v[122:125]
	v_mfma_f32_16x16x32_bf16 v[114:117], v[180:183], v[188:191], v[114:117]
	v_mfma_f32_16x16x32_bf16 v[106:109], v[172:175], v[196:199], v[106:109]
	v_mfma_f32_16x16x32_bf16 v[98:101], v[180:183], v[196:199], v[98:101]
	v_mfma_f32_16x16x32_bf16 v[90:93], v[172:175], v[204:207], v[90:93]
	v_mfma_f32_16x16x32_bf16 v[82:85], v[180:183], v[204:207], v[82:85]
	v_mfma_f32_16x16x32_bf16 v[74:77], v[172:175], v[212:215], v[74:77]
	v_mfma_f32_16x16x32_bf16 v[66:69], v[180:183], v[212:215], v[66:69]
	s_barrier
	s_setprio 0
	s_add_i32 s40, s58, s33
	v_lshl_add_u64 v[218:219], v[218:219], 0, s[8:9]
	s_mov_b32 m0, s40
	ds_read_b128 v[184:187], v155 offset:49152
	ds_read_b128 v[188:191], v155 offset:50176
	ds_read_b128 v[192:195], v155 offset:51200
	ds_read_b128 v[196:199], v155 offset:52224
	ds_read_b128 v[200:203], v155 offset:53248
	ds_read_b128 v[204:207], v155 offset:54272
	ds_read_b128 v[208:211], v155 offset:55296
	ds_read_b128 v[212:215], v155 offset:56320
	global_load_lds_dwordx4 v[218:219], off
	s_add_i32 m0, s40, 0x2000
	s_add_u32 s34, s34, 0x80080
	v_lshl_add_u64 v[218:219], v[220:221], 0, s[8:9]
	s_addc_u32 s35, s35, 0
	s_add_i32 s40, s59, s33
	global_load_lds_dwordx4 v[218:219], off
	v_lshl_add_u64 v[218:219], s[34:35], 0, v[134:135]
	s_mov_b32 m0, s40
	s_nop 0
	global_load_lds_dwordx4 v[218:219], off
	v_lshl_add_u64 v[218:219], s[34:35], 0, v[130:131]
	s_add_i32 m0, s40, 0x2000
	s_nop 0
	global_load_lds_dwordx4 v[218:219], off
	v_lshl_add_u64 v[218:219], v[222:223], 0, s[8:9]
	s_mov_b32 m0, s48
	s_nop 0
	global_load_lds_dwordx4 v[218:219], off
	v_lshl_add_u64 v[218:219], v[224:225], 0, s[8:9]
	s_mov_b32 m0, s49
	s_nop 0
	global_load_lds_dwordx4 v[218:219], off
	s_waitcnt vmcnt(8)
	s_waitcnt lgkmcnt(0)
	s_setprio 1
	s_barrier
	v_mfma_f32_16x16x32_bf16 v[62:65], v[146:149], v[184:187], v[62:65]
	v_mfma_f32_16x16x32_bf16 v[54:57], v[160:163], v[184:187], v[54:57]
	v_mfma_f32_16x16x32_bf16 v[46:49], v[146:149], v[192:195], v[46:49]
	v_mfma_f32_16x16x32_bf16 v[38:41], v[160:163], v[192:195], v[38:41]
	v_mfma_f32_16x16x32_bf16 v[30:33], v[146:149], v[200:203], v[30:33]
	v_mfma_f32_16x16x32_bf16 v[22:25], v[160:163], v[200:203], v[22:25]
	v_mfma_f32_16x16x32_bf16 v[14:17], v[146:149], v[208:211], v[14:17]
	v_mfma_f32_16x16x32_bf16 v[6:9], v[160:163], v[208:211], v[6:9]
	v_mfma_f32_16x16x32_bf16 v[62:65], v[156:159], v[188:191], v[62:65]
	v_mfma_f32_16x16x32_bf16 v[54:57], v[164:167], v[188:191], v[54:57]
	v_mfma_f32_16x16x32_bf16 v[46:49], v[156:159], v[196:199], v[46:49]
	v_mfma_f32_16x16x32_bf16 v[38:41], v[164:167], v[196:199], v[38:41]
	v_mfma_f32_16x16x32_bf16 v[30:33], v[156:159], v[204:207], v[30:33]
	v_mfma_f32_16x16x32_bf16 v[22:25], v[164:167], v[204:207], v[22:25]
	v_mfma_f32_16x16x32_bf16 v[14:17], v[156:159], v[212:215], v[14:17]
	v_mfma_f32_16x16x32_bf16 v[6:9], v[164:167], v[212:215], v[6:9]
	s_setprio 0
	s_setprio 1
	v_mfma_f32_16x16x32_bf16 v[58:61], v[168:171], v[184:187], v[58:61]
	v_mfma_f32_16x16x32_bf16 v[50:53], v[176:179], v[184:187], v[50:53]
	v_mfma_f32_16x16x32_bf16 v[42:45], v[168:171], v[192:195], v[42:45]
	v_mfma_f32_16x16x32_bf16 v[34:37], v[176:179], v[192:195], v[34:37]
	v_mfma_f32_16x16x32_bf16 v[26:29], v[168:171], v[200:203], v[26:29]
	v_mfma_f32_16x16x32_bf16 v[18:21], v[176:179], v[200:203], v[18:21]
	v_mfma_f32_16x16x32_bf16 v[10:13], v[168:171], v[208:211], v[10:13]
	v_mfma_f32_16x16x32_bf16 v[2:5], v[176:179], v[208:211], v[2:5]
	v_mfma_f32_16x16x32_bf16 v[58:61], v[172:175], v[188:191], v[58:61]
	v_mfma_f32_16x16x32_bf16 v[50:53], v[180:183], v[188:191], v[50:53]
	v_mfma_f32_16x16x32_bf16 v[42:45], v[172:175], v[196:199], v[42:45]
	v_mfma_f32_16x16x32_bf16 v[34:37], v[180:183], v[196:199], v[34:37]
	v_mfma_f32_16x16x32_bf16 v[26:29], v[172:175], v[204:207], v[26:29]
	v_mfma_f32_16x16x32_bf16 v[18:21], v[180:183], v[204:207], v[18:21]
	v_mfma_f32_16x16x32_bf16 v[10:13], v[172:175], v[212:215], v[10:13]
	v_mfma_f32_16x16x32_bf16 v[2:5], v[180:183], v[212:215], v[2:5]
	s_barrier
	s_setprio 0
	s_add_i32 s57, s57, 2
	s_add_u32 s38, s38, 0x100
	s_addc_u32 s39, s39, 0
	s_add_u32 s55, s55, 0x100
	s_addc_u32 s56, s56, 0
	s_cmp_gt_u32 s57, 29
	s_cbranch_scc0 .LBB0_3835
	s_and_b64 vcc, exec, s[12:13]
	s_cbranch_vccz .LBB0_3838
	s_barrier

.LBB0_3930:
	ds_read_b128 v[144:147], v155
	ds_read_b128 v[148:151], v155 offset:1024
	ds_read_b128 v[158:161], v155 offset:2048
	ds_read_b128 v[162:165], v155 offset:3072
	ds_read_b128 v[166:169], v156
	ds_read_b128 v[170:173], v156 offset:1024
	ds_read_b128 v[174:177], v156 offset:2048
	ds_read_b128 v[178:181], v156 offset:3072
	s_add_u32 s20, s18, 0xffea0080
	s_addc_u32 s21, s19, -1
	s_cmpk_eq_i32 s45, 0x54
	s_cselect_b32 s23, s5, s21
	s_cselect_b32 s22, s4, s20
	s_cselect_b32 s21, s17, s1
	s_cselect_b32 s20, s16, s0
	v_lshl_add_u64 v[214:215], s[18:19], 0, v[136:137]
	s_add_i32 m0, s30, 0xc000
	ds_read_b128 v[182:185], v157
	ds_read_b128 v[186:189], v157 offset:1024
	ds_read_b128 v[190:193], v157 offset:2048
	ds_read_b128 v[194:197], v157 offset:3072
	ds_read_b128 v[198:201], v157 offset:4096
	ds_read_b128 v[202:205], v157 offset:5120
	ds_read_b128 v[206:209], v157 offset:6144
	ds_read_b128 v[210:213], v157 offset:7168
	global_load_lds_dwordx4 v[214:215], off
	v_lshl_add_u64 v[214:215], s[18:19], 0, v[138:139]
	s_add_i32 m0, s30, 0xe000
	s_nop 0
	global_load_lds_dwordx4 v[214:215], off
	s_waitcnt vmcnt(8)
	s_waitcnt lgkmcnt(0)
	s_setprio 1
	s_barrier
	v_mfma_f32_16x16x32_bf16 v[124:127], v[144:147], v[182:185], v[124:127]
	v_mfma_f32_16x16x32_bf16 v[120:123], v[158:161], v[182:185], v[120:123]
	v_mfma_f32_16x16x32_bf16 v[116:119], v[144:147], v[190:193], v[116:119]
	v_mfma_f32_16x16x32_bf16 v[112:115], v[158:161], v[190:193], v[112:115]
	v_mfma_f32_16x16x32_bf16 v[92:95], v[144:147], v[198:201], v[92:95]
	v_mfma_f32_16x16x32_bf16 v[88:91], v[158:161], v[198:201], v[88:91]
	v_mfma_f32_16x16x32_bf16 v[84:87], v[144:147], v[206:209], v[84:87]
	v_mfma_f32_16x16x32_bf16 v[80:83], v[158:161], v[206:209], v[80:83]
	v_mfma_f32_16x16x32_bf16 v[124:127], v[148:151], v[186:189], v[124:127]
	v_mfma_f32_16x16x32_bf16 v[120:123], v[162:165], v[186:189], v[120:123]
	v_mfma_f32_16x16x32_bf16 v[116:119], v[148:151], v[194:197], v[116:119]
	v_mfma_f32_16x16x32_bf16 v[112:115], v[162:165], v[194:197], v[112:115]
	v_mfma_f32_16x16x32_bf16 v[92:95], v[148:151], v[202:205], v[92:95]
	v_mfma_f32_16x16x32_bf16 v[88:91], v[162:165], v[202:205], v[88:91]
	v_mfma_f32_16x16x32_bf16 v[84:87], v[148:151], v[210:213], v[84:87]
	v_mfma_f32_16x16x32_bf16 v[80:83], v[162:165], v[210:213], v[80:83]
	s_setprio 0
	s_setprio 1
	v_mfma_f32_16x16x32_bf16 v[108:111], v[166:169], v[182:185], v[108:111]
	v_mfma_f32_16x16x32_bf16 v[104:107], v[174:177], v[182:185], v[104:107]
	v_mfma_f32_16x16x32_bf16 v[100:103], v[166:169], v[190:193], v[100:103]
	v_mfma_f32_16x16x32_bf16 v[96:99], v[174:177], v[190:193], v[96:99]
	v_mfma_f32_16x16x32_bf16 v[76:79], v[166:169], v[198:201], v[76:79]
	v_mfma_f32_16x16x32_bf16 v[72:75], v[174:177], v[198:201], v[72:75]
	v_mfma_f32_16x16x32_bf16 v[68:71], v[166:169], v[206:209], v[68:71]
	v_mfma_f32_16x16x32_bf16 v[64:67], v[174:177], v[206:209], v[64:67]
	v_mfma_f32_16x16x32_bf16 v[108:111], v[170:173], v[186:189], v[108:111]
	v_mfma_f32_16x16x32_bf16 v[104:107], v[178:181], v[186:189], v[104:107]
	v_mfma_f32_16x16x32_bf16 v[100:103], v[170:173], v[194:197], v[100:103]
	v_mfma_f32_16x16x32_bf16 v[96:99], v[178:181], v[194:197], v[96:99]
	v_mfma_f32_16x16x32_bf16 v[76:79], v[170:173], v[202:205], v[76:79]
	v_mfma_f32_16x16x32_bf16 v[72:75], v[178:181], v[202:205], v[72:75]
	v_mfma_f32_16x16x32_bf16 v[68:71], v[170:173], v[210:213], v[68:71]
	v_mfma_f32_16x16x32_bf16 v[64:67], v[178:181], v[210:213], v[64:67]
	s_barrier
	s_setprio 0
	s_add_i32 s46, s39, s27
	v_lshl_add_u64 v[214:215], s[20:21], 0, v[130:131]
	s_mov_b32 m0, s46
	ds_read_b128 v[182:185], v157 offset:16384
	ds_read_b128 v[186:189], v157 offset:17408
	ds_read_b128 v[190:193], v157 offset:18432
	ds_read_b128 v[194:197], v157 offset:19456
	ds_read_b128 v[198:201], v157 offset:20480
	ds_read_b128 v[202:205], v157 offset:21504
	ds_read_b128 v[206:209], v157 offset:22528
	ds_read_b128 v[210:213], v157 offset:23552
	global_load_lds_dwordx4 v[214:215], off
	s_add_i32 m0, s46, 0x2000
	s_add_u32 s46, s20, 0x160000
	v_lshl_add_u64 v[216:217], s[20:21], 0, v[134:135]
	s_addc_u32 s47, s21, 0
	s_add_i32 s48, s40, s27
	global_load_lds_dwordx4 v[216:217], off
	v_lshl_add_u64 v[218:219], s[46:47], 0, v[130:131]
	s_mov_b32 m0, s48
	v_lshl_add_u64 v[220:221], s[22:23], 0, v[132:133]
	global_load_lds_dwordx4 v[218:219], off
	v_lshl_add_u64 v[218:219], s[46:47], 0, v[134:135]
	s_add_i32 m0, s48, 0x2000
	s_nop 0
	global_load_lds_dwordx4 v[218:219], off
	v_lshl_add_u64 v[218:219], s[22:23], 0, v[128:129]
	s_mov_b32 m0, s30
	s_nop 0
	global_load_lds_dwordx4 v[218:219], off
	s_mov_b32 m0, s31
	s_nop 0
	global_load_lds_dwordx4 v[220:221], off
	s_waitcnt vmcnt(8)
	s_waitcnt lgkmcnt(0)
	s_setprio 1
	s_barrier
	v_mfma_f32_16x16x32_bf16 v[60:63], v[144:147], v[182:185], v[60:63]
	v_mfma_f32_16x16x32_bf16 v[56:59], v[158:161], v[182:185], v[56:59]
	v_mfma_f32_16x16x32_bf16 v[52:55], v[144:147], v[190:193], v[52:55]
	v_mfma_f32_16x16x32_bf16 v[48:51], v[158:161], v[190:193], v[48:51]
	v_mfma_f32_16x16x32_bf16 v[28:31], v[144:147], v[198:201], v[28:31]
	v_mfma_f32_16x16x32_bf16 v[24:27], v[158:161], v[198:201], v[24:27]
	v_mfma_f32_16x16x32_bf16 v[20:23], v[144:147], v[206:209], v[20:23]
	v_mfma_f32_16x16x32_bf16 v[16:19], v[158:161], v[206:209], v[16:19]
	v_mfma_f32_16x16x32_bf16 v[60:63], v[148:151], v[186:189], v[60:63]
	v_mfma_f32_16x16x32_bf16 v[56:59], v[162:165], v[186:189], v[56:59]
	v_mfma_f32_16x16x32_bf16 v[52:55], v[148:151], v[194:197], v[52:55]
	v_mfma_f32_16x16x32_bf16 v[48:51], v[162:165], v[194:197], v[48:51]
	v_mfma_f32_16x16x32_bf16 v[28:31], v[148:151], v[202:205], v[28:31]
	v_mfma_f32_16x16x32_bf16 v[24:27], v[162:165], v[202:205], v[24:27]
	v_mfma_f32_16x16x32_bf16 v[20:23], v[148:151], v[210:213], v[20:23]
	v_mfma_f32_16x16x32_bf16 v[16:19], v[162:165], v[210:213], v[16:19]
	s_setprio 0
	s_setprio 1
	v_mfma_f32_16x16x32_bf16 v[44:47], v[166:169], v[182:185], v[44:47]
	v_mfma_f32_16x16x32_bf16 v[40:43], v[174:177], v[182:185], v[40:43]
	v_mfma_f32_16x16x32_bf16 v[36:39], v[166:169], v[190:193], v[36:39]
	v_mfma_f32_16x16x32_bf16 v[32:35], v[174:177], v[190:193], v[32:35]
	v_mfma_f32_16x16x32_bf16 v[12:15], v[166:169], v[198:201], v[12:15]
	v_mfma_f32_16x16x32_bf16 v[8:11], v[174:177], v[198:201], v[8:11]
	v_mfma_f32_16x16x32_bf16 v[4:7], v[166:169], v[206:209], v[4:7]
	v_mfma_f32_16x16x32_bf16 v[0:3], v[174:177], v[206:209], v[0:3]
	v_mfma_f32_16x16x32_bf16 v[44:47], v[170:173], v[186:189], v[44:47]
	v_mfma_f32_16x16x32_bf16 v[40:43], v[178:181], v[186:189], v[40:43]
	v_mfma_f32_16x16x32_bf16 v[36:39], v[170:173], v[194:197], v[36:39]
	v_mfma_f32_16x16x32_bf16 v[32:35], v[178:181], v[194:197], v[32:35]
	v_mfma_f32_16x16x32_bf16 v[12:15], v[170:173], v[202:205], v[12:15]
	v_mfma_f32_16x16x32_bf16 v[8:11], v[178:181], v[202:205], v[8:11]
	v_mfma_f32_16x16x32_bf16 v[4:7], v[170:173], v[210:213], v[4:7]
	v_mfma_f32_16x16x32_bf16 v[0:3], v[178:181], v[210:213], v[0:3]
	s_barrier
	s_setprio 0
	s_add_i32 s46, 0, 0x18000
	s_add_i32 s47, 0, 0x1c000
	v_add_u32_e32 v162, s46, v153
	v_add_u32_e32 v178, s47, v153
	ds_read_b128 v[144:147], v162
	ds_read_b128 v[148:151], v162 offset:1024
	ds_read_b128 v[158:161], v162 offset:2048
	ds_read_b128 v[162:165], v162 offset:3072
	ds_read_b128 v[166:169], v178
	ds_read_b128 v[170:173], v178 offset:1024
	ds_read_b128 v[174:177], v178 offset:2048
	ds_read_b128 v[178:181], v178 offset:3072
	s_add_u32 s22, s22, 0x160000
	s_addc_u32 s23, s23, 0
	s_mov_b32 m0, s33
	v_lshl_add_u64 v[222:223], s[22:23], 0, v[128:129]
	ds_read_b128 v[182:185], v157 offset:32768
	ds_read_b128 v[186:189], v157 offset:33792
	ds_read_b128 v[190:193], v157 offset:34816
	ds_read_b128 v[194:197], v157 offset:35840
	ds_read_b128 v[198:201], v157 offset:36864
	ds_read_b128 v[202:205], v157 offset:37888
	ds_read_b128 v[206:209], v157 offset:38912
	ds_read_b128 v[210:213], v157 offset:39936
	global_load_lds_dwordx4 v[222:223], off
	v_lshl_add_u64 v[222:223], s[22:23], 0, v[132:133]
	s_mov_b32 m0, s34
	s_nop 0
	global_load_lds_dwordx4 v[222:223], off
	s_waitcnt vmcnt(8)
	s_waitcnt lgkmcnt(0)
	s_setprio 1
	s_barrier
	v_mfma_f32_16x16x32_bf16 v[124:127], v[144:147], v[182:185], v[124:127]
	v_mfma_f32_16x16x32_bf16 v[120:123], v[158:161], v[182:185], v[120:123]
	v_mfma_f32_16x16x32_bf16 v[116:119], v[144:147], v[190:193], v[116:119]
	v_mfma_f32_16x16x32_bf16 v[112:115], v[158:161], v[190:193], v[112:115]
	v_mfma_f32_16x16x32_bf16 v[92:95], v[144:147], v[198:201], v[92:95]
	v_mfma_f32_16x16x32_bf16 v[88:91], v[158:161], v[198:201], v[88:91]
	v_mfma_f32_16x16x32_bf16 v[84:87], v[144:147], v[206:209], v[84:87]
	v_mfma_f32_16x16x32_bf16 v[80:83], v[158:161], v[206:209], v[80:83]
	v_mfma_f32_16x16x32_bf16 v[124:127], v[148:151], v[186:189], v[124:127]
	v_mfma_f32_16x16x32_bf16 v[120:123], v[162:165], v[186:189], v[120:123]
	v_mfma_f32_16x16x32_bf16 v[116:119], v[148:151], v[194:197], v[116:119]
	v_mfma_f32_16x16x32_bf16 v[112:115], v[162:165], v[194:197], v[112:115]
	v_mfma_f32_16x16x32_bf16 v[92:95], v[148:151], v[202:205], v[92:95]
	v_mfma_f32_16x16x32_bf16 v[88:91], v[162:165], v[202:205], v[88:91]
	v_mfma_f32_16x16x32_bf16 v[84:87], v[148:151], v[210:213], v[84:87]
	v_mfma_f32_16x16x32_bf16 v[80:83], v[162:165], v[210:213], v[80:83]
	s_setprio 0
	s_setprio 1
	v_mfma_f32_16x16x32_bf16 v[108:111], v[166:169], v[182:185], v[108:111]
	v_mfma_f32_16x16x32_bf16 v[104:107], v[174:177], v[182:185], v[104:107]
	v_mfma_f32_16x16x32_bf16 v[100:103], v[166:169], v[190:193], v[100:103]
	v_mfma_f32_16x16x32_bf16 v[96:99], v[174:177], v[190:193], v[96:99]
	v_mfma_f32_16x16x32_bf16 v[76:79], v[166:169], v[198:201], v[76:79]
	v_mfma_f32_16x16x32_bf16 v[72:75], v[174:177], v[198:201], v[72:75]
	v_mfma_f32_16x16x32_bf16 v[68:71], v[166:169], v[206:209], v[68:71]
	v_mfma_f32_16x16x32_bf16 v[64:67], v[174:177], v[206:209], v[64:67]
	v_mfma_f32_16x16x32_bf16 v[108:111], v[170:173], v[186:189], v[108:111]
	v_mfma_f32_16x16x32_bf16 v[104:107], v[178:181], v[186:189], v[104:107]
	v_mfma_f32_16x16x32_bf16 v[100:103], v[170:173], v[194:197], v[100:103]
	v_mfma_f32_16x16x32_bf16 v[96:99], v[178:181], v[194:197], v[96:99]
	v_mfma_f32_16x16x32_bf16 v[76:79], v[170:173], v[202:205], v[76:79]
	v_mfma_f32_16x16x32_bf16 v[72:75], v[178:181], v[202:205], v[72:75]
	v_mfma_f32_16x16x32_bf16 v[68:71], v[170:173], v[210:213], v[68:71]
	v_mfma_f32_16x16x32_bf16 v[64:67], v[178:181], v[210:213], v[64:67]
	s_barrier
	s_setprio 0
	s_add_i32 s22, s46, s27
	v_lshl_add_u64 v[214:215], v[214:215], 0, s[12:13]
	s_mov_b32 m0, s22
	ds_read_b128 v[182:185], v157 offset:49152
	ds_read_b128 v[186:189], v157 offset:50176
	ds_read_b128 v[190:193], v157 offset:51200
	ds_read_b128 v[194:197], v157 offset:52224
	ds_read_b128 v[198:201], v157 offset:53248
	ds_read_b128 v[202:205], v157 offset:54272
	ds_read_b128 v[206:209], v157 offset:55296
	ds_read_b128 v[210:213], v157 offset:56320
	global_load_lds_dwordx4 v[214:215], off
	s_add_i32 m0, s22, 0x2000
	s_add_u32 s20, s20, 0x160080
	v_lshl_add_u64 v[214:215], v[216:217], 0, s[12:13]
	s_addc_u32 s21, s21, 0
	s_add_i32 s22, s47, s27
	global_load_lds_dwordx4 v[214:215], off
	v_lshl_add_u64 v[214:215], s[20:21], 0, v[130:131]
	s_mov_b32 m0, s22
	s_nop 0
	global_load_lds_dwordx4 v[214:215], off
	v_lshl_add_u64 v[214:215], s[20:21], 0, v[134:135]
	s_add_i32 m0, s22, 0x2000
	s_nop 0
	global_load_lds_dwordx4 v[214:215], off
	v_lshl_add_u64 v[214:215], v[218:219], 0, s[12:13]
	s_mov_b32 m0, s36
	s_nop 0
	global_load_lds_dwordx4 v[214:215], off
	v_lshl_add_u64 v[214:215], v[220:221], 0, s[12:13]
	s_mov_b32 m0, s37
	s_nop 0
	global_load_lds_dwordx4 v[214:215], off
	s_waitcnt vmcnt(8)
	s_waitcnt lgkmcnt(0)
	s_setprio 1
	s_barrier
	v_mfma_f32_16x16x32_bf16 v[60:63], v[144:147], v[182:185], v[60:63]
	v_mfma_f32_16x16x32_bf16 v[56:59], v[158:161], v[182:185], v[56:59]
	v_mfma_f32_16x16x32_bf16 v[52:55], v[144:147], v[190:193], v[52:55]
	v_mfma_f32_16x16x32_bf16 v[48:51], v[158:161], v[190:193], v[48:51]
	v_mfma_f32_16x16x32_bf16 v[28:31], v[144:147], v[198:201], v[28:31]
	v_mfma_f32_16x16x32_bf16 v[24:27], v[158:161], v[198:201], v[24:27]
	v_mfma_f32_16x16x32_bf16 v[20:23], v[144:147], v[206:209], v[20:23]
	v_mfma_f32_16x16x32_bf16 v[16:19], v[158:161], v[206:209], v[16:19]
	v_mfma_f32_16x16x32_bf16 v[60:63], v[148:151], v[186:189], v[60:63]
	v_mfma_f32_16x16x32_bf16 v[56:59], v[162:165], v[186:189], v[56:59]
	v_mfma_f32_16x16x32_bf16 v[52:55], v[148:151], v[194:197], v[52:55]
	v_mfma_f32_16x16x32_bf16 v[48:51], v[162:165], v[194:197], v[48:51]
	v_mfma_f32_16x16x32_bf16 v[28:31], v[148:151], v[202:205], v[28:31]
	v_mfma_f32_16x16x32_bf16 v[24:27], v[162:165], v[202:205], v[24:27]
	v_mfma_f32_16x16x32_bf16 v[20:23], v[148:151], v[210:213], v[20:23]
	v_mfma_f32_16x16x32_bf16 v[16:19], v[162:165], v[210:213], v[16:19]
	s_setprio 0
	s_setprio 1
	v_mfma_f32_16x16x32_bf16 v[44:47], v[166:169], v[182:185], v[44:47]
	v_mfma_f32_16x16x32_bf16 v[40:43], v[174:177], v[182:185], v[40:43]
	v_mfma_f32_16x16x32_bf16 v[36:39], v[166:169], v[190:193], v[36:39]
	v_mfma_f32_16x16x32_bf16 v[32:35], v[174:177], v[190:193], v[32:35]
	v_mfma_f32_16x16x32_bf16 v[12:15], v[166:169], v[198:201], v[12:15]
	v_mfma_f32_16x16x32_bf16 v[8:11], v[174:177], v[198:201], v[8:11]
	v_mfma_f32_16x16x32_bf16 v[4:7], v[166:169], v[206:209], v[4:7]
	v_mfma_f32_16x16x32_bf16 v[0:3], v[174:177], v[206:209], v[0:3]
	v_mfma_f32_16x16x32_bf16 v[44:47], v[170:173], v[186:189], v[44:47]
	v_mfma_f32_16x16x32_bf16 v[40:43], v[178:181], v[186:189], v[40:43]
	v_mfma_f32_16x16x32_bf16 v[36:39], v[170:173], v[194:197], v[36:39]
	v_mfma_f32_16x16x32_bf16 v[32:35], v[178:181], v[194:197], v[32:35]
	v_mfma_f32_16x16x32_bf16 v[12:15], v[170:173], v[202:205], v[12:15]
	v_mfma_f32_16x16x32_bf16 v[8:11], v[178:181], v[202:205], v[8:11]
	v_mfma_f32_16x16x32_bf16 v[4:7], v[170:173], v[210:213], v[4:7]
	v_mfma_f32_16x16x32_bf16 v[0:3], v[178:181], v[210:213], v[0:3]
	s_barrier
	s_setprio 0
	s_add_i32 s45, s45, 2
	s_add_u32 s18, s18, 0x100
	s_addc_u32 s19, s19, 0
	s_add_u32 s0, s0, 0x100
	s_addc_u32 s1, s1, 0
	s_cmpk_gt_u32 s45, 0x55
	s_cbranch_scc0 .LBB0_3930
	s_and_b64 vcc, exec, s[14:15]
	s_cbranch_vccz .LBB0_3933
	s_barrier
